# x-update: sample rows spread over all workgroups (wave gw%4==0 finishes sample row gw/4) + rs hoist + stage-2 batching (run 1)
# speedup vs baseline: 1.0221x; 1.0136x over previous
.LBB0_446:
	s_waitcnt lgkmcnt(0)
	v_cndmask_b32_e64 v0, 0, 1, s[24:25]
	v_cmp_ne_u32_e64 s[0:1], 1, v0
	s_andn2_b64 vcc, exec, s[24:25]
	s_nop 0
	v_writelane_b32 v235, s0, 52
	s_barrier
	s_nop 0
	v_writelane_b32 v235, s1, 53
	v_mbcnt_lo_u32_b32 v0, -1, 0
	v_mbcnt_hi_u32_b32 v0, -1, v0
	s_cbranch_vccnz .LBB0_465
	v_lshlrev_b32_e32 v2, 3, v0
	v_ashrrev_i32_e32 v3, 31, v2
	v_readlane_b32 s4, v235, 4
	v_lshlrev_b64 v[4:5], 1, v[2:3]
	v_lshlrev_b64 v[2:3], 2, v[2:3]
	v_readlane_b32 s5, v235, 5
	v_readlane_b32 s6, v235, 6
	v_readlane_b32 s7, v235, 7
	v_readlane_b32 s8, v235, 8
	v_readlane_b32 s9, v235, 9
	v_readlane_b32 s10, v235, 10
	v_readlane_b32 s11, v235, 11
	v_readlane_b32 s12, v235, 12
	v_readlane_b32 s13, v235, 13
	v_readlane_b32 s14, v235, 14
	v_readlane_b32 s15, v235, 15
	v_readlane_b32 s16, v235, 16
	v_readlane_b32 s17, v235, 17
	v_readlane_b32 s18, v235, 18
	v_readlane_b32 s19, v235, 19
	v_lshl_add_u64 v[60:61], s[86:87], 0, v[4:5]
	v_lshl_add_u64 v[62:63], s[90:91], 0, v[2:3]
	v_lshl_add_u64 v[64:65], s[54:55], 0, v[4:5]
	v_lshl_add_u64 v[66:67], s[14:15], 0, v[2:3]
	s_mov_b32 s1, 0
	v_cmp_eq_u32_e64 s[4:5], 0, v0
	s_mov_b64 s[6:7], 0x200000
	s_mov_b64 s[8:9], 0x200800
	s_mov_b64 s[10:11], 0x400000
	s_mov_b64 s[12:13], 0x400800
	s_mov_b64 s[14:15], 0x600000
	s_mov_b64 s[16:17], 0x600800
	s_mov_b64 s[18:19], 0x800000
	s_mov_b32 s48, 0x800000
	s_mov_b64 s[20:21], 0x800800
	s_mov_b64 s[22:23], 0xa00000
	s_mov_b64 s[24:25], 0xa00800
	s_mov_b64 s[26:27], 0xc00000
	s_mov_b64 s[28:29], 0xc00800
	s_mov_b64 s[34:35], 0xe00000
	s_mov_b64 s[36:37], 0xe00800
	v_mov_b32_e32 v104, 0
	v_mov_b32_e32 v105, 0x358637bd
	s_mov_b32 s40, s80
	v_mbcnt_lo_u32_b32 v176, -1, 0
	v_mbcnt_hi_u32_b32 v176, -1, v176
	v_readlane_b32 s98, v235, 49
	v_readlane_b32 s99, v235, 20
	v_readlane_b32 s100, v235, 14
	v_readlane_b32 s101, v235, 15
	s_nop 3
	s_lshr_b32 vcc_lo, s98, 3
	s_and_b32 vcc_hi, vcc_lo, 7
	s_lshr_b32 vcc_lo, vcc_lo, 3
	s_lshl_b32 vcc_lo, vcc_lo, 3
	s_add_i32 vcc_lo, vcc_lo, s99
	s_lshl_b32 s98, vcc_hi, 8
	s_add_i32 s98, s98, vcc_lo
	s_mov_b32 s99, s98
	v_mov_b32_e32 v183, s99
	v_lshlrev_b32_e32 v177, 4, v176
	s_lshl_b32 s99, s99, 11
	v_add_u32_e32 v177, s99, v177
	v_add_u32_e32 v178, 0x1800000, v177
	v_add_u32_e32 v179, 0x9e00000, v177
	v_lshlrev_b32_e32 v180, 5, v176
	global_load_dwordx4 v[128:131], v180, s[100:101]
	global_load_dwordx4 v[132:135], v180, s[100:101] offset:16
	global_load_dwordx4 v[136:139], v180, s[100:101] offset:2048
	global_load_dwordx4 v[140:143], v180, s[100:101] offset:2064
	v_mov_b32_e32 v182, 0x358637bd
	global_load_dwordx4 v[0:3], v178, s[78:79]
	global_load_dwordx4 v[4:7], v178, s[78:79] offset:1024
	global_load_dwordx4 v[8:11], v179, s[78:79]
	global_load_dwordx4 v[12:15], v179, s[78:79] offset:1024
	v_add_u32_e32 v178, 0x400000, v178
	v_add_u32_e32 v179, 0x400000, v179
	global_load_dwordx4 v[16:19], v178, s[78:79]
	global_load_dwordx4 v[20:23], v178, s[78:79] offset:1024
	global_load_dwordx4 v[24:27], v179, s[78:79]
	global_load_dwordx4 v[28:31], v179, s[78:79] offset:1024
	v_add_u32_e32 v178, 0x400000, v178
	v_add_u32_e32 v179, 0x400000, v179
	global_load_dwordx4 v[32:35], v178, s[78:79]
	global_load_dwordx4 v[36:39], v178, s[78:79] offset:1024
	global_load_dwordx4 v[40:43], v179, s[78:79]
	global_load_dwordx4 v[44:47], v179, s[78:79] offset:1024
	v_add_u32_e32 v178, 0x400000, v178
	v_add_u32_e32 v179, 0x400000, v179
	global_load_dwordx4 v[48:51], v178, s[78:79]
	global_load_dwordx4 v[52:55], v178, s[78:79] offset:1024
	global_load_dwordx4 v[56:59], v179, s[78:79]
	global_load_dwordx4 v[60:63], v179, s[78:79] offset:1024
	v_add_u32_e32 v178, 0x400000, v178
	v_add_u32_e32 v179, 0x400000, v179
	global_load_dwordx4 v[64:67], v178, s[78:79]
	global_load_dwordx4 v[68:71], v178, s[78:79] offset:1024
	global_load_dwordx4 v[72:75], v179, s[78:79]
	global_load_dwordx4 v[76:79], v179, s[78:79] offset:1024
	v_add_u32_e32 v178, 0x400000, v178
	v_add_u32_e32 v179, 0x400000, v179
	global_load_dwordx4 v[80:83], v178, s[78:79]
	global_load_dwordx4 v[84:87], v178, s[78:79] offset:1024
	global_load_dwordx4 v[88:91], v179, s[78:79]
	global_load_dwordx4 v[92:95], v179, s[78:79] offset:1024
	v_add_u32_e32 v178, 0x400000, v178
	v_add_u32_e32 v179, 0x400000, v179
	global_load_dwordx4 v[96:99], v178, s[78:79]
	global_load_dwordx4 v[100:103], v178, s[78:79] offset:1024
	global_load_dwordx4 v[104:107], v179, s[78:79]
	global_load_dwordx4 v[108:111], v179, s[78:79] offset:1024
	v_add_u32_e32 v178, 0x400000, v178
	v_add_u32_e32 v179, 0x400000, v179
	global_load_dwordx4 v[112:115], v178, s[78:79]
	global_load_dwordx4 v[116:119], v178, s[78:79] offset:1024
	global_load_dwordx4 v[120:123], v179, s[78:79]
	global_load_dwordx4 v[124:127], v179, s[78:79] offset:1024
	v_lshlrev_b32_e32 v237, 2, v183
	v_add_u32_e32 v237, 0x10000, v237
	v_mov_b32_e32 v179, s98
	s_waitcnt vmcnt(28)
	v_lshlrev_b32_e32 v144, 16, v0
	v_and_b32_e32 v145, 0xffff0000, v0
	v_lshlrev_b32_e32 v146, 16, v1
	v_and_b32_e32 v147, 0xffff0000, v1
	v_lshlrev_b32_e32 v148, 16, v2
	v_and_b32_e32 v149, 0xffff0000, v2
	v_lshlrev_b32_e32 v150, 16, v3
	v_and_b32_e32 v151, 0xffff0000, v3
	v_lshlrev_b32_e32 v152, 16, v4
	v_and_b32_e32 v153, 0xffff0000, v4
	v_lshlrev_b32_e32 v154, 16, v5
	v_and_b32_e32 v155, 0xffff0000, v5
	v_lshlrev_b32_e32 v156, 16, v6
	v_and_b32_e32 v157, 0xffff0000, v6
	v_lshlrev_b32_e32 v158, 16, v7
	v_and_b32_e32 v159, 0xffff0000, v7
	v_lshlrev_b32_e32 v160, 16, v8
	v_and_b32_e32 v161, 0xffff0000, v8
	v_lshlrev_b32_e32 v162, 16, v9
	v_and_b32_e32 v163, 0xffff0000, v9
	v_lshlrev_b32_e32 v164, 16, v10
	v_and_b32_e32 v165, 0xffff0000, v10
	v_lshlrev_b32_e32 v166, 16, v11
	v_and_b32_e32 v167, 0xffff0000, v11
	v_lshlrev_b32_e32 v168, 16, v12
	v_and_b32_e32 v169, 0xffff0000, v12
	v_lshlrev_b32_e32 v170, 16, v13
	v_and_b32_e32 v171, 0xffff0000, v13
	v_lshlrev_b32_e32 v172, 16, v14
	v_and_b32_e32 v173, 0xffff0000, v14
	v_lshlrev_b32_e32 v174, 16, v15
	v_and_b32_e32 v175, 0xffff0000, v15
	v_pk_mul_f32 v[252:253], v[160:161], v[160:161]
	v_pk_mul_f32 v[254:255], v[162:163], v[162:163]
	v_pk_fma_f32 v[252:253], v[164:165], v[164:165], v[252:253]
	v_pk_fma_f32 v[254:255], v[166:167], v[166:167], v[254:255]
	v_pk_fma_f32 v[252:253], v[168:169], v[168:169], v[252:253]
	v_pk_fma_f32 v[254:255], v[170:171], v[170:171], v[254:255]
	v_pk_fma_f32 v[252:253], v[172:173], v[172:173], v[252:253]
	v_pk_fma_f32 v[254:255], v[174:175], v[174:175], v[254:255]
	v_pk_add_f32 v[252:253], v[252:253], v[254:255]
	s_nop 0
	v_add_f32_e32 v183, v252, v253
	s_nop 1
	v_add_f32_dpp v183, v183, v183 quad_perm:[1,0,3,2] row_mask:0xf bank_mask:0xf bound_ctrl:1
	s_nop 1
	v_add_f32_dpp v183, v183, v183 quad_perm:[2,3,0,1] row_mask:0xf bank_mask:0xf bound_ctrl:1
	s_nop 1
	v_add_f32_dpp v183, v183, v183 row_half_mirror row_mask:0xf bank_mask:0xf bound_ctrl:1
	s_nop 1
	v_add_f32_dpp v183, v183, v183 row_mirror row_mask:0xf bank_mask:0xf bound_ctrl:1
	s_nop 1
	v_readlane_b32 s98, v183, 0
	v_readlane_b32 s99, v183, 16
	v_readlane_b32 s100, v183, 32
	v_readlane_b32 s101, v183, 48
	s_nop 1
	v_mov_b32_e32 v183, s98
	v_add_f32_e32 v183, s99, v183
	v_add_f32_e32 v183, s100, v183
	v_add_f32_e32 v183, s101, v183
	v_fmamk_f32 v183, v183, 0x3a800000, v182
	v_cmp_gt_f32_e32 vcc, 0x800000, v183
	v_mul_f32_e32 v181, 0x4b800000, v183
	s_nop 1
	v_cndmask_b32_e32 v183, v183, v181, vcc
	v_rsq_f32_e32 v183, v183
	s_nop 0
	v_mul_f32_e32 v181, 0x45800000, v183
	v_cndmask_b32_e32 v184, v183, v181, vcc
	v_mov_b32_e32 v185, v184
	v_pk_mul_f32 v[160:161], v[160:161], v[184:185]
	v_pk_mul_f32 v[162:163], v[162:163], v[184:185]
	v_pk_mul_f32 v[164:165], v[164:165], v[184:185]
	v_pk_mul_f32 v[166:167], v[166:167], v[184:185]
	v_pk_mul_f32 v[168:169], v[168:169], v[184:185]
	v_pk_mul_f32 v[170:171], v[170:171], v[184:185]
	v_pk_mul_f32 v[172:173], v[172:173], v[184:185]
	v_pk_mul_f32 v[174:175], v[174:175], v[184:185]
	v_pk_fma_f32 v[144:145], v[160:161], v[128:129], v[144:145]
	v_pk_fma_f32 v[146:147], v[162:163], v[130:131], v[146:147]
	v_pk_fma_f32 v[148:149], v[164:165], v[132:133], v[148:149]
	v_pk_fma_f32 v[150:151], v[166:167], v[134:135], v[150:151]
	v_pk_fma_f32 v[152:153], v[168:169], v[136:137], v[152:153]
	v_pk_fma_f32 v[154:155], v[170:171], v[138:139], v[154:155]
	v_pk_fma_f32 v[156:157], v[172:173], v[140:141], v[156:157]
	v_pk_fma_f32 v[158:159], v[174:175], v[142:143], v[158:159]
	v_pk_mul_f32 v[252:253], v[144:145], v[144:145]
	v_pk_mul_f32 v[254:255], v[146:147], v[146:147]
	v_pk_fma_f32 v[252:253], v[148:149], v[148:149], v[252:253]
	v_pk_fma_f32 v[254:255], v[150:151], v[150:151], v[254:255]
	v_pk_fma_f32 v[252:253], v[152:153], v[152:153], v[252:253]
	v_pk_fma_f32 v[254:255], v[154:155], v[154:155], v[254:255]
	v_pk_fma_f32 v[252:253], v[156:157], v[156:157], v[252:253]
	v_pk_fma_f32 v[254:255], v[158:159], v[158:159], v[254:255]
	v_pk_add_f32 v[252:253], v[252:253], v[254:255]
	s_nop 0
	v_add_f32_e32 v183, v252, v253
	s_nop 1
	v_add_f32_dpp v183, v183, v183 quad_perm:[1,0,3,2] row_mask:0xf bank_mask:0xf bound_ctrl:1
	s_nop 1
	v_add_f32_dpp v183, v183, v183 quad_perm:[2,3,0,1] row_mask:0xf bank_mask:0xf bound_ctrl:1
	s_nop 1
	v_add_f32_dpp v183, v183, v183 row_half_mirror row_mask:0xf bank_mask:0xf bound_ctrl:1
	s_nop 1
	v_add_f32_dpp v183, v183, v183 row_mirror row_mask:0xf bank_mask:0xf bound_ctrl:1
	s_nop 1
	v_readlane_b32 s98, v183, 0
	v_readlane_b32 s99, v183, 16
	v_readlane_b32 s100, v183, 32
	v_readlane_b32 s101, v183, 48
	s_nop 1
	v_mov_b32_e32 v183, s98
	v_add_f32_e32 v183, s99, v183
	v_add_f32_e32 v183, s100, v183
	v_add_f32_e32 v183, s101, v183
	v_fmamk_f32 v183, v183, 0x3a800000, v182
	v_cmp_gt_f32_e32 vcc, 0x800000, v183
	v_mul_f32_e32 v181, 0x4b800000, v183
	s_nop 1
	v_cndmask_b32_e32 v183, v183, v181, vcc
	v_rsq_f32_e32 v183, v183
	s_nop 0
	v_mul_f32_e32 v181, 0x45800000, v183
	v_cndmask_b32_e32 v184, v183, v181, vcc
	v_mov_b32_e32 v185, v184
	v_cvt_pk_bf16_f32 v0, v144, v145
	v_cvt_pk_bf16_f32 v1, v146, v147
	v_cvt_pk_bf16_f32 v2, v148, v149
	v_cvt_pk_bf16_f32 v3, v150, v151
	v_cvt_pk_bf16_f32 v4, v152, v153
	v_cvt_pk_bf16_f32 v5, v154, v155
	v_cvt_pk_bf16_f32 v6, v156, v157
	v_cvt_pk_bf16_f32 v7, v158, v159
	v_add_u32_e32 v181, 0x1800000, v177
	global_store_dwordx4 v181, v[0:3], s[78:79]
	global_store_dwordx4 v181, v[4:7], s[78:79] offset:1024
	v_add_u32_e32 v236, 0x0, v237
	s_mov_b64 exec, 1
	global_store_dword v236, v184, s[78:79]
	s_mov_b64 exec, -1
	s_waitcnt vmcnt(24)
	v_lshlrev_b32_e32 v144, 16, v16
	v_and_b32_e32 v145, 0xffff0000, v16
	v_lshlrev_b32_e32 v146, 16, v17
	v_and_b32_e32 v147, 0xffff0000, v17
	v_lshlrev_b32_e32 v148, 16, v18
	v_and_b32_e32 v149, 0xffff0000, v18
	v_lshlrev_b32_e32 v150, 16, v19
	v_and_b32_e32 v151, 0xffff0000, v19
	v_lshlrev_b32_e32 v152, 16, v20
	v_and_b32_e32 v153, 0xffff0000, v20
	v_lshlrev_b32_e32 v154, 16, v21
	v_and_b32_e32 v155, 0xffff0000, v21
	v_lshlrev_b32_e32 v156, 16, v22
	v_and_b32_e32 v157, 0xffff0000, v22
	v_lshlrev_b32_e32 v158, 16, v23
	v_and_b32_e32 v159, 0xffff0000, v23
	v_lshlrev_b32_e32 v160, 16, v24
	v_and_b32_e32 v161, 0xffff0000, v24
	v_lshlrev_b32_e32 v162, 16, v25
	v_and_b32_e32 v163, 0xffff0000, v25
	v_lshlrev_b32_e32 v164, 16, v26
	v_and_b32_e32 v165, 0xffff0000, v26
	v_lshlrev_b32_e32 v166, 16, v27
	v_and_b32_e32 v167, 0xffff0000, v27
	v_lshlrev_b32_e32 v168, 16, v28
	v_and_b32_e32 v169, 0xffff0000, v28
	v_lshlrev_b32_e32 v170, 16, v29
	v_and_b32_e32 v171, 0xffff0000, v29
	v_lshlrev_b32_e32 v172, 16, v30
	v_and_b32_e32 v173, 0xffff0000, v30
	v_lshlrev_b32_e32 v174, 16, v31
	v_and_b32_e32 v175, 0xffff0000, v31
	v_pk_mul_f32 v[252:253], v[160:161], v[160:161]
	v_pk_mul_f32 v[254:255], v[162:163], v[162:163]
	v_pk_fma_f32 v[252:253], v[164:165], v[164:165], v[252:253]
	v_pk_fma_f32 v[254:255], v[166:167], v[166:167], v[254:255]
	v_pk_fma_f32 v[252:253], v[168:169], v[168:169], v[252:253]
	v_pk_fma_f32 v[254:255], v[170:171], v[170:171], v[254:255]
	v_pk_fma_f32 v[252:253], v[172:173], v[172:173], v[252:253]
	v_pk_fma_f32 v[254:255], v[174:175], v[174:175], v[254:255]
	v_pk_add_f32 v[252:253], v[252:253], v[254:255]
	s_nop 0
	v_add_f32_e32 v183, v252, v253
	s_nop 1
	v_add_f32_dpp v183, v183, v183 quad_perm:[1,0,3,2] row_mask:0xf bank_mask:0xf bound_ctrl:1
	s_nop 1
	v_add_f32_dpp v183, v183, v183 quad_perm:[2,3,0,1] row_mask:0xf bank_mask:0xf bound_ctrl:1
	s_nop 1
	v_add_f32_dpp v183, v183, v183 row_half_mirror row_mask:0xf bank_mask:0xf bound_ctrl:1
	s_nop 1
	v_add_f32_dpp v183, v183, v183 row_mirror row_mask:0xf bank_mask:0xf bound_ctrl:1
	s_nop 1
	v_readlane_b32 s98, v183, 0
	v_readlane_b32 s99, v183, 16
	v_readlane_b32 s100, v183, 32
	v_readlane_b32 s101, v183, 48
	s_nop 1
	v_mov_b32_e32 v183, s98
	v_add_f32_e32 v183, s99, v183
	v_add_f32_e32 v183, s100, v183
	v_add_f32_e32 v183, s101, v183
	v_fmamk_f32 v183, v183, 0x3a800000, v182
	v_cmp_gt_f32_e32 vcc, 0x800000, v183
	v_mul_f32_e32 v181, 0x4b800000, v183
	s_nop 1
	v_cndmask_b32_e32 v183, v183, v181, vcc
	v_rsq_f32_e32 v183, v183
	s_nop 0
	v_mul_f32_e32 v181, 0x45800000, v183
	v_cndmask_b32_e32 v184, v183, v181, vcc
	v_mov_b32_e32 v185, v184
	v_pk_mul_f32 v[160:161], v[160:161], v[184:185]
	v_pk_mul_f32 v[162:163], v[162:163], v[184:185]
	v_pk_mul_f32 v[164:165], v[164:165], v[184:185]
	v_pk_mul_f32 v[166:167], v[166:167], v[184:185]
	v_pk_mul_f32 v[168:169], v[168:169], v[184:185]
	v_pk_mul_f32 v[170:171], v[170:171], v[184:185]
	v_pk_mul_f32 v[172:173], v[172:173], v[184:185]
	v_pk_mul_f32 v[174:175], v[174:175], v[184:185]
	v_pk_fma_f32 v[144:145], v[160:161], v[128:129], v[144:145]
	v_pk_fma_f32 v[146:147], v[162:163], v[130:131], v[146:147]
	v_pk_fma_f32 v[148:149], v[164:165], v[132:133], v[148:149]
	v_pk_fma_f32 v[150:151], v[166:167], v[134:135], v[150:151]
	v_pk_fma_f32 v[152:153], v[168:169], v[136:137], v[152:153]
	v_pk_fma_f32 v[154:155], v[170:171], v[138:139], v[154:155]
	v_pk_fma_f32 v[156:157], v[172:173], v[140:141], v[156:157]
	v_pk_fma_f32 v[158:159], v[174:175], v[142:143], v[158:159]
	v_pk_mul_f32 v[252:253], v[144:145], v[144:145]
	v_pk_mul_f32 v[254:255], v[146:147], v[146:147]
	v_pk_fma_f32 v[252:253], v[148:149], v[148:149], v[252:253]
	v_pk_fma_f32 v[254:255], v[150:151], v[150:151], v[254:255]
	v_pk_fma_f32 v[252:253], v[152:153], v[152:153], v[252:253]
	v_pk_fma_f32 v[254:255], v[154:155], v[154:155], v[254:255]
	v_pk_fma_f32 v[252:253], v[156:157], v[156:157], v[252:253]
	v_pk_fma_f32 v[254:255], v[158:159], v[158:159], v[254:255]
	v_pk_add_f32 v[252:253], v[252:253], v[254:255]
	s_nop 0
	v_add_f32_e32 v183, v252, v253
	s_nop 1
	v_add_f32_dpp v183, v183, v183 quad_perm:[1,0,3,2] row_mask:0xf bank_mask:0xf bound_ctrl:1
	s_nop 1
	v_add_f32_dpp v183, v183, v183 quad_perm:[2,3,0,1] row_mask:0xf bank_mask:0xf bound_ctrl:1
	s_nop 1
	v_add_f32_dpp v183, v183, v183 row_half_mirror row_mask:0xf bank_mask:0xf bound_ctrl:1
	s_nop 1
	v_add_f32_dpp v183, v183, v183 row_mirror row_mask:0xf bank_mask:0xf bound_ctrl:1
	s_nop 1
	v_readlane_b32 s98, v183, 0
	v_readlane_b32 s99, v183, 16
	v_readlane_b32 s100, v183, 32
	v_readlane_b32 s101, v183, 48
	s_nop 1
	v_mov_b32_e32 v183, s98
	v_add_f32_e32 v183, s99, v183
	v_add_f32_e32 v183, s100, v183
	v_add_f32_e32 v183, s101, v183
	v_fmamk_f32 v183, v183, 0x3a800000, v182
	v_cmp_gt_f32_e32 vcc, 0x800000, v183
	v_mul_f32_e32 v181, 0x4b800000, v183
	s_nop 1
	v_cndmask_b32_e32 v183, v183, v181, vcc
	v_rsq_f32_e32 v183, v183
	s_nop 0
	v_mul_f32_e32 v181, 0x45800000, v183
	v_cndmask_b32_e32 v184, v183, v181, vcc
	v_mov_b32_e32 v185, v184
	v_cvt_pk_bf16_f32 v16, v144, v145
	v_cvt_pk_bf16_f32 v17, v146, v147
	v_cvt_pk_bf16_f32 v18, v148, v149
	v_cvt_pk_bf16_f32 v19, v150, v151
	v_cvt_pk_bf16_f32 v20, v152, v153
	v_cvt_pk_bf16_f32 v21, v154, v155
	v_cvt_pk_bf16_f32 v22, v156, v157
	v_cvt_pk_bf16_f32 v23, v158, v159
	v_add_u32_e32 v181, 0x1c00000, v177
	global_store_dwordx4 v181, v[16:19], s[78:79]
	global_store_dwordx4 v181, v[20:23], s[78:79] offset:1024
	v_add_u32_e32 v236, 0x2000, v237
	s_mov_b64 exec, 1
	global_store_dword v236, v184, s[78:79]
	s_mov_b64 exec, -1
	s_waitcnt vmcnt(20)
	v_lshlrev_b32_e32 v144, 16, v32
	v_and_b32_e32 v145, 0xffff0000, v32
	v_lshlrev_b32_e32 v146, 16, v33
	v_and_b32_e32 v147, 0xffff0000, v33
	v_lshlrev_b32_e32 v148, 16, v34
	v_and_b32_e32 v149, 0xffff0000, v34
	v_lshlrev_b32_e32 v150, 16, v35
	v_and_b32_e32 v151, 0xffff0000, v35
	v_lshlrev_b32_e32 v152, 16, v36
	v_and_b32_e32 v153, 0xffff0000, v36
	v_lshlrev_b32_e32 v154, 16, v37
	v_and_b32_e32 v155, 0xffff0000, v37
	v_lshlrev_b32_e32 v156, 16, v38
	v_and_b32_e32 v157, 0xffff0000, v38
	v_lshlrev_b32_e32 v158, 16, v39
	v_and_b32_e32 v159, 0xffff0000, v39
	v_lshlrev_b32_e32 v160, 16, v40
	v_and_b32_e32 v161, 0xffff0000, v40
	v_lshlrev_b32_e32 v162, 16, v41
	v_and_b32_e32 v163, 0xffff0000, v41
	v_lshlrev_b32_e32 v164, 16, v42
	v_and_b32_e32 v165, 0xffff0000, v42
	v_lshlrev_b32_e32 v166, 16, v43
	v_and_b32_e32 v167, 0xffff0000, v43
	v_lshlrev_b32_e32 v168, 16, v44
	v_and_b32_e32 v169, 0xffff0000, v44
	v_lshlrev_b32_e32 v170, 16, v45
	v_and_b32_e32 v171, 0xffff0000, v45
	v_lshlrev_b32_e32 v172, 16, v46
	v_and_b32_e32 v173, 0xffff0000, v46
	v_lshlrev_b32_e32 v174, 16, v47
	v_and_b32_e32 v175, 0xffff0000, v47
	v_pk_mul_f32 v[252:253], v[160:161], v[160:161]
	v_pk_mul_f32 v[254:255], v[162:163], v[162:163]
	v_pk_fma_f32 v[252:253], v[164:165], v[164:165], v[252:253]
	v_pk_fma_f32 v[254:255], v[166:167], v[166:167], v[254:255]
	v_pk_fma_f32 v[252:253], v[168:169], v[168:169], v[252:253]
	v_pk_fma_f32 v[254:255], v[170:171], v[170:171], v[254:255]
	v_pk_fma_f32 v[252:253], v[172:173], v[172:173], v[252:253]
	v_pk_fma_f32 v[254:255], v[174:175], v[174:175], v[254:255]
	v_pk_add_f32 v[252:253], v[252:253], v[254:255]
	s_nop 0
	v_add_f32_e32 v183, v252, v253
	s_nop 1
	v_add_f32_dpp v183, v183, v183 quad_perm:[1,0,3,2] row_mask:0xf bank_mask:0xf bound_ctrl:1
	s_nop 1
	v_add_f32_dpp v183, v183, v183 quad_perm:[2,3,0,1] row_mask:0xf bank_mask:0xf bound_ctrl:1
	s_nop 1
	v_add_f32_dpp v183, v183, v183 row_half_mirror row_mask:0xf bank_mask:0xf bound_ctrl:1
	s_nop 1
	v_add_f32_dpp v183, v183, v183 row_mirror row_mask:0xf bank_mask:0xf bound_ctrl:1
	s_nop 1
	v_readlane_b32 s98, v183, 0
	v_readlane_b32 s99, v183, 16
	v_readlane_b32 s100, v183, 32
	v_readlane_b32 s101, v183, 48
	s_nop 1
	v_mov_b32_e32 v183, s98
	v_add_f32_e32 v183, s99, v183
	v_add_f32_e32 v183, s100, v183
	v_add_f32_e32 v183, s101, v183
	v_fmamk_f32 v183, v183, 0x3a800000, v182
	v_cmp_gt_f32_e32 vcc, 0x800000, v183
	v_mul_f32_e32 v181, 0x4b800000, v183
	s_nop 1
	v_cndmask_b32_e32 v183, v183, v181, vcc
	v_rsq_f32_e32 v183, v183
	s_nop 0
	v_mul_f32_e32 v181, 0x45800000, v183
	v_cndmask_b32_e32 v184, v183, v181, vcc
	v_mov_b32_e32 v185, v184
	v_pk_mul_f32 v[160:161], v[160:161], v[184:185]
	v_pk_mul_f32 v[162:163], v[162:163], v[184:185]
	v_pk_mul_f32 v[164:165], v[164:165], v[184:185]
	v_pk_mul_f32 v[166:167], v[166:167], v[184:185]
	v_pk_mul_f32 v[168:169], v[168:169], v[184:185]
	v_pk_mul_f32 v[170:171], v[170:171], v[184:185]
	v_pk_mul_f32 v[172:173], v[172:173], v[184:185]
	v_pk_mul_f32 v[174:175], v[174:175], v[184:185]
	v_pk_fma_f32 v[144:145], v[160:161], v[128:129], v[144:145]
	v_pk_fma_f32 v[146:147], v[162:163], v[130:131], v[146:147]
	v_pk_fma_f32 v[148:149], v[164:165], v[132:133], v[148:149]
	v_pk_fma_f32 v[150:151], v[166:167], v[134:135], v[150:151]
	v_pk_fma_f32 v[152:153], v[168:169], v[136:137], v[152:153]
	v_pk_fma_f32 v[154:155], v[170:171], v[138:139], v[154:155]
	v_pk_fma_f32 v[156:157], v[172:173], v[140:141], v[156:157]
	v_pk_fma_f32 v[158:159], v[174:175], v[142:143], v[158:159]
	v_pk_mul_f32 v[252:253], v[144:145], v[144:145]
	v_pk_mul_f32 v[254:255], v[146:147], v[146:147]
	v_pk_fma_f32 v[252:253], v[148:149], v[148:149], v[252:253]
	v_pk_fma_f32 v[254:255], v[150:151], v[150:151], v[254:255]
	v_pk_fma_f32 v[252:253], v[152:153], v[152:153], v[252:253]
	v_pk_fma_f32 v[254:255], v[154:155], v[154:155], v[254:255]
	v_pk_fma_f32 v[252:253], v[156:157], v[156:157], v[252:253]
	v_pk_fma_f32 v[254:255], v[158:159], v[158:159], v[254:255]
	v_pk_add_f32 v[252:253], v[252:253], v[254:255]
	s_nop 0
	v_add_f32_e32 v183, v252, v253
	s_nop 1
	v_add_f32_dpp v183, v183, v183 quad_perm:[1,0,3,2] row_mask:0xf bank_mask:0xf bound_ctrl:1
	s_nop 1
	v_add_f32_dpp v183, v183, v183 quad_perm:[2,3,0,1] row_mask:0xf bank_mask:0xf bound_ctrl:1
	s_nop 1
	v_add_f32_dpp v183, v183, v183 row_half_mirror row_mask:0xf bank_mask:0xf bound_ctrl:1
	s_nop 1
	v_add_f32_dpp v183, v183, v183 row_mirror row_mask:0xf bank_mask:0xf bound_ctrl:1
	s_nop 1
	v_readlane_b32 s98, v183, 0
	v_readlane_b32 s99, v183, 16
	v_readlane_b32 s100, v183, 32
	v_readlane_b32 s101, v183, 48
	s_nop 1
	v_mov_b32_e32 v183, s98
	v_add_f32_e32 v183, s99, v183
	v_add_f32_e32 v183, s100, v183
	v_add_f32_e32 v183, s101, v183
	v_fmamk_f32 v183, v183, 0x3a800000, v182
	v_cmp_gt_f32_e32 vcc, 0x800000, v183
	v_mul_f32_e32 v181, 0x4b800000, v183
	s_nop 1
	v_cndmask_b32_e32 v183, v183, v181, vcc
	v_rsq_f32_e32 v183, v183
	s_nop 0
	v_mul_f32_e32 v181, 0x45800000, v183
	v_cndmask_b32_e32 v184, v183, v181, vcc
	v_mov_b32_e32 v185, v184
	v_cvt_pk_bf16_f32 v32, v144, v145
	v_cvt_pk_bf16_f32 v33, v146, v147
	v_cvt_pk_bf16_f32 v34, v148, v149
	v_cvt_pk_bf16_f32 v35, v150, v151
	v_cvt_pk_bf16_f32 v36, v152, v153
	v_cvt_pk_bf16_f32 v37, v154, v155
	v_cvt_pk_bf16_f32 v38, v156, v157
	v_cvt_pk_bf16_f32 v39, v158, v159
	v_add_u32_e32 v181, 0x2000000, v177
	global_store_dwordx4 v181, v[32:35], s[78:79]
	global_store_dwordx4 v181, v[36:39], s[78:79] offset:1024
	v_add_u32_e32 v236, 0x4000, v237
	s_mov_b64 exec, 1
	global_store_dword v236, v184, s[78:79]
	s_mov_b64 exec, -1
	s_waitcnt vmcnt(16)
	v_lshlrev_b32_e32 v144, 16, v48
	v_and_b32_e32 v145, 0xffff0000, v48
	v_lshlrev_b32_e32 v146, 16, v49
	v_and_b32_e32 v147, 0xffff0000, v49
	v_lshlrev_b32_e32 v148, 16, v50
	v_and_b32_e32 v149, 0xffff0000, v50
	v_lshlrev_b32_e32 v150, 16, v51
	v_and_b32_e32 v151, 0xffff0000, v51
	v_lshlrev_b32_e32 v152, 16, v52
	v_and_b32_e32 v153, 0xffff0000, v52
	v_lshlrev_b32_e32 v154, 16, v53
	v_and_b32_e32 v155, 0xffff0000, v53
	v_lshlrev_b32_e32 v156, 16, v54
	v_and_b32_e32 v157, 0xffff0000, v54
	v_lshlrev_b32_e32 v158, 16, v55
	v_and_b32_e32 v159, 0xffff0000, v55
	v_lshlrev_b32_e32 v160, 16, v56
	v_and_b32_e32 v161, 0xffff0000, v56
	v_lshlrev_b32_e32 v162, 16, v57
	v_and_b32_e32 v163, 0xffff0000, v57
	v_lshlrev_b32_e32 v164, 16, v58
	v_and_b32_e32 v165, 0xffff0000, v58
	v_lshlrev_b32_e32 v166, 16, v59
	v_and_b32_e32 v167, 0xffff0000, v59
	v_lshlrev_b32_e32 v168, 16, v60
	v_and_b32_e32 v169, 0xffff0000, v60
	v_lshlrev_b32_e32 v170, 16, v61
	v_and_b32_e32 v171, 0xffff0000, v61
	v_lshlrev_b32_e32 v172, 16, v62
	v_and_b32_e32 v173, 0xffff0000, v62
	v_lshlrev_b32_e32 v174, 16, v63
	v_and_b32_e32 v175, 0xffff0000, v63
	v_pk_mul_f32 v[252:253], v[160:161], v[160:161]
	v_pk_mul_f32 v[254:255], v[162:163], v[162:163]
	v_pk_fma_f32 v[252:253], v[164:165], v[164:165], v[252:253]
	v_pk_fma_f32 v[254:255], v[166:167], v[166:167], v[254:255]
	v_pk_fma_f32 v[252:253], v[168:169], v[168:169], v[252:253]
	v_pk_fma_f32 v[254:255], v[170:171], v[170:171], v[254:255]
	v_pk_fma_f32 v[252:253], v[172:173], v[172:173], v[252:253]
	v_pk_fma_f32 v[254:255], v[174:175], v[174:175], v[254:255]
	v_pk_add_f32 v[252:253], v[252:253], v[254:255]
	s_nop 0
	v_add_f32_e32 v183, v252, v253
	s_nop 1
	v_add_f32_dpp v183, v183, v183 quad_perm:[1,0,3,2] row_mask:0xf bank_mask:0xf bound_ctrl:1
	s_nop 1
	v_add_f32_dpp v183, v183, v183 quad_perm:[2,3,0,1] row_mask:0xf bank_mask:0xf bound_ctrl:1
	s_nop 1
	v_add_f32_dpp v183, v183, v183 row_half_mirror row_mask:0xf bank_mask:0xf bound_ctrl:1
	s_nop 1
	v_add_f32_dpp v183, v183, v183 row_mirror row_mask:0xf bank_mask:0xf bound_ctrl:1
	s_nop 1
	v_readlane_b32 s98, v183, 0
	v_readlane_b32 s99, v183, 16
	v_readlane_b32 s100, v183, 32
	v_readlane_b32 s101, v183, 48
	s_nop 1
	v_mov_b32_e32 v183, s98
	v_add_f32_e32 v183, s99, v183
	v_add_f32_e32 v183, s100, v183
	v_add_f32_e32 v183, s101, v183
	v_fmamk_f32 v183, v183, 0x3a800000, v182
	v_cmp_gt_f32_e32 vcc, 0x800000, v183
	v_mul_f32_e32 v181, 0x4b800000, v183
	s_nop 1
	v_cndmask_b32_e32 v183, v183, v181, vcc
	v_rsq_f32_e32 v183, v183
	s_nop 0
	v_mul_f32_e32 v181, 0x45800000, v183
	v_cndmask_b32_e32 v184, v183, v181, vcc
	v_mov_b32_e32 v185, v184
	v_pk_mul_f32 v[160:161], v[160:161], v[184:185]
	v_pk_mul_f32 v[162:163], v[162:163], v[184:185]
	v_pk_mul_f32 v[164:165], v[164:165], v[184:185]
	v_pk_mul_f32 v[166:167], v[166:167], v[184:185]
	v_pk_mul_f32 v[168:169], v[168:169], v[184:185]
	v_pk_mul_f32 v[170:171], v[170:171], v[184:185]
	v_pk_mul_f32 v[172:173], v[172:173], v[184:185]
	v_pk_mul_f32 v[174:175], v[174:175], v[184:185]
	v_pk_fma_f32 v[144:145], v[160:161], v[128:129], v[144:145]
	v_pk_fma_f32 v[146:147], v[162:163], v[130:131], v[146:147]
	v_pk_fma_f32 v[148:149], v[164:165], v[132:133], v[148:149]
	v_pk_fma_f32 v[150:151], v[166:167], v[134:135], v[150:151]
	v_pk_fma_f32 v[152:153], v[168:169], v[136:137], v[152:153]
	v_pk_fma_f32 v[154:155], v[170:171], v[138:139], v[154:155]
	v_pk_fma_f32 v[156:157], v[172:173], v[140:141], v[156:157]
	v_pk_fma_f32 v[158:159], v[174:175], v[142:143], v[158:159]
	v_pk_mul_f32 v[252:253], v[144:145], v[144:145]
	v_pk_mul_f32 v[254:255], v[146:147], v[146:147]
	v_pk_fma_f32 v[252:253], v[148:149], v[148:149], v[252:253]
	v_pk_fma_f32 v[254:255], v[150:151], v[150:151], v[254:255]
	v_pk_fma_f32 v[252:253], v[152:153], v[152:153], v[252:253]
	v_pk_fma_f32 v[254:255], v[154:155], v[154:155], v[254:255]
	v_pk_fma_f32 v[252:253], v[156:157], v[156:157], v[252:253]
	v_pk_fma_f32 v[254:255], v[158:159], v[158:159], v[254:255]
	v_pk_add_f32 v[252:253], v[252:253], v[254:255]
	s_nop 0
	v_add_f32_e32 v183, v252, v253
	s_nop 1
	v_add_f32_dpp v183, v183, v183 quad_perm:[1,0,3,2] row_mask:0xf bank_mask:0xf bound_ctrl:1
	s_nop 1
	v_add_f32_dpp v183, v183, v183 quad_perm:[2,3,0,1] row_mask:0xf bank_mask:0xf bound_ctrl:1
	s_nop 1
	v_add_f32_dpp v183, v183, v183 row_half_mirror row_mask:0xf bank_mask:0xf bound_ctrl:1
	s_nop 1
	v_add_f32_dpp v183, v183, v183 row_mirror row_mask:0xf bank_mask:0xf bound_ctrl:1
	s_nop 1
	v_readlane_b32 s98, v183, 0
	v_readlane_b32 s99, v183, 16
	v_readlane_b32 s100, v183, 32
	v_readlane_b32 s101, v183, 48
	s_nop 1
	v_mov_b32_e32 v183, s98
	v_add_f32_e32 v183, s99, v183
	v_add_f32_e32 v183, s100, v183
	v_add_f32_e32 v183, s101, v183
	v_fmamk_f32 v183, v183, 0x3a800000, v182
	v_cmp_gt_f32_e32 vcc, 0x800000, v183
	v_mul_f32_e32 v181, 0x4b800000, v183
	s_nop 1
	v_cndmask_b32_e32 v183, v183, v181, vcc
	v_rsq_f32_e32 v183, v183
	s_nop 0
	v_mul_f32_e32 v181, 0x45800000, v183
	v_cndmask_b32_e32 v184, v183, v181, vcc
	v_mov_b32_e32 v185, v184
	v_cvt_pk_bf16_f32 v48, v144, v145
	v_cvt_pk_bf16_f32 v49, v146, v147
	v_cvt_pk_bf16_f32 v50, v148, v149
	v_cvt_pk_bf16_f32 v51, v150, v151
	v_cvt_pk_bf16_f32 v52, v152, v153
	v_cvt_pk_bf16_f32 v53, v154, v155
	v_cvt_pk_bf16_f32 v54, v156, v157
	v_cvt_pk_bf16_f32 v55, v158, v159
	v_add_u32_e32 v181, 0x2400000, v177
	global_store_dwordx4 v181, v[48:51], s[78:79]
	global_store_dwordx4 v181, v[52:55], s[78:79] offset:1024
	v_add_u32_e32 v236, 0x6000, v237
	s_mov_b64 exec, 1
	global_store_dword v236, v184, s[78:79]
	s_mov_b64 exec, -1
	s_waitcnt vmcnt(12)
	v_lshlrev_b32_e32 v144, 16, v64
	v_and_b32_e32 v145, 0xffff0000, v64
	v_lshlrev_b32_e32 v146, 16, v65
	v_and_b32_e32 v147, 0xffff0000, v65
	v_lshlrev_b32_e32 v148, 16, v66
	v_and_b32_e32 v149, 0xffff0000, v66
	v_lshlrev_b32_e32 v150, 16, v67
	v_and_b32_e32 v151, 0xffff0000, v67
	v_lshlrev_b32_e32 v152, 16, v68
	v_and_b32_e32 v153, 0xffff0000, v68
	v_lshlrev_b32_e32 v154, 16, v69
	v_and_b32_e32 v155, 0xffff0000, v69
	v_lshlrev_b32_e32 v156, 16, v70
	v_and_b32_e32 v157, 0xffff0000, v70
	v_lshlrev_b32_e32 v158, 16, v71
	v_and_b32_e32 v159, 0xffff0000, v71
	v_lshlrev_b32_e32 v160, 16, v72
	v_and_b32_e32 v161, 0xffff0000, v72
	v_lshlrev_b32_e32 v162, 16, v73
	v_and_b32_e32 v163, 0xffff0000, v73
	v_lshlrev_b32_e32 v164, 16, v74
	v_and_b32_e32 v165, 0xffff0000, v74
	v_lshlrev_b32_e32 v166, 16, v75
	v_and_b32_e32 v167, 0xffff0000, v75
	v_lshlrev_b32_e32 v168, 16, v76
	v_and_b32_e32 v169, 0xffff0000, v76
	v_lshlrev_b32_e32 v170, 16, v77
	v_and_b32_e32 v171, 0xffff0000, v77
	v_lshlrev_b32_e32 v172, 16, v78
	v_and_b32_e32 v173, 0xffff0000, v78
	v_lshlrev_b32_e32 v174, 16, v79
	v_and_b32_e32 v175, 0xffff0000, v79
	v_pk_mul_f32 v[252:253], v[160:161], v[160:161]
	v_pk_mul_f32 v[254:255], v[162:163], v[162:163]
	v_pk_fma_f32 v[252:253], v[164:165], v[164:165], v[252:253]
	v_pk_fma_f32 v[254:255], v[166:167], v[166:167], v[254:255]
	v_pk_fma_f32 v[252:253], v[168:169], v[168:169], v[252:253]
	v_pk_fma_f32 v[254:255], v[170:171], v[170:171], v[254:255]
	v_pk_fma_f32 v[252:253], v[172:173], v[172:173], v[252:253]
	v_pk_fma_f32 v[254:255], v[174:175], v[174:175], v[254:255]
	v_pk_add_f32 v[252:253], v[252:253], v[254:255]
	s_nop 0
	v_add_f32_e32 v183, v252, v253
	s_nop 1
	v_add_f32_dpp v183, v183, v183 quad_perm:[1,0,3,2] row_mask:0xf bank_mask:0xf bound_ctrl:1
	s_nop 1
	v_add_f32_dpp v183, v183, v183 quad_perm:[2,3,0,1] row_mask:0xf bank_mask:0xf bound_ctrl:1
	s_nop 1
	v_add_f32_dpp v183, v183, v183 row_half_mirror row_mask:0xf bank_mask:0xf bound_ctrl:1
	s_nop 1
	v_add_f32_dpp v183, v183, v183 row_mirror row_mask:0xf bank_mask:0xf bound_ctrl:1
	s_nop 1
	v_readlane_b32 s98, v183, 0
	v_readlane_b32 s99, v183, 16
	v_readlane_b32 s100, v183, 32
	v_readlane_b32 s101, v183, 48
	s_nop 1
	v_mov_b32_e32 v183, s98
	v_add_f32_e32 v183, s99, v183
	v_add_f32_e32 v183, s100, v183
	v_add_f32_e32 v183, s101, v183
	v_fmamk_f32 v183, v183, 0x3a800000, v182
	v_cmp_gt_f32_e32 vcc, 0x800000, v183
	v_mul_f32_e32 v181, 0x4b800000, v183
	s_nop 1
	v_cndmask_b32_e32 v183, v183, v181, vcc
	v_rsq_f32_e32 v183, v183
	s_nop 0
	v_mul_f32_e32 v181, 0x45800000, v183
	v_cndmask_b32_e32 v184, v183, v181, vcc
	v_mov_b32_e32 v185, v184
	v_pk_mul_f32 v[160:161], v[160:161], v[184:185]
	v_pk_mul_f32 v[162:163], v[162:163], v[184:185]
	v_pk_mul_f32 v[164:165], v[164:165], v[184:185]
	v_pk_mul_f32 v[166:167], v[166:167], v[184:185]
	v_pk_mul_f32 v[168:169], v[168:169], v[184:185]
	v_pk_mul_f32 v[170:171], v[170:171], v[184:185]
	v_pk_mul_f32 v[172:173], v[172:173], v[184:185]
	v_pk_mul_f32 v[174:175], v[174:175], v[184:185]
	v_pk_fma_f32 v[144:145], v[160:161], v[128:129], v[144:145]
	v_pk_fma_f32 v[146:147], v[162:163], v[130:131], v[146:147]
	v_pk_fma_f32 v[148:149], v[164:165], v[132:133], v[148:149]
	v_pk_fma_f32 v[150:151], v[166:167], v[134:135], v[150:151]
	v_pk_fma_f32 v[152:153], v[168:169], v[136:137], v[152:153]
	v_pk_fma_f32 v[154:155], v[170:171], v[138:139], v[154:155]
	v_pk_fma_f32 v[156:157], v[172:173], v[140:141], v[156:157]
	v_pk_fma_f32 v[158:159], v[174:175], v[142:143], v[158:159]
	v_pk_mul_f32 v[252:253], v[144:145], v[144:145]
	v_pk_mul_f32 v[254:255], v[146:147], v[146:147]
	v_pk_fma_f32 v[252:253], v[148:149], v[148:149], v[252:253]
	v_pk_fma_f32 v[254:255], v[150:151], v[150:151], v[254:255]
	v_pk_fma_f32 v[252:253], v[152:153], v[152:153], v[252:253]
	v_pk_fma_f32 v[254:255], v[154:155], v[154:155], v[254:255]
	v_pk_fma_f32 v[252:253], v[156:157], v[156:157], v[252:253]
	v_pk_fma_f32 v[254:255], v[158:159], v[158:159], v[254:255]
	v_pk_add_f32 v[252:253], v[252:253], v[254:255]
	s_nop 0
	v_add_f32_e32 v183, v252, v253
	s_nop 1
	v_add_f32_dpp v183, v183, v183 quad_perm:[1,0,3,2] row_mask:0xf bank_mask:0xf bound_ctrl:1
	s_nop 1
	v_add_f32_dpp v183, v183, v183 quad_perm:[2,3,0,1] row_mask:0xf bank_mask:0xf bound_ctrl:1
	s_nop 1
	v_add_f32_dpp v183, v183, v183 row_half_mirror row_mask:0xf bank_mask:0xf bound_ctrl:1
	s_nop 1
	v_add_f32_dpp v183, v183, v183 row_mirror row_mask:0xf bank_mask:0xf bound_ctrl:1
	s_nop 1
	v_readlane_b32 s98, v183, 0
	v_readlane_b32 s99, v183, 16
	v_readlane_b32 s100, v183, 32
	v_readlane_b32 s101, v183, 48
	s_nop 1
	v_mov_b32_e32 v183, s98
	v_add_f32_e32 v183, s99, v183
	v_add_f32_e32 v183, s100, v183
	v_add_f32_e32 v183, s101, v183
	v_fmamk_f32 v183, v183, 0x3a800000, v182
	v_cmp_gt_f32_e32 vcc, 0x800000, v183
	v_mul_f32_e32 v181, 0x4b800000, v183
	s_nop 1
	v_cndmask_b32_e32 v183, v183, v181, vcc
	v_rsq_f32_e32 v183, v183
	s_nop 0
	v_mul_f32_e32 v181, 0x45800000, v183
	v_cndmask_b32_e32 v184, v183, v181, vcc
	v_mov_b32_e32 v185, v184
	v_cvt_pk_bf16_f32 v64, v144, v145
	v_cvt_pk_bf16_f32 v65, v146, v147
	v_cvt_pk_bf16_f32 v66, v148, v149
	v_cvt_pk_bf16_f32 v67, v150, v151
	v_cvt_pk_bf16_f32 v68, v152, v153
	v_cvt_pk_bf16_f32 v69, v154, v155
	v_cvt_pk_bf16_f32 v70, v156, v157
	v_cvt_pk_bf16_f32 v71, v158, v159
	v_add_u32_e32 v181, 0x2800000, v177
	global_store_dwordx4 v181, v[64:67], s[78:79]
	global_store_dwordx4 v181, v[68:71], s[78:79] offset:1024
	v_add_u32_e32 v236, 0x8000, v237
	s_mov_b64 exec, 1
	global_store_dword v236, v184, s[78:79]
	s_mov_b64 exec, -1
	s_waitcnt vmcnt(8)
	v_lshlrev_b32_e32 v144, 16, v80
	v_and_b32_e32 v145, 0xffff0000, v80
	v_lshlrev_b32_e32 v146, 16, v81
	v_and_b32_e32 v147, 0xffff0000, v81
	v_lshlrev_b32_e32 v148, 16, v82
	v_and_b32_e32 v149, 0xffff0000, v82
	v_lshlrev_b32_e32 v150, 16, v83
	v_and_b32_e32 v151, 0xffff0000, v83
	v_lshlrev_b32_e32 v152, 16, v84
	v_and_b32_e32 v153, 0xffff0000, v84
	v_lshlrev_b32_e32 v154, 16, v85
	v_and_b32_e32 v155, 0xffff0000, v85
	v_lshlrev_b32_e32 v156, 16, v86
	v_and_b32_e32 v157, 0xffff0000, v86
	v_lshlrev_b32_e32 v158, 16, v87
	v_and_b32_e32 v159, 0xffff0000, v87
	v_lshlrev_b32_e32 v160, 16, v88
	v_and_b32_e32 v161, 0xffff0000, v88
	v_lshlrev_b32_e32 v162, 16, v89
	v_and_b32_e32 v163, 0xffff0000, v89
	v_lshlrev_b32_e32 v164, 16, v90
	v_and_b32_e32 v165, 0xffff0000, v90
	v_lshlrev_b32_e32 v166, 16, v91
	v_and_b32_e32 v167, 0xffff0000, v91
	v_lshlrev_b32_e32 v168, 16, v92
	v_and_b32_e32 v169, 0xffff0000, v92
	v_lshlrev_b32_e32 v170, 16, v93
	v_and_b32_e32 v171, 0xffff0000, v93
	v_lshlrev_b32_e32 v172, 16, v94
	v_and_b32_e32 v173, 0xffff0000, v94
	v_lshlrev_b32_e32 v174, 16, v95
	v_and_b32_e32 v175, 0xffff0000, v95
	v_pk_mul_f32 v[252:253], v[160:161], v[160:161]
	v_pk_mul_f32 v[254:255], v[162:163], v[162:163]
	v_pk_fma_f32 v[252:253], v[164:165], v[164:165], v[252:253]
	v_pk_fma_f32 v[254:255], v[166:167], v[166:167], v[254:255]
	v_pk_fma_f32 v[252:253], v[168:169], v[168:169], v[252:253]
	v_pk_fma_f32 v[254:255], v[170:171], v[170:171], v[254:255]
	v_pk_fma_f32 v[252:253], v[172:173], v[172:173], v[252:253]
	v_pk_fma_f32 v[254:255], v[174:175], v[174:175], v[254:255]
	v_pk_add_f32 v[252:253], v[252:253], v[254:255]
	s_nop 0
	v_add_f32_e32 v183, v252, v253
	s_nop 1
	v_add_f32_dpp v183, v183, v183 quad_perm:[1,0,3,2] row_mask:0xf bank_mask:0xf bound_ctrl:1
	s_nop 1
	v_add_f32_dpp v183, v183, v183 quad_perm:[2,3,0,1] row_mask:0xf bank_mask:0xf bound_ctrl:1
	s_nop 1
	v_add_f32_dpp v183, v183, v183 row_half_mirror row_mask:0xf bank_mask:0xf bound_ctrl:1
	s_nop 1
	v_add_f32_dpp v183, v183, v183 row_mirror row_mask:0xf bank_mask:0xf bound_ctrl:1
	s_nop 1
	v_readlane_b32 s98, v183, 0
	v_readlane_b32 s99, v183, 16
	v_readlane_b32 s100, v183, 32
	v_readlane_b32 s101, v183, 48
	s_nop 1
	v_mov_b32_e32 v183, s98
	v_add_f32_e32 v183, s99, v183
	v_add_f32_e32 v183, s100, v183
	v_add_f32_e32 v183, s101, v183
	v_fmamk_f32 v183, v183, 0x3a800000, v182
	v_cmp_gt_f32_e32 vcc, 0x800000, v183
	v_mul_f32_e32 v181, 0x4b800000, v183
	s_nop 1
	v_cndmask_b32_e32 v183, v183, v181, vcc
	v_rsq_f32_e32 v183, v183
	s_nop 0
	v_mul_f32_e32 v181, 0x45800000, v183
	v_cndmask_b32_e32 v184, v183, v181, vcc
	v_mov_b32_e32 v185, v184
	v_pk_mul_f32 v[160:161], v[160:161], v[184:185]
	v_pk_mul_f32 v[162:163], v[162:163], v[184:185]
	v_pk_mul_f32 v[164:165], v[164:165], v[184:185]
	v_pk_mul_f32 v[166:167], v[166:167], v[184:185]
	v_pk_mul_f32 v[168:169], v[168:169], v[184:185]
	v_pk_mul_f32 v[170:171], v[170:171], v[184:185]
	v_pk_mul_f32 v[172:173], v[172:173], v[184:185]
	v_pk_mul_f32 v[174:175], v[174:175], v[184:185]
	v_pk_fma_f32 v[144:145], v[160:161], v[128:129], v[144:145]
	v_pk_fma_f32 v[146:147], v[162:163], v[130:131], v[146:147]
	v_pk_fma_f32 v[148:149], v[164:165], v[132:133], v[148:149]
	v_pk_fma_f32 v[150:151], v[166:167], v[134:135], v[150:151]
	v_pk_fma_f32 v[152:153], v[168:169], v[136:137], v[152:153]
	v_pk_fma_f32 v[154:155], v[170:171], v[138:139], v[154:155]
	v_pk_fma_f32 v[156:157], v[172:173], v[140:141], v[156:157]
	v_pk_fma_f32 v[158:159], v[174:175], v[142:143], v[158:159]
	v_pk_mul_f32 v[252:253], v[144:145], v[144:145]
	v_pk_mul_f32 v[254:255], v[146:147], v[146:147]
	v_pk_fma_f32 v[252:253], v[148:149], v[148:149], v[252:253]
	v_pk_fma_f32 v[254:255], v[150:151], v[150:151], v[254:255]
	v_pk_fma_f32 v[252:253], v[152:153], v[152:153], v[252:253]
	v_pk_fma_f32 v[254:255], v[154:155], v[154:155], v[254:255]
	v_pk_fma_f32 v[252:253], v[156:157], v[156:157], v[252:253]
	v_pk_fma_f32 v[254:255], v[158:159], v[158:159], v[254:255]
	v_pk_add_f32 v[252:253], v[252:253], v[254:255]
	s_nop 0
	v_add_f32_e32 v183, v252, v253
	s_nop 1
	v_add_f32_dpp v183, v183, v183 quad_perm:[1,0,3,2] row_mask:0xf bank_mask:0xf bound_ctrl:1
	s_nop 1
	v_add_f32_dpp v183, v183, v183 quad_perm:[2,3,0,1] row_mask:0xf bank_mask:0xf bound_ctrl:1
	s_nop 1
	v_add_f32_dpp v183, v183, v183 row_half_mirror row_mask:0xf bank_mask:0xf bound_ctrl:1
	s_nop 1
	v_add_f32_dpp v183, v183, v183 row_mirror row_mask:0xf bank_mask:0xf bound_ctrl:1
	s_nop 1
	v_readlane_b32 s98, v183, 0
	v_readlane_b32 s99, v183, 16
	v_readlane_b32 s100, v183, 32
	v_readlane_b32 s101, v183, 48
	s_nop 1
	v_mov_b32_e32 v183, s98
	v_add_f32_e32 v183, s99, v183
	v_add_f32_e32 v183, s100, v183
	v_add_f32_e32 v183, s101, v183
	v_fmamk_f32 v183, v183, 0x3a800000, v182
	v_cmp_gt_f32_e32 vcc, 0x800000, v183
	v_mul_f32_e32 v181, 0x4b800000, v183
	s_nop 1
	v_cndmask_b32_e32 v183, v183, v181, vcc
	v_rsq_f32_e32 v183, v183
	s_nop 0
	v_mul_f32_e32 v181, 0x45800000, v183
	v_cndmask_b32_e32 v184, v183, v181, vcc
	v_mov_b32_e32 v185, v184
	v_cvt_pk_bf16_f32 v80, v144, v145
	v_cvt_pk_bf16_f32 v81, v146, v147
	v_cvt_pk_bf16_f32 v82, v148, v149
	v_cvt_pk_bf16_f32 v83, v150, v151
	v_cvt_pk_bf16_f32 v84, v152, v153
	v_cvt_pk_bf16_f32 v85, v154, v155
	v_cvt_pk_bf16_f32 v86, v156, v157
	v_cvt_pk_bf16_f32 v87, v158, v159
	v_add_u32_e32 v181, 0x2c00000, v177
	global_store_dwordx4 v181, v[80:83], s[78:79]
	global_store_dwordx4 v181, v[84:87], s[78:79] offset:1024
	v_add_u32_e32 v236, 0xa000, v237
	s_mov_b64 exec, 1
	global_store_dword v236, v184, s[78:79]
	s_mov_b64 exec, -1
	s_waitcnt vmcnt(4)
	v_lshlrev_b32_e32 v144, 16, v96
	v_and_b32_e32 v145, 0xffff0000, v96
	v_lshlrev_b32_e32 v146, 16, v97
	v_and_b32_e32 v147, 0xffff0000, v97
	v_lshlrev_b32_e32 v148, 16, v98
	v_and_b32_e32 v149, 0xffff0000, v98
	v_lshlrev_b32_e32 v150, 16, v99
	v_and_b32_e32 v151, 0xffff0000, v99
	v_lshlrev_b32_e32 v152, 16, v100
	v_and_b32_e32 v153, 0xffff0000, v100
	v_lshlrev_b32_e32 v154, 16, v101
	v_and_b32_e32 v155, 0xffff0000, v101
	v_lshlrev_b32_e32 v156, 16, v102
	v_and_b32_e32 v157, 0xffff0000, v102
	v_lshlrev_b32_e32 v158, 16, v103
	v_and_b32_e32 v159, 0xffff0000, v103
	v_lshlrev_b32_e32 v160, 16, v104
	v_and_b32_e32 v161, 0xffff0000, v104
	v_lshlrev_b32_e32 v162, 16, v105
	v_and_b32_e32 v163, 0xffff0000, v105
	v_lshlrev_b32_e32 v164, 16, v106
	v_and_b32_e32 v165, 0xffff0000, v106
	v_lshlrev_b32_e32 v166, 16, v107
	v_and_b32_e32 v167, 0xffff0000, v107
	v_lshlrev_b32_e32 v168, 16, v108
	v_and_b32_e32 v169, 0xffff0000, v108
	v_lshlrev_b32_e32 v170, 16, v109
	v_and_b32_e32 v171, 0xffff0000, v109
	v_lshlrev_b32_e32 v172, 16, v110
	v_and_b32_e32 v173, 0xffff0000, v110
	v_lshlrev_b32_e32 v174, 16, v111
	v_and_b32_e32 v175, 0xffff0000, v111
	v_pk_mul_f32 v[252:253], v[160:161], v[160:161]
	v_pk_mul_f32 v[254:255], v[162:163], v[162:163]
	v_pk_fma_f32 v[252:253], v[164:165], v[164:165], v[252:253]
	v_pk_fma_f32 v[254:255], v[166:167], v[166:167], v[254:255]
	v_pk_fma_f32 v[252:253], v[168:169], v[168:169], v[252:253]
	v_pk_fma_f32 v[254:255], v[170:171], v[170:171], v[254:255]
	v_pk_fma_f32 v[252:253], v[172:173], v[172:173], v[252:253]
	v_pk_fma_f32 v[254:255], v[174:175], v[174:175], v[254:255]
	v_pk_add_f32 v[252:253], v[252:253], v[254:255]
	s_nop 0
	v_add_f32_e32 v183, v252, v253
	s_nop 1
	v_add_f32_dpp v183, v183, v183 quad_perm:[1,0,3,2] row_mask:0xf bank_mask:0xf bound_ctrl:1
	s_nop 1
	v_add_f32_dpp v183, v183, v183 quad_perm:[2,3,0,1] row_mask:0xf bank_mask:0xf bound_ctrl:1
	s_nop 1
	v_add_f32_dpp v183, v183, v183 row_half_mirror row_mask:0xf bank_mask:0xf bound_ctrl:1
	s_nop 1
	v_add_f32_dpp v183, v183, v183 row_mirror row_mask:0xf bank_mask:0xf bound_ctrl:1
	s_nop 1
	v_readlane_b32 s98, v183, 0
	v_readlane_b32 s99, v183, 16
	v_readlane_b32 s100, v183, 32
	v_readlane_b32 s101, v183, 48
	s_nop 1
	v_mov_b32_e32 v183, s98
	v_add_f32_e32 v183, s99, v183
	v_add_f32_e32 v183, s100, v183
	v_add_f32_e32 v183, s101, v183
	v_fmamk_f32 v183, v183, 0x3a800000, v182
	v_cmp_gt_f32_e32 vcc, 0x800000, v183
	v_mul_f32_e32 v181, 0x4b800000, v183
	s_nop 1
	v_cndmask_b32_e32 v183, v183, v181, vcc
	v_rsq_f32_e32 v183, v183
	s_nop 0
	v_mul_f32_e32 v181, 0x45800000, v183
	v_cndmask_b32_e32 v184, v183, v181, vcc
	v_mov_b32_e32 v185, v184
	v_pk_mul_f32 v[160:161], v[160:161], v[184:185]
	v_pk_mul_f32 v[162:163], v[162:163], v[184:185]
	v_pk_mul_f32 v[164:165], v[164:165], v[184:185]
	v_pk_mul_f32 v[166:167], v[166:167], v[184:185]
	v_pk_mul_f32 v[168:169], v[168:169], v[184:185]
	v_pk_mul_f32 v[170:171], v[170:171], v[184:185]
	v_pk_mul_f32 v[172:173], v[172:173], v[184:185]
	v_pk_mul_f32 v[174:175], v[174:175], v[184:185]
	v_pk_fma_f32 v[144:145], v[160:161], v[128:129], v[144:145]
	v_pk_fma_f32 v[146:147], v[162:163], v[130:131], v[146:147]
	v_pk_fma_f32 v[148:149], v[164:165], v[132:133], v[148:149]
	v_pk_fma_f32 v[150:151], v[166:167], v[134:135], v[150:151]
	v_pk_fma_f32 v[152:153], v[168:169], v[136:137], v[152:153]
	v_pk_fma_f32 v[154:155], v[170:171], v[138:139], v[154:155]
	v_pk_fma_f32 v[156:157], v[172:173], v[140:141], v[156:157]
	v_pk_fma_f32 v[158:159], v[174:175], v[142:143], v[158:159]
	v_pk_mul_f32 v[252:253], v[144:145], v[144:145]
	v_pk_mul_f32 v[254:255], v[146:147], v[146:147]
	v_pk_fma_f32 v[252:253], v[148:149], v[148:149], v[252:253]
	v_pk_fma_f32 v[254:255], v[150:151], v[150:151], v[254:255]
	v_pk_fma_f32 v[252:253], v[152:153], v[152:153], v[252:253]
	v_pk_fma_f32 v[254:255], v[154:155], v[154:155], v[254:255]
	v_pk_fma_f32 v[252:253], v[156:157], v[156:157], v[252:253]
	v_pk_fma_f32 v[254:255], v[158:159], v[158:159], v[254:255]
	v_pk_add_f32 v[252:253], v[252:253], v[254:255]
	s_nop 0
	v_add_f32_e32 v183, v252, v253
	s_nop 1
	v_add_f32_dpp v183, v183, v183 quad_perm:[1,0,3,2] row_mask:0xf bank_mask:0xf bound_ctrl:1
	s_nop 1
	v_add_f32_dpp v183, v183, v183 quad_perm:[2,3,0,1] row_mask:0xf bank_mask:0xf bound_ctrl:1
	s_nop 1
	v_add_f32_dpp v183, v183, v183 row_half_mirror row_mask:0xf bank_mask:0xf bound_ctrl:1
	s_nop 1
	v_add_f32_dpp v183, v183, v183 row_mirror row_mask:0xf bank_mask:0xf bound_ctrl:1
	s_nop 1
	v_readlane_b32 s98, v183, 0
	v_readlane_b32 s99, v183, 16
	v_readlane_b32 s100, v183, 32
	v_readlane_b32 s101, v183, 48
	s_nop 1
	v_mov_b32_e32 v183, s98
	v_add_f32_e32 v183, s99, v183
	v_add_f32_e32 v183, s100, v183
	v_add_f32_e32 v183, s101, v183
	v_fmamk_f32 v183, v183, 0x3a800000, v182
	v_cmp_gt_f32_e32 vcc, 0x800000, v183
	v_mul_f32_e32 v181, 0x4b800000, v183
	s_nop 1
	v_cndmask_b32_e32 v183, v183, v181, vcc
	v_rsq_f32_e32 v183, v183
	s_nop 0
	v_mul_f32_e32 v181, 0x45800000, v183
	v_cndmask_b32_e32 v184, v183, v181, vcc
	v_mov_b32_e32 v185, v184
	v_cvt_pk_bf16_f32 v96, v144, v145
	v_cvt_pk_bf16_f32 v97, v146, v147
	v_cvt_pk_bf16_f32 v98, v148, v149
	v_cvt_pk_bf16_f32 v99, v150, v151
	v_cvt_pk_bf16_f32 v100, v152, v153
	v_cvt_pk_bf16_f32 v101, v154, v155
	v_cvt_pk_bf16_f32 v102, v156, v157
	v_cvt_pk_bf16_f32 v103, v158, v159
	v_add_u32_e32 v181, 0x3000000, v177
	global_store_dwordx4 v181, v[96:99], s[78:79]
	global_store_dwordx4 v181, v[100:103], s[78:79] offset:1024
	v_add_u32_e32 v236, 0xc000, v237
	s_mov_b64 exec, 1
	global_store_dword v236, v184, s[78:79]
	s_mov_b64 exec, -1
	s_waitcnt vmcnt(0)
	v_lshlrev_b32_e32 v144, 16, v112
	v_and_b32_e32 v145, 0xffff0000, v112
	v_lshlrev_b32_e32 v146, 16, v113
	v_and_b32_e32 v147, 0xffff0000, v113
	v_lshlrev_b32_e32 v148, 16, v114
	v_and_b32_e32 v149, 0xffff0000, v114
	v_lshlrev_b32_e32 v150, 16, v115
	v_and_b32_e32 v151, 0xffff0000, v115
	v_lshlrev_b32_e32 v152, 16, v116
	v_and_b32_e32 v153, 0xffff0000, v116
	v_lshlrev_b32_e32 v154, 16, v117
	v_and_b32_e32 v155, 0xffff0000, v117
	v_lshlrev_b32_e32 v156, 16, v118
	v_and_b32_e32 v157, 0xffff0000, v118
	v_lshlrev_b32_e32 v158, 16, v119
	v_and_b32_e32 v159, 0xffff0000, v119
	v_lshlrev_b32_e32 v160, 16, v120
	v_and_b32_e32 v161, 0xffff0000, v120
	v_lshlrev_b32_e32 v162, 16, v121
	v_and_b32_e32 v163, 0xffff0000, v121
	v_lshlrev_b32_e32 v164, 16, v122
	v_and_b32_e32 v165, 0xffff0000, v122
	v_lshlrev_b32_e32 v166, 16, v123
	v_and_b32_e32 v167, 0xffff0000, v123
	v_lshlrev_b32_e32 v168, 16, v124
	v_and_b32_e32 v169, 0xffff0000, v124
	v_lshlrev_b32_e32 v170, 16, v125
	v_and_b32_e32 v171, 0xffff0000, v125
	v_lshlrev_b32_e32 v172, 16, v126
	v_and_b32_e32 v173, 0xffff0000, v126
	v_lshlrev_b32_e32 v174, 16, v127
	v_and_b32_e32 v175, 0xffff0000, v127
	v_pk_mul_f32 v[252:253], v[160:161], v[160:161]
	v_pk_mul_f32 v[254:255], v[162:163], v[162:163]
	v_pk_fma_f32 v[252:253], v[164:165], v[164:165], v[252:253]
	v_pk_fma_f32 v[254:255], v[166:167], v[166:167], v[254:255]
	v_pk_fma_f32 v[252:253], v[168:169], v[168:169], v[252:253]
	v_pk_fma_f32 v[254:255], v[170:171], v[170:171], v[254:255]
	v_pk_fma_f32 v[252:253], v[172:173], v[172:173], v[252:253]
	v_pk_fma_f32 v[254:255], v[174:175], v[174:175], v[254:255]
	v_pk_add_f32 v[252:253], v[252:253], v[254:255]
	s_nop 0
	v_add_f32_e32 v183, v252, v253
	s_nop 1
	v_add_f32_dpp v183, v183, v183 quad_perm:[1,0,3,2] row_mask:0xf bank_mask:0xf bound_ctrl:1
	s_nop 1
	v_add_f32_dpp v183, v183, v183 quad_perm:[2,3,0,1] row_mask:0xf bank_mask:0xf bound_ctrl:1
	s_nop 1
	v_add_f32_dpp v183, v183, v183 row_half_mirror row_mask:0xf bank_mask:0xf bound_ctrl:1
	s_nop 1
	v_add_f32_dpp v183, v183, v183 row_mirror row_mask:0xf bank_mask:0xf bound_ctrl:1
	s_nop 1
	v_readlane_b32 s98, v183, 0
	v_readlane_b32 s99, v183, 16
	v_readlane_b32 s100, v183, 32
	v_readlane_b32 s101, v183, 48
	s_nop 1
	v_mov_b32_e32 v183, s98
	v_add_f32_e32 v183, s99, v183
	v_add_f32_e32 v183, s100, v183
	v_add_f32_e32 v183, s101, v183
	v_fmamk_f32 v183, v183, 0x3a800000, v182
	v_cmp_gt_f32_e32 vcc, 0x800000, v183
	v_mul_f32_e32 v181, 0x4b800000, v183
	s_nop 1
	v_cndmask_b32_e32 v183, v183, v181, vcc
	v_rsq_f32_e32 v183, v183
	s_nop 0
	v_mul_f32_e32 v181, 0x45800000, v183
	v_cndmask_b32_e32 v184, v183, v181, vcc
	v_mov_b32_e32 v185, v184
	v_pk_mul_f32 v[160:161], v[160:161], v[184:185]
	v_pk_mul_f32 v[162:163], v[162:163], v[184:185]
	v_pk_mul_f32 v[164:165], v[164:165], v[184:185]
	v_pk_mul_f32 v[166:167], v[166:167], v[184:185]
	v_pk_mul_f32 v[168:169], v[168:169], v[184:185]
	v_pk_mul_f32 v[170:171], v[170:171], v[184:185]
	v_pk_mul_f32 v[172:173], v[172:173], v[184:185]
	v_pk_mul_f32 v[174:175], v[174:175], v[184:185]
	v_pk_fma_f32 v[144:145], v[160:161], v[128:129], v[144:145]
	v_pk_fma_f32 v[146:147], v[162:163], v[130:131], v[146:147]
	v_pk_fma_f32 v[148:149], v[164:165], v[132:133], v[148:149]
	v_pk_fma_f32 v[150:151], v[166:167], v[134:135], v[150:151]
	v_pk_fma_f32 v[152:153], v[168:169], v[136:137], v[152:153]
	v_pk_fma_f32 v[154:155], v[170:171], v[138:139], v[154:155]
	v_pk_fma_f32 v[156:157], v[172:173], v[140:141], v[156:157]
	v_pk_fma_f32 v[158:159], v[174:175], v[142:143], v[158:159]
	v_pk_mul_f32 v[252:253], v[144:145], v[144:145]
	v_pk_mul_f32 v[254:255], v[146:147], v[146:147]
	v_pk_fma_f32 v[252:253], v[148:149], v[148:149], v[252:253]
	v_pk_fma_f32 v[254:255], v[150:151], v[150:151], v[254:255]
	v_pk_fma_f32 v[252:253], v[152:153], v[152:153], v[252:253]
	v_pk_fma_f32 v[254:255], v[154:155], v[154:155], v[254:255]
	v_pk_fma_f32 v[252:253], v[156:157], v[156:157], v[252:253]
	v_pk_fma_f32 v[254:255], v[158:159], v[158:159], v[254:255]
	v_pk_add_f32 v[252:253], v[252:253], v[254:255]
	s_nop 0
	v_add_f32_e32 v183, v252, v253
	s_nop 1
	v_add_f32_dpp v183, v183, v183 quad_perm:[1,0,3,2] row_mask:0xf bank_mask:0xf bound_ctrl:1
	s_nop 1
	v_add_f32_dpp v183, v183, v183 quad_perm:[2,3,0,1] row_mask:0xf bank_mask:0xf bound_ctrl:1
	s_nop 1
	v_add_f32_dpp v183, v183, v183 row_half_mirror row_mask:0xf bank_mask:0xf bound_ctrl:1
	s_nop 1
	v_add_f32_dpp v183, v183, v183 row_mirror row_mask:0xf bank_mask:0xf bound_ctrl:1
	s_nop 1
	v_readlane_b32 s98, v183, 0
	v_readlane_b32 s99, v183, 16
	v_readlane_b32 s100, v183, 32
	v_readlane_b32 s101, v183, 48
	s_nop 1
	v_mov_b32_e32 v183, s98
	v_add_f32_e32 v183, s99, v183
	v_add_f32_e32 v183, s100, v183
	v_add_f32_e32 v183, s101, v183
	v_fmamk_f32 v183, v183, 0x3a800000, v182
	v_cmp_gt_f32_e32 vcc, 0x800000, v183
	v_mul_f32_e32 v181, 0x4b800000, v183
	s_nop 1
	v_cndmask_b32_e32 v183, v183, v181, vcc
	v_rsq_f32_e32 v183, v183
	s_nop 0
	v_mul_f32_e32 v181, 0x45800000, v183
	v_cndmask_b32_e32 v184, v183, v181, vcc
	v_mov_b32_e32 v185, v184
	v_cvt_pk_bf16_f32 v112, v144, v145
	v_cvt_pk_bf16_f32 v113, v146, v147
	v_cvt_pk_bf16_f32 v114, v148, v149
	v_cvt_pk_bf16_f32 v115, v150, v151
	v_cvt_pk_bf16_f32 v116, v152, v153
	v_cvt_pk_bf16_f32 v117, v154, v155
	v_cvt_pk_bf16_f32 v118, v156, v157
	v_cvt_pk_bf16_f32 v119, v158, v159
	v_add_u32_e32 v181, 0x3400000, v177
	global_store_dwordx4 v181, v[112:115], s[78:79]
	global_store_dwordx4 v181, v[116:119], s[78:79] offset:1024
	v_add_u32_e32 v236, 0xe000, v237
	s_mov_b64 exec, 1
	global_store_dword v236, v184, s[78:79]
	s_mov_b64 exec, -1
	v_readfirstlane_b32 s98, v179
	s_nop 3
	s_and_b32 s99, s98, 3
	s_cmp_lg_u32 s99, 0
	s_cbranch_scc1 .Lmyxupd_done_0
	v_lshrrev_b32_e32 v179, 2, v179
	v_lshlrev_b32_e32 v177, 4, v176
	v_lshl_add_u32 v177, v179, 11, v177
	v_lshlrev_b32_e32 v237, 2, v179
	v_add_u32_e32 v237, 0x10000, v237
	v_add_u32_e32 v181, 0x3800000, v177
	global_load_dwordx4 v[0:3], v181, s[78:79]
	global_load_dwordx4 v[4:7], v181, s[78:79] offset:1024
	v_lshl_add_u32 v183, v179, 12, v180
	v_add_u32_e32 v183, 0xbf00000, v183
	v_add_u32_e32 v181, 0x0, v183
	global_load_dwordx4 v[8:11], v181, s[78:79]
	global_load_dwordx4 v[12:15], v181, s[78:79] offset:16
	global_load_dwordx4 v[16:19], v181, s[78:79] offset:2048
	global_load_dwordx4 v[20:23], v181, s[78:79] offset:2064
	v_add_u32_e32 v181, 0x200000, v183
	global_load_dwordx4 v[24:27], v181, s[78:79]
	global_load_dwordx4 v[28:31], v181, s[78:79] offset:16
	global_load_dwordx4 v[32:35], v181, s[78:79] offset:2048
	global_load_dwordx4 v[36:39], v181, s[78:79] offset:2064
	v_add_u32_e32 v181, 0x400000, v183
	global_load_dwordx4 v[40:43], v181, s[78:79]
	global_load_dwordx4 v[44:47], v181, s[78:79] offset:16
	global_load_dwordx4 v[48:51], v181, s[78:79] offset:2048
	global_load_dwordx4 v[52:55], v181, s[78:79] offset:2064
	v_add_u32_e32 v181, 0x600000, v183
	global_load_dwordx4 v[56:59], v181, s[78:79]
	global_load_dwordx4 v[60:63], v181, s[78:79] offset:16
	global_load_dwordx4 v[64:67], v181, s[78:79] offset:2048
	global_load_dwordx4 v[68:71], v181, s[78:79] offset:2064
	v_add_u32_e32 v181, 0x800000, v183
	global_load_dwordx4 v[72:75], v181, s[78:79]
	global_load_dwordx4 v[76:79], v181, s[78:79] offset:16
	global_load_dwordx4 v[80:83], v181, s[78:79] offset:2048
	global_load_dwordx4 v[84:87], v181, s[78:79] offset:2064
	v_add_u32_e32 v181, 0xa00000, v183
	global_load_dwordx4 v[88:91], v181, s[78:79]
	global_load_dwordx4 v[92:95], v181, s[78:79] offset:16
	global_load_dwordx4 v[96:99], v181, s[78:79] offset:2048
	global_load_dwordx4 v[100:103], v181, s[78:79] offset:2064
	s_waitcnt vmcnt(20)
	v_pk_add_f32 v[160:161], v[8:9], 0 op_sel_hi:[1,0]
	v_pk_add_f32 v[162:163], v[10:11], 0 op_sel_hi:[1,0]
	v_pk_add_f32 v[164:165], v[12:13], 0 op_sel_hi:[1,0]
	v_pk_add_f32 v[166:167], v[14:15], 0 op_sel_hi:[1,0]
	v_pk_add_f32 v[168:169], v[16:17], 0 op_sel_hi:[1,0]
	v_pk_add_f32 v[170:171], v[18:19], 0 op_sel_hi:[1,0]
	v_pk_add_f32 v[172:173], v[20:21], 0 op_sel_hi:[1,0]
	v_pk_add_f32 v[174:175], v[22:23], 0 op_sel_hi:[1,0]
	s_waitcnt vmcnt(16)
	v_pk_add_f32 v[160:161], v[160:161], v[24:25]
	v_pk_add_f32 v[162:163], v[162:163], v[26:27]
	v_pk_add_f32 v[164:165], v[164:165], v[28:29]
	v_pk_add_f32 v[166:167], v[166:167], v[30:31]
	v_pk_add_f32 v[168:169], v[168:169], v[32:33]
	v_pk_add_f32 v[170:171], v[170:171], v[34:35]
	v_pk_add_f32 v[172:173], v[172:173], v[36:37]
	v_pk_add_f32 v[174:175], v[174:175], v[38:39]
	s_waitcnt vmcnt(12)
	v_pk_add_f32 v[160:161], v[160:161], v[40:41]
	v_pk_add_f32 v[162:163], v[162:163], v[42:43]
	v_pk_add_f32 v[164:165], v[164:165], v[44:45]
	v_pk_add_f32 v[166:167], v[166:167], v[46:47]
	v_pk_add_f32 v[168:169], v[168:169], v[48:49]
	v_pk_add_f32 v[170:171], v[170:171], v[50:51]
	v_pk_add_f32 v[172:173], v[172:173], v[52:53]
	v_pk_add_f32 v[174:175], v[174:175], v[54:55]
	s_waitcnt vmcnt(8)
	v_pk_add_f32 v[160:161], v[160:161], v[56:57]
	v_pk_add_f32 v[162:163], v[162:163], v[58:59]
	v_pk_add_f32 v[164:165], v[164:165], v[60:61]
	v_pk_add_f32 v[166:167], v[166:167], v[62:63]
	v_pk_add_f32 v[168:169], v[168:169], v[64:65]
	v_pk_add_f32 v[170:171], v[170:171], v[66:67]
	v_pk_add_f32 v[172:173], v[172:173], v[68:69]
	v_pk_add_f32 v[174:175], v[174:175], v[70:71]
	s_waitcnt vmcnt(4)
	v_pk_add_f32 v[160:161], v[160:161], v[72:73]
	v_pk_add_f32 v[162:163], v[162:163], v[74:75]
	v_pk_add_f32 v[164:165], v[164:165], v[76:77]
	v_pk_add_f32 v[166:167], v[166:167], v[78:79]
	v_pk_add_f32 v[168:169], v[168:169], v[80:81]
	v_pk_add_f32 v[170:171], v[170:171], v[82:83]
	v_pk_add_f32 v[172:173], v[172:173], v[84:85]
	v_pk_add_f32 v[174:175], v[174:175], v[86:87]
	s_waitcnt vmcnt(0)
	v_pk_add_f32 v[160:161], v[160:161], v[88:89]
	v_pk_add_f32 v[162:163], v[162:163], v[90:91]
	v_pk_add_f32 v[164:165], v[164:165], v[92:93]
	v_pk_add_f32 v[166:167], v[166:167], v[94:95]
	v_pk_add_f32 v[168:169], v[168:169], v[96:97]
	v_pk_add_f32 v[170:171], v[170:171], v[98:99]
	v_pk_add_f32 v[172:173], v[172:173], v[100:101]
	v_pk_add_f32 v[174:175], v[174:175], v[102:103]
	v_lshlrev_b32_e32 v144, 16, v0
	v_and_b32_e32 v145, 0xffff0000, v0
	v_lshlrev_b32_e32 v146, 16, v1
	v_and_b32_e32 v147, 0xffff0000, v1
	v_lshlrev_b32_e32 v148, 16, v2
	v_and_b32_e32 v149, 0xffff0000, v2
	v_lshlrev_b32_e32 v150, 16, v3
	v_and_b32_e32 v151, 0xffff0000, v3
	v_lshlrev_b32_e32 v152, 16, v4
	v_and_b32_e32 v153, 0xffff0000, v4
	v_lshlrev_b32_e32 v154, 16, v5
	v_and_b32_e32 v155, 0xffff0000, v5
	v_lshlrev_b32_e32 v156, 16, v6
	v_and_b32_e32 v157, 0xffff0000, v6
	v_lshlrev_b32_e32 v158, 16, v7
	v_and_b32_e32 v159, 0xffff0000, v7
	v_add_u32_e32 v181, 0xc00000, v183
	global_load_dwordx4 v[8:11], v181, s[78:79]
	global_load_dwordx4 v[12:15], v181, s[78:79] offset:16
	global_load_dwordx4 v[16:19], v181, s[78:79] offset:2048
	global_load_dwordx4 v[20:23], v181, s[78:79] offset:2064
	v_add_u32_e32 v181, 0xe00000, v183
	global_load_dwordx4 v[24:27], v181, s[78:79]
	global_load_dwordx4 v[28:31], v181, s[78:79] offset:16
	global_load_dwordx4 v[32:35], v181, s[78:79] offset:2048
	global_load_dwordx4 v[36:39], v181, s[78:79] offset:2064
	s_waitcnt vmcnt(4)
	v_pk_add_f32 v[160:161], v[160:161], v[8:9]
	v_pk_add_f32 v[162:163], v[162:163], v[10:11]
	v_pk_add_f32 v[164:165], v[164:165], v[12:13]
	v_pk_add_f32 v[166:167], v[166:167], v[14:15]
	v_pk_add_f32 v[168:169], v[168:169], v[16:17]
	v_pk_add_f32 v[170:171], v[170:171], v[18:19]
	v_pk_add_f32 v[172:173], v[172:173], v[20:21]
	v_pk_add_f32 v[174:175], v[174:175], v[22:23]
	s_waitcnt vmcnt(0)
	v_pk_add_f32 v[160:161], v[160:161], v[24:25]
	v_pk_add_f32 v[162:163], v[162:163], v[26:27]
	v_pk_add_f32 v[164:165], v[164:165], v[28:29]
	v_pk_add_f32 v[166:167], v[166:167], v[30:31]
	v_pk_add_f32 v[168:169], v[168:169], v[32:33]
	v_pk_add_f32 v[170:171], v[170:171], v[34:35]
	v_pk_add_f32 v[172:173], v[172:173], v[36:37]
	v_pk_add_f32 v[174:175], v[174:175], v[38:39]
	v_pk_mul_f32 v[252:253], v[160:161], v[160:161]
	v_pk_mul_f32 v[254:255], v[162:163], v[162:163]
	v_pk_fma_f32 v[252:253], v[164:165], v[164:165], v[252:253]
	v_pk_fma_f32 v[254:255], v[166:167], v[166:167], v[254:255]
	v_pk_fma_f32 v[252:253], v[168:169], v[168:169], v[252:253]
	v_pk_fma_f32 v[254:255], v[170:171], v[170:171], v[254:255]
	v_pk_fma_f32 v[252:253], v[172:173], v[172:173], v[252:253]
	v_pk_fma_f32 v[254:255], v[174:175], v[174:175], v[254:255]
	v_pk_add_f32 v[252:253], v[252:253], v[254:255]
	s_nop 0
	v_add_f32_e32 v183, v252, v253
	s_nop 1
	v_add_f32_dpp v183, v183, v183 quad_perm:[1,0,3,2] row_mask:0xf bank_mask:0xf bound_ctrl:1
	s_nop 1
	v_add_f32_dpp v183, v183, v183 quad_perm:[2,3,0,1] row_mask:0xf bank_mask:0xf bound_ctrl:1
	s_nop 1
	v_add_f32_dpp v183, v183, v183 row_half_mirror row_mask:0xf bank_mask:0xf bound_ctrl:1
	s_nop 1
	v_add_f32_dpp v183, v183, v183 row_mirror row_mask:0xf bank_mask:0xf bound_ctrl:1
	s_nop 1
	v_readlane_b32 s98, v183, 0
	v_readlane_b32 s99, v183, 16
	v_readlane_b32 s100, v183, 32
	v_readlane_b32 s101, v183, 48
	s_nop 1
	v_mov_b32_e32 v183, s98
	v_add_f32_e32 v183, s99, v183
	v_add_f32_e32 v183, s100, v183
	v_add_f32_e32 v183, s101, v183
	v_fmamk_f32 v183, v183, 0x3a800000, v182
	v_cmp_gt_f32_e32 vcc, 0x800000, v183
	v_mul_f32_e32 v181, 0x4b800000, v183
	s_nop 1
	v_cndmask_b32_e32 v183, v183, v181, vcc
	v_rsq_f32_e32 v183, v183
	s_nop 0
	v_mul_f32_e32 v181, 0x45800000, v183
	v_cndmask_b32_e32 v184, v183, v181, vcc
	v_mov_b32_e32 v185, v184
	v_pk_mul_f32 v[160:161], v[160:161], v[184:185]
	v_pk_mul_f32 v[162:163], v[162:163], v[184:185]
	v_pk_mul_f32 v[164:165], v[164:165], v[184:185]
	v_pk_mul_f32 v[166:167], v[166:167], v[184:185]
	v_pk_mul_f32 v[168:169], v[168:169], v[184:185]
	v_pk_mul_f32 v[170:171], v[170:171], v[184:185]
	v_pk_mul_f32 v[172:173], v[172:173], v[184:185]
	v_pk_mul_f32 v[174:175], v[174:175], v[184:185]
	v_pk_fma_f32 v[144:145], v[160:161], v[128:129], v[144:145]
	v_pk_fma_f32 v[146:147], v[162:163], v[130:131], v[146:147]
	v_pk_fma_f32 v[148:149], v[164:165], v[132:133], v[148:149]
	v_pk_fma_f32 v[150:151], v[166:167], v[134:135], v[150:151]
	v_pk_fma_f32 v[152:153], v[168:169], v[136:137], v[152:153]
	v_pk_fma_f32 v[154:155], v[170:171], v[138:139], v[154:155]
	v_pk_fma_f32 v[156:157], v[172:173], v[140:141], v[156:157]
	v_pk_fma_f32 v[158:159], v[174:175], v[142:143], v[158:159]
	v_pk_mul_f32 v[252:253], v[144:145], v[144:145]
	v_pk_mul_f32 v[254:255], v[146:147], v[146:147]
	v_pk_fma_f32 v[252:253], v[148:149], v[148:149], v[252:253]
	v_pk_fma_f32 v[254:255], v[150:151], v[150:151], v[254:255]
	v_pk_fma_f32 v[252:253], v[152:153], v[152:153], v[252:253]
	v_pk_fma_f32 v[254:255], v[154:155], v[154:155], v[254:255]
	v_pk_fma_f32 v[252:253], v[156:157], v[156:157], v[252:253]
	v_pk_fma_f32 v[254:255], v[158:159], v[158:159], v[254:255]
	v_pk_add_f32 v[252:253], v[252:253], v[254:255]
	s_nop 0
	v_add_f32_e32 v183, v252, v253
	s_nop 1
	v_add_f32_dpp v183, v183, v183 quad_perm:[1,0,3,2] row_mask:0xf bank_mask:0xf bound_ctrl:1
	s_nop 1
	v_add_f32_dpp v183, v183, v183 quad_perm:[2,3,0,1] row_mask:0xf bank_mask:0xf bound_ctrl:1
	s_nop 1
	v_add_f32_dpp v183, v183, v183 row_half_mirror row_mask:0xf bank_mask:0xf bound_ctrl:1
	s_nop 1
	v_add_f32_dpp v183, v183, v183 row_mirror row_mask:0xf bank_mask:0xf bound_ctrl:1
	s_nop 1
	v_readlane_b32 s98, v183, 0
	v_readlane_b32 s99, v183, 16
	v_readlane_b32 s100, v183, 32
	v_readlane_b32 s101, v183, 48
	s_nop 1
	v_mov_b32_e32 v183, s98
	v_add_f32_e32 v183, s99, v183
	v_add_f32_e32 v183, s100, v183
	v_add_f32_e32 v183, s101, v183
	v_fmamk_f32 v183, v183, 0x3a800000, v182
	v_cmp_gt_f32_e32 vcc, 0x800000, v183
	v_mul_f32_e32 v181, 0x4b800000, v183
	s_nop 1
	v_cndmask_b32_e32 v183, v183, v181, vcc
	v_rsq_f32_e32 v183, v183
	s_nop 0
	v_mul_f32_e32 v181, 0x45800000, v183
	v_cndmask_b32_e32 v184, v183, v181, vcc
	v_mov_b32_e32 v185, v184
	v_cvt_pk_bf16_f32 v0, v144, v145
	v_cvt_pk_bf16_f32 v1, v146, v147
	v_cvt_pk_bf16_f32 v2, v148, v149
	v_cvt_pk_bf16_f32 v3, v150, v151
	v_cvt_pk_bf16_f32 v4, v152, v153
	v_cvt_pk_bf16_f32 v5, v154, v155
	v_cvt_pk_bf16_f32 v6, v156, v157
	v_cvt_pk_bf16_f32 v7, v158, v159
	v_add_u32_e32 v181, 0x3800000, v177
	global_store_dwordx4 v181, v[0:3], s[78:79]
	global_store_dwordx4 v181, v[4:7], s[78:79] offset:1024
	v_add_u32_e32 v236, 0x10000, v237
	s_mov_b64 exec, 1
	global_store_dword v236, v184, s[78:79]
	s_mov_b64 exec, -1

.LBB0_721:
	v_readlane_b32 s0, v235, 52
	v_readlane_b32 s1, v235, 53
	s_and_b64 vcc, exec, s[0:1]
	s_waitcnt lgkmcnt(0)
	s_barrier
	v_mbcnt_lo_u32_b32 v0, -1, 0
	v_mbcnt_hi_u32_b32 v0, -1, v0
	v_writelane_b32 v234, s93, 4
	s_cbranch_vccnz .LBB0_741
	v_readlane_b32 s4, v235, 4
	v_readlane_b32 s8, v235, 8
	v_readlane_b32 s9, v235, 9
	v_readlane_b32 s6, v235, 6
	v_readlane_b32 s7, v235, 7
	v_readlane_b32 s12, v235, 12
	v_readlane_b32 s13, v235, 13
	v_readlane_b32 s8, v235, 61
	v_readlane_b32 s10, v235, 10
	v_readlane_b32 s6, v235, 0
	v_readlane_b32 s9, v235, 62
	s_mov_b32 s12, s8
	s_ashr_i32 s13, s8, 31
	v_lshlrev_b32_e32 v2, 3, v0
	v_readlane_b32 s11, v235, 11
	s_lshl_b32 s6, s6, 4
	s_add_i32 s0, s8, 0xffffc000
	s_lshl_b64 s[8:9], s[12:13], 2
	s_mov_b32 s10, s12
	v_ashrrev_i32_e32 v3, 31, v2
	v_readlane_b32 s5, v235, 5
	v_readlane_b32 s14, v235, 14
	v_readlane_b32 s15, v235, 15
	v_readlane_b32 s16, v235, 16
	v_readlane_b32 s17, v235, 17
	v_readlane_b32 s18, v235, 18
	v_readlane_b32 s19, v235, 19
	v_readlane_b32 s7, v235, 1
	s_add_u32 s80, s8, 0x10000
	v_writelane_b32 v235, s10, 61
	v_lshlrev_b64 v[4:5], 1, v[2:3]
	v_lshlrev_b64 v[2:3], 2, v[2:3]
	s_addc_u32 s14, s9, 0
	s_ashr_i32 s7, s6, 31
	v_writelane_b32 v235, s11, 62
	s_lshl_b64 s[10:11], s[12:13], 11
	v_lshl_add_u64 v[152:153], s[86:87], 0, v[4:5]
	v_lshl_add_u64 v[154:155], s[90:91], 0, v[2:3]
	v_lshl_add_u64 v[156:157], s[54:55], 0, v[4:5]
	v_lshl_add_u64 v[158:159], s[18:19], 0, v[2:3]
	s_mov_b32 s1, 0
	v_cmp_eq_u32_e64 s[4:5], 0, v0
	s_lshl_b64 s[8:9], s[6:7], 2
	v_lshl_add_u64 v[160:161], s[10:11], 0, v[4:5]
	s_lshl_b64 s[10:11], s[6:7], 11
	s_mov_b64 s[24:25], 0x600000
	s_mov_b64 s[26:27], 0x600800
	s_mov_b64 s[28:29], 0x800000
	s_mov_b32 s7, 0x800000
	s_mov_b64 s[36:37], 0x800800
	s_mov_b64 s[38:39], 0xa00000
	s_mov_b64 s[40:41], 0xa00800
	s_mov_b64 s[42:43], 0xc00000
	s_mov_b64 s[44:45], 0xc00800
	s_mov_b64 s[46:47], 0xe00000
	s_mov_b64 s[48:49], 0xe00800
	s_mov_b64 s[50:51], 0x1000000
	s_mov_b32 s15, 0x1000000
	s_mov_b64 s[12:13], 0x1000800
	s_mov_b64 s[82:83], 0x1200000
	s_mov_b32 s16, 0x1200000
	s_mov_b64 s[90:91], 0x1200800
	s_mov_b64 s[20:21], 0x1400000
	s_mov_b32 s17, 0x1400000
	s_mov_b64 s[22:23], 0x1400800
	v_mov_b32_e32 v215, 0
	v_mov_b32_e32 v216, 0x358637bd
	v_mbcnt_lo_u32_b32 v176, -1, 0
	v_mbcnt_hi_u32_b32 v176, -1, v176
	v_readlane_b32 s98, v235, 49
	v_readlane_b32 s99, v235, 20
	v_readlane_b32 s100, v235, 18
	v_readlane_b32 s101, v235, 19
	s_nop 3
	s_lshr_b32 vcc_lo, s98, 3
	s_and_b32 vcc_hi, vcc_lo, 7
	s_lshr_b32 vcc_lo, vcc_lo, 3
	s_lshl_b32 vcc_lo, vcc_lo, 3
	s_add_i32 vcc_lo, vcc_lo, s99
	s_lshl_b32 s98, vcc_hi, 8
	s_add_i32 s98, s98, vcc_lo
	s_mov_b32 s99, s98
	v_mov_b32_e32 v183, s99
	v_lshlrev_b32_e32 v177, 4, v176
	s_lshl_b32 s99, s99, 11
	v_add_u32_e32 v177, s99, v177
	v_add_u32_e32 v178, 0x1800000, v177
	v_add_u32_e32 v179, 0x9e00000, v177
	v_lshlrev_b32_e32 v180, 5, v176
	global_load_dwordx4 v[128:131], v180, s[100:101]
	global_load_dwordx4 v[132:135], v180, s[100:101] offset:16
	global_load_dwordx4 v[136:139], v180, s[100:101] offset:2048
	global_load_dwordx4 v[140:143], v180, s[100:101] offset:2064
	v_mov_b32_e32 v182, 0x358637bd
	global_load_dwordx4 v[0:3], v178, s[78:79]
	global_load_dwordx4 v[4:7], v178, s[78:79] offset:1024
	global_load_dwordx4 v[8:11], v179, s[78:79]
	global_load_dwordx4 v[12:15], v179, s[78:79] offset:1024
	v_add_u32_e32 v178, 0x400000, v178
	v_add_u32_e32 v179, 0x400000, v179
	global_load_dwordx4 v[16:19], v178, s[78:79]
	global_load_dwordx4 v[20:23], v178, s[78:79] offset:1024
	global_load_dwordx4 v[24:27], v179, s[78:79]
	global_load_dwordx4 v[28:31], v179, s[78:79] offset:1024
	v_add_u32_e32 v178, 0x400000, v178
	v_add_u32_e32 v179, 0x400000, v179
	global_load_dwordx4 v[32:35], v178, s[78:79]
	global_load_dwordx4 v[36:39], v178, s[78:79] offset:1024
	global_load_dwordx4 v[40:43], v179, s[78:79]
	global_load_dwordx4 v[44:47], v179, s[78:79] offset:1024
	v_add_u32_e32 v178, 0x400000, v178
	v_add_u32_e32 v179, 0x400000, v179
	global_load_dwordx4 v[48:51], v178, s[78:79]
	global_load_dwordx4 v[52:55], v178, s[78:79] offset:1024
	global_load_dwordx4 v[56:59], v179, s[78:79]
	global_load_dwordx4 v[60:63], v179, s[78:79] offset:1024
	v_add_u32_e32 v178, 0x400000, v178
	v_add_u32_e32 v179, 0x400000, v179
	global_load_dwordx4 v[64:67], v178, s[78:79]
	global_load_dwordx4 v[68:71], v178, s[78:79] offset:1024
	global_load_dwordx4 v[72:75], v179, s[78:79]
	global_load_dwordx4 v[76:79], v179, s[78:79] offset:1024
	v_add_u32_e32 v178, 0x400000, v178
	v_add_u32_e32 v179, 0x400000, v179
	global_load_dwordx4 v[80:83], v178, s[78:79]
	global_load_dwordx4 v[84:87], v178, s[78:79] offset:1024
	global_load_dwordx4 v[88:91], v179, s[78:79]
	global_load_dwordx4 v[92:95], v179, s[78:79] offset:1024
	v_add_u32_e32 v178, 0x400000, v178
	v_add_u32_e32 v179, 0x400000, v179
	global_load_dwordx4 v[96:99], v178, s[78:79]
	global_load_dwordx4 v[100:103], v178, s[78:79] offset:1024
	global_load_dwordx4 v[104:107], v179, s[78:79]
	global_load_dwordx4 v[108:111], v179, s[78:79] offset:1024
	v_add_u32_e32 v178, 0x400000, v178
	v_add_u32_e32 v179, 0x400000, v179
	global_load_dwordx4 v[112:115], v178, s[78:79]
	global_load_dwordx4 v[116:119], v178, s[78:79] offset:1024
	global_load_dwordx4 v[120:123], v179, s[78:79]
	global_load_dwordx4 v[124:127], v179, s[78:79] offset:1024
	v_lshlrev_b32_e32 v237, 2, v183
	v_add_u32_e32 v237, 0x10000, v237
	v_mov_b32_e32 v179, s98
	s_waitcnt vmcnt(28)
	v_lshlrev_b32_e32 v144, 16, v0
	v_and_b32_e32 v145, 0xffff0000, v0
	v_lshlrev_b32_e32 v146, 16, v1
	v_and_b32_e32 v147, 0xffff0000, v1
	v_lshlrev_b32_e32 v148, 16, v2
	v_and_b32_e32 v149, 0xffff0000, v2
	v_lshlrev_b32_e32 v150, 16, v3
	v_and_b32_e32 v151, 0xffff0000, v3
	v_lshlrev_b32_e32 v152, 16, v4
	v_and_b32_e32 v153, 0xffff0000, v4
	v_lshlrev_b32_e32 v154, 16, v5
	v_and_b32_e32 v155, 0xffff0000, v5
	v_lshlrev_b32_e32 v156, 16, v6
	v_and_b32_e32 v157, 0xffff0000, v6
	v_lshlrev_b32_e32 v158, 16, v7
	v_and_b32_e32 v159, 0xffff0000, v7
	v_lshlrev_b32_e32 v160, 16, v8
	v_and_b32_e32 v161, 0xffff0000, v8
	v_lshlrev_b32_e32 v162, 16, v9
	v_and_b32_e32 v163, 0xffff0000, v9
	v_lshlrev_b32_e32 v164, 16, v10
	v_and_b32_e32 v165, 0xffff0000, v10
	v_lshlrev_b32_e32 v166, 16, v11
	v_and_b32_e32 v167, 0xffff0000, v11
	v_lshlrev_b32_e32 v168, 16, v12
	v_and_b32_e32 v169, 0xffff0000, v12
	v_lshlrev_b32_e32 v170, 16, v13
	v_and_b32_e32 v171, 0xffff0000, v13
	v_lshlrev_b32_e32 v172, 16, v14
	v_and_b32_e32 v173, 0xffff0000, v14
	v_lshlrev_b32_e32 v174, 16, v15
	v_and_b32_e32 v175, 0xffff0000, v15
	v_pk_mul_f32 v[252:253], v[160:161], v[160:161]
	v_pk_mul_f32 v[254:255], v[162:163], v[162:163]
	v_pk_fma_f32 v[252:253], v[164:165], v[164:165], v[252:253]
	v_pk_fma_f32 v[254:255], v[166:167], v[166:167], v[254:255]
	v_pk_fma_f32 v[252:253], v[168:169], v[168:169], v[252:253]
	v_pk_fma_f32 v[254:255], v[170:171], v[170:171], v[254:255]
	v_pk_fma_f32 v[252:253], v[172:173], v[172:173], v[252:253]
	v_pk_fma_f32 v[254:255], v[174:175], v[174:175], v[254:255]
	v_pk_add_f32 v[252:253], v[252:253], v[254:255]
	s_nop 0
	v_add_f32_e32 v183, v252, v253
	s_nop 1
	v_add_f32_dpp v183, v183, v183 quad_perm:[1,0,3,2] row_mask:0xf bank_mask:0xf bound_ctrl:1
	s_nop 1
	v_add_f32_dpp v183, v183, v183 quad_perm:[2,3,0,1] row_mask:0xf bank_mask:0xf bound_ctrl:1
	s_nop 1
	v_add_f32_dpp v183, v183, v183 row_half_mirror row_mask:0xf bank_mask:0xf bound_ctrl:1
	s_nop 1
	v_add_f32_dpp v183, v183, v183 row_mirror row_mask:0xf bank_mask:0xf bound_ctrl:1
	s_nop 1
	v_readlane_b32 s98, v183, 0
	v_readlane_b32 s99, v183, 16
	v_readlane_b32 s100, v183, 32
	v_readlane_b32 s101, v183, 48
	s_nop 1
	v_mov_b32_e32 v183, s98
	v_add_f32_e32 v183, s99, v183
	v_add_f32_e32 v183, s100, v183
	v_add_f32_e32 v183, s101, v183
	v_fmamk_f32 v183, v183, 0x3a800000, v182
	v_cmp_gt_f32_e32 vcc, 0x800000, v183
	v_mul_f32_e32 v181, 0x4b800000, v183
	s_nop 1
	v_cndmask_b32_e32 v183, v183, v181, vcc
	v_rsq_f32_e32 v183, v183
	s_nop 0
	v_mul_f32_e32 v181, 0x45800000, v183
	v_cndmask_b32_e32 v184, v183, v181, vcc
	v_mov_b32_e32 v185, v184
	v_pk_mul_f32 v[160:161], v[160:161], v[184:185]
	v_pk_mul_f32 v[162:163], v[162:163], v[184:185]
	v_pk_mul_f32 v[164:165], v[164:165], v[184:185]
	v_pk_mul_f32 v[166:167], v[166:167], v[184:185]
	v_pk_mul_f32 v[168:169], v[168:169], v[184:185]
	v_pk_mul_f32 v[170:171], v[170:171], v[184:185]
	v_pk_mul_f32 v[172:173], v[172:173], v[184:185]
	v_pk_mul_f32 v[174:175], v[174:175], v[184:185]
	v_pk_fma_f32 v[144:145], v[160:161], v[128:129], v[144:145]
	v_pk_fma_f32 v[146:147], v[162:163], v[130:131], v[146:147]
	v_pk_fma_f32 v[148:149], v[164:165], v[132:133], v[148:149]
	v_pk_fma_f32 v[150:151], v[166:167], v[134:135], v[150:151]
	v_pk_fma_f32 v[152:153], v[168:169], v[136:137], v[152:153]
	v_pk_fma_f32 v[154:155], v[170:171], v[138:139], v[154:155]
	v_pk_fma_f32 v[156:157], v[172:173], v[140:141], v[156:157]
	v_pk_fma_f32 v[158:159], v[174:175], v[142:143], v[158:159]
	v_pk_mul_f32 v[252:253], v[144:145], v[144:145]
	v_pk_mul_f32 v[254:255], v[146:147], v[146:147]
	v_pk_fma_f32 v[252:253], v[148:149], v[148:149], v[252:253]
	v_pk_fma_f32 v[254:255], v[150:151], v[150:151], v[254:255]
	v_pk_fma_f32 v[252:253], v[152:153], v[152:153], v[252:253]
	v_pk_fma_f32 v[254:255], v[154:155], v[154:155], v[254:255]
	v_pk_fma_f32 v[252:253], v[156:157], v[156:157], v[252:253]
	v_pk_fma_f32 v[254:255], v[158:159], v[158:159], v[254:255]
	v_pk_add_f32 v[252:253], v[252:253], v[254:255]
	s_nop 0
	v_add_f32_e32 v183, v252, v253
	s_nop 1
	v_add_f32_dpp v183, v183, v183 quad_perm:[1,0,3,2] row_mask:0xf bank_mask:0xf bound_ctrl:1
	s_nop 1
	v_add_f32_dpp v183, v183, v183 quad_perm:[2,3,0,1] row_mask:0xf bank_mask:0xf bound_ctrl:1
	s_nop 1
	v_add_f32_dpp v183, v183, v183 row_half_mirror row_mask:0xf bank_mask:0xf bound_ctrl:1
	s_nop 1
	v_add_f32_dpp v183, v183, v183 row_mirror row_mask:0xf bank_mask:0xf bound_ctrl:1
	s_nop 1
	v_readlane_b32 s98, v183, 0
	v_readlane_b32 s99, v183, 16
	v_readlane_b32 s100, v183, 32
	v_readlane_b32 s101, v183, 48
	s_nop 1
	v_mov_b32_e32 v183, s98
	v_add_f32_e32 v183, s99, v183
	v_add_f32_e32 v183, s100, v183
	v_add_f32_e32 v183, s101, v183
	v_fmamk_f32 v183, v183, 0x3a800000, v182
	v_cmp_gt_f32_e32 vcc, 0x800000, v183
	v_mul_f32_e32 v181, 0x4b800000, v183
	s_nop 1
	v_cndmask_b32_e32 v183, v183, v181, vcc
	v_rsq_f32_e32 v183, v183
	s_nop 0
	v_mul_f32_e32 v181, 0x45800000, v183
	v_cndmask_b32_e32 v184, v183, v181, vcc
	v_mov_b32_e32 v185, v184
	v_cvt_pk_bf16_f32 v0, v144, v145
	v_cvt_pk_bf16_f32 v1, v146, v147
	v_cvt_pk_bf16_f32 v2, v148, v149
	v_cvt_pk_bf16_f32 v3, v150, v151
	v_cvt_pk_bf16_f32 v4, v152, v153
	v_cvt_pk_bf16_f32 v5, v154, v155
	v_cvt_pk_bf16_f32 v6, v156, v157
	v_cvt_pk_bf16_f32 v7, v158, v159
	v_add_u32_e32 v181, 0x1800000, v177
	global_store_dwordx4 v181, v[0:3], s[78:79]
	global_store_dwordx4 v181, v[4:7], s[78:79] offset:1024
	v_add_u32_e32 v236, 0x0, v237
	s_mov_b64 exec, 1
	global_store_dword v236, v184, s[78:79]
	s_mov_b64 exec, -1
	s_waitcnt vmcnt(24)
	v_lshlrev_b32_e32 v144, 16, v16
	v_and_b32_e32 v145, 0xffff0000, v16
	v_lshlrev_b32_e32 v146, 16, v17
	v_and_b32_e32 v147, 0xffff0000, v17
	v_lshlrev_b32_e32 v148, 16, v18
	v_and_b32_e32 v149, 0xffff0000, v18
	v_lshlrev_b32_e32 v150, 16, v19
	v_and_b32_e32 v151, 0xffff0000, v19
	v_lshlrev_b32_e32 v152, 16, v20
	v_and_b32_e32 v153, 0xffff0000, v20
	v_lshlrev_b32_e32 v154, 16, v21
	v_and_b32_e32 v155, 0xffff0000, v21
	v_lshlrev_b32_e32 v156, 16, v22
	v_and_b32_e32 v157, 0xffff0000, v22
	v_lshlrev_b32_e32 v158, 16, v23
	v_and_b32_e32 v159, 0xffff0000, v23
	v_lshlrev_b32_e32 v160, 16, v24
	v_and_b32_e32 v161, 0xffff0000, v24
	v_lshlrev_b32_e32 v162, 16, v25
	v_and_b32_e32 v163, 0xffff0000, v25
	v_lshlrev_b32_e32 v164, 16, v26
	v_and_b32_e32 v165, 0xffff0000, v26
	v_lshlrev_b32_e32 v166, 16, v27
	v_and_b32_e32 v167, 0xffff0000, v27
	v_lshlrev_b32_e32 v168, 16, v28
	v_and_b32_e32 v169, 0xffff0000, v28
	v_lshlrev_b32_e32 v170, 16, v29
	v_and_b32_e32 v171, 0xffff0000, v29
	v_lshlrev_b32_e32 v172, 16, v30
	v_and_b32_e32 v173, 0xffff0000, v30
	v_lshlrev_b32_e32 v174, 16, v31
	v_and_b32_e32 v175, 0xffff0000, v31
	v_pk_mul_f32 v[252:253], v[160:161], v[160:161]
	v_pk_mul_f32 v[254:255], v[162:163], v[162:163]
	v_pk_fma_f32 v[252:253], v[164:165], v[164:165], v[252:253]
	v_pk_fma_f32 v[254:255], v[166:167], v[166:167], v[254:255]
	v_pk_fma_f32 v[252:253], v[168:169], v[168:169], v[252:253]
	v_pk_fma_f32 v[254:255], v[170:171], v[170:171], v[254:255]
	v_pk_fma_f32 v[252:253], v[172:173], v[172:173], v[252:253]
	v_pk_fma_f32 v[254:255], v[174:175], v[174:175], v[254:255]
	v_pk_add_f32 v[252:253], v[252:253], v[254:255]
	s_nop 0
	v_add_f32_e32 v183, v252, v253
	s_nop 1
	v_add_f32_dpp v183, v183, v183 quad_perm:[1,0,3,2] row_mask:0xf bank_mask:0xf bound_ctrl:1
	s_nop 1
	v_add_f32_dpp v183, v183, v183 quad_perm:[2,3,0,1] row_mask:0xf bank_mask:0xf bound_ctrl:1
	s_nop 1
	v_add_f32_dpp v183, v183, v183 row_half_mirror row_mask:0xf bank_mask:0xf bound_ctrl:1
	s_nop 1
	v_add_f32_dpp v183, v183, v183 row_mirror row_mask:0xf bank_mask:0xf bound_ctrl:1
	s_nop 1
	v_readlane_b32 s98, v183, 0
	v_readlane_b32 s99, v183, 16
	v_readlane_b32 s100, v183, 32
	v_readlane_b32 s101, v183, 48
	s_nop 1
	v_mov_b32_e32 v183, s98
	v_add_f32_e32 v183, s99, v183
	v_add_f32_e32 v183, s100, v183
	v_add_f32_e32 v183, s101, v183
	v_fmamk_f32 v183, v183, 0x3a800000, v182
	v_cmp_gt_f32_e32 vcc, 0x800000, v183
	v_mul_f32_e32 v181, 0x4b800000, v183
	s_nop 1
	v_cndmask_b32_e32 v183, v183, v181, vcc
	v_rsq_f32_e32 v183, v183
	s_nop 0
	v_mul_f32_e32 v181, 0x45800000, v183
	v_cndmask_b32_e32 v184, v183, v181, vcc
	v_mov_b32_e32 v185, v184
	v_pk_mul_f32 v[160:161], v[160:161], v[184:185]
	v_pk_mul_f32 v[162:163], v[162:163], v[184:185]
	v_pk_mul_f32 v[164:165], v[164:165], v[184:185]
	v_pk_mul_f32 v[166:167], v[166:167], v[184:185]
	v_pk_mul_f32 v[168:169], v[168:169], v[184:185]
	v_pk_mul_f32 v[170:171], v[170:171], v[184:185]
	v_pk_mul_f32 v[172:173], v[172:173], v[184:185]
	v_pk_mul_f32 v[174:175], v[174:175], v[184:185]
	v_pk_fma_f32 v[144:145], v[160:161], v[128:129], v[144:145]
	v_pk_fma_f32 v[146:147], v[162:163], v[130:131], v[146:147]
	v_pk_fma_f32 v[148:149], v[164:165], v[132:133], v[148:149]
	v_pk_fma_f32 v[150:151], v[166:167], v[134:135], v[150:151]
	v_pk_fma_f32 v[152:153], v[168:169], v[136:137], v[152:153]
	v_pk_fma_f32 v[154:155], v[170:171], v[138:139], v[154:155]
	v_pk_fma_f32 v[156:157], v[172:173], v[140:141], v[156:157]
	v_pk_fma_f32 v[158:159], v[174:175], v[142:143], v[158:159]
	v_pk_mul_f32 v[252:253], v[144:145], v[144:145]
	v_pk_mul_f32 v[254:255], v[146:147], v[146:147]
	v_pk_fma_f32 v[252:253], v[148:149], v[148:149], v[252:253]
	v_pk_fma_f32 v[254:255], v[150:151], v[150:151], v[254:255]
	v_pk_fma_f32 v[252:253], v[152:153], v[152:153], v[252:253]
	v_pk_fma_f32 v[254:255], v[154:155], v[154:155], v[254:255]
	v_pk_fma_f32 v[252:253], v[156:157], v[156:157], v[252:253]
	v_pk_fma_f32 v[254:255], v[158:159], v[158:159], v[254:255]
	v_pk_add_f32 v[252:253], v[252:253], v[254:255]
	s_nop 0
	v_add_f32_e32 v183, v252, v253
	s_nop 1
	v_add_f32_dpp v183, v183, v183 quad_perm:[1,0,3,2] row_mask:0xf bank_mask:0xf bound_ctrl:1
	s_nop 1
	v_add_f32_dpp v183, v183, v183 quad_perm:[2,3,0,1] row_mask:0xf bank_mask:0xf bound_ctrl:1
	s_nop 1
	v_add_f32_dpp v183, v183, v183 row_half_mirror row_mask:0xf bank_mask:0xf bound_ctrl:1
	s_nop 1
	v_add_f32_dpp v183, v183, v183 row_mirror row_mask:0xf bank_mask:0xf bound_ctrl:1
	s_nop 1
	v_readlane_b32 s98, v183, 0
	v_readlane_b32 s99, v183, 16
	v_readlane_b32 s100, v183, 32
	v_readlane_b32 s101, v183, 48
	s_nop 1
	v_mov_b32_e32 v183, s98
	v_add_f32_e32 v183, s99, v183
	v_add_f32_e32 v183, s100, v183
	v_add_f32_e32 v183, s101, v183
	v_fmamk_f32 v183, v183, 0x3a800000, v182
	v_cmp_gt_f32_e32 vcc, 0x800000, v183
	v_mul_f32_e32 v181, 0x4b800000, v183
	s_nop 1
	v_cndmask_b32_e32 v183, v183, v181, vcc
	v_rsq_f32_e32 v183, v183
	s_nop 0
	v_mul_f32_e32 v181, 0x45800000, v183
	v_cndmask_b32_e32 v184, v183, v181, vcc
	v_mov_b32_e32 v185, v184
	v_cvt_pk_bf16_f32 v16, v144, v145
	v_cvt_pk_bf16_f32 v17, v146, v147
	v_cvt_pk_bf16_f32 v18, v148, v149
	v_cvt_pk_bf16_f32 v19, v150, v151
	v_cvt_pk_bf16_f32 v20, v152, v153
	v_cvt_pk_bf16_f32 v21, v154, v155
	v_cvt_pk_bf16_f32 v22, v156, v157
	v_cvt_pk_bf16_f32 v23, v158, v159
	v_add_u32_e32 v181, 0x1c00000, v177
	global_store_dwordx4 v181, v[16:19], s[78:79]
	global_store_dwordx4 v181, v[20:23], s[78:79] offset:1024
	v_add_u32_e32 v236, 0x2000, v237
	s_mov_b64 exec, 1
	global_store_dword v236, v184, s[78:79]
	s_mov_b64 exec, -1
	s_waitcnt vmcnt(20)
	v_lshlrev_b32_e32 v144, 16, v32
	v_and_b32_e32 v145, 0xffff0000, v32
	v_lshlrev_b32_e32 v146, 16, v33
	v_and_b32_e32 v147, 0xffff0000, v33
	v_lshlrev_b32_e32 v148, 16, v34
	v_and_b32_e32 v149, 0xffff0000, v34
	v_lshlrev_b32_e32 v150, 16, v35
	v_and_b32_e32 v151, 0xffff0000, v35
	v_lshlrev_b32_e32 v152, 16, v36
	v_and_b32_e32 v153, 0xffff0000, v36
	v_lshlrev_b32_e32 v154, 16, v37
	v_and_b32_e32 v155, 0xffff0000, v37
	v_lshlrev_b32_e32 v156, 16, v38
	v_and_b32_e32 v157, 0xffff0000, v38
	v_lshlrev_b32_e32 v158, 16, v39
	v_and_b32_e32 v159, 0xffff0000, v39
	v_lshlrev_b32_e32 v160, 16, v40
	v_and_b32_e32 v161, 0xffff0000, v40
	v_lshlrev_b32_e32 v162, 16, v41
	v_and_b32_e32 v163, 0xffff0000, v41
	v_lshlrev_b32_e32 v164, 16, v42
	v_and_b32_e32 v165, 0xffff0000, v42
	v_lshlrev_b32_e32 v166, 16, v43
	v_and_b32_e32 v167, 0xffff0000, v43
	v_lshlrev_b32_e32 v168, 16, v44
	v_and_b32_e32 v169, 0xffff0000, v44
	v_lshlrev_b32_e32 v170, 16, v45
	v_and_b32_e32 v171, 0xffff0000, v45
	v_lshlrev_b32_e32 v172, 16, v46
	v_and_b32_e32 v173, 0xffff0000, v46
	v_lshlrev_b32_e32 v174, 16, v47
	v_and_b32_e32 v175, 0xffff0000, v47
	v_pk_mul_f32 v[252:253], v[160:161], v[160:161]
	v_pk_mul_f32 v[254:255], v[162:163], v[162:163]
	v_pk_fma_f32 v[252:253], v[164:165], v[164:165], v[252:253]
	v_pk_fma_f32 v[254:255], v[166:167], v[166:167], v[254:255]
	v_pk_fma_f32 v[252:253], v[168:169], v[168:169], v[252:253]
	v_pk_fma_f32 v[254:255], v[170:171], v[170:171], v[254:255]
	v_pk_fma_f32 v[252:253], v[172:173], v[172:173], v[252:253]
	v_pk_fma_f32 v[254:255], v[174:175], v[174:175], v[254:255]
	v_pk_add_f32 v[252:253], v[252:253], v[254:255]
	s_nop 0
	v_add_f32_e32 v183, v252, v253
	s_nop 1
	v_add_f32_dpp v183, v183, v183 quad_perm:[1,0,3,2] row_mask:0xf bank_mask:0xf bound_ctrl:1
	s_nop 1
	v_add_f32_dpp v183, v183, v183 quad_perm:[2,3,0,1] row_mask:0xf bank_mask:0xf bound_ctrl:1
	s_nop 1
	v_add_f32_dpp v183, v183, v183 row_half_mirror row_mask:0xf bank_mask:0xf bound_ctrl:1
	s_nop 1
	v_add_f32_dpp v183, v183, v183 row_mirror row_mask:0xf bank_mask:0xf bound_ctrl:1
	s_nop 1
	v_readlane_b32 s98, v183, 0
	v_readlane_b32 s99, v183, 16
	v_readlane_b32 s100, v183, 32
	v_readlane_b32 s101, v183, 48
	s_nop 1
	v_mov_b32_e32 v183, s98
	v_add_f32_e32 v183, s99, v183
	v_add_f32_e32 v183, s100, v183
	v_add_f32_e32 v183, s101, v183
	v_fmamk_f32 v183, v183, 0x3a800000, v182
	v_cmp_gt_f32_e32 vcc, 0x800000, v183
	v_mul_f32_e32 v181, 0x4b800000, v183
	s_nop 1
	v_cndmask_b32_e32 v183, v183, v181, vcc
	v_rsq_f32_e32 v183, v183
	s_nop 0
	v_mul_f32_e32 v181, 0x45800000, v183
	v_cndmask_b32_e32 v184, v183, v181, vcc
	v_mov_b32_e32 v185, v184
	v_pk_mul_f32 v[160:161], v[160:161], v[184:185]
	v_pk_mul_f32 v[162:163], v[162:163], v[184:185]
	v_pk_mul_f32 v[164:165], v[164:165], v[184:185]
	v_pk_mul_f32 v[166:167], v[166:167], v[184:185]
	v_pk_mul_f32 v[168:169], v[168:169], v[184:185]
	v_pk_mul_f32 v[170:171], v[170:171], v[184:185]
	v_pk_mul_f32 v[172:173], v[172:173], v[184:185]
	v_pk_mul_f32 v[174:175], v[174:175], v[184:185]
	v_pk_fma_f32 v[144:145], v[160:161], v[128:129], v[144:145]
	v_pk_fma_f32 v[146:147], v[162:163], v[130:131], v[146:147]
	v_pk_fma_f32 v[148:149], v[164:165], v[132:133], v[148:149]
	v_pk_fma_f32 v[150:151], v[166:167], v[134:135], v[150:151]
	v_pk_fma_f32 v[152:153], v[168:169], v[136:137], v[152:153]
	v_pk_fma_f32 v[154:155], v[170:171], v[138:139], v[154:155]
	v_pk_fma_f32 v[156:157], v[172:173], v[140:141], v[156:157]
	v_pk_fma_f32 v[158:159], v[174:175], v[142:143], v[158:159]
	v_pk_mul_f32 v[252:253], v[144:145], v[144:145]
	v_pk_mul_f32 v[254:255], v[146:147], v[146:147]
	v_pk_fma_f32 v[252:253], v[148:149], v[148:149], v[252:253]
	v_pk_fma_f32 v[254:255], v[150:151], v[150:151], v[254:255]
	v_pk_fma_f32 v[252:253], v[152:153], v[152:153], v[252:253]
	v_pk_fma_f32 v[254:255], v[154:155], v[154:155], v[254:255]
	v_pk_fma_f32 v[252:253], v[156:157], v[156:157], v[252:253]
	v_pk_fma_f32 v[254:255], v[158:159], v[158:159], v[254:255]
	v_pk_add_f32 v[252:253], v[252:253], v[254:255]
	s_nop 0
	v_add_f32_e32 v183, v252, v253
	s_nop 1
	v_add_f32_dpp v183, v183, v183 quad_perm:[1,0,3,2] row_mask:0xf bank_mask:0xf bound_ctrl:1
	s_nop 1
	v_add_f32_dpp v183, v183, v183 quad_perm:[2,3,0,1] row_mask:0xf bank_mask:0xf bound_ctrl:1
	s_nop 1
	v_add_f32_dpp v183, v183, v183 row_half_mirror row_mask:0xf bank_mask:0xf bound_ctrl:1
	s_nop 1
	v_add_f32_dpp v183, v183, v183 row_mirror row_mask:0xf bank_mask:0xf bound_ctrl:1
	s_nop 1
	v_readlane_b32 s98, v183, 0
	v_readlane_b32 s99, v183, 16
	v_readlane_b32 s100, v183, 32
	v_readlane_b32 s101, v183, 48
	s_nop 1
	v_mov_b32_e32 v183, s98
	v_add_f32_e32 v183, s99, v183
	v_add_f32_e32 v183, s100, v183
	v_add_f32_e32 v183, s101, v183
	v_fmamk_f32 v183, v183, 0x3a800000, v182
	v_cmp_gt_f32_e32 vcc, 0x800000, v183
	v_mul_f32_e32 v181, 0x4b800000, v183
	s_nop 1
	v_cndmask_b32_e32 v183, v183, v181, vcc
	v_rsq_f32_e32 v183, v183
	s_nop 0
	v_mul_f32_e32 v181, 0x45800000, v183
	v_cndmask_b32_e32 v184, v183, v181, vcc
	v_mov_b32_e32 v185, v184
	v_cvt_pk_bf16_f32 v32, v144, v145
	v_cvt_pk_bf16_f32 v33, v146, v147
	v_cvt_pk_bf16_f32 v34, v148, v149
	v_cvt_pk_bf16_f32 v35, v150, v151
	v_cvt_pk_bf16_f32 v36, v152, v153
	v_cvt_pk_bf16_f32 v37, v154, v155
	v_cvt_pk_bf16_f32 v38, v156, v157
	v_cvt_pk_bf16_f32 v39, v158, v159
	v_add_u32_e32 v181, 0x2000000, v177
	global_store_dwordx4 v181, v[32:35], s[78:79]
	global_store_dwordx4 v181, v[36:39], s[78:79] offset:1024
	v_add_u32_e32 v236, 0x4000, v237
	s_mov_b64 exec, 1
	global_store_dword v236, v184, s[78:79]
	s_mov_b64 exec, -1
	s_waitcnt vmcnt(16)
	v_lshlrev_b32_e32 v144, 16, v48
	v_and_b32_e32 v145, 0xffff0000, v48
	v_lshlrev_b32_e32 v146, 16, v49
	v_and_b32_e32 v147, 0xffff0000, v49
	v_lshlrev_b32_e32 v148, 16, v50
	v_and_b32_e32 v149, 0xffff0000, v50
	v_lshlrev_b32_e32 v150, 16, v51
	v_and_b32_e32 v151, 0xffff0000, v51
	v_lshlrev_b32_e32 v152, 16, v52
	v_and_b32_e32 v153, 0xffff0000, v52
	v_lshlrev_b32_e32 v154, 16, v53
	v_and_b32_e32 v155, 0xffff0000, v53
	v_lshlrev_b32_e32 v156, 16, v54
	v_and_b32_e32 v157, 0xffff0000, v54
	v_lshlrev_b32_e32 v158, 16, v55
	v_and_b32_e32 v159, 0xffff0000, v55
	v_lshlrev_b32_e32 v160, 16, v56
	v_and_b32_e32 v161, 0xffff0000, v56
	v_lshlrev_b32_e32 v162, 16, v57
	v_and_b32_e32 v163, 0xffff0000, v57
	v_lshlrev_b32_e32 v164, 16, v58
	v_and_b32_e32 v165, 0xffff0000, v58
	v_lshlrev_b32_e32 v166, 16, v59
	v_and_b32_e32 v167, 0xffff0000, v59
	v_lshlrev_b32_e32 v168, 16, v60
	v_and_b32_e32 v169, 0xffff0000, v60
	v_lshlrev_b32_e32 v170, 16, v61
	v_and_b32_e32 v171, 0xffff0000, v61
	v_lshlrev_b32_e32 v172, 16, v62
	v_and_b32_e32 v173, 0xffff0000, v62
	v_lshlrev_b32_e32 v174, 16, v63
	v_and_b32_e32 v175, 0xffff0000, v63
	v_pk_mul_f32 v[252:253], v[160:161], v[160:161]
	v_pk_mul_f32 v[254:255], v[162:163], v[162:163]
	v_pk_fma_f32 v[252:253], v[164:165], v[164:165], v[252:253]
	v_pk_fma_f32 v[254:255], v[166:167], v[166:167], v[254:255]
	v_pk_fma_f32 v[252:253], v[168:169], v[168:169], v[252:253]
	v_pk_fma_f32 v[254:255], v[170:171], v[170:171], v[254:255]
	v_pk_fma_f32 v[252:253], v[172:173], v[172:173], v[252:253]
	v_pk_fma_f32 v[254:255], v[174:175], v[174:175], v[254:255]
	v_pk_add_f32 v[252:253], v[252:253], v[254:255]
	s_nop 0
	v_add_f32_e32 v183, v252, v253
	s_nop 1
	v_add_f32_dpp v183, v183, v183 quad_perm:[1,0,3,2] row_mask:0xf bank_mask:0xf bound_ctrl:1
	s_nop 1
	v_add_f32_dpp v183, v183, v183 quad_perm:[2,3,0,1] row_mask:0xf bank_mask:0xf bound_ctrl:1
	s_nop 1
	v_add_f32_dpp v183, v183, v183 row_half_mirror row_mask:0xf bank_mask:0xf bound_ctrl:1
	s_nop 1
	v_add_f32_dpp v183, v183, v183 row_mirror row_mask:0xf bank_mask:0xf bound_ctrl:1
	s_nop 1
	v_readlane_b32 s98, v183, 0
	v_readlane_b32 s99, v183, 16
	v_readlane_b32 s100, v183, 32
	v_readlane_b32 s101, v183, 48
	s_nop 1
	v_mov_b32_e32 v183, s98
	v_add_f32_e32 v183, s99, v183
	v_add_f32_e32 v183, s100, v183
	v_add_f32_e32 v183, s101, v183
	v_fmamk_f32 v183, v183, 0x3a800000, v182
	v_cmp_gt_f32_e32 vcc, 0x800000, v183
	v_mul_f32_e32 v181, 0x4b800000, v183
	s_nop 1
	v_cndmask_b32_e32 v183, v183, v181, vcc
	v_rsq_f32_e32 v183, v183
	s_nop 0
	v_mul_f32_e32 v181, 0x45800000, v183
	v_cndmask_b32_e32 v184, v183, v181, vcc
	v_mov_b32_e32 v185, v184
	v_pk_mul_f32 v[160:161], v[160:161], v[184:185]
	v_pk_mul_f32 v[162:163], v[162:163], v[184:185]
	v_pk_mul_f32 v[164:165], v[164:165], v[184:185]
	v_pk_mul_f32 v[166:167], v[166:167], v[184:185]
	v_pk_mul_f32 v[168:169], v[168:169], v[184:185]
	v_pk_mul_f32 v[170:171], v[170:171], v[184:185]
	v_pk_mul_f32 v[172:173], v[172:173], v[184:185]
	v_pk_mul_f32 v[174:175], v[174:175], v[184:185]
	v_pk_fma_f32 v[144:145], v[160:161], v[128:129], v[144:145]
	v_pk_fma_f32 v[146:147], v[162:163], v[130:131], v[146:147]
	v_pk_fma_f32 v[148:149], v[164:165], v[132:133], v[148:149]
	v_pk_fma_f32 v[150:151], v[166:167], v[134:135], v[150:151]
	v_pk_fma_f32 v[152:153], v[168:169], v[136:137], v[152:153]
	v_pk_fma_f32 v[154:155], v[170:171], v[138:139], v[154:155]
	v_pk_fma_f32 v[156:157], v[172:173], v[140:141], v[156:157]
	v_pk_fma_f32 v[158:159], v[174:175], v[142:143], v[158:159]
	v_pk_mul_f32 v[252:253], v[144:145], v[144:145]
	v_pk_mul_f32 v[254:255], v[146:147], v[146:147]
	v_pk_fma_f32 v[252:253], v[148:149], v[148:149], v[252:253]
	v_pk_fma_f32 v[254:255], v[150:151], v[150:151], v[254:255]
	v_pk_fma_f32 v[252:253], v[152:153], v[152:153], v[252:253]
	v_pk_fma_f32 v[254:255], v[154:155], v[154:155], v[254:255]
	v_pk_fma_f32 v[252:253], v[156:157], v[156:157], v[252:253]
	v_pk_fma_f32 v[254:255], v[158:159], v[158:159], v[254:255]
	v_pk_add_f32 v[252:253], v[252:253], v[254:255]
	s_nop 0
	v_add_f32_e32 v183, v252, v253
	s_nop 1
	v_add_f32_dpp v183, v183, v183 quad_perm:[1,0,3,2] row_mask:0xf bank_mask:0xf bound_ctrl:1
	s_nop 1
	v_add_f32_dpp v183, v183, v183 quad_perm:[2,3,0,1] row_mask:0xf bank_mask:0xf bound_ctrl:1
	s_nop 1
	v_add_f32_dpp v183, v183, v183 row_half_mirror row_mask:0xf bank_mask:0xf bound_ctrl:1
	s_nop 1
	v_add_f32_dpp v183, v183, v183 row_mirror row_mask:0xf bank_mask:0xf bound_ctrl:1
	s_nop 1
	v_readlane_b32 s98, v183, 0
	v_readlane_b32 s99, v183, 16
	v_readlane_b32 s100, v183, 32
	v_readlane_b32 s101, v183, 48
	s_nop 1
	v_mov_b32_e32 v183, s98
	v_add_f32_e32 v183, s99, v183
	v_add_f32_e32 v183, s100, v183
	v_add_f32_e32 v183, s101, v183
	v_fmamk_f32 v183, v183, 0x3a800000, v182
	v_cmp_gt_f32_e32 vcc, 0x800000, v183
	v_mul_f32_e32 v181, 0x4b800000, v183
	s_nop 1
	v_cndmask_b32_e32 v183, v183, v181, vcc
	v_rsq_f32_e32 v183, v183
	s_nop 0
	v_mul_f32_e32 v181, 0x45800000, v183
	v_cndmask_b32_e32 v184, v183, v181, vcc
	v_mov_b32_e32 v185, v184
	v_cvt_pk_bf16_f32 v48, v144, v145
	v_cvt_pk_bf16_f32 v49, v146, v147
	v_cvt_pk_bf16_f32 v50, v148, v149
	v_cvt_pk_bf16_f32 v51, v150, v151
	v_cvt_pk_bf16_f32 v52, v152, v153
	v_cvt_pk_bf16_f32 v53, v154, v155
	v_cvt_pk_bf16_f32 v54, v156, v157
	v_cvt_pk_bf16_f32 v55, v158, v159
	v_add_u32_e32 v181, 0x2400000, v177
	global_store_dwordx4 v181, v[48:51], s[78:79]
	global_store_dwordx4 v181, v[52:55], s[78:79] offset:1024
	v_add_u32_e32 v236, 0x6000, v237
	s_mov_b64 exec, 1
	global_store_dword v236, v184, s[78:79]
	s_mov_b64 exec, -1
	s_waitcnt vmcnt(12)
	v_lshlrev_b32_e32 v144, 16, v64
	v_and_b32_e32 v145, 0xffff0000, v64
	v_lshlrev_b32_e32 v146, 16, v65
	v_and_b32_e32 v147, 0xffff0000, v65
	v_lshlrev_b32_e32 v148, 16, v66
	v_and_b32_e32 v149, 0xffff0000, v66
	v_lshlrev_b32_e32 v150, 16, v67
	v_and_b32_e32 v151, 0xffff0000, v67
	v_lshlrev_b32_e32 v152, 16, v68
	v_and_b32_e32 v153, 0xffff0000, v68
	v_lshlrev_b32_e32 v154, 16, v69
	v_and_b32_e32 v155, 0xffff0000, v69
	v_lshlrev_b32_e32 v156, 16, v70
	v_and_b32_e32 v157, 0xffff0000, v70
	v_lshlrev_b32_e32 v158, 16, v71
	v_and_b32_e32 v159, 0xffff0000, v71
	v_lshlrev_b32_e32 v160, 16, v72
	v_and_b32_e32 v161, 0xffff0000, v72
	v_lshlrev_b32_e32 v162, 16, v73
	v_and_b32_e32 v163, 0xffff0000, v73
	v_lshlrev_b32_e32 v164, 16, v74
	v_and_b32_e32 v165, 0xffff0000, v74
	v_lshlrev_b32_e32 v166, 16, v75
	v_and_b32_e32 v167, 0xffff0000, v75
	v_lshlrev_b32_e32 v168, 16, v76
	v_and_b32_e32 v169, 0xffff0000, v76
	v_lshlrev_b32_e32 v170, 16, v77
	v_and_b32_e32 v171, 0xffff0000, v77
	v_lshlrev_b32_e32 v172, 16, v78
	v_and_b32_e32 v173, 0xffff0000, v78
	v_lshlrev_b32_e32 v174, 16, v79
	v_and_b32_e32 v175, 0xffff0000, v79
	v_pk_mul_f32 v[252:253], v[160:161], v[160:161]
	v_pk_mul_f32 v[254:255], v[162:163], v[162:163]
	v_pk_fma_f32 v[252:253], v[164:165], v[164:165], v[252:253]
	v_pk_fma_f32 v[254:255], v[166:167], v[166:167], v[254:255]
	v_pk_fma_f32 v[252:253], v[168:169], v[168:169], v[252:253]
	v_pk_fma_f32 v[254:255], v[170:171], v[170:171], v[254:255]
	v_pk_fma_f32 v[252:253], v[172:173], v[172:173], v[252:253]
	v_pk_fma_f32 v[254:255], v[174:175], v[174:175], v[254:255]
	v_pk_add_f32 v[252:253], v[252:253], v[254:255]
	s_nop 0
	v_add_f32_e32 v183, v252, v253
	s_nop 1
	v_add_f32_dpp v183, v183, v183 quad_perm:[1,0,3,2] row_mask:0xf bank_mask:0xf bound_ctrl:1
	s_nop 1
	v_add_f32_dpp v183, v183, v183 quad_perm:[2,3,0,1] row_mask:0xf bank_mask:0xf bound_ctrl:1
	s_nop 1
	v_add_f32_dpp v183, v183, v183 row_half_mirror row_mask:0xf bank_mask:0xf bound_ctrl:1
	s_nop 1
	v_add_f32_dpp v183, v183, v183 row_mirror row_mask:0xf bank_mask:0xf bound_ctrl:1
	s_nop 1
	v_readlane_b32 s98, v183, 0
	v_readlane_b32 s99, v183, 16
	v_readlane_b32 s100, v183, 32
	v_readlane_b32 s101, v183, 48
	s_nop 1
	v_mov_b32_e32 v183, s98
	v_add_f32_e32 v183, s99, v183
	v_add_f32_e32 v183, s100, v183
	v_add_f32_e32 v183, s101, v183
	v_fmamk_f32 v183, v183, 0x3a800000, v182
	v_cmp_gt_f32_e32 vcc, 0x800000, v183
	v_mul_f32_e32 v181, 0x4b800000, v183
	s_nop 1
	v_cndmask_b32_e32 v183, v183, v181, vcc
	v_rsq_f32_e32 v183, v183
	s_nop 0
	v_mul_f32_e32 v181, 0x45800000, v183
	v_cndmask_b32_e32 v184, v183, v181, vcc
	v_mov_b32_e32 v185, v184
	v_pk_mul_f32 v[160:161], v[160:161], v[184:185]
	v_pk_mul_f32 v[162:163], v[162:163], v[184:185]
	v_pk_mul_f32 v[164:165], v[164:165], v[184:185]
	v_pk_mul_f32 v[166:167], v[166:167], v[184:185]
	v_pk_mul_f32 v[168:169], v[168:169], v[184:185]
	v_pk_mul_f32 v[170:171], v[170:171], v[184:185]
	v_pk_mul_f32 v[172:173], v[172:173], v[184:185]
	v_pk_mul_f32 v[174:175], v[174:175], v[184:185]
	v_pk_fma_f32 v[144:145], v[160:161], v[128:129], v[144:145]
	v_pk_fma_f32 v[146:147], v[162:163], v[130:131], v[146:147]
	v_pk_fma_f32 v[148:149], v[164:165], v[132:133], v[148:149]
	v_pk_fma_f32 v[150:151], v[166:167], v[134:135], v[150:151]
	v_pk_fma_f32 v[152:153], v[168:169], v[136:137], v[152:153]
	v_pk_fma_f32 v[154:155], v[170:171], v[138:139], v[154:155]
	v_pk_fma_f32 v[156:157], v[172:173], v[140:141], v[156:157]
	v_pk_fma_f32 v[158:159], v[174:175], v[142:143], v[158:159]
	v_pk_mul_f32 v[252:253], v[144:145], v[144:145]
	v_pk_mul_f32 v[254:255], v[146:147], v[146:147]
	v_pk_fma_f32 v[252:253], v[148:149], v[148:149], v[252:253]
	v_pk_fma_f32 v[254:255], v[150:151], v[150:151], v[254:255]
	v_pk_fma_f32 v[252:253], v[152:153], v[152:153], v[252:253]
	v_pk_fma_f32 v[254:255], v[154:155], v[154:155], v[254:255]
	v_pk_fma_f32 v[252:253], v[156:157], v[156:157], v[252:253]
	v_pk_fma_f32 v[254:255], v[158:159], v[158:159], v[254:255]
	v_pk_add_f32 v[252:253], v[252:253], v[254:255]
	s_nop 0
	v_add_f32_e32 v183, v252, v253
	s_nop 1
	v_add_f32_dpp v183, v183, v183 quad_perm:[1,0,3,2] row_mask:0xf bank_mask:0xf bound_ctrl:1
	s_nop 1
	v_add_f32_dpp v183, v183, v183 quad_perm:[2,3,0,1] row_mask:0xf bank_mask:0xf bound_ctrl:1
	s_nop 1
	v_add_f32_dpp v183, v183, v183 row_half_mirror row_mask:0xf bank_mask:0xf bound_ctrl:1
	s_nop 1
	v_add_f32_dpp v183, v183, v183 row_mirror row_mask:0xf bank_mask:0xf bound_ctrl:1
	s_nop 1
	v_readlane_b32 s98, v183, 0
	v_readlane_b32 s99, v183, 16
	v_readlane_b32 s100, v183, 32
	v_readlane_b32 s101, v183, 48
	s_nop 1
	v_mov_b32_e32 v183, s98
	v_add_f32_e32 v183, s99, v183
	v_add_f32_e32 v183, s100, v183
	v_add_f32_e32 v183, s101, v183
	v_fmamk_f32 v183, v183, 0x3a800000, v182
	v_cmp_gt_f32_e32 vcc, 0x800000, v183
	v_mul_f32_e32 v181, 0x4b800000, v183
	s_nop 1
	v_cndmask_b32_e32 v183, v183, v181, vcc
	v_rsq_f32_e32 v183, v183
	s_nop 0
	v_mul_f32_e32 v181, 0x45800000, v183
	v_cndmask_b32_e32 v184, v183, v181, vcc
	v_mov_b32_e32 v185, v184
	v_cvt_pk_bf16_f32 v64, v144, v145
	v_cvt_pk_bf16_f32 v65, v146, v147
	v_cvt_pk_bf16_f32 v66, v148, v149
	v_cvt_pk_bf16_f32 v67, v150, v151
	v_cvt_pk_bf16_f32 v68, v152, v153
	v_cvt_pk_bf16_f32 v69, v154, v155
	v_cvt_pk_bf16_f32 v70, v156, v157
	v_cvt_pk_bf16_f32 v71, v158, v159
	v_add_u32_e32 v181, 0x2800000, v177
	global_store_dwordx4 v181, v[64:67], s[78:79]
	global_store_dwordx4 v181, v[68:71], s[78:79] offset:1024
	v_add_u32_e32 v236, 0x8000, v237
	s_mov_b64 exec, 1
	global_store_dword v236, v184, s[78:79]
	s_mov_b64 exec, -1
	s_waitcnt vmcnt(8)
	v_lshlrev_b32_e32 v144, 16, v80
	v_and_b32_e32 v145, 0xffff0000, v80
	v_lshlrev_b32_e32 v146, 16, v81
	v_and_b32_e32 v147, 0xffff0000, v81
	v_lshlrev_b32_e32 v148, 16, v82
	v_and_b32_e32 v149, 0xffff0000, v82
	v_lshlrev_b32_e32 v150, 16, v83
	v_and_b32_e32 v151, 0xffff0000, v83
	v_lshlrev_b32_e32 v152, 16, v84
	v_and_b32_e32 v153, 0xffff0000, v84
	v_lshlrev_b32_e32 v154, 16, v85
	v_and_b32_e32 v155, 0xffff0000, v85
	v_lshlrev_b32_e32 v156, 16, v86
	v_and_b32_e32 v157, 0xffff0000, v86
	v_lshlrev_b32_e32 v158, 16, v87
	v_and_b32_e32 v159, 0xffff0000, v87
	v_lshlrev_b32_e32 v160, 16, v88
	v_and_b32_e32 v161, 0xffff0000, v88
	v_lshlrev_b32_e32 v162, 16, v89
	v_and_b32_e32 v163, 0xffff0000, v89
	v_lshlrev_b32_e32 v164, 16, v90
	v_and_b32_e32 v165, 0xffff0000, v90
	v_lshlrev_b32_e32 v166, 16, v91
	v_and_b32_e32 v167, 0xffff0000, v91
	v_lshlrev_b32_e32 v168, 16, v92
	v_and_b32_e32 v169, 0xffff0000, v92
	v_lshlrev_b32_e32 v170, 16, v93
	v_and_b32_e32 v171, 0xffff0000, v93
	v_lshlrev_b32_e32 v172, 16, v94
	v_and_b32_e32 v173, 0xffff0000, v94
	v_lshlrev_b32_e32 v174, 16, v95
	v_and_b32_e32 v175, 0xffff0000, v95
	v_pk_mul_f32 v[252:253], v[160:161], v[160:161]
	v_pk_mul_f32 v[254:255], v[162:163], v[162:163]
	v_pk_fma_f32 v[252:253], v[164:165], v[164:165], v[252:253]
	v_pk_fma_f32 v[254:255], v[166:167], v[166:167], v[254:255]
	v_pk_fma_f32 v[252:253], v[168:169], v[168:169], v[252:253]
	v_pk_fma_f32 v[254:255], v[170:171], v[170:171], v[254:255]
	v_pk_fma_f32 v[252:253], v[172:173], v[172:173], v[252:253]
	v_pk_fma_f32 v[254:255], v[174:175], v[174:175], v[254:255]
	v_pk_add_f32 v[252:253], v[252:253], v[254:255]
	s_nop 0
	v_add_f32_e32 v183, v252, v253
	s_nop 1
	v_add_f32_dpp v183, v183, v183 quad_perm:[1,0,3,2] row_mask:0xf bank_mask:0xf bound_ctrl:1
	s_nop 1
	v_add_f32_dpp v183, v183, v183 quad_perm:[2,3,0,1] row_mask:0xf bank_mask:0xf bound_ctrl:1
	s_nop 1
	v_add_f32_dpp v183, v183, v183 row_half_mirror row_mask:0xf bank_mask:0xf bound_ctrl:1
	s_nop 1
	v_add_f32_dpp v183, v183, v183 row_mirror row_mask:0xf bank_mask:0xf bound_ctrl:1
	s_nop 1
	v_readlane_b32 s98, v183, 0
	v_readlane_b32 s99, v183, 16
	v_readlane_b32 s100, v183, 32
	v_readlane_b32 s101, v183, 48
	s_nop 1
	v_mov_b32_e32 v183, s98
	v_add_f32_e32 v183, s99, v183
	v_add_f32_e32 v183, s100, v183
	v_add_f32_e32 v183, s101, v183
	v_fmamk_f32 v183, v183, 0x3a800000, v182
	v_cmp_gt_f32_e32 vcc, 0x800000, v183
	v_mul_f32_e32 v181, 0x4b800000, v183
	s_nop 1
	v_cndmask_b32_e32 v183, v183, v181, vcc
	v_rsq_f32_e32 v183, v183
	s_nop 0
	v_mul_f32_e32 v181, 0x45800000, v183
	v_cndmask_b32_e32 v184, v183, v181, vcc
	v_mov_b32_e32 v185, v184
	v_pk_mul_f32 v[160:161], v[160:161], v[184:185]
	v_pk_mul_f32 v[162:163], v[162:163], v[184:185]
	v_pk_mul_f32 v[164:165], v[164:165], v[184:185]
	v_pk_mul_f32 v[166:167], v[166:167], v[184:185]
	v_pk_mul_f32 v[168:169], v[168:169], v[184:185]
	v_pk_mul_f32 v[170:171], v[170:171], v[184:185]
	v_pk_mul_f32 v[172:173], v[172:173], v[184:185]
	v_pk_mul_f32 v[174:175], v[174:175], v[184:185]
	v_pk_fma_f32 v[144:145], v[160:161], v[128:129], v[144:145]
	v_pk_fma_f32 v[146:147], v[162:163], v[130:131], v[146:147]
	v_pk_fma_f32 v[148:149], v[164:165], v[132:133], v[148:149]
	v_pk_fma_f32 v[150:151], v[166:167], v[134:135], v[150:151]
	v_pk_fma_f32 v[152:153], v[168:169], v[136:137], v[152:153]
	v_pk_fma_f32 v[154:155], v[170:171], v[138:139], v[154:155]
	v_pk_fma_f32 v[156:157], v[172:173], v[140:141], v[156:157]
	v_pk_fma_f32 v[158:159], v[174:175], v[142:143], v[158:159]
	v_pk_mul_f32 v[252:253], v[144:145], v[144:145]
	v_pk_mul_f32 v[254:255], v[146:147], v[146:147]
	v_pk_fma_f32 v[252:253], v[148:149], v[148:149], v[252:253]
	v_pk_fma_f32 v[254:255], v[150:151], v[150:151], v[254:255]
	v_pk_fma_f32 v[252:253], v[152:153], v[152:153], v[252:253]
	v_pk_fma_f32 v[254:255], v[154:155], v[154:155], v[254:255]
	v_pk_fma_f32 v[252:253], v[156:157], v[156:157], v[252:253]
	v_pk_fma_f32 v[254:255], v[158:159], v[158:159], v[254:255]
	v_pk_add_f32 v[252:253], v[252:253], v[254:255]
	s_nop 0
	v_add_f32_e32 v183, v252, v253
	s_nop 1
	v_add_f32_dpp v183, v183, v183 quad_perm:[1,0,3,2] row_mask:0xf bank_mask:0xf bound_ctrl:1
	s_nop 1
	v_add_f32_dpp v183, v183, v183 quad_perm:[2,3,0,1] row_mask:0xf bank_mask:0xf bound_ctrl:1
	s_nop 1
	v_add_f32_dpp v183, v183, v183 row_half_mirror row_mask:0xf bank_mask:0xf bound_ctrl:1
	s_nop 1
	v_add_f32_dpp v183, v183, v183 row_mirror row_mask:0xf bank_mask:0xf bound_ctrl:1
	s_nop 1
	v_readlane_b32 s98, v183, 0
	v_readlane_b32 s99, v183, 16
	v_readlane_b32 s100, v183, 32
	v_readlane_b32 s101, v183, 48
	s_nop 1
	v_mov_b32_e32 v183, s98
	v_add_f32_e32 v183, s99, v183
	v_add_f32_e32 v183, s100, v183
	v_add_f32_e32 v183, s101, v183
	v_fmamk_f32 v183, v183, 0x3a800000, v182
	v_cmp_gt_f32_e32 vcc, 0x800000, v183
	v_mul_f32_e32 v181, 0x4b800000, v183
	s_nop 1
	v_cndmask_b32_e32 v183, v183, v181, vcc
	v_rsq_f32_e32 v183, v183
	s_nop 0
	v_mul_f32_e32 v181, 0x45800000, v183
	v_cndmask_b32_e32 v184, v183, v181, vcc
	v_mov_b32_e32 v185, v184
	v_cvt_pk_bf16_f32 v80, v144, v145
	v_cvt_pk_bf16_f32 v81, v146, v147
	v_cvt_pk_bf16_f32 v82, v148, v149
	v_cvt_pk_bf16_f32 v83, v150, v151
	v_cvt_pk_bf16_f32 v84, v152, v153
	v_cvt_pk_bf16_f32 v85, v154, v155
	v_cvt_pk_bf16_f32 v86, v156, v157
	v_cvt_pk_bf16_f32 v87, v158, v159
	v_add_u32_e32 v181, 0x2c00000, v177
	global_store_dwordx4 v181, v[80:83], s[78:79]
	global_store_dwordx4 v181, v[84:87], s[78:79] offset:1024
	v_add_u32_e32 v236, 0xa000, v237
	s_mov_b64 exec, 1
	global_store_dword v236, v184, s[78:79]
	s_mov_b64 exec, -1
	s_waitcnt vmcnt(4)
	v_lshlrev_b32_e32 v144, 16, v96
	v_and_b32_e32 v145, 0xffff0000, v96
	v_lshlrev_b32_e32 v146, 16, v97
	v_and_b32_e32 v147, 0xffff0000, v97
	v_lshlrev_b32_e32 v148, 16, v98
	v_and_b32_e32 v149, 0xffff0000, v98
	v_lshlrev_b32_e32 v150, 16, v99
	v_and_b32_e32 v151, 0xffff0000, v99
	v_lshlrev_b32_e32 v152, 16, v100
	v_and_b32_e32 v153, 0xffff0000, v100
	v_lshlrev_b32_e32 v154, 16, v101
	v_and_b32_e32 v155, 0xffff0000, v101
	v_lshlrev_b32_e32 v156, 16, v102
	v_and_b32_e32 v157, 0xffff0000, v102
	v_lshlrev_b32_e32 v158, 16, v103
	v_and_b32_e32 v159, 0xffff0000, v103
	v_lshlrev_b32_e32 v160, 16, v104
	v_and_b32_e32 v161, 0xffff0000, v104
	v_lshlrev_b32_e32 v162, 16, v105
	v_and_b32_e32 v163, 0xffff0000, v105
	v_lshlrev_b32_e32 v164, 16, v106
	v_and_b32_e32 v165, 0xffff0000, v106
	v_lshlrev_b32_e32 v166, 16, v107
	v_and_b32_e32 v167, 0xffff0000, v107
	v_lshlrev_b32_e32 v168, 16, v108
	v_and_b32_e32 v169, 0xffff0000, v108
	v_lshlrev_b32_e32 v170, 16, v109
	v_and_b32_e32 v171, 0xffff0000, v109
	v_lshlrev_b32_e32 v172, 16, v110
	v_and_b32_e32 v173, 0xffff0000, v110
	v_lshlrev_b32_e32 v174, 16, v111
	v_and_b32_e32 v175, 0xffff0000, v111
	v_pk_mul_f32 v[252:253], v[160:161], v[160:161]
	v_pk_mul_f32 v[254:255], v[162:163], v[162:163]
	v_pk_fma_f32 v[252:253], v[164:165], v[164:165], v[252:253]
	v_pk_fma_f32 v[254:255], v[166:167], v[166:167], v[254:255]
	v_pk_fma_f32 v[252:253], v[168:169], v[168:169], v[252:253]
	v_pk_fma_f32 v[254:255], v[170:171], v[170:171], v[254:255]
	v_pk_fma_f32 v[252:253], v[172:173], v[172:173], v[252:253]
	v_pk_fma_f32 v[254:255], v[174:175], v[174:175], v[254:255]
	v_pk_add_f32 v[252:253], v[252:253], v[254:255]
	s_nop 0
	v_add_f32_e32 v183, v252, v253
	s_nop 1
	v_add_f32_dpp v183, v183, v183 quad_perm:[1,0,3,2] row_mask:0xf bank_mask:0xf bound_ctrl:1
	s_nop 1
	v_add_f32_dpp v183, v183, v183 quad_perm:[2,3,0,1] row_mask:0xf bank_mask:0xf bound_ctrl:1
	s_nop 1
	v_add_f32_dpp v183, v183, v183 row_half_mirror row_mask:0xf bank_mask:0xf bound_ctrl:1
	s_nop 1
	v_add_f32_dpp v183, v183, v183 row_mirror row_mask:0xf bank_mask:0xf bound_ctrl:1
	s_nop 1
	v_readlane_b32 s98, v183, 0
	v_readlane_b32 s99, v183, 16
	v_readlane_b32 s100, v183, 32
	v_readlane_b32 s101, v183, 48
	s_nop 1
	v_mov_b32_e32 v183, s98
	v_add_f32_e32 v183, s99, v183
	v_add_f32_e32 v183, s100, v183
	v_add_f32_e32 v183, s101, v183
	v_fmamk_f32 v183, v183, 0x3a800000, v182
	v_cmp_gt_f32_e32 vcc, 0x800000, v183
	v_mul_f32_e32 v181, 0x4b800000, v183
	s_nop 1
	v_cndmask_b32_e32 v183, v183, v181, vcc
	v_rsq_f32_e32 v183, v183
	s_nop 0
	v_mul_f32_e32 v181, 0x45800000, v183
	v_cndmask_b32_e32 v184, v183, v181, vcc
	v_mov_b32_e32 v185, v184
	v_pk_mul_f32 v[160:161], v[160:161], v[184:185]
	v_pk_mul_f32 v[162:163], v[162:163], v[184:185]
	v_pk_mul_f32 v[164:165], v[164:165], v[184:185]
	v_pk_mul_f32 v[166:167], v[166:167], v[184:185]
	v_pk_mul_f32 v[168:169], v[168:169], v[184:185]
	v_pk_mul_f32 v[170:171], v[170:171], v[184:185]
	v_pk_mul_f32 v[172:173], v[172:173], v[184:185]
	v_pk_mul_f32 v[174:175], v[174:175], v[184:185]
	v_pk_fma_f32 v[144:145], v[160:161], v[128:129], v[144:145]
	v_pk_fma_f32 v[146:147], v[162:163], v[130:131], v[146:147]
	v_pk_fma_f32 v[148:149], v[164:165], v[132:133], v[148:149]
	v_pk_fma_f32 v[150:151], v[166:167], v[134:135], v[150:151]
	v_pk_fma_f32 v[152:153], v[168:169], v[136:137], v[152:153]
	v_pk_fma_f32 v[154:155], v[170:171], v[138:139], v[154:155]
	v_pk_fma_f32 v[156:157], v[172:173], v[140:141], v[156:157]
	v_pk_fma_f32 v[158:159], v[174:175], v[142:143], v[158:159]
	v_pk_mul_f32 v[252:253], v[144:145], v[144:145]
	v_pk_mul_f32 v[254:255], v[146:147], v[146:147]
	v_pk_fma_f32 v[252:253], v[148:149], v[148:149], v[252:253]
	v_pk_fma_f32 v[254:255], v[150:151], v[150:151], v[254:255]
	v_pk_fma_f32 v[252:253], v[152:153], v[152:153], v[252:253]
	v_pk_fma_f32 v[254:255], v[154:155], v[154:155], v[254:255]
	v_pk_fma_f32 v[252:253], v[156:157], v[156:157], v[252:253]
	v_pk_fma_f32 v[254:255], v[158:159], v[158:159], v[254:255]
	v_pk_add_f32 v[252:253], v[252:253], v[254:255]
	s_nop 0
	v_add_f32_e32 v183, v252, v253
	s_nop 1
	v_add_f32_dpp v183, v183, v183 quad_perm:[1,0,3,2] row_mask:0xf bank_mask:0xf bound_ctrl:1
	s_nop 1
	v_add_f32_dpp v183, v183, v183 quad_perm:[2,3,0,1] row_mask:0xf bank_mask:0xf bound_ctrl:1
	s_nop 1
	v_add_f32_dpp v183, v183, v183 row_half_mirror row_mask:0xf bank_mask:0xf bound_ctrl:1
	s_nop 1
	v_add_f32_dpp v183, v183, v183 row_mirror row_mask:0xf bank_mask:0xf bound_ctrl:1
	s_nop 1
	v_readlane_b32 s98, v183, 0
	v_readlane_b32 s99, v183, 16
	v_readlane_b32 s100, v183, 32
	v_readlane_b32 s101, v183, 48
	s_nop 1
	v_mov_b32_e32 v183, s98
	v_add_f32_e32 v183, s99, v183
	v_add_f32_e32 v183, s100, v183
	v_add_f32_e32 v183, s101, v183
	v_fmamk_f32 v183, v183, 0x3a800000, v182
	v_cmp_gt_f32_e32 vcc, 0x800000, v183
	v_mul_f32_e32 v181, 0x4b800000, v183
	s_nop 1
	v_cndmask_b32_e32 v183, v183, v181, vcc
	v_rsq_f32_e32 v183, v183
	s_nop 0
	v_mul_f32_e32 v181, 0x45800000, v183
	v_cndmask_b32_e32 v184, v183, v181, vcc
	v_mov_b32_e32 v185, v184
	v_cvt_pk_bf16_f32 v96, v144, v145
	v_cvt_pk_bf16_f32 v97, v146, v147
	v_cvt_pk_bf16_f32 v98, v148, v149
	v_cvt_pk_bf16_f32 v99, v150, v151
	v_cvt_pk_bf16_f32 v100, v152, v153
	v_cvt_pk_bf16_f32 v101, v154, v155
	v_cvt_pk_bf16_f32 v102, v156, v157
	v_cvt_pk_bf16_f32 v103, v158, v159
	v_add_u32_e32 v181, 0x3000000, v177
	global_store_dwordx4 v181, v[96:99], s[78:79]
	global_store_dwordx4 v181, v[100:103], s[78:79] offset:1024
	v_add_u32_e32 v236, 0xc000, v237
	s_mov_b64 exec, 1
	global_store_dword v236, v184, s[78:79]
	s_mov_b64 exec, -1
	s_waitcnt vmcnt(0)
	v_lshlrev_b32_e32 v144, 16, v112
	v_and_b32_e32 v145, 0xffff0000, v112
	v_lshlrev_b32_e32 v146, 16, v113
	v_and_b32_e32 v147, 0xffff0000, v113
	v_lshlrev_b32_e32 v148, 16, v114
	v_and_b32_e32 v149, 0xffff0000, v114
	v_lshlrev_b32_e32 v150, 16, v115
	v_and_b32_e32 v151, 0xffff0000, v115
	v_lshlrev_b32_e32 v152, 16, v116
	v_and_b32_e32 v153, 0xffff0000, v116
	v_lshlrev_b32_e32 v154, 16, v117
	v_and_b32_e32 v155, 0xffff0000, v117
	v_lshlrev_b32_e32 v156, 16, v118
	v_and_b32_e32 v157, 0xffff0000, v118
	v_lshlrev_b32_e32 v158, 16, v119
	v_and_b32_e32 v159, 0xffff0000, v119
	v_lshlrev_b32_e32 v160, 16, v120
	v_and_b32_e32 v161, 0xffff0000, v120
	v_lshlrev_b32_e32 v162, 16, v121
	v_and_b32_e32 v163, 0xffff0000, v121
	v_lshlrev_b32_e32 v164, 16, v122
	v_and_b32_e32 v165, 0xffff0000, v122
	v_lshlrev_b32_e32 v166, 16, v123
	v_and_b32_e32 v167, 0xffff0000, v123
	v_lshlrev_b32_e32 v168, 16, v124
	v_and_b32_e32 v169, 0xffff0000, v124
	v_lshlrev_b32_e32 v170, 16, v125
	v_and_b32_e32 v171, 0xffff0000, v125
	v_lshlrev_b32_e32 v172, 16, v126
	v_and_b32_e32 v173, 0xffff0000, v126
	v_lshlrev_b32_e32 v174, 16, v127
	v_and_b32_e32 v175, 0xffff0000, v127
	v_pk_mul_f32 v[252:253], v[160:161], v[160:161]
	v_pk_mul_f32 v[254:255], v[162:163], v[162:163]
	v_pk_fma_f32 v[252:253], v[164:165], v[164:165], v[252:253]
	v_pk_fma_f32 v[254:255], v[166:167], v[166:167], v[254:255]
	v_pk_fma_f32 v[252:253], v[168:169], v[168:169], v[252:253]
	v_pk_fma_f32 v[254:255], v[170:171], v[170:171], v[254:255]
	v_pk_fma_f32 v[252:253], v[172:173], v[172:173], v[252:253]
	v_pk_fma_f32 v[254:255], v[174:175], v[174:175], v[254:255]
	v_pk_add_f32 v[252:253], v[252:253], v[254:255]
	s_nop 0
	v_add_f32_e32 v183, v252, v253
	s_nop 1
	v_add_f32_dpp v183, v183, v183 quad_perm:[1,0,3,2] row_mask:0xf bank_mask:0xf bound_ctrl:1
	s_nop 1
	v_add_f32_dpp v183, v183, v183 quad_perm:[2,3,0,1] row_mask:0xf bank_mask:0xf bound_ctrl:1
	s_nop 1
	v_add_f32_dpp v183, v183, v183 row_half_mirror row_mask:0xf bank_mask:0xf bound_ctrl:1
	s_nop 1
	v_add_f32_dpp v183, v183, v183 row_mirror row_mask:0xf bank_mask:0xf bound_ctrl:1
	s_nop 1
	v_readlane_b32 s98, v183, 0
	v_readlane_b32 s99, v183, 16
	v_readlane_b32 s100, v183, 32
	v_readlane_b32 s101, v183, 48
	s_nop 1
	v_mov_b32_e32 v183, s98
	v_add_f32_e32 v183, s99, v183
	v_add_f32_e32 v183, s100, v183
	v_add_f32_e32 v183, s101, v183
	v_fmamk_f32 v183, v183, 0x3a800000, v182
	v_cmp_gt_f32_e32 vcc, 0x800000, v183
	v_mul_f32_e32 v181, 0x4b800000, v183
	s_nop 1
	v_cndmask_b32_e32 v183, v183, v181, vcc
	v_rsq_f32_e32 v183, v183
	s_nop 0
	v_mul_f32_e32 v181, 0x45800000, v183
	v_cndmask_b32_e32 v184, v183, v181, vcc
	v_mov_b32_e32 v185, v184
	v_pk_mul_f32 v[160:161], v[160:161], v[184:185]
	v_pk_mul_f32 v[162:163], v[162:163], v[184:185]
	v_pk_mul_f32 v[164:165], v[164:165], v[184:185]
	v_pk_mul_f32 v[166:167], v[166:167], v[184:185]
	v_pk_mul_f32 v[168:169], v[168:169], v[184:185]
	v_pk_mul_f32 v[170:171], v[170:171], v[184:185]
	v_pk_mul_f32 v[172:173], v[172:173], v[184:185]
	v_pk_mul_f32 v[174:175], v[174:175], v[184:185]
	v_pk_fma_f32 v[144:145], v[160:161], v[128:129], v[144:145]
	v_pk_fma_f32 v[146:147], v[162:163], v[130:131], v[146:147]
	v_pk_fma_f32 v[148:149], v[164:165], v[132:133], v[148:149]
	v_pk_fma_f32 v[150:151], v[166:167], v[134:135], v[150:151]
	v_pk_fma_f32 v[152:153], v[168:169], v[136:137], v[152:153]
	v_pk_fma_f32 v[154:155], v[170:171], v[138:139], v[154:155]
	v_pk_fma_f32 v[156:157], v[172:173], v[140:141], v[156:157]
	v_pk_fma_f32 v[158:159], v[174:175], v[142:143], v[158:159]
	v_pk_mul_f32 v[252:253], v[144:145], v[144:145]
	v_pk_mul_f32 v[254:255], v[146:147], v[146:147]
	v_pk_fma_f32 v[252:253], v[148:149], v[148:149], v[252:253]
	v_pk_fma_f32 v[254:255], v[150:151], v[150:151], v[254:255]
	v_pk_fma_f32 v[252:253], v[152:153], v[152:153], v[252:253]
	v_pk_fma_f32 v[254:255], v[154:155], v[154:155], v[254:255]
	v_pk_fma_f32 v[252:253], v[156:157], v[156:157], v[252:253]
	v_pk_fma_f32 v[254:255], v[158:159], v[158:159], v[254:255]
	v_pk_add_f32 v[252:253], v[252:253], v[254:255]
	s_nop 0
	v_add_f32_e32 v183, v252, v253
	s_nop 1
	v_add_f32_dpp v183, v183, v183 quad_perm:[1,0,3,2] row_mask:0xf bank_mask:0xf bound_ctrl:1
	s_nop 1
	v_add_f32_dpp v183, v183, v183 quad_perm:[2,3,0,1] row_mask:0xf bank_mask:0xf bound_ctrl:1
	s_nop 1
	v_add_f32_dpp v183, v183, v183 row_half_mirror row_mask:0xf bank_mask:0xf bound_ctrl:1
	s_nop 1
	v_add_f32_dpp v183, v183, v183 row_mirror row_mask:0xf bank_mask:0xf bound_ctrl:1
	s_nop 1
	v_readlane_b32 s98, v183, 0
	v_readlane_b32 s99, v183, 16
	v_readlane_b32 s100, v183, 32
	v_readlane_b32 s101, v183, 48
	s_nop 1
	v_mov_b32_e32 v183, s98
	v_add_f32_e32 v183, s99, v183
	v_add_f32_e32 v183, s100, v183
	v_add_f32_e32 v183, s101, v183
	v_fmamk_f32 v183, v183, 0x3a800000, v182
	v_cmp_gt_f32_e32 vcc, 0x800000, v183
	v_mul_f32_e32 v181, 0x4b800000, v183
	s_nop 1
	v_cndmask_b32_e32 v183, v183, v181, vcc
	v_rsq_f32_e32 v183, v183
	s_nop 0
	v_mul_f32_e32 v181, 0x45800000, v183
	v_cndmask_b32_e32 v184, v183, v181, vcc
	v_mov_b32_e32 v185, v184
	v_cvt_pk_bf16_f32 v112, v144, v145
	v_cvt_pk_bf16_f32 v113, v146, v147
	v_cvt_pk_bf16_f32 v114, v148, v149
	v_cvt_pk_bf16_f32 v115, v150, v151
	v_cvt_pk_bf16_f32 v116, v152, v153
	v_cvt_pk_bf16_f32 v117, v154, v155
	v_cvt_pk_bf16_f32 v118, v156, v157
	v_cvt_pk_bf16_f32 v119, v158, v159
	v_add_u32_e32 v181, 0x3400000, v177
	global_store_dwordx4 v181, v[112:115], s[78:79]
	global_store_dwordx4 v181, v[116:119], s[78:79] offset:1024
	v_add_u32_e32 v236, 0xe000, v237
	s_mov_b64 exec, 1
	global_store_dword v236, v184, s[78:79]
	s_mov_b64 exec, -1
	v_readfirstlane_b32 s98, v179
	s_nop 3
	s_and_b32 s99, s98, 3
	s_cmp_lg_u32 s99, 0
	s_cbranch_scc1 .Lmyxupd_done_1
	v_lshrrev_b32_e32 v179, 2, v179
	v_lshlrev_b32_e32 v177, 4, v176
	v_lshl_add_u32 v177, v179, 11, v177
	v_lshlrev_b32_e32 v237, 2, v179
	v_add_u32_e32 v237, 0x10000, v237
	v_add_u32_e32 v181, 0x3800000, v177
	global_load_dwordx4 v[0:3], v181, s[78:79]
	global_load_dwordx4 v[4:7], v181, s[78:79] offset:1024
	v_lshl_add_u32 v183, v179, 12, v180
	v_add_u32_e32 v183, 0xbf00000, v183
	v_add_u32_e32 v181, 0x0, v183
	global_load_dwordx4 v[8:11], v181, s[78:79]
	global_load_dwordx4 v[12:15], v181, s[78:79] offset:16
	global_load_dwordx4 v[16:19], v181, s[78:79] offset:2048
	global_load_dwordx4 v[20:23], v181, s[78:79] offset:2064
	v_add_u32_e32 v181, 0x200000, v183
	global_load_dwordx4 v[24:27], v181, s[78:79]
	global_load_dwordx4 v[28:31], v181, s[78:79] offset:16
	global_load_dwordx4 v[32:35], v181, s[78:79] offset:2048
	global_load_dwordx4 v[36:39], v181, s[78:79] offset:2064
	v_add_u32_e32 v181, 0x400000, v183
	global_load_dwordx4 v[40:43], v181, s[78:79]
	global_load_dwordx4 v[44:47], v181, s[78:79] offset:16
	global_load_dwordx4 v[48:51], v181, s[78:79] offset:2048
	global_load_dwordx4 v[52:55], v181, s[78:79] offset:2064
	v_add_u32_e32 v181, 0x600000, v183
	global_load_dwordx4 v[56:59], v181, s[78:79]
	global_load_dwordx4 v[60:63], v181, s[78:79] offset:16
	global_load_dwordx4 v[64:67], v181, s[78:79] offset:2048
	global_load_dwordx4 v[68:71], v181, s[78:79] offset:2064
	v_add_u32_e32 v181, 0x800000, v183
	global_load_dwordx4 v[72:75], v181, s[78:79]
	global_load_dwordx4 v[76:79], v181, s[78:79] offset:16
	global_load_dwordx4 v[80:83], v181, s[78:79] offset:2048
	global_load_dwordx4 v[84:87], v181, s[78:79] offset:2064
	v_add_u32_e32 v181, 0xa00000, v183
	global_load_dwordx4 v[88:91], v181, s[78:79]
	global_load_dwordx4 v[92:95], v181, s[78:79] offset:16
	global_load_dwordx4 v[96:99], v181, s[78:79] offset:2048
	global_load_dwordx4 v[100:103], v181, s[78:79] offset:2064
	s_waitcnt vmcnt(20)
	v_pk_add_f32 v[160:161], v[8:9], 0 op_sel_hi:[1,0]
	v_pk_add_f32 v[162:163], v[10:11], 0 op_sel_hi:[1,0]
	v_pk_add_f32 v[164:165], v[12:13], 0 op_sel_hi:[1,0]
	v_pk_add_f32 v[166:167], v[14:15], 0 op_sel_hi:[1,0]
	v_pk_add_f32 v[168:169], v[16:17], 0 op_sel_hi:[1,0]
	v_pk_add_f32 v[170:171], v[18:19], 0 op_sel_hi:[1,0]
	v_pk_add_f32 v[172:173], v[20:21], 0 op_sel_hi:[1,0]
	v_pk_add_f32 v[174:175], v[22:23], 0 op_sel_hi:[1,0]
	s_waitcnt vmcnt(16)
	v_pk_add_f32 v[160:161], v[160:161], v[24:25]
	v_pk_add_f32 v[162:163], v[162:163], v[26:27]
	v_pk_add_f32 v[164:165], v[164:165], v[28:29]
	v_pk_add_f32 v[166:167], v[166:167], v[30:31]
	v_pk_add_f32 v[168:169], v[168:169], v[32:33]
	v_pk_add_f32 v[170:171], v[170:171], v[34:35]
	v_pk_add_f32 v[172:173], v[172:173], v[36:37]
	v_pk_add_f32 v[174:175], v[174:175], v[38:39]
	s_waitcnt vmcnt(12)
	v_pk_add_f32 v[160:161], v[160:161], v[40:41]
	v_pk_add_f32 v[162:163], v[162:163], v[42:43]
	v_pk_add_f32 v[164:165], v[164:165], v[44:45]
	v_pk_add_f32 v[166:167], v[166:167], v[46:47]
	v_pk_add_f32 v[168:169], v[168:169], v[48:49]
	v_pk_add_f32 v[170:171], v[170:171], v[50:51]
	v_pk_add_f32 v[172:173], v[172:173], v[52:53]
	v_pk_add_f32 v[174:175], v[174:175], v[54:55]
	s_waitcnt vmcnt(8)
	v_pk_add_f32 v[160:161], v[160:161], v[56:57]
	v_pk_add_f32 v[162:163], v[162:163], v[58:59]
	v_pk_add_f32 v[164:165], v[164:165], v[60:61]
	v_pk_add_f32 v[166:167], v[166:167], v[62:63]
	v_pk_add_f32 v[168:169], v[168:169], v[64:65]
	v_pk_add_f32 v[170:171], v[170:171], v[66:67]
	v_pk_add_f32 v[172:173], v[172:173], v[68:69]
	v_pk_add_f32 v[174:175], v[174:175], v[70:71]
	s_waitcnt vmcnt(4)
	v_pk_add_f32 v[160:161], v[160:161], v[72:73]
	v_pk_add_f32 v[162:163], v[162:163], v[74:75]
	v_pk_add_f32 v[164:165], v[164:165], v[76:77]
	v_pk_add_f32 v[166:167], v[166:167], v[78:79]
	v_pk_add_f32 v[168:169], v[168:169], v[80:81]
	v_pk_add_f32 v[170:171], v[170:171], v[82:83]
	v_pk_add_f32 v[172:173], v[172:173], v[84:85]
	v_pk_add_f32 v[174:175], v[174:175], v[86:87]
	s_waitcnt vmcnt(0)
	v_pk_add_f32 v[160:161], v[160:161], v[88:89]
	v_pk_add_f32 v[162:163], v[162:163], v[90:91]
	v_pk_add_f32 v[164:165], v[164:165], v[92:93]
	v_pk_add_f32 v[166:167], v[166:167], v[94:95]
	v_pk_add_f32 v[168:169], v[168:169], v[96:97]
	v_pk_add_f32 v[170:171], v[170:171], v[98:99]
	v_pk_add_f32 v[172:173], v[172:173], v[100:101]
	v_pk_add_f32 v[174:175], v[174:175], v[102:103]
	v_lshlrev_b32_e32 v144, 16, v0
	v_and_b32_e32 v145, 0xffff0000, v0
	v_lshlrev_b32_e32 v146, 16, v1
	v_and_b32_e32 v147, 0xffff0000, v1
	v_lshlrev_b32_e32 v148, 16, v2
	v_and_b32_e32 v149, 0xffff0000, v2
	v_lshlrev_b32_e32 v150, 16, v3
	v_and_b32_e32 v151, 0xffff0000, v3
	v_lshlrev_b32_e32 v152, 16, v4
	v_and_b32_e32 v153, 0xffff0000, v4
	v_lshlrev_b32_e32 v154, 16, v5
	v_and_b32_e32 v155, 0xffff0000, v5
	v_lshlrev_b32_e32 v156, 16, v6
	v_and_b32_e32 v157, 0xffff0000, v6
	v_lshlrev_b32_e32 v158, 16, v7
	v_and_b32_e32 v159, 0xffff0000, v7
	v_add_u32_e32 v181, 0xc00000, v183
	global_load_dwordx4 v[8:11], v181, s[78:79]
	global_load_dwordx4 v[12:15], v181, s[78:79] offset:16
	global_load_dwordx4 v[16:19], v181, s[78:79] offset:2048
	global_load_dwordx4 v[20:23], v181, s[78:79] offset:2064
	v_add_u32_e32 v181, 0xe00000, v183
	global_load_dwordx4 v[24:27], v181, s[78:79]
	global_load_dwordx4 v[28:31], v181, s[78:79] offset:16
	global_load_dwordx4 v[32:35], v181, s[78:79] offset:2048
	global_load_dwordx4 v[36:39], v181, s[78:79] offset:2064
	v_add_u32_e32 v181, 0x1000000, v183
	global_load_dwordx4 v[40:43], v181, s[78:79]
	global_load_dwordx4 v[44:47], v181, s[78:79] offset:16
	global_load_dwordx4 v[48:51], v181, s[78:79] offset:2048
	global_load_dwordx4 v[52:55], v181, s[78:79] offset:2064
	v_add_u32_e32 v181, 0x1200000, v183
	global_load_dwordx4 v[56:59], v181, s[78:79]
	global_load_dwordx4 v[60:63], v181, s[78:79] offset:16
	global_load_dwordx4 v[64:67], v181, s[78:79] offset:2048
	global_load_dwordx4 v[68:71], v181, s[78:79] offset:2064
	v_add_u32_e32 v181, 0x1400000, v183
	global_load_dwordx4 v[72:75], v181, s[78:79]
	global_load_dwordx4 v[76:79], v181, s[78:79] offset:16
	global_load_dwordx4 v[80:83], v181, s[78:79] offset:2048
	global_load_dwordx4 v[84:87], v181, s[78:79] offset:2064
	s_waitcnt vmcnt(16)
	v_pk_add_f32 v[160:161], v[160:161], v[8:9]
	v_pk_add_f32 v[162:163], v[162:163], v[10:11]
	v_pk_add_f32 v[164:165], v[164:165], v[12:13]
	v_pk_add_f32 v[166:167], v[166:167], v[14:15]
	v_pk_add_f32 v[168:169], v[168:169], v[16:17]
	v_pk_add_f32 v[170:171], v[170:171], v[18:19]
	v_pk_add_f32 v[172:173], v[172:173], v[20:21]
	v_pk_add_f32 v[174:175], v[174:175], v[22:23]
	s_waitcnt vmcnt(12)
	v_pk_add_f32 v[160:161], v[160:161], v[24:25]
	v_pk_add_f32 v[162:163], v[162:163], v[26:27]
	v_pk_add_f32 v[164:165], v[164:165], v[28:29]
	v_pk_add_f32 v[166:167], v[166:167], v[30:31]
	v_pk_add_f32 v[168:169], v[168:169], v[32:33]
	v_pk_add_f32 v[170:171], v[170:171], v[34:35]
	v_pk_add_f32 v[172:173], v[172:173], v[36:37]
	v_pk_add_f32 v[174:175], v[174:175], v[38:39]
	s_waitcnt vmcnt(8)
	v_pk_add_f32 v[160:161], v[160:161], v[40:41]
	v_pk_add_f32 v[162:163], v[162:163], v[42:43]
	v_pk_add_f32 v[164:165], v[164:165], v[44:45]
	v_pk_add_f32 v[166:167], v[166:167], v[46:47]
	v_pk_add_f32 v[168:169], v[168:169], v[48:49]
	v_pk_add_f32 v[170:171], v[170:171], v[50:51]
	v_pk_add_f32 v[172:173], v[172:173], v[52:53]
	v_pk_add_f32 v[174:175], v[174:175], v[54:55]
	s_waitcnt vmcnt(4)
	v_pk_add_f32 v[160:161], v[160:161], v[56:57]
	v_pk_add_f32 v[162:163], v[162:163], v[58:59]
	v_pk_add_f32 v[164:165], v[164:165], v[60:61]
	v_pk_add_f32 v[166:167], v[166:167], v[62:63]
	v_pk_add_f32 v[168:169], v[168:169], v[64:65]
	v_pk_add_f32 v[170:171], v[170:171], v[66:67]
	v_pk_add_f32 v[172:173], v[172:173], v[68:69]
	v_pk_add_f32 v[174:175], v[174:175], v[70:71]
	s_waitcnt vmcnt(0)
	v_pk_add_f32 v[160:161], v[160:161], v[72:73]
	v_pk_add_f32 v[162:163], v[162:163], v[74:75]
	v_pk_add_f32 v[164:165], v[164:165], v[76:77]
	v_pk_add_f32 v[166:167], v[166:167], v[78:79]
	v_pk_add_f32 v[168:169], v[168:169], v[80:81]
	v_pk_add_f32 v[170:171], v[170:171], v[82:83]
	v_pk_add_f32 v[172:173], v[172:173], v[84:85]
	v_pk_add_f32 v[174:175], v[174:175], v[86:87]
	v_pk_mul_f32 v[252:253], v[160:161], v[160:161]
	v_pk_mul_f32 v[254:255], v[162:163], v[162:163]
	v_pk_fma_f32 v[252:253], v[164:165], v[164:165], v[252:253]
	v_pk_fma_f32 v[254:255], v[166:167], v[166:167], v[254:255]
	v_pk_fma_f32 v[252:253], v[168:169], v[168:169], v[252:253]
	v_pk_fma_f32 v[254:255], v[170:171], v[170:171], v[254:255]
	v_pk_fma_f32 v[252:253], v[172:173], v[172:173], v[252:253]
	v_pk_fma_f32 v[254:255], v[174:175], v[174:175], v[254:255]
	v_pk_add_f32 v[252:253], v[252:253], v[254:255]
	s_nop 0
	v_add_f32_e32 v183, v252, v253
	s_nop 1
	v_add_f32_dpp v183, v183, v183 quad_perm:[1,0,3,2] row_mask:0xf bank_mask:0xf bound_ctrl:1
	s_nop 1
	v_add_f32_dpp v183, v183, v183 quad_perm:[2,3,0,1] row_mask:0xf bank_mask:0xf bound_ctrl:1
	s_nop 1
	v_add_f32_dpp v183, v183, v183 row_half_mirror row_mask:0xf bank_mask:0xf bound_ctrl:1
	s_nop 1
	v_add_f32_dpp v183, v183, v183 row_mirror row_mask:0xf bank_mask:0xf bound_ctrl:1
	s_nop 1
	v_readlane_b32 s98, v183, 0
	v_readlane_b32 s99, v183, 16
	v_readlane_b32 s100, v183, 32
	v_readlane_b32 s101, v183, 48
	s_nop 1
	v_mov_b32_e32 v183, s98
	v_add_f32_e32 v183, s99, v183
	v_add_f32_e32 v183, s100, v183
	v_add_f32_e32 v183, s101, v183
	v_fmamk_f32 v183, v183, 0x3a800000, v182
	v_cmp_gt_f32_e32 vcc, 0x800000, v183
	v_mul_f32_e32 v181, 0x4b800000, v183
	s_nop 1
	v_cndmask_b32_e32 v183, v183, v181, vcc
	v_rsq_f32_e32 v183, v183
	s_nop 0
	v_mul_f32_e32 v181, 0x45800000, v183
	v_cndmask_b32_e32 v184, v183, v181, vcc
	v_mov_b32_e32 v185, v184
	v_pk_mul_f32 v[160:161], v[160:161], v[184:185]
	v_pk_mul_f32 v[162:163], v[162:163], v[184:185]
	v_pk_mul_f32 v[164:165], v[164:165], v[184:185]
	v_pk_mul_f32 v[166:167], v[166:167], v[184:185]
	v_pk_mul_f32 v[168:169], v[168:169], v[184:185]
	v_pk_mul_f32 v[170:171], v[170:171], v[184:185]
	v_pk_mul_f32 v[172:173], v[172:173], v[184:185]
	v_pk_mul_f32 v[174:175], v[174:175], v[184:185]
	v_pk_fma_f32 v[144:145], v[160:161], v[128:129], v[144:145]
	v_pk_fma_f32 v[146:147], v[162:163], v[130:131], v[146:147]
	v_pk_fma_f32 v[148:149], v[164:165], v[132:133], v[148:149]
	v_pk_fma_f32 v[150:151], v[166:167], v[134:135], v[150:151]
	v_pk_fma_f32 v[152:153], v[168:169], v[136:137], v[152:153]
	v_pk_fma_f32 v[154:155], v[170:171], v[138:139], v[154:155]
	v_pk_fma_f32 v[156:157], v[172:173], v[140:141], v[156:157]
	v_pk_fma_f32 v[158:159], v[174:175], v[142:143], v[158:159]
	v_pk_mul_f32 v[252:253], v[144:145], v[144:145]
	v_pk_mul_f32 v[254:255], v[146:147], v[146:147]
	v_pk_fma_f32 v[252:253], v[148:149], v[148:149], v[252:253]
	v_pk_fma_f32 v[254:255], v[150:151], v[150:151], v[254:255]
	v_pk_fma_f32 v[252:253], v[152:153], v[152:153], v[252:253]
	v_pk_fma_f32 v[254:255], v[154:155], v[154:155], v[254:255]
	v_pk_fma_f32 v[252:253], v[156:157], v[156:157], v[252:253]
	v_pk_fma_f32 v[254:255], v[158:159], v[158:159], v[254:255]
	v_pk_add_f32 v[252:253], v[252:253], v[254:255]
	s_nop 0
	v_add_f32_e32 v183, v252, v253
	s_nop 1
	v_add_f32_dpp v183, v183, v183 quad_perm:[1,0,3,2] row_mask:0xf bank_mask:0xf bound_ctrl:1
	s_nop 1
	v_add_f32_dpp v183, v183, v183 quad_perm:[2,3,0,1] row_mask:0xf bank_mask:0xf bound_ctrl:1
	s_nop 1
	v_add_f32_dpp v183, v183, v183 row_half_mirror row_mask:0xf bank_mask:0xf bound_ctrl:1
	s_nop 1
	v_add_f32_dpp v183, v183, v183 row_mirror row_mask:0xf bank_mask:0xf bound_ctrl:1
	s_nop 1
	v_readlane_b32 s98, v183, 0
	v_readlane_b32 s99, v183, 16
	v_readlane_b32 s100, v183, 32
	v_readlane_b32 s101, v183, 48
	s_nop 1
	v_mov_b32_e32 v183, s98
	v_add_f32_e32 v183, s99, v183
	v_add_f32_e32 v183, s100, v183
	v_add_f32_e32 v183, s101, v183
	v_fmamk_f32 v183, v183, 0x3a800000, v182
	v_cmp_gt_f32_e32 vcc, 0x800000, v183
	v_mul_f32_e32 v181, 0x4b800000, v183
	s_nop 1
	v_cndmask_b32_e32 v183, v183, v181, vcc
	v_rsq_f32_e32 v183, v183
	s_nop 0
	v_mul_f32_e32 v181, 0x45800000, v183
	v_cndmask_b32_e32 v184, v183, v181, vcc
	v_mov_b32_e32 v185, v184
	v_cvt_pk_bf16_f32 v0, v144, v145
	v_cvt_pk_bf16_f32 v1, v146, v147
	v_cvt_pk_bf16_f32 v2, v148, v149
	v_cvt_pk_bf16_f32 v3, v150, v151
	v_cvt_pk_bf16_f32 v4, v152, v153
	v_cvt_pk_bf16_f32 v5, v154, v155
	v_cvt_pk_bf16_f32 v6, v156, v157
	v_cvt_pk_bf16_f32 v7, v158, v159
	v_add_u32_e32 v181, 0x3800000, v177
	global_store_dwordx4 v181, v[0:3], s[78:79]
	global_store_dwordx4 v181, v[4:7], s[78:79] offset:1024
	v_add_u32_e32 v236, 0x10000, v237
	s_mov_b64 exec, 1
	global_store_dword v236, v184, s[78:79]
	s_mov_b64 exec, -1

.LBB0_1154:
	v_readlane_b32 s0, v235, 52
	v_readlane_b32 s1, v235, 53
	s_and_b64 vcc, exec, s[0:1]
	s_waitcnt lgkmcnt(0)
	s_barrier
	v_mbcnt_lo_u32_b32 v0, -1, 0
	v_mbcnt_hi_u32_b32 v0, -1, v0
	s_cbranch_vccnz .LBB0_1174
	v_lshlrev_b32_e32 v2, 3, v0
	v_ashrrev_i32_e32 v3, 31, v2
	v_readlane_b32 s4, v235, 4
	v_lshlrev_b64 v[4:5], 1, v[2:3]
	v_lshlrev_b64 v[2:3], 2, v[2:3]
	v_readlane_b32 s14, v235, 14
	v_readlane_b32 s15, v235, 15
	v_lshl_add_u64 v[62:63], s[90:91], 0, v[2:3]
	v_readlane_b32 s5, v235, 5
	v_readlane_b32 s6, v235, 6
	v_readlane_b32 s7, v235, 7
	v_readlane_b32 s8, v235, 8
	v_readlane_b32 s9, v235, 9
	v_readlane_b32 s10, v235, 10
	v_readlane_b32 s11, v235, 11
	v_readlane_b32 s12, v235, 12
	v_readlane_b32 s13, v235, 13
	v_readlane_b32 s16, v235, 16
	v_readlane_b32 s17, v235, 17
	v_readlane_b32 s18, v235, 18
	v_readlane_b32 s19, v235, 19
	v_lshl_add_u64 v[2:3], s[14:15], 0, v[2:3]
	s_mov_b64 s[0:1], 0x1000
	v_lshl_add_u64 v[60:61], s[86:87], 0, v[4:5]
	v_lshl_add_u64 v[64:65], s[54:55], 0, v[4:5]
	v_lshl_add_u64 v[66:67], v[2:3], 0, s[0:1]
	s_mov_b32 s1, 0
	v_cmp_eq_u32_e64 s[12:13], 0, v0
	s_mov_b64 s[4:5], 0x200000
	s_mov_b64 s[6:7], 0x200800
	s_mov_b64 s[8:9], 0x400000
	s_mov_b64 s[10:11], 0x400800
	s_mov_b64 s[14:15], 0x600000
	s_mov_b64 s[16:17], 0x600800
	s_mov_b64 s[18:19], 0x800000
	s_mov_b32 s48, 0x800000
	s_mov_b64 s[20:21], 0x800800
	s_mov_b64 s[22:23], 0xa00000
	s_mov_b64 s[24:25], 0xa00800
	s_mov_b64 s[26:27], 0xc00000
	s_mov_b64 s[28:29], 0xc00800
	s_mov_b64 s[36:37], 0xe00000
	s_mov_b64 s[38:39], 0xe00800
	v_mov_b32_e32 v104, 0
	v_mov_b32_e32 v105, 0x358637bd
	v_readlane_b32 s42, v235, 61
	v_readlane_b32 s43, v235, 62
	v_mbcnt_lo_u32_b32 v176, -1, 0
	v_mbcnt_hi_u32_b32 v176, -1, v176
	v_readlane_b32 s98, v235, 49
	v_readlane_b32 s99, v235, 20
	v_readlane_b32 s100, v235, 14
	v_readlane_b32 s101, v235, 15
	s_nop 3
	s_lshr_b32 vcc_lo, s98, 3
	s_and_b32 vcc_hi, vcc_lo, 7
	s_lshr_b32 vcc_lo, vcc_lo, 3
	s_lshl_b32 vcc_lo, vcc_lo, 3
	s_add_i32 vcc_lo, vcc_lo, s99
	s_lshl_b32 s98, vcc_hi, 8
	s_add_i32 s98, s98, vcc_lo
	s_mov_b32 s99, s98
	v_mov_b32_e32 v183, s99
	v_lshlrev_b32_e32 v177, 4, v176
	s_lshl_b32 s99, s99, 11
	v_add_u32_e32 v177, s99, v177
	v_add_u32_e32 v178, 0x1800000, v177
	v_add_u32_e32 v179, 0x9e00000, v177
	v_lshlrev_b32_e32 v180, 5, v176
	v_add_u32_e32 v181, 0x1000, v180
	global_load_dwordx4 v[128:131], v181, s[100:101]
	global_load_dwordx4 v[132:135], v181, s[100:101] offset:16
	global_load_dwordx4 v[136:139], v181, s[100:101] offset:2048
	global_load_dwordx4 v[140:143], v181, s[100:101] offset:2064
	v_mov_b32_e32 v182, 0x358637bd
	global_load_dwordx4 v[0:3], v178, s[78:79]
	global_load_dwordx4 v[4:7], v178, s[78:79] offset:1024
	global_load_dwordx4 v[8:11], v179, s[78:79]
	global_load_dwordx4 v[12:15], v179, s[78:79] offset:1024
	v_add_u32_e32 v178, 0x400000, v178
	v_add_u32_e32 v179, 0x400000, v179
	global_load_dwordx4 v[16:19], v178, s[78:79]
	global_load_dwordx4 v[20:23], v178, s[78:79] offset:1024
	global_load_dwordx4 v[24:27], v179, s[78:79]
	global_load_dwordx4 v[28:31], v179, s[78:79] offset:1024
	v_add_u32_e32 v178, 0x400000, v178
	v_add_u32_e32 v179, 0x400000, v179
	global_load_dwordx4 v[32:35], v178, s[78:79]
	global_load_dwordx4 v[36:39], v178, s[78:79] offset:1024
	global_load_dwordx4 v[40:43], v179, s[78:79]
	global_load_dwordx4 v[44:47], v179, s[78:79] offset:1024
	v_add_u32_e32 v178, 0x400000, v178
	v_add_u32_e32 v179, 0x400000, v179
	global_load_dwordx4 v[48:51], v178, s[78:79]
	global_load_dwordx4 v[52:55], v178, s[78:79] offset:1024
	global_load_dwordx4 v[56:59], v179, s[78:79]
	global_load_dwordx4 v[60:63], v179, s[78:79] offset:1024
	v_add_u32_e32 v178, 0x400000, v178
	v_add_u32_e32 v179, 0x400000, v179
	global_load_dwordx4 v[64:67], v178, s[78:79]
	global_load_dwordx4 v[68:71], v178, s[78:79] offset:1024
	global_load_dwordx4 v[72:75], v179, s[78:79]
	global_load_dwordx4 v[76:79], v179, s[78:79] offset:1024
	v_add_u32_e32 v178, 0x400000, v178
	v_add_u32_e32 v179, 0x400000, v179
	global_load_dwordx4 v[80:83], v178, s[78:79]
	global_load_dwordx4 v[84:87], v178, s[78:79] offset:1024
	global_load_dwordx4 v[88:91], v179, s[78:79]
	global_load_dwordx4 v[92:95], v179, s[78:79] offset:1024
	v_add_u32_e32 v178, 0x400000, v178
	v_add_u32_e32 v179, 0x400000, v179
	global_load_dwordx4 v[96:99], v178, s[78:79]
	global_load_dwordx4 v[100:103], v178, s[78:79] offset:1024
	global_load_dwordx4 v[104:107], v179, s[78:79]
	global_load_dwordx4 v[108:111], v179, s[78:79] offset:1024
	v_add_u32_e32 v178, 0x400000, v178
	v_add_u32_e32 v179, 0x400000, v179
	global_load_dwordx4 v[112:115], v178, s[78:79]
	global_load_dwordx4 v[116:119], v178, s[78:79] offset:1024
	global_load_dwordx4 v[120:123], v179, s[78:79]
	global_load_dwordx4 v[124:127], v179, s[78:79] offset:1024
	v_lshlrev_b32_e32 v237, 2, v183
	v_add_u32_e32 v237, 0x10000, v237
	v_mov_b32_e32 v179, s98
	s_waitcnt vmcnt(28)
	v_lshlrev_b32_e32 v144, 16, v0
	v_and_b32_e32 v145, 0xffff0000, v0
	v_lshlrev_b32_e32 v146, 16, v1
	v_and_b32_e32 v147, 0xffff0000, v1
	v_lshlrev_b32_e32 v148, 16, v2
	v_and_b32_e32 v149, 0xffff0000, v2
	v_lshlrev_b32_e32 v150, 16, v3
	v_and_b32_e32 v151, 0xffff0000, v3
	v_lshlrev_b32_e32 v152, 16, v4
	v_and_b32_e32 v153, 0xffff0000, v4
	v_lshlrev_b32_e32 v154, 16, v5
	v_and_b32_e32 v155, 0xffff0000, v5
	v_lshlrev_b32_e32 v156, 16, v6
	v_and_b32_e32 v157, 0xffff0000, v6
	v_lshlrev_b32_e32 v158, 16, v7
	v_and_b32_e32 v159, 0xffff0000, v7
	v_lshlrev_b32_e32 v160, 16, v8
	v_and_b32_e32 v161, 0xffff0000, v8
	v_lshlrev_b32_e32 v162, 16, v9
	v_and_b32_e32 v163, 0xffff0000, v9
	v_lshlrev_b32_e32 v164, 16, v10
	v_and_b32_e32 v165, 0xffff0000, v10
	v_lshlrev_b32_e32 v166, 16, v11
	v_and_b32_e32 v167, 0xffff0000, v11
	v_lshlrev_b32_e32 v168, 16, v12
	v_and_b32_e32 v169, 0xffff0000, v12
	v_lshlrev_b32_e32 v170, 16, v13
	v_and_b32_e32 v171, 0xffff0000, v13
	v_lshlrev_b32_e32 v172, 16, v14
	v_and_b32_e32 v173, 0xffff0000, v14
	v_lshlrev_b32_e32 v174, 16, v15
	v_and_b32_e32 v175, 0xffff0000, v15
	v_pk_mul_f32 v[252:253], v[160:161], v[160:161]
	v_pk_mul_f32 v[254:255], v[162:163], v[162:163]
	v_pk_fma_f32 v[252:253], v[164:165], v[164:165], v[252:253]
	v_pk_fma_f32 v[254:255], v[166:167], v[166:167], v[254:255]
	v_pk_fma_f32 v[252:253], v[168:169], v[168:169], v[252:253]
	v_pk_fma_f32 v[254:255], v[170:171], v[170:171], v[254:255]
	v_pk_fma_f32 v[252:253], v[172:173], v[172:173], v[252:253]
	v_pk_fma_f32 v[254:255], v[174:175], v[174:175], v[254:255]
	v_pk_add_f32 v[252:253], v[252:253], v[254:255]
	s_nop 0
	v_add_f32_e32 v183, v252, v253
	s_nop 1
	v_add_f32_dpp v183, v183, v183 quad_perm:[1,0,3,2] row_mask:0xf bank_mask:0xf bound_ctrl:1
	s_nop 1
	v_add_f32_dpp v183, v183, v183 quad_perm:[2,3,0,1] row_mask:0xf bank_mask:0xf bound_ctrl:1
	s_nop 1
	v_add_f32_dpp v183, v183, v183 row_half_mirror row_mask:0xf bank_mask:0xf bound_ctrl:1
	s_nop 1
	v_add_f32_dpp v183, v183, v183 row_mirror row_mask:0xf bank_mask:0xf bound_ctrl:1
	s_nop 1
	v_readlane_b32 s98, v183, 0
	v_readlane_b32 s99, v183, 16
	v_readlane_b32 s100, v183, 32
	v_readlane_b32 s101, v183, 48
	s_nop 1
	v_mov_b32_e32 v183, s98
	v_add_f32_e32 v183, s99, v183
	v_add_f32_e32 v183, s100, v183
	v_add_f32_e32 v183, s101, v183
	v_fmamk_f32 v183, v183, 0x3a800000, v182
	v_cmp_gt_f32_e32 vcc, 0x800000, v183
	v_mul_f32_e32 v181, 0x4b800000, v183
	s_nop 1
	v_cndmask_b32_e32 v183, v183, v181, vcc
	v_rsq_f32_e32 v183, v183
	s_nop 0
	v_mul_f32_e32 v181, 0x45800000, v183
	v_cndmask_b32_e32 v184, v183, v181, vcc
	v_mov_b32_e32 v185, v184
	v_pk_mul_f32 v[160:161], v[160:161], v[184:185]
	v_pk_mul_f32 v[162:163], v[162:163], v[184:185]
	v_pk_mul_f32 v[164:165], v[164:165], v[184:185]
	v_pk_mul_f32 v[166:167], v[166:167], v[184:185]
	v_pk_mul_f32 v[168:169], v[168:169], v[184:185]
	v_pk_mul_f32 v[170:171], v[170:171], v[184:185]
	v_pk_mul_f32 v[172:173], v[172:173], v[184:185]
	v_pk_mul_f32 v[174:175], v[174:175], v[184:185]
	v_pk_fma_f32 v[144:145], v[160:161], v[128:129], v[144:145]
	v_pk_fma_f32 v[146:147], v[162:163], v[130:131], v[146:147]
	v_pk_fma_f32 v[148:149], v[164:165], v[132:133], v[148:149]
	v_pk_fma_f32 v[150:151], v[166:167], v[134:135], v[150:151]
	v_pk_fma_f32 v[152:153], v[168:169], v[136:137], v[152:153]
	v_pk_fma_f32 v[154:155], v[170:171], v[138:139], v[154:155]
	v_pk_fma_f32 v[156:157], v[172:173], v[140:141], v[156:157]
	v_pk_fma_f32 v[158:159], v[174:175], v[142:143], v[158:159]
	v_pk_mul_f32 v[252:253], v[144:145], v[144:145]
	v_pk_mul_f32 v[254:255], v[146:147], v[146:147]
	v_pk_fma_f32 v[252:253], v[148:149], v[148:149], v[252:253]
	v_pk_fma_f32 v[254:255], v[150:151], v[150:151], v[254:255]
	v_pk_fma_f32 v[252:253], v[152:153], v[152:153], v[252:253]
	v_pk_fma_f32 v[254:255], v[154:155], v[154:155], v[254:255]
	v_pk_fma_f32 v[252:253], v[156:157], v[156:157], v[252:253]
	v_pk_fma_f32 v[254:255], v[158:159], v[158:159], v[254:255]
	v_pk_add_f32 v[252:253], v[252:253], v[254:255]
	s_nop 0
	v_add_f32_e32 v183, v252, v253
	s_nop 1
	v_add_f32_dpp v183, v183, v183 quad_perm:[1,0,3,2] row_mask:0xf bank_mask:0xf bound_ctrl:1
	s_nop 1
	v_add_f32_dpp v183, v183, v183 quad_perm:[2,3,0,1] row_mask:0xf bank_mask:0xf bound_ctrl:1
	s_nop 1
	v_add_f32_dpp v183, v183, v183 row_half_mirror row_mask:0xf bank_mask:0xf bound_ctrl:1
	s_nop 1
	v_add_f32_dpp v183, v183, v183 row_mirror row_mask:0xf bank_mask:0xf bound_ctrl:1
	s_nop 1
	v_readlane_b32 s98, v183, 0
	v_readlane_b32 s99, v183, 16
	v_readlane_b32 s100, v183, 32
	v_readlane_b32 s101, v183, 48
	s_nop 1
	v_mov_b32_e32 v183, s98
	v_add_f32_e32 v183, s99, v183
	v_add_f32_e32 v183, s100, v183
	v_add_f32_e32 v183, s101, v183
	v_fmamk_f32 v183, v183, 0x3a800000, v182
	v_cmp_gt_f32_e32 vcc, 0x800000, v183
	v_mul_f32_e32 v181, 0x4b800000, v183
	s_nop 1
	v_cndmask_b32_e32 v183, v183, v181, vcc
	v_rsq_f32_e32 v183, v183
	s_nop 0
	v_mul_f32_e32 v181, 0x45800000, v183
	v_cndmask_b32_e32 v184, v183, v181, vcc
	v_mov_b32_e32 v185, v184
	v_cvt_pk_bf16_f32 v0, v144, v145
	v_cvt_pk_bf16_f32 v1, v146, v147
	v_cvt_pk_bf16_f32 v2, v148, v149
	v_cvt_pk_bf16_f32 v3, v150, v151
	v_cvt_pk_bf16_f32 v4, v152, v153
	v_cvt_pk_bf16_f32 v5, v154, v155
	v_cvt_pk_bf16_f32 v6, v156, v157
	v_cvt_pk_bf16_f32 v7, v158, v159
	v_add_u32_e32 v181, 0x1800000, v177
	global_store_dwordx4 v181, v[0:3], s[78:79]
	global_store_dwordx4 v181, v[4:7], s[78:79] offset:1024
	v_add_u32_e32 v236, 0x0, v237
	s_mov_b64 exec, 1
	global_store_dword v236, v184, s[78:79]
	s_mov_b64 exec, -1
	s_waitcnt vmcnt(24)
	v_lshlrev_b32_e32 v144, 16, v16
	v_and_b32_e32 v145, 0xffff0000, v16
	v_lshlrev_b32_e32 v146, 16, v17
	v_and_b32_e32 v147, 0xffff0000, v17
	v_lshlrev_b32_e32 v148, 16, v18
	v_and_b32_e32 v149, 0xffff0000, v18
	v_lshlrev_b32_e32 v150, 16, v19
	v_and_b32_e32 v151, 0xffff0000, v19
	v_lshlrev_b32_e32 v152, 16, v20
	v_and_b32_e32 v153, 0xffff0000, v20
	v_lshlrev_b32_e32 v154, 16, v21
	v_and_b32_e32 v155, 0xffff0000, v21
	v_lshlrev_b32_e32 v156, 16, v22
	v_and_b32_e32 v157, 0xffff0000, v22
	v_lshlrev_b32_e32 v158, 16, v23
	v_and_b32_e32 v159, 0xffff0000, v23
	v_lshlrev_b32_e32 v160, 16, v24
	v_and_b32_e32 v161, 0xffff0000, v24
	v_lshlrev_b32_e32 v162, 16, v25
	v_and_b32_e32 v163, 0xffff0000, v25
	v_lshlrev_b32_e32 v164, 16, v26
	v_and_b32_e32 v165, 0xffff0000, v26
	v_lshlrev_b32_e32 v166, 16, v27
	v_and_b32_e32 v167, 0xffff0000, v27
	v_lshlrev_b32_e32 v168, 16, v28
	v_and_b32_e32 v169, 0xffff0000, v28
	v_lshlrev_b32_e32 v170, 16, v29
	v_and_b32_e32 v171, 0xffff0000, v29
	v_lshlrev_b32_e32 v172, 16, v30
	v_and_b32_e32 v173, 0xffff0000, v30
	v_lshlrev_b32_e32 v174, 16, v31
	v_and_b32_e32 v175, 0xffff0000, v31
	v_pk_mul_f32 v[252:253], v[160:161], v[160:161]
	v_pk_mul_f32 v[254:255], v[162:163], v[162:163]
	v_pk_fma_f32 v[252:253], v[164:165], v[164:165], v[252:253]
	v_pk_fma_f32 v[254:255], v[166:167], v[166:167], v[254:255]
	v_pk_fma_f32 v[252:253], v[168:169], v[168:169], v[252:253]
	v_pk_fma_f32 v[254:255], v[170:171], v[170:171], v[254:255]
	v_pk_fma_f32 v[252:253], v[172:173], v[172:173], v[252:253]
	v_pk_fma_f32 v[254:255], v[174:175], v[174:175], v[254:255]
	v_pk_add_f32 v[252:253], v[252:253], v[254:255]
	s_nop 0
	v_add_f32_e32 v183, v252, v253
	s_nop 1
	v_add_f32_dpp v183, v183, v183 quad_perm:[1,0,3,2] row_mask:0xf bank_mask:0xf bound_ctrl:1
	s_nop 1
	v_add_f32_dpp v183, v183, v183 quad_perm:[2,3,0,1] row_mask:0xf bank_mask:0xf bound_ctrl:1
	s_nop 1
	v_add_f32_dpp v183, v183, v183 row_half_mirror row_mask:0xf bank_mask:0xf bound_ctrl:1
	s_nop 1
	v_add_f32_dpp v183, v183, v183 row_mirror row_mask:0xf bank_mask:0xf bound_ctrl:1
	s_nop 1
	v_readlane_b32 s98, v183, 0
	v_readlane_b32 s99, v183, 16
	v_readlane_b32 s100, v183, 32
	v_readlane_b32 s101, v183, 48
	s_nop 1
	v_mov_b32_e32 v183, s98
	v_add_f32_e32 v183, s99, v183
	v_add_f32_e32 v183, s100, v183
	v_add_f32_e32 v183, s101, v183
	v_fmamk_f32 v183, v183, 0x3a800000, v182
	v_cmp_gt_f32_e32 vcc, 0x800000, v183
	v_mul_f32_e32 v181, 0x4b800000, v183
	s_nop 1
	v_cndmask_b32_e32 v183, v183, v181, vcc
	v_rsq_f32_e32 v183, v183
	s_nop 0
	v_mul_f32_e32 v181, 0x45800000, v183
	v_cndmask_b32_e32 v184, v183, v181, vcc
	v_mov_b32_e32 v185, v184
	v_pk_mul_f32 v[160:161], v[160:161], v[184:185]
	v_pk_mul_f32 v[162:163], v[162:163], v[184:185]
	v_pk_mul_f32 v[164:165], v[164:165], v[184:185]
	v_pk_mul_f32 v[166:167], v[166:167], v[184:185]
	v_pk_mul_f32 v[168:169], v[168:169], v[184:185]
	v_pk_mul_f32 v[170:171], v[170:171], v[184:185]
	v_pk_mul_f32 v[172:173], v[172:173], v[184:185]
	v_pk_mul_f32 v[174:175], v[174:175], v[184:185]
	v_pk_fma_f32 v[144:145], v[160:161], v[128:129], v[144:145]
	v_pk_fma_f32 v[146:147], v[162:163], v[130:131], v[146:147]
	v_pk_fma_f32 v[148:149], v[164:165], v[132:133], v[148:149]
	v_pk_fma_f32 v[150:151], v[166:167], v[134:135], v[150:151]
	v_pk_fma_f32 v[152:153], v[168:169], v[136:137], v[152:153]
	v_pk_fma_f32 v[154:155], v[170:171], v[138:139], v[154:155]
	v_pk_fma_f32 v[156:157], v[172:173], v[140:141], v[156:157]
	v_pk_fma_f32 v[158:159], v[174:175], v[142:143], v[158:159]
	v_pk_mul_f32 v[252:253], v[144:145], v[144:145]
	v_pk_mul_f32 v[254:255], v[146:147], v[146:147]
	v_pk_fma_f32 v[252:253], v[148:149], v[148:149], v[252:253]
	v_pk_fma_f32 v[254:255], v[150:151], v[150:151], v[254:255]
	v_pk_fma_f32 v[252:253], v[152:153], v[152:153], v[252:253]
	v_pk_fma_f32 v[254:255], v[154:155], v[154:155], v[254:255]
	v_pk_fma_f32 v[252:253], v[156:157], v[156:157], v[252:253]
	v_pk_fma_f32 v[254:255], v[158:159], v[158:159], v[254:255]
	v_pk_add_f32 v[252:253], v[252:253], v[254:255]
	s_nop 0
	v_add_f32_e32 v183, v252, v253
	s_nop 1
	v_add_f32_dpp v183, v183, v183 quad_perm:[1,0,3,2] row_mask:0xf bank_mask:0xf bound_ctrl:1
	s_nop 1
	v_add_f32_dpp v183, v183, v183 quad_perm:[2,3,0,1] row_mask:0xf bank_mask:0xf bound_ctrl:1
	s_nop 1
	v_add_f32_dpp v183, v183, v183 row_half_mirror row_mask:0xf bank_mask:0xf bound_ctrl:1
	s_nop 1
	v_add_f32_dpp v183, v183, v183 row_mirror row_mask:0xf bank_mask:0xf bound_ctrl:1
	s_nop 1
	v_readlane_b32 s98, v183, 0
	v_readlane_b32 s99, v183, 16
	v_readlane_b32 s100, v183, 32
	v_readlane_b32 s101, v183, 48
	s_nop 1
	v_mov_b32_e32 v183, s98
	v_add_f32_e32 v183, s99, v183
	v_add_f32_e32 v183, s100, v183
	v_add_f32_e32 v183, s101, v183
	v_fmamk_f32 v183, v183, 0x3a800000, v182
	v_cmp_gt_f32_e32 vcc, 0x800000, v183
	v_mul_f32_e32 v181, 0x4b800000, v183
	s_nop 1
	v_cndmask_b32_e32 v183, v183, v181, vcc
	v_rsq_f32_e32 v183, v183
	s_nop 0
	v_mul_f32_e32 v181, 0x45800000, v183
	v_cndmask_b32_e32 v184, v183, v181, vcc
	v_mov_b32_e32 v185, v184
	v_cvt_pk_bf16_f32 v16, v144, v145
	v_cvt_pk_bf16_f32 v17, v146, v147
	v_cvt_pk_bf16_f32 v18, v148, v149
	v_cvt_pk_bf16_f32 v19, v150, v151
	v_cvt_pk_bf16_f32 v20, v152, v153
	v_cvt_pk_bf16_f32 v21, v154, v155
	v_cvt_pk_bf16_f32 v22, v156, v157
	v_cvt_pk_bf16_f32 v23, v158, v159
	v_add_u32_e32 v181, 0x1c00000, v177
	global_store_dwordx4 v181, v[16:19], s[78:79]
	global_store_dwordx4 v181, v[20:23], s[78:79] offset:1024
	v_add_u32_e32 v236, 0x2000, v237
	s_mov_b64 exec, 1
	global_store_dword v236, v184, s[78:79]
	s_mov_b64 exec, -1
	s_waitcnt vmcnt(20)
	v_lshlrev_b32_e32 v144, 16, v32
	v_and_b32_e32 v145, 0xffff0000, v32
	v_lshlrev_b32_e32 v146, 16, v33
	v_and_b32_e32 v147, 0xffff0000, v33
	v_lshlrev_b32_e32 v148, 16, v34
	v_and_b32_e32 v149, 0xffff0000, v34
	v_lshlrev_b32_e32 v150, 16, v35
	v_and_b32_e32 v151, 0xffff0000, v35
	v_lshlrev_b32_e32 v152, 16, v36
	v_and_b32_e32 v153, 0xffff0000, v36
	v_lshlrev_b32_e32 v154, 16, v37
	v_and_b32_e32 v155, 0xffff0000, v37
	v_lshlrev_b32_e32 v156, 16, v38
	v_and_b32_e32 v157, 0xffff0000, v38
	v_lshlrev_b32_e32 v158, 16, v39
	v_and_b32_e32 v159, 0xffff0000, v39
	v_lshlrev_b32_e32 v160, 16, v40
	v_and_b32_e32 v161, 0xffff0000, v40
	v_lshlrev_b32_e32 v162, 16, v41
	v_and_b32_e32 v163, 0xffff0000, v41
	v_lshlrev_b32_e32 v164, 16, v42
	v_and_b32_e32 v165, 0xffff0000, v42
	v_lshlrev_b32_e32 v166, 16, v43
	v_and_b32_e32 v167, 0xffff0000, v43
	v_lshlrev_b32_e32 v168, 16, v44
	v_and_b32_e32 v169, 0xffff0000, v44
	v_lshlrev_b32_e32 v170, 16, v45
	v_and_b32_e32 v171, 0xffff0000, v45
	v_lshlrev_b32_e32 v172, 16, v46
	v_and_b32_e32 v173, 0xffff0000, v46
	v_lshlrev_b32_e32 v174, 16, v47
	v_and_b32_e32 v175, 0xffff0000, v47
	v_pk_mul_f32 v[252:253], v[160:161], v[160:161]
	v_pk_mul_f32 v[254:255], v[162:163], v[162:163]
	v_pk_fma_f32 v[252:253], v[164:165], v[164:165], v[252:253]
	v_pk_fma_f32 v[254:255], v[166:167], v[166:167], v[254:255]
	v_pk_fma_f32 v[252:253], v[168:169], v[168:169], v[252:253]
	v_pk_fma_f32 v[254:255], v[170:171], v[170:171], v[254:255]
	v_pk_fma_f32 v[252:253], v[172:173], v[172:173], v[252:253]
	v_pk_fma_f32 v[254:255], v[174:175], v[174:175], v[254:255]
	v_pk_add_f32 v[252:253], v[252:253], v[254:255]
	s_nop 0
	v_add_f32_e32 v183, v252, v253
	s_nop 1
	v_add_f32_dpp v183, v183, v183 quad_perm:[1,0,3,2] row_mask:0xf bank_mask:0xf bound_ctrl:1
	s_nop 1
	v_add_f32_dpp v183, v183, v183 quad_perm:[2,3,0,1] row_mask:0xf bank_mask:0xf bound_ctrl:1
	s_nop 1
	v_add_f32_dpp v183, v183, v183 row_half_mirror row_mask:0xf bank_mask:0xf bound_ctrl:1
	s_nop 1
	v_add_f32_dpp v183, v183, v183 row_mirror row_mask:0xf bank_mask:0xf bound_ctrl:1
	s_nop 1
	v_readlane_b32 s98, v183, 0
	v_readlane_b32 s99, v183, 16
	v_readlane_b32 s100, v183, 32
	v_readlane_b32 s101, v183, 48
	s_nop 1
	v_mov_b32_e32 v183, s98
	v_add_f32_e32 v183, s99, v183
	v_add_f32_e32 v183, s100, v183
	v_add_f32_e32 v183, s101, v183
	v_fmamk_f32 v183, v183, 0x3a800000, v182
	v_cmp_gt_f32_e32 vcc, 0x800000, v183
	v_mul_f32_e32 v181, 0x4b800000, v183
	s_nop 1
	v_cndmask_b32_e32 v183, v183, v181, vcc
	v_rsq_f32_e32 v183, v183
	s_nop 0
	v_mul_f32_e32 v181, 0x45800000, v183
	v_cndmask_b32_e32 v184, v183, v181, vcc
	v_mov_b32_e32 v185, v184
	v_pk_mul_f32 v[160:161], v[160:161], v[184:185]
	v_pk_mul_f32 v[162:163], v[162:163], v[184:185]
	v_pk_mul_f32 v[164:165], v[164:165], v[184:185]
	v_pk_mul_f32 v[166:167], v[166:167], v[184:185]
	v_pk_mul_f32 v[168:169], v[168:169], v[184:185]
	v_pk_mul_f32 v[170:171], v[170:171], v[184:185]
	v_pk_mul_f32 v[172:173], v[172:173], v[184:185]
	v_pk_mul_f32 v[174:175], v[174:175], v[184:185]
	v_pk_fma_f32 v[144:145], v[160:161], v[128:129], v[144:145]
	v_pk_fma_f32 v[146:147], v[162:163], v[130:131], v[146:147]
	v_pk_fma_f32 v[148:149], v[164:165], v[132:133], v[148:149]
	v_pk_fma_f32 v[150:151], v[166:167], v[134:135], v[150:151]
	v_pk_fma_f32 v[152:153], v[168:169], v[136:137], v[152:153]
	v_pk_fma_f32 v[154:155], v[170:171], v[138:139], v[154:155]
	v_pk_fma_f32 v[156:157], v[172:173], v[140:141], v[156:157]
	v_pk_fma_f32 v[158:159], v[174:175], v[142:143], v[158:159]
	v_pk_mul_f32 v[252:253], v[144:145], v[144:145]
	v_pk_mul_f32 v[254:255], v[146:147], v[146:147]
	v_pk_fma_f32 v[252:253], v[148:149], v[148:149], v[252:253]
	v_pk_fma_f32 v[254:255], v[150:151], v[150:151], v[254:255]
	v_pk_fma_f32 v[252:253], v[152:153], v[152:153], v[252:253]
	v_pk_fma_f32 v[254:255], v[154:155], v[154:155], v[254:255]
	v_pk_fma_f32 v[252:253], v[156:157], v[156:157], v[252:253]
	v_pk_fma_f32 v[254:255], v[158:159], v[158:159], v[254:255]
	v_pk_add_f32 v[252:253], v[252:253], v[254:255]
	s_nop 0
	v_add_f32_e32 v183, v252, v253
	s_nop 1
	v_add_f32_dpp v183, v183, v183 quad_perm:[1,0,3,2] row_mask:0xf bank_mask:0xf bound_ctrl:1
	s_nop 1
	v_add_f32_dpp v183, v183, v183 quad_perm:[2,3,0,1] row_mask:0xf bank_mask:0xf bound_ctrl:1
	s_nop 1
	v_add_f32_dpp v183, v183, v183 row_half_mirror row_mask:0xf bank_mask:0xf bound_ctrl:1
	s_nop 1
	v_add_f32_dpp v183, v183, v183 row_mirror row_mask:0xf bank_mask:0xf bound_ctrl:1
	s_nop 1
	v_readlane_b32 s98, v183, 0
	v_readlane_b32 s99, v183, 16
	v_readlane_b32 s100, v183, 32
	v_readlane_b32 s101, v183, 48
	s_nop 1
	v_mov_b32_e32 v183, s98
	v_add_f32_e32 v183, s99, v183
	v_add_f32_e32 v183, s100, v183
	v_add_f32_e32 v183, s101, v183
	v_fmamk_f32 v183, v183, 0x3a800000, v182
	v_cmp_gt_f32_e32 vcc, 0x800000, v183
	v_mul_f32_e32 v181, 0x4b800000, v183
	s_nop 1
	v_cndmask_b32_e32 v183, v183, v181, vcc
	v_rsq_f32_e32 v183, v183
	s_nop 0
	v_mul_f32_e32 v181, 0x45800000, v183
	v_cndmask_b32_e32 v184, v183, v181, vcc
	v_mov_b32_e32 v185, v184
	v_cvt_pk_bf16_f32 v32, v144, v145
	v_cvt_pk_bf16_f32 v33, v146, v147
	v_cvt_pk_bf16_f32 v34, v148, v149
	v_cvt_pk_bf16_f32 v35, v150, v151
	v_cvt_pk_bf16_f32 v36, v152, v153
	v_cvt_pk_bf16_f32 v37, v154, v155
	v_cvt_pk_bf16_f32 v38, v156, v157
	v_cvt_pk_bf16_f32 v39, v158, v159
	v_add_u32_e32 v181, 0x2000000, v177
	global_store_dwordx4 v181, v[32:35], s[78:79]
	global_store_dwordx4 v181, v[36:39], s[78:79] offset:1024
	v_add_u32_e32 v236, 0x4000, v237
	s_mov_b64 exec, 1
	global_store_dword v236, v184, s[78:79]
	s_mov_b64 exec, -1
	s_waitcnt vmcnt(16)
	v_lshlrev_b32_e32 v144, 16, v48
	v_and_b32_e32 v145, 0xffff0000, v48
	v_lshlrev_b32_e32 v146, 16, v49
	v_and_b32_e32 v147, 0xffff0000, v49
	v_lshlrev_b32_e32 v148, 16, v50
	v_and_b32_e32 v149, 0xffff0000, v50
	v_lshlrev_b32_e32 v150, 16, v51
	v_and_b32_e32 v151, 0xffff0000, v51
	v_lshlrev_b32_e32 v152, 16, v52
	v_and_b32_e32 v153, 0xffff0000, v52
	v_lshlrev_b32_e32 v154, 16, v53
	v_and_b32_e32 v155, 0xffff0000, v53
	v_lshlrev_b32_e32 v156, 16, v54
	v_and_b32_e32 v157, 0xffff0000, v54
	v_lshlrev_b32_e32 v158, 16, v55
	v_and_b32_e32 v159, 0xffff0000, v55
	v_lshlrev_b32_e32 v160, 16, v56
	v_and_b32_e32 v161, 0xffff0000, v56
	v_lshlrev_b32_e32 v162, 16, v57
	v_and_b32_e32 v163, 0xffff0000, v57
	v_lshlrev_b32_e32 v164, 16, v58
	v_and_b32_e32 v165, 0xffff0000, v58
	v_lshlrev_b32_e32 v166, 16, v59
	v_and_b32_e32 v167, 0xffff0000, v59
	v_lshlrev_b32_e32 v168, 16, v60
	v_and_b32_e32 v169, 0xffff0000, v60
	v_lshlrev_b32_e32 v170, 16, v61
	v_and_b32_e32 v171, 0xffff0000, v61
	v_lshlrev_b32_e32 v172, 16, v62
	v_and_b32_e32 v173, 0xffff0000, v62
	v_lshlrev_b32_e32 v174, 16, v63
	v_and_b32_e32 v175, 0xffff0000, v63
	v_pk_mul_f32 v[252:253], v[160:161], v[160:161]
	v_pk_mul_f32 v[254:255], v[162:163], v[162:163]
	v_pk_fma_f32 v[252:253], v[164:165], v[164:165], v[252:253]
	v_pk_fma_f32 v[254:255], v[166:167], v[166:167], v[254:255]
	v_pk_fma_f32 v[252:253], v[168:169], v[168:169], v[252:253]
	v_pk_fma_f32 v[254:255], v[170:171], v[170:171], v[254:255]
	v_pk_fma_f32 v[252:253], v[172:173], v[172:173], v[252:253]
	v_pk_fma_f32 v[254:255], v[174:175], v[174:175], v[254:255]
	v_pk_add_f32 v[252:253], v[252:253], v[254:255]
	s_nop 0
	v_add_f32_e32 v183, v252, v253
	s_nop 1
	v_add_f32_dpp v183, v183, v183 quad_perm:[1,0,3,2] row_mask:0xf bank_mask:0xf bound_ctrl:1
	s_nop 1
	v_add_f32_dpp v183, v183, v183 quad_perm:[2,3,0,1] row_mask:0xf bank_mask:0xf bound_ctrl:1
	s_nop 1
	v_add_f32_dpp v183, v183, v183 row_half_mirror row_mask:0xf bank_mask:0xf bound_ctrl:1
	s_nop 1
	v_add_f32_dpp v183, v183, v183 row_mirror row_mask:0xf bank_mask:0xf bound_ctrl:1
	s_nop 1
	v_readlane_b32 s98, v183, 0
	v_readlane_b32 s99, v183, 16
	v_readlane_b32 s100, v183, 32
	v_readlane_b32 s101, v183, 48
	s_nop 1
	v_mov_b32_e32 v183, s98
	v_add_f32_e32 v183, s99, v183
	v_add_f32_e32 v183, s100, v183
	v_add_f32_e32 v183, s101, v183
	v_fmamk_f32 v183, v183, 0x3a800000, v182
	v_cmp_gt_f32_e32 vcc, 0x800000, v183
	v_mul_f32_e32 v181, 0x4b800000, v183
	s_nop 1
	v_cndmask_b32_e32 v183, v183, v181, vcc
	v_rsq_f32_e32 v183, v183
	s_nop 0
	v_mul_f32_e32 v181, 0x45800000, v183
	v_cndmask_b32_e32 v184, v183, v181, vcc
	v_mov_b32_e32 v185, v184
	v_pk_mul_f32 v[160:161], v[160:161], v[184:185]
	v_pk_mul_f32 v[162:163], v[162:163], v[184:185]
	v_pk_mul_f32 v[164:165], v[164:165], v[184:185]
	v_pk_mul_f32 v[166:167], v[166:167], v[184:185]
	v_pk_mul_f32 v[168:169], v[168:169], v[184:185]
	v_pk_mul_f32 v[170:171], v[170:171], v[184:185]
	v_pk_mul_f32 v[172:173], v[172:173], v[184:185]
	v_pk_mul_f32 v[174:175], v[174:175], v[184:185]
	v_pk_fma_f32 v[144:145], v[160:161], v[128:129], v[144:145]
	v_pk_fma_f32 v[146:147], v[162:163], v[130:131], v[146:147]
	v_pk_fma_f32 v[148:149], v[164:165], v[132:133], v[148:149]
	v_pk_fma_f32 v[150:151], v[166:167], v[134:135], v[150:151]
	v_pk_fma_f32 v[152:153], v[168:169], v[136:137], v[152:153]
	v_pk_fma_f32 v[154:155], v[170:171], v[138:139], v[154:155]
	v_pk_fma_f32 v[156:157], v[172:173], v[140:141], v[156:157]
	v_pk_fma_f32 v[158:159], v[174:175], v[142:143], v[158:159]
	v_pk_mul_f32 v[252:253], v[144:145], v[144:145]
	v_pk_mul_f32 v[254:255], v[146:147], v[146:147]
	v_pk_fma_f32 v[252:253], v[148:149], v[148:149], v[252:253]
	v_pk_fma_f32 v[254:255], v[150:151], v[150:151], v[254:255]
	v_pk_fma_f32 v[252:253], v[152:153], v[152:153], v[252:253]
	v_pk_fma_f32 v[254:255], v[154:155], v[154:155], v[254:255]
	v_pk_fma_f32 v[252:253], v[156:157], v[156:157], v[252:253]
	v_pk_fma_f32 v[254:255], v[158:159], v[158:159], v[254:255]
	v_pk_add_f32 v[252:253], v[252:253], v[254:255]
	s_nop 0
	v_add_f32_e32 v183, v252, v253
	s_nop 1
	v_add_f32_dpp v183, v183, v183 quad_perm:[1,0,3,2] row_mask:0xf bank_mask:0xf bound_ctrl:1
	s_nop 1
	v_add_f32_dpp v183, v183, v183 quad_perm:[2,3,0,1] row_mask:0xf bank_mask:0xf bound_ctrl:1
	s_nop 1
	v_add_f32_dpp v183, v183, v183 row_half_mirror row_mask:0xf bank_mask:0xf bound_ctrl:1
	s_nop 1
	v_add_f32_dpp v183, v183, v183 row_mirror row_mask:0xf bank_mask:0xf bound_ctrl:1
	s_nop 1
	v_readlane_b32 s98, v183, 0
	v_readlane_b32 s99, v183, 16
	v_readlane_b32 s100, v183, 32
	v_readlane_b32 s101, v183, 48
	s_nop 1
	v_mov_b32_e32 v183, s98
	v_add_f32_e32 v183, s99, v183
	v_add_f32_e32 v183, s100, v183
	v_add_f32_e32 v183, s101, v183
	v_fmamk_f32 v183, v183, 0x3a800000, v182
	v_cmp_gt_f32_e32 vcc, 0x800000, v183
	v_mul_f32_e32 v181, 0x4b800000, v183
	s_nop 1
	v_cndmask_b32_e32 v183, v183, v181, vcc
	v_rsq_f32_e32 v183, v183
	s_nop 0
	v_mul_f32_e32 v181, 0x45800000, v183
	v_cndmask_b32_e32 v184, v183, v181, vcc
	v_mov_b32_e32 v185, v184
	v_cvt_pk_bf16_f32 v48, v144, v145
	v_cvt_pk_bf16_f32 v49, v146, v147
	v_cvt_pk_bf16_f32 v50, v148, v149
	v_cvt_pk_bf16_f32 v51, v150, v151
	v_cvt_pk_bf16_f32 v52, v152, v153
	v_cvt_pk_bf16_f32 v53, v154, v155
	v_cvt_pk_bf16_f32 v54, v156, v157
	v_cvt_pk_bf16_f32 v55, v158, v159
	v_add_u32_e32 v181, 0x2400000, v177
	global_store_dwordx4 v181, v[48:51], s[78:79]
	global_store_dwordx4 v181, v[52:55], s[78:79] offset:1024
	v_add_u32_e32 v236, 0x6000, v237
	s_mov_b64 exec, 1
	global_store_dword v236, v184, s[78:79]
	s_mov_b64 exec, -1
	s_waitcnt vmcnt(12)
	v_lshlrev_b32_e32 v144, 16, v64
	v_and_b32_e32 v145, 0xffff0000, v64
	v_lshlrev_b32_e32 v146, 16, v65
	v_and_b32_e32 v147, 0xffff0000, v65
	v_lshlrev_b32_e32 v148, 16, v66
	v_and_b32_e32 v149, 0xffff0000, v66
	v_lshlrev_b32_e32 v150, 16, v67
	v_and_b32_e32 v151, 0xffff0000, v67
	v_lshlrev_b32_e32 v152, 16, v68
	v_and_b32_e32 v153, 0xffff0000, v68
	v_lshlrev_b32_e32 v154, 16, v69
	v_and_b32_e32 v155, 0xffff0000, v69
	v_lshlrev_b32_e32 v156, 16, v70
	v_and_b32_e32 v157, 0xffff0000, v70
	v_lshlrev_b32_e32 v158, 16, v71
	v_and_b32_e32 v159, 0xffff0000, v71
	v_lshlrev_b32_e32 v160, 16, v72
	v_and_b32_e32 v161, 0xffff0000, v72
	v_lshlrev_b32_e32 v162, 16, v73
	v_and_b32_e32 v163, 0xffff0000, v73
	v_lshlrev_b32_e32 v164, 16, v74
	v_and_b32_e32 v165, 0xffff0000, v74
	v_lshlrev_b32_e32 v166, 16, v75
	v_and_b32_e32 v167, 0xffff0000, v75
	v_lshlrev_b32_e32 v168, 16, v76
	v_and_b32_e32 v169, 0xffff0000, v76
	v_lshlrev_b32_e32 v170, 16, v77
	v_and_b32_e32 v171, 0xffff0000, v77
	v_lshlrev_b32_e32 v172, 16, v78
	v_and_b32_e32 v173, 0xffff0000, v78
	v_lshlrev_b32_e32 v174, 16, v79
	v_and_b32_e32 v175, 0xffff0000, v79
	v_pk_mul_f32 v[252:253], v[160:161], v[160:161]
	v_pk_mul_f32 v[254:255], v[162:163], v[162:163]
	v_pk_fma_f32 v[252:253], v[164:165], v[164:165], v[252:253]
	v_pk_fma_f32 v[254:255], v[166:167], v[166:167], v[254:255]
	v_pk_fma_f32 v[252:253], v[168:169], v[168:169], v[252:253]
	v_pk_fma_f32 v[254:255], v[170:171], v[170:171], v[254:255]
	v_pk_fma_f32 v[252:253], v[172:173], v[172:173], v[252:253]
	v_pk_fma_f32 v[254:255], v[174:175], v[174:175], v[254:255]
	v_pk_add_f32 v[252:253], v[252:253], v[254:255]
	s_nop 0
	v_add_f32_e32 v183, v252, v253
	s_nop 1
	v_add_f32_dpp v183, v183, v183 quad_perm:[1,0,3,2] row_mask:0xf bank_mask:0xf bound_ctrl:1
	s_nop 1
	v_add_f32_dpp v183, v183, v183 quad_perm:[2,3,0,1] row_mask:0xf bank_mask:0xf bound_ctrl:1
	s_nop 1
	v_add_f32_dpp v183, v183, v183 row_half_mirror row_mask:0xf bank_mask:0xf bound_ctrl:1
	s_nop 1
	v_add_f32_dpp v183, v183, v183 row_mirror row_mask:0xf bank_mask:0xf bound_ctrl:1
	s_nop 1
	v_readlane_b32 s98, v183, 0
	v_readlane_b32 s99, v183, 16
	v_readlane_b32 s100, v183, 32
	v_readlane_b32 s101, v183, 48
	s_nop 1
	v_mov_b32_e32 v183, s98
	v_add_f32_e32 v183, s99, v183
	v_add_f32_e32 v183, s100, v183
	v_add_f32_e32 v183, s101, v183
	v_fmamk_f32 v183, v183, 0x3a800000, v182
	v_cmp_gt_f32_e32 vcc, 0x800000, v183
	v_mul_f32_e32 v181, 0x4b800000, v183
	s_nop 1
	v_cndmask_b32_e32 v183, v183, v181, vcc
	v_rsq_f32_e32 v183, v183
	s_nop 0
	v_mul_f32_e32 v181, 0x45800000, v183
	v_cndmask_b32_e32 v184, v183, v181, vcc
	v_mov_b32_e32 v185, v184
	v_pk_mul_f32 v[160:161], v[160:161], v[184:185]
	v_pk_mul_f32 v[162:163], v[162:163], v[184:185]
	v_pk_mul_f32 v[164:165], v[164:165], v[184:185]
	v_pk_mul_f32 v[166:167], v[166:167], v[184:185]
	v_pk_mul_f32 v[168:169], v[168:169], v[184:185]
	v_pk_mul_f32 v[170:171], v[170:171], v[184:185]
	v_pk_mul_f32 v[172:173], v[172:173], v[184:185]
	v_pk_mul_f32 v[174:175], v[174:175], v[184:185]
	v_pk_fma_f32 v[144:145], v[160:161], v[128:129], v[144:145]
	v_pk_fma_f32 v[146:147], v[162:163], v[130:131], v[146:147]
	v_pk_fma_f32 v[148:149], v[164:165], v[132:133], v[148:149]
	v_pk_fma_f32 v[150:151], v[166:167], v[134:135], v[150:151]
	v_pk_fma_f32 v[152:153], v[168:169], v[136:137], v[152:153]
	v_pk_fma_f32 v[154:155], v[170:171], v[138:139], v[154:155]
	v_pk_fma_f32 v[156:157], v[172:173], v[140:141], v[156:157]
	v_pk_fma_f32 v[158:159], v[174:175], v[142:143], v[158:159]
	v_pk_mul_f32 v[252:253], v[144:145], v[144:145]
	v_pk_mul_f32 v[254:255], v[146:147], v[146:147]
	v_pk_fma_f32 v[252:253], v[148:149], v[148:149], v[252:253]
	v_pk_fma_f32 v[254:255], v[150:151], v[150:151], v[254:255]
	v_pk_fma_f32 v[252:253], v[152:153], v[152:153], v[252:253]
	v_pk_fma_f32 v[254:255], v[154:155], v[154:155], v[254:255]
	v_pk_fma_f32 v[252:253], v[156:157], v[156:157], v[252:253]
	v_pk_fma_f32 v[254:255], v[158:159], v[158:159], v[254:255]
	v_pk_add_f32 v[252:253], v[252:253], v[254:255]
	s_nop 0
	v_add_f32_e32 v183, v252, v253
	s_nop 1
	v_add_f32_dpp v183, v183, v183 quad_perm:[1,0,3,2] row_mask:0xf bank_mask:0xf bound_ctrl:1
	s_nop 1
	v_add_f32_dpp v183, v183, v183 quad_perm:[2,3,0,1] row_mask:0xf bank_mask:0xf bound_ctrl:1
	s_nop 1
	v_add_f32_dpp v183, v183, v183 row_half_mirror row_mask:0xf bank_mask:0xf bound_ctrl:1
	s_nop 1
	v_add_f32_dpp v183, v183, v183 row_mirror row_mask:0xf bank_mask:0xf bound_ctrl:1
	s_nop 1
	v_readlane_b32 s98, v183, 0
	v_readlane_b32 s99, v183, 16
	v_readlane_b32 s100, v183, 32
	v_readlane_b32 s101, v183, 48
	s_nop 1
	v_mov_b32_e32 v183, s98
	v_add_f32_e32 v183, s99, v183
	v_add_f32_e32 v183, s100, v183
	v_add_f32_e32 v183, s101, v183
	v_fmamk_f32 v183, v183, 0x3a800000, v182
	v_cmp_gt_f32_e32 vcc, 0x800000, v183
	v_mul_f32_e32 v181, 0x4b800000, v183
	s_nop 1
	v_cndmask_b32_e32 v183, v183, v181, vcc
	v_rsq_f32_e32 v183, v183
	s_nop 0
	v_mul_f32_e32 v181, 0x45800000, v183
	v_cndmask_b32_e32 v184, v183, v181, vcc
	v_mov_b32_e32 v185, v184
	v_cvt_pk_bf16_f32 v64, v144, v145
	v_cvt_pk_bf16_f32 v65, v146, v147
	v_cvt_pk_bf16_f32 v66, v148, v149
	v_cvt_pk_bf16_f32 v67, v150, v151
	v_cvt_pk_bf16_f32 v68, v152, v153
	v_cvt_pk_bf16_f32 v69, v154, v155
	v_cvt_pk_bf16_f32 v70, v156, v157
	v_cvt_pk_bf16_f32 v71, v158, v159
	v_add_u32_e32 v181, 0x2800000, v177
	global_store_dwordx4 v181, v[64:67], s[78:79]
	global_store_dwordx4 v181, v[68:71], s[78:79] offset:1024
	v_add_u32_e32 v236, 0x8000, v237
	s_mov_b64 exec, 1
	global_store_dword v236, v184, s[78:79]
	s_mov_b64 exec, -1
	s_waitcnt vmcnt(8)
	v_lshlrev_b32_e32 v144, 16, v80
	v_and_b32_e32 v145, 0xffff0000, v80
	v_lshlrev_b32_e32 v146, 16, v81
	v_and_b32_e32 v147, 0xffff0000, v81
	v_lshlrev_b32_e32 v148, 16, v82
	v_and_b32_e32 v149, 0xffff0000, v82
	v_lshlrev_b32_e32 v150, 16, v83
	v_and_b32_e32 v151, 0xffff0000, v83
	v_lshlrev_b32_e32 v152, 16, v84
	v_and_b32_e32 v153, 0xffff0000, v84
	v_lshlrev_b32_e32 v154, 16, v85
	v_and_b32_e32 v155, 0xffff0000, v85
	v_lshlrev_b32_e32 v156, 16, v86
	v_and_b32_e32 v157, 0xffff0000, v86
	v_lshlrev_b32_e32 v158, 16, v87
	v_and_b32_e32 v159, 0xffff0000, v87
	v_lshlrev_b32_e32 v160, 16, v88
	v_and_b32_e32 v161, 0xffff0000, v88
	v_lshlrev_b32_e32 v162, 16, v89
	v_and_b32_e32 v163, 0xffff0000, v89
	v_lshlrev_b32_e32 v164, 16, v90
	v_and_b32_e32 v165, 0xffff0000, v90
	v_lshlrev_b32_e32 v166, 16, v91
	v_and_b32_e32 v167, 0xffff0000, v91
	v_lshlrev_b32_e32 v168, 16, v92
	v_and_b32_e32 v169, 0xffff0000, v92
	v_lshlrev_b32_e32 v170, 16, v93
	v_and_b32_e32 v171, 0xffff0000, v93
	v_lshlrev_b32_e32 v172, 16, v94
	v_and_b32_e32 v173, 0xffff0000, v94
	v_lshlrev_b32_e32 v174, 16, v95
	v_and_b32_e32 v175, 0xffff0000, v95
	v_pk_mul_f32 v[252:253], v[160:161], v[160:161]
	v_pk_mul_f32 v[254:255], v[162:163], v[162:163]
	v_pk_fma_f32 v[252:253], v[164:165], v[164:165], v[252:253]
	v_pk_fma_f32 v[254:255], v[166:167], v[166:167], v[254:255]
	v_pk_fma_f32 v[252:253], v[168:169], v[168:169], v[252:253]
	v_pk_fma_f32 v[254:255], v[170:171], v[170:171], v[254:255]
	v_pk_fma_f32 v[252:253], v[172:173], v[172:173], v[252:253]
	v_pk_fma_f32 v[254:255], v[174:175], v[174:175], v[254:255]
	v_pk_add_f32 v[252:253], v[252:253], v[254:255]
	s_nop 0
	v_add_f32_e32 v183, v252, v253
	s_nop 1
	v_add_f32_dpp v183, v183, v183 quad_perm:[1,0,3,2] row_mask:0xf bank_mask:0xf bound_ctrl:1
	s_nop 1
	v_add_f32_dpp v183, v183, v183 quad_perm:[2,3,0,1] row_mask:0xf bank_mask:0xf bound_ctrl:1
	s_nop 1
	v_add_f32_dpp v183, v183, v183 row_half_mirror row_mask:0xf bank_mask:0xf bound_ctrl:1
	s_nop 1
	v_add_f32_dpp v183, v183, v183 row_mirror row_mask:0xf bank_mask:0xf bound_ctrl:1
	s_nop 1
	v_readlane_b32 s98, v183, 0
	v_readlane_b32 s99, v183, 16
	v_readlane_b32 s100, v183, 32
	v_readlane_b32 s101, v183, 48
	s_nop 1
	v_mov_b32_e32 v183, s98
	v_add_f32_e32 v183, s99, v183
	v_add_f32_e32 v183, s100, v183
	v_add_f32_e32 v183, s101, v183
	v_fmamk_f32 v183, v183, 0x3a800000, v182
	v_cmp_gt_f32_e32 vcc, 0x800000, v183
	v_mul_f32_e32 v181, 0x4b800000, v183
	s_nop 1
	v_cndmask_b32_e32 v183, v183, v181, vcc
	v_rsq_f32_e32 v183, v183
	s_nop 0
	v_mul_f32_e32 v181, 0x45800000, v183
	v_cndmask_b32_e32 v184, v183, v181, vcc
	v_mov_b32_e32 v185, v184
	v_pk_mul_f32 v[160:161], v[160:161], v[184:185]
	v_pk_mul_f32 v[162:163], v[162:163], v[184:185]
	v_pk_mul_f32 v[164:165], v[164:165], v[184:185]
	v_pk_mul_f32 v[166:167], v[166:167], v[184:185]
	v_pk_mul_f32 v[168:169], v[168:169], v[184:185]
	v_pk_mul_f32 v[170:171], v[170:171], v[184:185]
	v_pk_mul_f32 v[172:173], v[172:173], v[184:185]
	v_pk_mul_f32 v[174:175], v[174:175], v[184:185]
	v_pk_fma_f32 v[144:145], v[160:161], v[128:129], v[144:145]
	v_pk_fma_f32 v[146:147], v[162:163], v[130:131], v[146:147]
	v_pk_fma_f32 v[148:149], v[164:165], v[132:133], v[148:149]
	v_pk_fma_f32 v[150:151], v[166:167], v[134:135], v[150:151]
	v_pk_fma_f32 v[152:153], v[168:169], v[136:137], v[152:153]
	v_pk_fma_f32 v[154:155], v[170:171], v[138:139], v[154:155]
	v_pk_fma_f32 v[156:157], v[172:173], v[140:141], v[156:157]
	v_pk_fma_f32 v[158:159], v[174:175], v[142:143], v[158:159]
	v_pk_mul_f32 v[252:253], v[144:145], v[144:145]
	v_pk_mul_f32 v[254:255], v[146:147], v[146:147]
	v_pk_fma_f32 v[252:253], v[148:149], v[148:149], v[252:253]
	v_pk_fma_f32 v[254:255], v[150:151], v[150:151], v[254:255]
	v_pk_fma_f32 v[252:253], v[152:153], v[152:153], v[252:253]
	v_pk_fma_f32 v[254:255], v[154:155], v[154:155], v[254:255]
	v_pk_fma_f32 v[252:253], v[156:157], v[156:157], v[252:253]
	v_pk_fma_f32 v[254:255], v[158:159], v[158:159], v[254:255]
	v_pk_add_f32 v[252:253], v[252:253], v[254:255]
	s_nop 0
	v_add_f32_e32 v183, v252, v253
	s_nop 1
	v_add_f32_dpp v183, v183, v183 quad_perm:[1,0,3,2] row_mask:0xf bank_mask:0xf bound_ctrl:1
	s_nop 1
	v_add_f32_dpp v183, v183, v183 quad_perm:[2,3,0,1] row_mask:0xf bank_mask:0xf bound_ctrl:1
	s_nop 1
	v_add_f32_dpp v183, v183, v183 row_half_mirror row_mask:0xf bank_mask:0xf bound_ctrl:1
	s_nop 1
	v_add_f32_dpp v183, v183, v183 row_mirror row_mask:0xf bank_mask:0xf bound_ctrl:1
	s_nop 1
	v_readlane_b32 s98, v183, 0
	v_readlane_b32 s99, v183, 16
	v_readlane_b32 s100, v183, 32
	v_readlane_b32 s101, v183, 48
	s_nop 1
	v_mov_b32_e32 v183, s98
	v_add_f32_e32 v183, s99, v183
	v_add_f32_e32 v183, s100, v183
	v_add_f32_e32 v183, s101, v183
	v_fmamk_f32 v183, v183, 0x3a800000, v182
	v_cmp_gt_f32_e32 vcc, 0x800000, v183
	v_mul_f32_e32 v181, 0x4b800000, v183
	s_nop 1
	v_cndmask_b32_e32 v183, v183, v181, vcc
	v_rsq_f32_e32 v183, v183
	s_nop 0
	v_mul_f32_e32 v181, 0x45800000, v183
	v_cndmask_b32_e32 v184, v183, v181, vcc
	v_mov_b32_e32 v185, v184
	v_cvt_pk_bf16_f32 v80, v144, v145
	v_cvt_pk_bf16_f32 v81, v146, v147
	v_cvt_pk_bf16_f32 v82, v148, v149
	v_cvt_pk_bf16_f32 v83, v150, v151
	v_cvt_pk_bf16_f32 v84, v152, v153
	v_cvt_pk_bf16_f32 v85, v154, v155
	v_cvt_pk_bf16_f32 v86, v156, v157
	v_cvt_pk_bf16_f32 v87, v158, v159
	v_add_u32_e32 v181, 0x2c00000, v177
	global_store_dwordx4 v181, v[80:83], s[78:79]
	global_store_dwordx4 v181, v[84:87], s[78:79] offset:1024
	v_add_u32_e32 v236, 0xa000, v237
	s_mov_b64 exec, 1
	global_store_dword v236, v184, s[78:79]
	s_mov_b64 exec, -1
	s_waitcnt vmcnt(4)
	v_lshlrev_b32_e32 v144, 16, v96
	v_and_b32_e32 v145, 0xffff0000, v96
	v_lshlrev_b32_e32 v146, 16, v97
	v_and_b32_e32 v147, 0xffff0000, v97
	v_lshlrev_b32_e32 v148, 16, v98
	v_and_b32_e32 v149, 0xffff0000, v98
	v_lshlrev_b32_e32 v150, 16, v99
	v_and_b32_e32 v151, 0xffff0000, v99
	v_lshlrev_b32_e32 v152, 16, v100
	v_and_b32_e32 v153, 0xffff0000, v100
	v_lshlrev_b32_e32 v154, 16, v101
	v_and_b32_e32 v155, 0xffff0000, v101
	v_lshlrev_b32_e32 v156, 16, v102
	v_and_b32_e32 v157, 0xffff0000, v102
	v_lshlrev_b32_e32 v158, 16, v103
	v_and_b32_e32 v159, 0xffff0000, v103
	v_lshlrev_b32_e32 v160, 16, v104
	v_and_b32_e32 v161, 0xffff0000, v104
	v_lshlrev_b32_e32 v162, 16, v105
	v_and_b32_e32 v163, 0xffff0000, v105
	v_lshlrev_b32_e32 v164, 16, v106
	v_and_b32_e32 v165, 0xffff0000, v106
	v_lshlrev_b32_e32 v166, 16, v107
	v_and_b32_e32 v167, 0xffff0000, v107
	v_lshlrev_b32_e32 v168, 16, v108
	v_and_b32_e32 v169, 0xffff0000, v108
	v_lshlrev_b32_e32 v170, 16, v109
	v_and_b32_e32 v171, 0xffff0000, v109
	v_lshlrev_b32_e32 v172, 16, v110
	v_and_b32_e32 v173, 0xffff0000, v110
	v_lshlrev_b32_e32 v174, 16, v111
	v_and_b32_e32 v175, 0xffff0000, v111
	v_pk_mul_f32 v[252:253], v[160:161], v[160:161]
	v_pk_mul_f32 v[254:255], v[162:163], v[162:163]
	v_pk_fma_f32 v[252:253], v[164:165], v[164:165], v[252:253]
	v_pk_fma_f32 v[254:255], v[166:167], v[166:167], v[254:255]
	v_pk_fma_f32 v[252:253], v[168:169], v[168:169], v[252:253]
	v_pk_fma_f32 v[254:255], v[170:171], v[170:171], v[254:255]
	v_pk_fma_f32 v[252:253], v[172:173], v[172:173], v[252:253]
	v_pk_fma_f32 v[254:255], v[174:175], v[174:175], v[254:255]
	v_pk_add_f32 v[252:253], v[252:253], v[254:255]
	s_nop 0
	v_add_f32_e32 v183, v252, v253
	s_nop 1
	v_add_f32_dpp v183, v183, v183 quad_perm:[1,0,3,2] row_mask:0xf bank_mask:0xf bound_ctrl:1
	s_nop 1
	v_add_f32_dpp v183, v183, v183 quad_perm:[2,3,0,1] row_mask:0xf bank_mask:0xf bound_ctrl:1
	s_nop 1
	v_add_f32_dpp v183, v183, v183 row_half_mirror row_mask:0xf bank_mask:0xf bound_ctrl:1
	s_nop 1
	v_add_f32_dpp v183, v183, v183 row_mirror row_mask:0xf bank_mask:0xf bound_ctrl:1
	s_nop 1
	v_readlane_b32 s98, v183, 0
	v_readlane_b32 s99, v183, 16
	v_readlane_b32 s100, v183, 32
	v_readlane_b32 s101, v183, 48
	s_nop 1
	v_mov_b32_e32 v183, s98
	v_add_f32_e32 v183, s99, v183
	v_add_f32_e32 v183, s100, v183
	v_add_f32_e32 v183, s101, v183
	v_fmamk_f32 v183, v183, 0x3a800000, v182
	v_cmp_gt_f32_e32 vcc, 0x800000, v183
	v_mul_f32_e32 v181, 0x4b800000, v183
	s_nop 1
	v_cndmask_b32_e32 v183, v183, v181, vcc
	v_rsq_f32_e32 v183, v183
	s_nop 0
	v_mul_f32_e32 v181, 0x45800000, v183
	v_cndmask_b32_e32 v184, v183, v181, vcc
	v_mov_b32_e32 v185, v184
	v_pk_mul_f32 v[160:161], v[160:161], v[184:185]
	v_pk_mul_f32 v[162:163], v[162:163], v[184:185]
	v_pk_mul_f32 v[164:165], v[164:165], v[184:185]
	v_pk_mul_f32 v[166:167], v[166:167], v[184:185]
	v_pk_mul_f32 v[168:169], v[168:169], v[184:185]
	v_pk_mul_f32 v[170:171], v[170:171], v[184:185]
	v_pk_mul_f32 v[172:173], v[172:173], v[184:185]
	v_pk_mul_f32 v[174:175], v[174:175], v[184:185]
	v_pk_fma_f32 v[144:145], v[160:161], v[128:129], v[144:145]
	v_pk_fma_f32 v[146:147], v[162:163], v[130:131], v[146:147]
	v_pk_fma_f32 v[148:149], v[164:165], v[132:133], v[148:149]
	v_pk_fma_f32 v[150:151], v[166:167], v[134:135], v[150:151]
	v_pk_fma_f32 v[152:153], v[168:169], v[136:137], v[152:153]
	v_pk_fma_f32 v[154:155], v[170:171], v[138:139], v[154:155]
	v_pk_fma_f32 v[156:157], v[172:173], v[140:141], v[156:157]
	v_pk_fma_f32 v[158:159], v[174:175], v[142:143], v[158:159]
	v_pk_mul_f32 v[252:253], v[144:145], v[144:145]
	v_pk_mul_f32 v[254:255], v[146:147], v[146:147]
	v_pk_fma_f32 v[252:253], v[148:149], v[148:149], v[252:253]
	v_pk_fma_f32 v[254:255], v[150:151], v[150:151], v[254:255]
	v_pk_fma_f32 v[252:253], v[152:153], v[152:153], v[252:253]
	v_pk_fma_f32 v[254:255], v[154:155], v[154:155], v[254:255]
	v_pk_fma_f32 v[252:253], v[156:157], v[156:157], v[252:253]
	v_pk_fma_f32 v[254:255], v[158:159], v[158:159], v[254:255]
	v_pk_add_f32 v[252:253], v[252:253], v[254:255]
	s_nop 0
	v_add_f32_e32 v183, v252, v253
	s_nop 1
	v_add_f32_dpp v183, v183, v183 quad_perm:[1,0,3,2] row_mask:0xf bank_mask:0xf bound_ctrl:1
	s_nop 1
	v_add_f32_dpp v183, v183, v183 quad_perm:[2,3,0,1] row_mask:0xf bank_mask:0xf bound_ctrl:1
	s_nop 1
	v_add_f32_dpp v183, v183, v183 row_half_mirror row_mask:0xf bank_mask:0xf bound_ctrl:1
	s_nop 1
	v_add_f32_dpp v183, v183, v183 row_mirror row_mask:0xf bank_mask:0xf bound_ctrl:1
	s_nop 1
	v_readlane_b32 s98, v183, 0
	v_readlane_b32 s99, v183, 16
	v_readlane_b32 s100, v183, 32
	v_readlane_b32 s101, v183, 48
	s_nop 1
	v_mov_b32_e32 v183, s98
	v_add_f32_e32 v183, s99, v183
	v_add_f32_e32 v183, s100, v183
	v_add_f32_e32 v183, s101, v183
	v_fmamk_f32 v183, v183, 0x3a800000, v182
	v_cmp_gt_f32_e32 vcc, 0x800000, v183
	v_mul_f32_e32 v181, 0x4b800000, v183
	s_nop 1
	v_cndmask_b32_e32 v183, v183, v181, vcc
	v_rsq_f32_e32 v183, v183
	s_nop 0
	v_mul_f32_e32 v181, 0x45800000, v183
	v_cndmask_b32_e32 v184, v183, v181, vcc
	v_mov_b32_e32 v185, v184
	v_cvt_pk_bf16_f32 v96, v144, v145
	v_cvt_pk_bf16_f32 v97, v146, v147
	v_cvt_pk_bf16_f32 v98, v148, v149
	v_cvt_pk_bf16_f32 v99, v150, v151
	v_cvt_pk_bf16_f32 v100, v152, v153
	v_cvt_pk_bf16_f32 v101, v154, v155
	v_cvt_pk_bf16_f32 v102, v156, v157
	v_cvt_pk_bf16_f32 v103, v158, v159
	v_add_u32_e32 v181, 0x3000000, v177
	global_store_dwordx4 v181, v[96:99], s[78:79]
	global_store_dwordx4 v181, v[100:103], s[78:79] offset:1024
	v_add_u32_e32 v236, 0xc000, v237
	s_mov_b64 exec, 1
	global_store_dword v236, v184, s[78:79]
	s_mov_b64 exec, -1
	s_waitcnt vmcnt(0)
	v_lshlrev_b32_e32 v144, 16, v112
	v_and_b32_e32 v145, 0xffff0000, v112
	v_lshlrev_b32_e32 v146, 16, v113
	v_and_b32_e32 v147, 0xffff0000, v113
	v_lshlrev_b32_e32 v148, 16, v114
	v_and_b32_e32 v149, 0xffff0000, v114
	v_lshlrev_b32_e32 v150, 16, v115
	v_and_b32_e32 v151, 0xffff0000, v115
	v_lshlrev_b32_e32 v152, 16, v116
	v_and_b32_e32 v153, 0xffff0000, v116
	v_lshlrev_b32_e32 v154, 16, v117
	v_and_b32_e32 v155, 0xffff0000, v117
	v_lshlrev_b32_e32 v156, 16, v118
	v_and_b32_e32 v157, 0xffff0000, v118
	v_lshlrev_b32_e32 v158, 16, v119
	v_and_b32_e32 v159, 0xffff0000, v119
	v_lshlrev_b32_e32 v160, 16, v120
	v_and_b32_e32 v161, 0xffff0000, v120
	v_lshlrev_b32_e32 v162, 16, v121
	v_and_b32_e32 v163, 0xffff0000, v121
	v_lshlrev_b32_e32 v164, 16, v122
	v_and_b32_e32 v165, 0xffff0000, v122
	v_lshlrev_b32_e32 v166, 16, v123
	v_and_b32_e32 v167, 0xffff0000, v123
	v_lshlrev_b32_e32 v168, 16, v124
	v_and_b32_e32 v169, 0xffff0000, v124
	v_lshlrev_b32_e32 v170, 16, v125
	v_and_b32_e32 v171, 0xffff0000, v125
	v_lshlrev_b32_e32 v172, 16, v126
	v_and_b32_e32 v173, 0xffff0000, v126
	v_lshlrev_b32_e32 v174, 16, v127
	v_and_b32_e32 v175, 0xffff0000, v127
	v_pk_mul_f32 v[252:253], v[160:161], v[160:161]
	v_pk_mul_f32 v[254:255], v[162:163], v[162:163]
	v_pk_fma_f32 v[252:253], v[164:165], v[164:165], v[252:253]
	v_pk_fma_f32 v[254:255], v[166:167], v[166:167], v[254:255]
	v_pk_fma_f32 v[252:253], v[168:169], v[168:169], v[252:253]
	v_pk_fma_f32 v[254:255], v[170:171], v[170:171], v[254:255]
	v_pk_fma_f32 v[252:253], v[172:173], v[172:173], v[252:253]
	v_pk_fma_f32 v[254:255], v[174:175], v[174:175], v[254:255]
	v_pk_add_f32 v[252:253], v[252:253], v[254:255]
	s_nop 0
	v_add_f32_e32 v183, v252, v253
	s_nop 1
	v_add_f32_dpp v183, v183, v183 quad_perm:[1,0,3,2] row_mask:0xf bank_mask:0xf bound_ctrl:1
	s_nop 1
	v_add_f32_dpp v183, v183, v183 quad_perm:[2,3,0,1] row_mask:0xf bank_mask:0xf bound_ctrl:1
	s_nop 1
	v_add_f32_dpp v183, v183, v183 row_half_mirror row_mask:0xf bank_mask:0xf bound_ctrl:1
	s_nop 1
	v_add_f32_dpp v183, v183, v183 row_mirror row_mask:0xf bank_mask:0xf bound_ctrl:1
	s_nop 1
	v_readlane_b32 s98, v183, 0
	v_readlane_b32 s99, v183, 16
	v_readlane_b32 s100, v183, 32
	v_readlane_b32 s101, v183, 48
	s_nop 1
	v_mov_b32_e32 v183, s98
	v_add_f32_e32 v183, s99, v183
	v_add_f32_e32 v183, s100, v183
	v_add_f32_e32 v183, s101, v183
	v_fmamk_f32 v183, v183, 0x3a800000, v182
	v_cmp_gt_f32_e32 vcc, 0x800000, v183
	v_mul_f32_e32 v181, 0x4b800000, v183
	s_nop 1
	v_cndmask_b32_e32 v183, v183, v181, vcc
	v_rsq_f32_e32 v183, v183
	s_nop 0
	v_mul_f32_e32 v181, 0x45800000, v183
	v_cndmask_b32_e32 v184, v183, v181, vcc
	v_mov_b32_e32 v185, v184
	v_pk_mul_f32 v[160:161], v[160:161], v[184:185]
	v_pk_mul_f32 v[162:163], v[162:163], v[184:185]
	v_pk_mul_f32 v[164:165], v[164:165], v[184:185]
	v_pk_mul_f32 v[166:167], v[166:167], v[184:185]
	v_pk_mul_f32 v[168:169], v[168:169], v[184:185]
	v_pk_mul_f32 v[170:171], v[170:171], v[184:185]
	v_pk_mul_f32 v[172:173], v[172:173], v[184:185]
	v_pk_mul_f32 v[174:175], v[174:175], v[184:185]
	v_pk_fma_f32 v[144:145], v[160:161], v[128:129], v[144:145]
	v_pk_fma_f32 v[146:147], v[162:163], v[130:131], v[146:147]
	v_pk_fma_f32 v[148:149], v[164:165], v[132:133], v[148:149]
	v_pk_fma_f32 v[150:151], v[166:167], v[134:135], v[150:151]
	v_pk_fma_f32 v[152:153], v[168:169], v[136:137], v[152:153]
	v_pk_fma_f32 v[154:155], v[170:171], v[138:139], v[154:155]
	v_pk_fma_f32 v[156:157], v[172:173], v[140:141], v[156:157]
	v_pk_fma_f32 v[158:159], v[174:175], v[142:143], v[158:159]
	v_pk_mul_f32 v[252:253], v[144:145], v[144:145]
	v_pk_mul_f32 v[254:255], v[146:147], v[146:147]
	v_pk_fma_f32 v[252:253], v[148:149], v[148:149], v[252:253]
	v_pk_fma_f32 v[254:255], v[150:151], v[150:151], v[254:255]
	v_pk_fma_f32 v[252:253], v[152:153], v[152:153], v[252:253]
	v_pk_fma_f32 v[254:255], v[154:155], v[154:155], v[254:255]
	v_pk_fma_f32 v[252:253], v[156:157], v[156:157], v[252:253]
	v_pk_fma_f32 v[254:255], v[158:159], v[158:159], v[254:255]
	v_pk_add_f32 v[252:253], v[252:253], v[254:255]
	s_nop 0
	v_add_f32_e32 v183, v252, v253
	s_nop 1
	v_add_f32_dpp v183, v183, v183 quad_perm:[1,0,3,2] row_mask:0xf bank_mask:0xf bound_ctrl:1
	s_nop 1
	v_add_f32_dpp v183, v183, v183 quad_perm:[2,3,0,1] row_mask:0xf bank_mask:0xf bound_ctrl:1
	s_nop 1
	v_add_f32_dpp v183, v183, v183 row_half_mirror row_mask:0xf bank_mask:0xf bound_ctrl:1
	s_nop 1
	v_add_f32_dpp v183, v183, v183 row_mirror row_mask:0xf bank_mask:0xf bound_ctrl:1
	s_nop 1
	v_readlane_b32 s98, v183, 0
	v_readlane_b32 s99, v183, 16
	v_readlane_b32 s100, v183, 32
	v_readlane_b32 s101, v183, 48
	s_nop 1
	v_mov_b32_e32 v183, s98
	v_add_f32_e32 v183, s99, v183
	v_add_f32_e32 v183, s100, v183
	v_add_f32_e32 v183, s101, v183
	v_fmamk_f32 v183, v183, 0x3a800000, v182
	v_cmp_gt_f32_e32 vcc, 0x800000, v183
	v_mul_f32_e32 v181, 0x4b800000, v183
	s_nop 1
	v_cndmask_b32_e32 v183, v183, v181, vcc
	v_rsq_f32_e32 v183, v183
	s_nop 0
	v_mul_f32_e32 v181, 0x45800000, v183
	v_cndmask_b32_e32 v184, v183, v181, vcc
	v_mov_b32_e32 v185, v184
	v_cvt_pk_bf16_f32 v112, v144, v145
	v_cvt_pk_bf16_f32 v113, v146, v147
	v_cvt_pk_bf16_f32 v114, v148, v149
	v_cvt_pk_bf16_f32 v115, v150, v151
	v_cvt_pk_bf16_f32 v116, v152, v153
	v_cvt_pk_bf16_f32 v117, v154, v155
	v_cvt_pk_bf16_f32 v118, v156, v157
	v_cvt_pk_bf16_f32 v119, v158, v159
	v_add_u32_e32 v181, 0x3400000, v177
	global_store_dwordx4 v181, v[112:115], s[78:79]
	global_store_dwordx4 v181, v[116:119], s[78:79] offset:1024
	v_add_u32_e32 v236, 0xe000, v237
	s_mov_b64 exec, 1
	global_store_dword v236, v184, s[78:79]
	s_mov_b64 exec, -1
	v_readfirstlane_b32 s98, v179
	s_nop 3
	s_and_b32 s99, s98, 3
	s_cmp_lg_u32 s99, 0
	s_cbranch_scc1 .Lmyxupd_done_2
	v_lshrrev_b32_e32 v179, 2, v179
	v_lshlrev_b32_e32 v177, 4, v176
	v_lshl_add_u32 v177, v179, 11, v177
	v_lshlrev_b32_e32 v237, 2, v179
	v_add_u32_e32 v237, 0x10000, v237
	v_add_u32_e32 v181, 0x3800000, v177
	global_load_dwordx4 v[0:3], v181, s[78:79]
	global_load_dwordx4 v[4:7], v181, s[78:79] offset:1024
	v_lshl_add_u32 v183, v179, 12, v180
	v_add_u32_e32 v183, 0xbf00000, v183
	v_add_u32_e32 v181, 0x0, v183
	global_load_dwordx4 v[8:11], v181, s[78:79]
	global_load_dwordx4 v[12:15], v181, s[78:79] offset:16
	global_load_dwordx4 v[16:19], v181, s[78:79] offset:2048
	global_load_dwordx4 v[20:23], v181, s[78:79] offset:2064
	v_add_u32_e32 v181, 0x200000, v183
	global_load_dwordx4 v[24:27], v181, s[78:79]
	global_load_dwordx4 v[28:31], v181, s[78:79] offset:16
	global_load_dwordx4 v[32:35], v181, s[78:79] offset:2048
	global_load_dwordx4 v[36:39], v181, s[78:79] offset:2064
	v_add_u32_e32 v181, 0x400000, v183
	global_load_dwordx4 v[40:43], v181, s[78:79]
	global_load_dwordx4 v[44:47], v181, s[78:79] offset:16
	global_load_dwordx4 v[48:51], v181, s[78:79] offset:2048
	global_load_dwordx4 v[52:55], v181, s[78:79] offset:2064
	v_add_u32_e32 v181, 0x600000, v183
	global_load_dwordx4 v[56:59], v181, s[78:79]
	global_load_dwordx4 v[60:63], v181, s[78:79] offset:16
	global_load_dwordx4 v[64:67], v181, s[78:79] offset:2048
	global_load_dwordx4 v[68:71], v181, s[78:79] offset:2064
	v_add_u32_e32 v181, 0x800000, v183
	global_load_dwordx4 v[72:75], v181, s[78:79]
	global_load_dwordx4 v[76:79], v181, s[78:79] offset:16
	global_load_dwordx4 v[80:83], v181, s[78:79] offset:2048
	global_load_dwordx4 v[84:87], v181, s[78:79] offset:2064
	v_add_u32_e32 v181, 0xa00000, v183
	global_load_dwordx4 v[88:91], v181, s[78:79]
	global_load_dwordx4 v[92:95], v181, s[78:79] offset:16
	global_load_dwordx4 v[96:99], v181, s[78:79] offset:2048
	global_load_dwordx4 v[100:103], v181, s[78:79] offset:2064
	s_waitcnt vmcnt(20)
	v_pk_add_f32 v[160:161], v[8:9], 0 op_sel_hi:[1,0]
	v_pk_add_f32 v[162:163], v[10:11], 0 op_sel_hi:[1,0]
	v_pk_add_f32 v[164:165], v[12:13], 0 op_sel_hi:[1,0]
	v_pk_add_f32 v[166:167], v[14:15], 0 op_sel_hi:[1,0]
	v_pk_add_f32 v[168:169], v[16:17], 0 op_sel_hi:[1,0]
	v_pk_add_f32 v[170:171], v[18:19], 0 op_sel_hi:[1,0]
	v_pk_add_f32 v[172:173], v[20:21], 0 op_sel_hi:[1,0]
	v_pk_add_f32 v[174:175], v[22:23], 0 op_sel_hi:[1,0]
	s_waitcnt vmcnt(16)
	v_pk_add_f32 v[160:161], v[160:161], v[24:25]
	v_pk_add_f32 v[162:163], v[162:163], v[26:27]
	v_pk_add_f32 v[164:165], v[164:165], v[28:29]
	v_pk_add_f32 v[166:167], v[166:167], v[30:31]
	v_pk_add_f32 v[168:169], v[168:169], v[32:33]
	v_pk_add_f32 v[170:171], v[170:171], v[34:35]
	v_pk_add_f32 v[172:173], v[172:173], v[36:37]
	v_pk_add_f32 v[174:175], v[174:175], v[38:39]
	s_waitcnt vmcnt(12)
	v_pk_add_f32 v[160:161], v[160:161], v[40:41]
	v_pk_add_f32 v[162:163], v[162:163], v[42:43]
	v_pk_add_f32 v[164:165], v[164:165], v[44:45]
	v_pk_add_f32 v[166:167], v[166:167], v[46:47]
	v_pk_add_f32 v[168:169], v[168:169], v[48:49]
	v_pk_add_f32 v[170:171], v[170:171], v[50:51]
	v_pk_add_f32 v[172:173], v[172:173], v[52:53]
	v_pk_add_f32 v[174:175], v[174:175], v[54:55]
	s_waitcnt vmcnt(8)
	v_pk_add_f32 v[160:161], v[160:161], v[56:57]
	v_pk_add_f32 v[162:163], v[162:163], v[58:59]
	v_pk_add_f32 v[164:165], v[164:165], v[60:61]
	v_pk_add_f32 v[166:167], v[166:167], v[62:63]
	v_pk_add_f32 v[168:169], v[168:169], v[64:65]
	v_pk_add_f32 v[170:171], v[170:171], v[66:67]
	v_pk_add_f32 v[172:173], v[172:173], v[68:69]
	v_pk_add_f32 v[174:175], v[174:175], v[70:71]
	s_waitcnt vmcnt(4)
	v_pk_add_f32 v[160:161], v[160:161], v[72:73]
	v_pk_add_f32 v[162:163], v[162:163], v[74:75]
	v_pk_add_f32 v[164:165], v[164:165], v[76:77]
	v_pk_add_f32 v[166:167], v[166:167], v[78:79]
	v_pk_add_f32 v[168:169], v[168:169], v[80:81]
	v_pk_add_f32 v[170:171], v[170:171], v[82:83]
	v_pk_add_f32 v[172:173], v[172:173], v[84:85]
	v_pk_add_f32 v[174:175], v[174:175], v[86:87]
	s_waitcnt vmcnt(0)
	v_pk_add_f32 v[160:161], v[160:161], v[88:89]
	v_pk_add_f32 v[162:163], v[162:163], v[90:91]
	v_pk_add_f32 v[164:165], v[164:165], v[92:93]
	v_pk_add_f32 v[166:167], v[166:167], v[94:95]
	v_pk_add_f32 v[168:169], v[168:169], v[96:97]
	v_pk_add_f32 v[170:171], v[170:171], v[98:99]
	v_pk_add_f32 v[172:173], v[172:173], v[100:101]
	v_pk_add_f32 v[174:175], v[174:175], v[102:103]
	v_lshlrev_b32_e32 v144, 16, v0
	v_and_b32_e32 v145, 0xffff0000, v0
	v_lshlrev_b32_e32 v146, 16, v1
	v_and_b32_e32 v147, 0xffff0000, v1
	v_lshlrev_b32_e32 v148, 16, v2
	v_and_b32_e32 v149, 0xffff0000, v2
	v_lshlrev_b32_e32 v150, 16, v3
	v_and_b32_e32 v151, 0xffff0000, v3
	v_lshlrev_b32_e32 v152, 16, v4
	v_and_b32_e32 v153, 0xffff0000, v4
	v_lshlrev_b32_e32 v154, 16, v5
	v_and_b32_e32 v155, 0xffff0000, v5
	v_lshlrev_b32_e32 v156, 16, v6
	v_and_b32_e32 v157, 0xffff0000, v6
	v_lshlrev_b32_e32 v158, 16, v7
	v_and_b32_e32 v159, 0xffff0000, v7
	v_add_u32_e32 v181, 0xc00000, v183
	global_load_dwordx4 v[8:11], v181, s[78:79]
	global_load_dwordx4 v[12:15], v181, s[78:79] offset:16
	global_load_dwordx4 v[16:19], v181, s[78:79] offset:2048
	global_load_dwordx4 v[20:23], v181, s[78:79] offset:2064
	v_add_u32_e32 v181, 0xe00000, v183
	global_load_dwordx4 v[24:27], v181, s[78:79]
	global_load_dwordx4 v[28:31], v181, s[78:79] offset:16
	global_load_dwordx4 v[32:35], v181, s[78:79] offset:2048
	global_load_dwordx4 v[36:39], v181, s[78:79] offset:2064
	s_waitcnt vmcnt(4)
	v_pk_add_f32 v[160:161], v[160:161], v[8:9]
	v_pk_add_f32 v[162:163], v[162:163], v[10:11]
	v_pk_add_f32 v[164:165], v[164:165], v[12:13]
	v_pk_add_f32 v[166:167], v[166:167], v[14:15]
	v_pk_add_f32 v[168:169], v[168:169], v[16:17]
	v_pk_add_f32 v[170:171], v[170:171], v[18:19]
	v_pk_add_f32 v[172:173], v[172:173], v[20:21]
	v_pk_add_f32 v[174:175], v[174:175], v[22:23]
	s_waitcnt vmcnt(0)
	v_pk_add_f32 v[160:161], v[160:161], v[24:25]
	v_pk_add_f32 v[162:163], v[162:163], v[26:27]
	v_pk_add_f32 v[164:165], v[164:165], v[28:29]
	v_pk_add_f32 v[166:167], v[166:167], v[30:31]
	v_pk_add_f32 v[168:169], v[168:169], v[32:33]
	v_pk_add_f32 v[170:171], v[170:171], v[34:35]
	v_pk_add_f32 v[172:173], v[172:173], v[36:37]
	v_pk_add_f32 v[174:175], v[174:175], v[38:39]
	v_pk_mul_f32 v[252:253], v[160:161], v[160:161]
	v_pk_mul_f32 v[254:255], v[162:163], v[162:163]
	v_pk_fma_f32 v[252:253], v[164:165], v[164:165], v[252:253]
	v_pk_fma_f32 v[254:255], v[166:167], v[166:167], v[254:255]
	v_pk_fma_f32 v[252:253], v[168:169], v[168:169], v[252:253]
	v_pk_fma_f32 v[254:255], v[170:171], v[170:171], v[254:255]
	v_pk_fma_f32 v[252:253], v[172:173], v[172:173], v[252:253]
	v_pk_fma_f32 v[254:255], v[174:175], v[174:175], v[254:255]
	v_pk_add_f32 v[252:253], v[252:253], v[254:255]
	s_nop 0
	v_add_f32_e32 v183, v252, v253
	s_nop 1
	v_add_f32_dpp v183, v183, v183 quad_perm:[1,0,3,2] row_mask:0xf bank_mask:0xf bound_ctrl:1
	s_nop 1
	v_add_f32_dpp v183, v183, v183 quad_perm:[2,3,0,1] row_mask:0xf bank_mask:0xf bound_ctrl:1
	s_nop 1
	v_add_f32_dpp v183, v183, v183 row_half_mirror row_mask:0xf bank_mask:0xf bound_ctrl:1
	s_nop 1
	v_add_f32_dpp v183, v183, v183 row_mirror row_mask:0xf bank_mask:0xf bound_ctrl:1
	s_nop 1
	v_readlane_b32 s98, v183, 0
	v_readlane_b32 s99, v183, 16
	v_readlane_b32 s100, v183, 32
	v_readlane_b32 s101, v183, 48
	s_nop 1
	v_mov_b32_e32 v183, s98
	v_add_f32_e32 v183, s99, v183
	v_add_f32_e32 v183, s100, v183
	v_add_f32_e32 v183, s101, v183
	v_fmamk_f32 v183, v183, 0x3a800000, v182
	v_cmp_gt_f32_e32 vcc, 0x800000, v183
	v_mul_f32_e32 v181, 0x4b800000, v183
	s_nop 1
	v_cndmask_b32_e32 v183, v183, v181, vcc
	v_rsq_f32_e32 v183, v183
	s_nop 0
	v_mul_f32_e32 v181, 0x45800000, v183
	v_cndmask_b32_e32 v184, v183, v181, vcc
	v_mov_b32_e32 v185, v184
	v_pk_mul_f32 v[160:161], v[160:161], v[184:185]
	v_pk_mul_f32 v[162:163], v[162:163], v[184:185]
	v_pk_mul_f32 v[164:165], v[164:165], v[184:185]
	v_pk_mul_f32 v[166:167], v[166:167], v[184:185]
	v_pk_mul_f32 v[168:169], v[168:169], v[184:185]
	v_pk_mul_f32 v[170:171], v[170:171], v[184:185]
	v_pk_mul_f32 v[172:173], v[172:173], v[184:185]
	v_pk_mul_f32 v[174:175], v[174:175], v[184:185]
	v_pk_fma_f32 v[144:145], v[160:161], v[128:129], v[144:145]
	v_pk_fma_f32 v[146:147], v[162:163], v[130:131], v[146:147]
	v_pk_fma_f32 v[148:149], v[164:165], v[132:133], v[148:149]
	v_pk_fma_f32 v[150:151], v[166:167], v[134:135], v[150:151]
	v_pk_fma_f32 v[152:153], v[168:169], v[136:137], v[152:153]
	v_pk_fma_f32 v[154:155], v[170:171], v[138:139], v[154:155]
	v_pk_fma_f32 v[156:157], v[172:173], v[140:141], v[156:157]
	v_pk_fma_f32 v[158:159], v[174:175], v[142:143], v[158:159]
	v_pk_mul_f32 v[252:253], v[144:145], v[144:145]
	v_pk_mul_f32 v[254:255], v[146:147], v[146:147]
	v_pk_fma_f32 v[252:253], v[148:149], v[148:149], v[252:253]
	v_pk_fma_f32 v[254:255], v[150:151], v[150:151], v[254:255]
	v_pk_fma_f32 v[252:253], v[152:153], v[152:153], v[252:253]
	v_pk_fma_f32 v[254:255], v[154:155], v[154:155], v[254:255]
	v_pk_fma_f32 v[252:253], v[156:157], v[156:157], v[252:253]
	v_pk_fma_f32 v[254:255], v[158:159], v[158:159], v[254:255]
	v_pk_add_f32 v[252:253], v[252:253], v[254:255]
	s_nop 0
	v_add_f32_e32 v183, v252, v253
	s_nop 1
	v_add_f32_dpp v183, v183, v183 quad_perm:[1,0,3,2] row_mask:0xf bank_mask:0xf bound_ctrl:1
	s_nop 1
	v_add_f32_dpp v183, v183, v183 quad_perm:[2,3,0,1] row_mask:0xf bank_mask:0xf bound_ctrl:1
	s_nop 1
	v_add_f32_dpp v183, v183, v183 row_half_mirror row_mask:0xf bank_mask:0xf bound_ctrl:1
	s_nop 1
	v_add_f32_dpp v183, v183, v183 row_mirror row_mask:0xf bank_mask:0xf bound_ctrl:1
	s_nop 1
	v_readlane_b32 s98, v183, 0
	v_readlane_b32 s99, v183, 16
	v_readlane_b32 s100, v183, 32
	v_readlane_b32 s101, v183, 48
	s_nop 1
	v_mov_b32_e32 v183, s98
	v_add_f32_e32 v183, s99, v183
	v_add_f32_e32 v183, s100, v183
	v_add_f32_e32 v183, s101, v183
	v_fmamk_f32 v183, v183, 0x3a800000, v182
	v_cmp_gt_f32_e32 vcc, 0x800000, v183
	v_mul_f32_e32 v181, 0x4b800000, v183
	s_nop 1
	v_cndmask_b32_e32 v183, v183, v181, vcc
	v_rsq_f32_e32 v183, v183
	s_nop 0
	v_mul_f32_e32 v181, 0x45800000, v183
	v_cndmask_b32_e32 v184, v183, v181, vcc
	v_mov_b32_e32 v185, v184
	v_cvt_pk_bf16_f32 v0, v144, v145
	v_cvt_pk_bf16_f32 v1, v146, v147
	v_cvt_pk_bf16_f32 v2, v148, v149
	v_cvt_pk_bf16_f32 v3, v150, v151
	v_cvt_pk_bf16_f32 v4, v152, v153
	v_cvt_pk_bf16_f32 v5, v154, v155
	v_cvt_pk_bf16_f32 v6, v156, v157
	v_cvt_pk_bf16_f32 v7, v158, v159
	v_add_u32_e32 v181, 0x3800000, v177
	global_store_dwordx4 v181, v[0:3], s[78:79]
	global_store_dwordx4 v181, v[4:7], s[78:79] offset:1024
	v_add_u32_e32 v236, 0x10000, v237
	s_mov_b64 exec, 1
	global_store_dword v236, v184, s[78:79]
	s_mov_b64 exec, -1

.LBB0_1430:
	v_readlane_b32 s0, v235, 52
	v_readlane_b32 s1, v235, 53
	s_and_b64 vcc, exec, s[0:1]
	s_waitcnt lgkmcnt(0)
	s_barrier
	v_mbcnt_lo_u32_b32 v0, -1, 0
	v_mbcnt_hi_u32_b32 v0, -1, v0
	s_cbranch_vccnz .LBB0_1450
	v_lshlrev_b32_e32 v2, 3, v0
	v_readlane_b32 s4, v235, 4
	v_ashrrev_i32_e32 v3, 31, v2
	v_readlane_b32 s6, v235, 6
	v_readlane_b32 s7, v235, 7
	v_lshlrev_b64 v[4:5], 1, v[2:3]
	v_lshlrev_b64 v[2:3], 2, v[2:3]
	v_readlane_b32 s5, v235, 5
	v_readlane_b32 s10, v235, 10
	v_readlane_b32 s11, v235, 11
	v_readlane_b32 s18, v235, 18
	v_readlane_b32 s19, v235, 19
	v_readlane_b32 s6, v235, 61
	v_lshl_add_u64 v[154:155], s[90:91], 0, v[2:3]
	v_readlane_b32 s8, v235, 8
	v_lshl_add_u64 v[2:3], s[18:19], 0, v[2:3]
	s_mov_b64 s[0:1], 0x1000
	v_readlane_b32 s4, v235, 0
	v_readlane_b32 s7, v235, 62
	s_mov_b32 s10, s6
	s_ashr_i32 s11, s6, 31
	v_readlane_b32 s9, v235, 9
	v_lshl_add_u64 v[158:159], v[2:3], 0, s[0:1]
	s_lshl_b32 s4, s4, 4
	s_add_i32 s0, s6, 0xffffc000
	s_lshl_b64 s[6:7], s[10:11], 2
	s_mov_b32 s8, s10
	v_readlane_b32 s12, v235, 12
	v_readlane_b32 s13, v235, 13
	v_readlane_b32 s14, v235, 14
	v_readlane_b32 s15, v235, 15
	v_readlane_b32 s16, v235, 16
	v_readlane_b32 s17, v235, 17
	v_readlane_b32 s5, v235, 1
	s_add_u32 s80, s6, 0x10000
	v_writelane_b32 v235, s8, 61
	s_addc_u32 s12, s7, 0
	s_ashr_i32 s5, s4, 31
	v_writelane_b32 v235, s9, 62
	s_lshl_b64 s[8:9], s[10:11], 11
	v_lshl_add_u64 v[152:153], s[86:87], 0, v[4:5]
	v_lshl_add_u64 v[156:157], s[54:55], 0, v[4:5]
	s_mov_b32 s1, 0
	v_cmp_eq_u32_e64 s[16:17], 0, v0
	s_lshl_b64 s[6:7], s[4:5], 2
	v_lshl_add_u64 v[160:161], s[8:9], 0, v[4:5]
	s_lshl_b64 s[8:9], s[4:5], 11
	s_mov_b64 s[20:21], 0x600000
	s_mov_b64 s[22:23], 0x600800
	s_mov_b64 s[24:25], 0x800000
	s_mov_b32 s5, 0x800000
	s_mov_b64 s[26:27], 0x800800
	s_mov_b64 s[28:29], 0xa00000
	s_mov_b64 s[36:37], 0xa00800
	s_mov_b64 s[38:39], 0xc00000
	s_mov_b64 s[40:41], 0xc00800
	s_mov_b64 s[42:43], 0xe00000
	s_mov_b64 s[44:45], 0xe00800
	s_mov_b64 s[46:47], 0x1000000
	s_mov_b32 s13, 0x1000000
	s_mov_b64 s[48:49], 0x1000800
	s_mov_b64 s[50:51], 0x1200000
	s_mov_b32 s14, 0x1200000
	s_mov_b64 s[10:11], 0x1200800
	s_mov_b64 s[82:83], 0x1400000
	s_mov_b32 s15, 0x1400000
	s_mov_b64 s[90:91], 0x1400800
	v_mov_b32_e32 v215, 0
	v_mov_b32_e32 v216, 0x358637bd
	v_mbcnt_lo_u32_b32 v176, -1, 0
	v_mbcnt_hi_u32_b32 v176, -1, v176
	v_readlane_b32 s98, v235, 49
	v_readlane_b32 s99, v235, 20
	v_readlane_b32 s100, v235, 18
	v_readlane_b32 s101, v235, 19
	s_nop 3
	s_lshr_b32 vcc_lo, s98, 3
	s_and_b32 vcc_hi, vcc_lo, 7
	s_lshr_b32 vcc_lo, vcc_lo, 3
	s_lshl_b32 vcc_lo, vcc_lo, 3
	s_add_i32 vcc_lo, vcc_lo, s99
	s_lshl_b32 s98, vcc_hi, 8
	s_add_i32 s98, s98, vcc_lo
	s_mov_b32 s99, s98
	v_mov_b32_e32 v183, s99
	v_lshlrev_b32_e32 v177, 4, v176
	s_lshl_b32 s99, s99, 11
	v_add_u32_e32 v177, s99, v177
	v_add_u32_e32 v178, 0x1800000, v177
	v_add_u32_e32 v179, 0x9e00000, v177
	v_lshlrev_b32_e32 v180, 5, v176
	v_add_u32_e32 v181, 0x1000, v180
	global_load_dwordx4 v[128:131], v181, s[100:101]
	global_load_dwordx4 v[132:135], v181, s[100:101] offset:16
	global_load_dwordx4 v[136:139], v181, s[100:101] offset:2048
	global_load_dwordx4 v[140:143], v181, s[100:101] offset:2064
	v_mov_b32_e32 v182, 0x358637bd
	global_load_dwordx4 v[0:3], v178, s[78:79]
	global_load_dwordx4 v[4:7], v178, s[78:79] offset:1024
	global_load_dwordx4 v[8:11], v179, s[78:79]
	global_load_dwordx4 v[12:15], v179, s[78:79] offset:1024
	v_add_u32_e32 v178, 0x400000, v178
	v_add_u32_e32 v179, 0x400000, v179
	global_load_dwordx4 v[16:19], v178, s[78:79]
	global_load_dwordx4 v[20:23], v178, s[78:79] offset:1024
	global_load_dwordx4 v[24:27], v179, s[78:79]
	global_load_dwordx4 v[28:31], v179, s[78:79] offset:1024
	v_add_u32_e32 v178, 0x400000, v178
	v_add_u32_e32 v179, 0x400000, v179
	global_load_dwordx4 v[32:35], v178, s[78:79]
	global_load_dwordx4 v[36:39], v178, s[78:79] offset:1024
	global_load_dwordx4 v[40:43], v179, s[78:79]
	global_load_dwordx4 v[44:47], v179, s[78:79] offset:1024
	v_add_u32_e32 v178, 0x400000, v178
	v_add_u32_e32 v179, 0x400000, v179
	global_load_dwordx4 v[48:51], v178, s[78:79]
	global_load_dwordx4 v[52:55], v178, s[78:79] offset:1024
	global_load_dwordx4 v[56:59], v179, s[78:79]
	global_load_dwordx4 v[60:63], v179, s[78:79] offset:1024
	v_add_u32_e32 v178, 0x400000, v178
	v_add_u32_e32 v179, 0x400000, v179
	global_load_dwordx4 v[64:67], v178, s[78:79]
	global_load_dwordx4 v[68:71], v178, s[78:79] offset:1024
	global_load_dwordx4 v[72:75], v179, s[78:79]
	global_load_dwordx4 v[76:79], v179, s[78:79] offset:1024
	v_add_u32_e32 v178, 0x400000, v178
	v_add_u32_e32 v179, 0x400000, v179
	global_load_dwordx4 v[80:83], v178, s[78:79]
	global_load_dwordx4 v[84:87], v178, s[78:79] offset:1024
	global_load_dwordx4 v[88:91], v179, s[78:79]
	global_load_dwordx4 v[92:95], v179, s[78:79] offset:1024
	v_add_u32_e32 v178, 0x400000, v178
	v_add_u32_e32 v179, 0x400000, v179
	global_load_dwordx4 v[96:99], v178, s[78:79]
	global_load_dwordx4 v[100:103], v178, s[78:79] offset:1024
	global_load_dwordx4 v[104:107], v179, s[78:79]
	global_load_dwordx4 v[108:111], v179, s[78:79] offset:1024
	v_add_u32_e32 v178, 0x400000, v178
	v_add_u32_e32 v179, 0x400000, v179
	global_load_dwordx4 v[112:115], v178, s[78:79]
	global_load_dwordx4 v[116:119], v178, s[78:79] offset:1024
	global_load_dwordx4 v[120:123], v179, s[78:79]
	global_load_dwordx4 v[124:127], v179, s[78:79] offset:1024
	v_lshlrev_b32_e32 v237, 2, v183
	v_add_u32_e32 v237, 0x10000, v237
	v_mov_b32_e32 v179, s98
	s_waitcnt vmcnt(28)
	v_lshlrev_b32_e32 v144, 16, v0
	v_and_b32_e32 v145, 0xffff0000, v0
	v_lshlrev_b32_e32 v146, 16, v1
	v_and_b32_e32 v147, 0xffff0000, v1
	v_lshlrev_b32_e32 v148, 16, v2
	v_and_b32_e32 v149, 0xffff0000, v2
	v_lshlrev_b32_e32 v150, 16, v3
	v_and_b32_e32 v151, 0xffff0000, v3
	v_lshlrev_b32_e32 v152, 16, v4
	v_and_b32_e32 v153, 0xffff0000, v4
	v_lshlrev_b32_e32 v154, 16, v5
	v_and_b32_e32 v155, 0xffff0000, v5
	v_lshlrev_b32_e32 v156, 16, v6
	v_and_b32_e32 v157, 0xffff0000, v6
	v_lshlrev_b32_e32 v158, 16, v7
	v_and_b32_e32 v159, 0xffff0000, v7
	v_lshlrev_b32_e32 v160, 16, v8
	v_and_b32_e32 v161, 0xffff0000, v8
	v_lshlrev_b32_e32 v162, 16, v9
	v_and_b32_e32 v163, 0xffff0000, v9
	v_lshlrev_b32_e32 v164, 16, v10
	v_and_b32_e32 v165, 0xffff0000, v10
	v_lshlrev_b32_e32 v166, 16, v11
	v_and_b32_e32 v167, 0xffff0000, v11
	v_lshlrev_b32_e32 v168, 16, v12
	v_and_b32_e32 v169, 0xffff0000, v12
	v_lshlrev_b32_e32 v170, 16, v13
	v_and_b32_e32 v171, 0xffff0000, v13
	v_lshlrev_b32_e32 v172, 16, v14
	v_and_b32_e32 v173, 0xffff0000, v14
	v_lshlrev_b32_e32 v174, 16, v15
	v_and_b32_e32 v175, 0xffff0000, v15
	v_pk_mul_f32 v[252:253], v[160:161], v[160:161]
	v_pk_mul_f32 v[254:255], v[162:163], v[162:163]
	v_pk_fma_f32 v[252:253], v[164:165], v[164:165], v[252:253]
	v_pk_fma_f32 v[254:255], v[166:167], v[166:167], v[254:255]
	v_pk_fma_f32 v[252:253], v[168:169], v[168:169], v[252:253]
	v_pk_fma_f32 v[254:255], v[170:171], v[170:171], v[254:255]
	v_pk_fma_f32 v[252:253], v[172:173], v[172:173], v[252:253]
	v_pk_fma_f32 v[254:255], v[174:175], v[174:175], v[254:255]
	v_pk_add_f32 v[252:253], v[252:253], v[254:255]
	s_nop 0
	v_add_f32_e32 v183, v252, v253
	s_nop 1
	v_add_f32_dpp v183, v183, v183 quad_perm:[1,0,3,2] row_mask:0xf bank_mask:0xf bound_ctrl:1
	s_nop 1
	v_add_f32_dpp v183, v183, v183 quad_perm:[2,3,0,1] row_mask:0xf bank_mask:0xf bound_ctrl:1
	s_nop 1
	v_add_f32_dpp v183, v183, v183 row_half_mirror row_mask:0xf bank_mask:0xf bound_ctrl:1
	s_nop 1
	v_add_f32_dpp v183, v183, v183 row_mirror row_mask:0xf bank_mask:0xf bound_ctrl:1
	s_nop 1
	v_readlane_b32 s98, v183, 0
	v_readlane_b32 s99, v183, 16
	v_readlane_b32 s100, v183, 32
	v_readlane_b32 s101, v183, 48
	s_nop 1
	v_mov_b32_e32 v183, s98
	v_add_f32_e32 v183, s99, v183
	v_add_f32_e32 v183, s100, v183
	v_add_f32_e32 v183, s101, v183
	v_fmamk_f32 v183, v183, 0x3a800000, v182
	v_cmp_gt_f32_e32 vcc, 0x800000, v183
	v_mul_f32_e32 v181, 0x4b800000, v183
	s_nop 1
	v_cndmask_b32_e32 v183, v183, v181, vcc
	v_rsq_f32_e32 v183, v183
	s_nop 0
	v_mul_f32_e32 v181, 0x45800000, v183
	v_cndmask_b32_e32 v184, v183, v181, vcc
	v_mov_b32_e32 v185, v184
	v_pk_mul_f32 v[160:161], v[160:161], v[184:185]
	v_pk_mul_f32 v[162:163], v[162:163], v[184:185]
	v_pk_mul_f32 v[164:165], v[164:165], v[184:185]
	v_pk_mul_f32 v[166:167], v[166:167], v[184:185]
	v_pk_mul_f32 v[168:169], v[168:169], v[184:185]
	v_pk_mul_f32 v[170:171], v[170:171], v[184:185]
	v_pk_mul_f32 v[172:173], v[172:173], v[184:185]
	v_pk_mul_f32 v[174:175], v[174:175], v[184:185]
	v_pk_fma_f32 v[144:145], v[160:161], v[128:129], v[144:145]
	v_pk_fma_f32 v[146:147], v[162:163], v[130:131], v[146:147]
	v_pk_fma_f32 v[148:149], v[164:165], v[132:133], v[148:149]
	v_pk_fma_f32 v[150:151], v[166:167], v[134:135], v[150:151]
	v_pk_fma_f32 v[152:153], v[168:169], v[136:137], v[152:153]
	v_pk_fma_f32 v[154:155], v[170:171], v[138:139], v[154:155]
	v_pk_fma_f32 v[156:157], v[172:173], v[140:141], v[156:157]
	v_pk_fma_f32 v[158:159], v[174:175], v[142:143], v[158:159]
	v_pk_mul_f32 v[252:253], v[144:145], v[144:145]
	v_pk_mul_f32 v[254:255], v[146:147], v[146:147]
	v_pk_fma_f32 v[252:253], v[148:149], v[148:149], v[252:253]
	v_pk_fma_f32 v[254:255], v[150:151], v[150:151], v[254:255]
	v_pk_fma_f32 v[252:253], v[152:153], v[152:153], v[252:253]
	v_pk_fma_f32 v[254:255], v[154:155], v[154:155], v[254:255]
	v_pk_fma_f32 v[252:253], v[156:157], v[156:157], v[252:253]
	v_pk_fma_f32 v[254:255], v[158:159], v[158:159], v[254:255]
	v_pk_add_f32 v[252:253], v[252:253], v[254:255]
	s_nop 0
	v_add_f32_e32 v183, v252, v253
	s_nop 1
	v_add_f32_dpp v183, v183, v183 quad_perm:[1,0,3,2] row_mask:0xf bank_mask:0xf bound_ctrl:1
	s_nop 1
	v_add_f32_dpp v183, v183, v183 quad_perm:[2,3,0,1] row_mask:0xf bank_mask:0xf bound_ctrl:1
	s_nop 1
	v_add_f32_dpp v183, v183, v183 row_half_mirror row_mask:0xf bank_mask:0xf bound_ctrl:1
	s_nop 1
	v_add_f32_dpp v183, v183, v183 row_mirror row_mask:0xf bank_mask:0xf bound_ctrl:1
	s_nop 1
	v_readlane_b32 s98, v183, 0
	v_readlane_b32 s99, v183, 16
	v_readlane_b32 s100, v183, 32
	v_readlane_b32 s101, v183, 48
	s_nop 1
	v_mov_b32_e32 v183, s98
	v_add_f32_e32 v183, s99, v183
	v_add_f32_e32 v183, s100, v183
	v_add_f32_e32 v183, s101, v183
	v_fmamk_f32 v183, v183, 0x3a800000, v182
	v_cmp_gt_f32_e32 vcc, 0x800000, v183
	v_mul_f32_e32 v181, 0x4b800000, v183
	s_nop 1
	v_cndmask_b32_e32 v183, v183, v181, vcc
	v_rsq_f32_e32 v183, v183
	s_nop 0
	v_mul_f32_e32 v181, 0x45800000, v183
	v_cndmask_b32_e32 v184, v183, v181, vcc
	v_mov_b32_e32 v185, v184
	v_cvt_pk_bf16_f32 v0, v144, v145
	v_cvt_pk_bf16_f32 v1, v146, v147
	v_cvt_pk_bf16_f32 v2, v148, v149
	v_cvt_pk_bf16_f32 v3, v150, v151
	v_cvt_pk_bf16_f32 v4, v152, v153
	v_cvt_pk_bf16_f32 v5, v154, v155
	v_cvt_pk_bf16_f32 v6, v156, v157
	v_cvt_pk_bf16_f32 v7, v158, v159
	v_add_u32_e32 v181, 0x1800000, v177
	global_store_dwordx4 v181, v[0:3], s[78:79]
	global_store_dwordx4 v181, v[4:7], s[78:79] offset:1024
	v_add_u32_e32 v236, 0x0, v237
	s_mov_b64 exec, 1
	global_store_dword v236, v184, s[78:79]
	s_mov_b64 exec, -1
	s_waitcnt vmcnt(24)
	v_lshlrev_b32_e32 v144, 16, v16
	v_and_b32_e32 v145, 0xffff0000, v16
	v_lshlrev_b32_e32 v146, 16, v17
	v_and_b32_e32 v147, 0xffff0000, v17
	v_lshlrev_b32_e32 v148, 16, v18
	v_and_b32_e32 v149, 0xffff0000, v18
	v_lshlrev_b32_e32 v150, 16, v19
	v_and_b32_e32 v151, 0xffff0000, v19
	v_lshlrev_b32_e32 v152, 16, v20
	v_and_b32_e32 v153, 0xffff0000, v20
	v_lshlrev_b32_e32 v154, 16, v21
	v_and_b32_e32 v155, 0xffff0000, v21
	v_lshlrev_b32_e32 v156, 16, v22
	v_and_b32_e32 v157, 0xffff0000, v22
	v_lshlrev_b32_e32 v158, 16, v23
	v_and_b32_e32 v159, 0xffff0000, v23
	v_lshlrev_b32_e32 v160, 16, v24
	v_and_b32_e32 v161, 0xffff0000, v24
	v_lshlrev_b32_e32 v162, 16, v25
	v_and_b32_e32 v163, 0xffff0000, v25
	v_lshlrev_b32_e32 v164, 16, v26
	v_and_b32_e32 v165, 0xffff0000, v26
	v_lshlrev_b32_e32 v166, 16, v27
	v_and_b32_e32 v167, 0xffff0000, v27
	v_lshlrev_b32_e32 v168, 16, v28
	v_and_b32_e32 v169, 0xffff0000, v28
	v_lshlrev_b32_e32 v170, 16, v29
	v_and_b32_e32 v171, 0xffff0000, v29
	v_lshlrev_b32_e32 v172, 16, v30
	v_and_b32_e32 v173, 0xffff0000, v30
	v_lshlrev_b32_e32 v174, 16, v31
	v_and_b32_e32 v175, 0xffff0000, v31
	v_pk_mul_f32 v[252:253], v[160:161], v[160:161]
	v_pk_mul_f32 v[254:255], v[162:163], v[162:163]
	v_pk_fma_f32 v[252:253], v[164:165], v[164:165], v[252:253]
	v_pk_fma_f32 v[254:255], v[166:167], v[166:167], v[254:255]
	v_pk_fma_f32 v[252:253], v[168:169], v[168:169], v[252:253]
	v_pk_fma_f32 v[254:255], v[170:171], v[170:171], v[254:255]
	v_pk_fma_f32 v[252:253], v[172:173], v[172:173], v[252:253]
	v_pk_fma_f32 v[254:255], v[174:175], v[174:175], v[254:255]
	v_pk_add_f32 v[252:253], v[252:253], v[254:255]
	s_nop 0
	v_add_f32_e32 v183, v252, v253
	s_nop 1
	v_add_f32_dpp v183, v183, v183 quad_perm:[1,0,3,2] row_mask:0xf bank_mask:0xf bound_ctrl:1
	s_nop 1
	v_add_f32_dpp v183, v183, v183 quad_perm:[2,3,0,1] row_mask:0xf bank_mask:0xf bound_ctrl:1
	s_nop 1
	v_add_f32_dpp v183, v183, v183 row_half_mirror row_mask:0xf bank_mask:0xf bound_ctrl:1
	s_nop 1
	v_add_f32_dpp v183, v183, v183 row_mirror row_mask:0xf bank_mask:0xf bound_ctrl:1
	s_nop 1
	v_readlane_b32 s98, v183, 0
	v_readlane_b32 s99, v183, 16
	v_readlane_b32 s100, v183, 32
	v_readlane_b32 s101, v183, 48
	s_nop 1
	v_mov_b32_e32 v183, s98
	v_add_f32_e32 v183, s99, v183
	v_add_f32_e32 v183, s100, v183
	v_add_f32_e32 v183, s101, v183
	v_fmamk_f32 v183, v183, 0x3a800000, v182
	v_cmp_gt_f32_e32 vcc, 0x800000, v183
	v_mul_f32_e32 v181, 0x4b800000, v183
	s_nop 1
	v_cndmask_b32_e32 v183, v183, v181, vcc
	v_rsq_f32_e32 v183, v183
	s_nop 0
	v_mul_f32_e32 v181, 0x45800000, v183
	v_cndmask_b32_e32 v184, v183, v181, vcc
	v_mov_b32_e32 v185, v184
	v_pk_mul_f32 v[160:161], v[160:161], v[184:185]
	v_pk_mul_f32 v[162:163], v[162:163], v[184:185]
	v_pk_mul_f32 v[164:165], v[164:165], v[184:185]
	v_pk_mul_f32 v[166:167], v[166:167], v[184:185]
	v_pk_mul_f32 v[168:169], v[168:169], v[184:185]
	v_pk_mul_f32 v[170:171], v[170:171], v[184:185]
	v_pk_mul_f32 v[172:173], v[172:173], v[184:185]
	v_pk_mul_f32 v[174:175], v[174:175], v[184:185]
	v_pk_fma_f32 v[144:145], v[160:161], v[128:129], v[144:145]
	v_pk_fma_f32 v[146:147], v[162:163], v[130:131], v[146:147]
	v_pk_fma_f32 v[148:149], v[164:165], v[132:133], v[148:149]
	v_pk_fma_f32 v[150:151], v[166:167], v[134:135], v[150:151]
	v_pk_fma_f32 v[152:153], v[168:169], v[136:137], v[152:153]
	v_pk_fma_f32 v[154:155], v[170:171], v[138:139], v[154:155]
	v_pk_fma_f32 v[156:157], v[172:173], v[140:141], v[156:157]
	v_pk_fma_f32 v[158:159], v[174:175], v[142:143], v[158:159]
	v_pk_mul_f32 v[252:253], v[144:145], v[144:145]
	v_pk_mul_f32 v[254:255], v[146:147], v[146:147]
	v_pk_fma_f32 v[252:253], v[148:149], v[148:149], v[252:253]
	v_pk_fma_f32 v[254:255], v[150:151], v[150:151], v[254:255]
	v_pk_fma_f32 v[252:253], v[152:153], v[152:153], v[252:253]
	v_pk_fma_f32 v[254:255], v[154:155], v[154:155], v[254:255]
	v_pk_fma_f32 v[252:253], v[156:157], v[156:157], v[252:253]
	v_pk_fma_f32 v[254:255], v[158:159], v[158:159], v[254:255]
	v_pk_add_f32 v[252:253], v[252:253], v[254:255]
	s_nop 0
	v_add_f32_e32 v183, v252, v253
	s_nop 1
	v_add_f32_dpp v183, v183, v183 quad_perm:[1,0,3,2] row_mask:0xf bank_mask:0xf bound_ctrl:1
	s_nop 1
	v_add_f32_dpp v183, v183, v183 quad_perm:[2,3,0,1] row_mask:0xf bank_mask:0xf bound_ctrl:1
	s_nop 1
	v_add_f32_dpp v183, v183, v183 row_half_mirror row_mask:0xf bank_mask:0xf bound_ctrl:1
	s_nop 1
	v_add_f32_dpp v183, v183, v183 row_mirror row_mask:0xf bank_mask:0xf bound_ctrl:1
	s_nop 1
	v_readlane_b32 s98, v183, 0
	v_readlane_b32 s99, v183, 16
	v_readlane_b32 s100, v183, 32
	v_readlane_b32 s101, v183, 48
	s_nop 1
	v_mov_b32_e32 v183, s98
	v_add_f32_e32 v183, s99, v183
	v_add_f32_e32 v183, s100, v183
	v_add_f32_e32 v183, s101, v183
	v_fmamk_f32 v183, v183, 0x3a800000, v182
	v_cmp_gt_f32_e32 vcc, 0x800000, v183
	v_mul_f32_e32 v181, 0x4b800000, v183
	s_nop 1
	v_cndmask_b32_e32 v183, v183, v181, vcc
	v_rsq_f32_e32 v183, v183
	s_nop 0
	v_mul_f32_e32 v181, 0x45800000, v183
	v_cndmask_b32_e32 v184, v183, v181, vcc
	v_mov_b32_e32 v185, v184
	v_cvt_pk_bf16_f32 v16, v144, v145
	v_cvt_pk_bf16_f32 v17, v146, v147
	v_cvt_pk_bf16_f32 v18, v148, v149
	v_cvt_pk_bf16_f32 v19, v150, v151
	v_cvt_pk_bf16_f32 v20, v152, v153
	v_cvt_pk_bf16_f32 v21, v154, v155
	v_cvt_pk_bf16_f32 v22, v156, v157
	v_cvt_pk_bf16_f32 v23, v158, v159
	v_add_u32_e32 v181, 0x1c00000, v177
	global_store_dwordx4 v181, v[16:19], s[78:79]
	global_store_dwordx4 v181, v[20:23], s[78:79] offset:1024
	v_add_u32_e32 v236, 0x2000, v237
	s_mov_b64 exec, 1
	global_store_dword v236, v184, s[78:79]
	s_mov_b64 exec, -1
	s_waitcnt vmcnt(20)
	v_lshlrev_b32_e32 v144, 16, v32
	v_and_b32_e32 v145, 0xffff0000, v32
	v_lshlrev_b32_e32 v146, 16, v33
	v_and_b32_e32 v147, 0xffff0000, v33
	v_lshlrev_b32_e32 v148, 16, v34
	v_and_b32_e32 v149, 0xffff0000, v34
	v_lshlrev_b32_e32 v150, 16, v35
	v_and_b32_e32 v151, 0xffff0000, v35
	v_lshlrev_b32_e32 v152, 16, v36
	v_and_b32_e32 v153, 0xffff0000, v36
	v_lshlrev_b32_e32 v154, 16, v37
	v_and_b32_e32 v155, 0xffff0000, v37
	v_lshlrev_b32_e32 v156, 16, v38
	v_and_b32_e32 v157, 0xffff0000, v38
	v_lshlrev_b32_e32 v158, 16, v39
	v_and_b32_e32 v159, 0xffff0000, v39
	v_lshlrev_b32_e32 v160, 16, v40
	v_and_b32_e32 v161, 0xffff0000, v40
	v_lshlrev_b32_e32 v162, 16, v41
	v_and_b32_e32 v163, 0xffff0000, v41
	v_lshlrev_b32_e32 v164, 16, v42
	v_and_b32_e32 v165, 0xffff0000, v42
	v_lshlrev_b32_e32 v166, 16, v43
	v_and_b32_e32 v167, 0xffff0000, v43
	v_lshlrev_b32_e32 v168, 16, v44
	v_and_b32_e32 v169, 0xffff0000, v44
	v_lshlrev_b32_e32 v170, 16, v45
	v_and_b32_e32 v171, 0xffff0000, v45
	v_lshlrev_b32_e32 v172, 16, v46
	v_and_b32_e32 v173, 0xffff0000, v46
	v_lshlrev_b32_e32 v174, 16, v47
	v_and_b32_e32 v175, 0xffff0000, v47
	v_pk_mul_f32 v[252:253], v[160:161], v[160:161]
	v_pk_mul_f32 v[254:255], v[162:163], v[162:163]
	v_pk_fma_f32 v[252:253], v[164:165], v[164:165], v[252:253]
	v_pk_fma_f32 v[254:255], v[166:167], v[166:167], v[254:255]
	v_pk_fma_f32 v[252:253], v[168:169], v[168:169], v[252:253]
	v_pk_fma_f32 v[254:255], v[170:171], v[170:171], v[254:255]
	v_pk_fma_f32 v[252:253], v[172:173], v[172:173], v[252:253]
	v_pk_fma_f32 v[254:255], v[174:175], v[174:175], v[254:255]
	v_pk_add_f32 v[252:253], v[252:253], v[254:255]
	s_nop 0
	v_add_f32_e32 v183, v252, v253
	s_nop 1
	v_add_f32_dpp v183, v183, v183 quad_perm:[1,0,3,2] row_mask:0xf bank_mask:0xf bound_ctrl:1
	s_nop 1
	v_add_f32_dpp v183, v183, v183 quad_perm:[2,3,0,1] row_mask:0xf bank_mask:0xf bound_ctrl:1
	s_nop 1
	v_add_f32_dpp v183, v183, v183 row_half_mirror row_mask:0xf bank_mask:0xf bound_ctrl:1
	s_nop 1
	v_add_f32_dpp v183, v183, v183 row_mirror row_mask:0xf bank_mask:0xf bound_ctrl:1
	s_nop 1
	v_readlane_b32 s98, v183, 0
	v_readlane_b32 s99, v183, 16
	v_readlane_b32 s100, v183, 32
	v_readlane_b32 s101, v183, 48
	s_nop 1
	v_mov_b32_e32 v183, s98
	v_add_f32_e32 v183, s99, v183
	v_add_f32_e32 v183, s100, v183
	v_add_f32_e32 v183, s101, v183
	v_fmamk_f32 v183, v183, 0x3a800000, v182
	v_cmp_gt_f32_e32 vcc, 0x800000, v183
	v_mul_f32_e32 v181, 0x4b800000, v183
	s_nop 1
	v_cndmask_b32_e32 v183, v183, v181, vcc
	v_rsq_f32_e32 v183, v183
	s_nop 0
	v_mul_f32_e32 v181, 0x45800000, v183
	v_cndmask_b32_e32 v184, v183, v181, vcc
	v_mov_b32_e32 v185, v184
	v_pk_mul_f32 v[160:161], v[160:161], v[184:185]
	v_pk_mul_f32 v[162:163], v[162:163], v[184:185]
	v_pk_mul_f32 v[164:165], v[164:165], v[184:185]
	v_pk_mul_f32 v[166:167], v[166:167], v[184:185]
	v_pk_mul_f32 v[168:169], v[168:169], v[184:185]
	v_pk_mul_f32 v[170:171], v[170:171], v[184:185]
	v_pk_mul_f32 v[172:173], v[172:173], v[184:185]
	v_pk_mul_f32 v[174:175], v[174:175], v[184:185]
	v_pk_fma_f32 v[144:145], v[160:161], v[128:129], v[144:145]
	v_pk_fma_f32 v[146:147], v[162:163], v[130:131], v[146:147]
	v_pk_fma_f32 v[148:149], v[164:165], v[132:133], v[148:149]
	v_pk_fma_f32 v[150:151], v[166:167], v[134:135], v[150:151]
	v_pk_fma_f32 v[152:153], v[168:169], v[136:137], v[152:153]
	v_pk_fma_f32 v[154:155], v[170:171], v[138:139], v[154:155]
	v_pk_fma_f32 v[156:157], v[172:173], v[140:141], v[156:157]
	v_pk_fma_f32 v[158:159], v[174:175], v[142:143], v[158:159]
	v_pk_mul_f32 v[252:253], v[144:145], v[144:145]
	v_pk_mul_f32 v[254:255], v[146:147], v[146:147]
	v_pk_fma_f32 v[252:253], v[148:149], v[148:149], v[252:253]
	v_pk_fma_f32 v[254:255], v[150:151], v[150:151], v[254:255]
	v_pk_fma_f32 v[252:253], v[152:153], v[152:153], v[252:253]
	v_pk_fma_f32 v[254:255], v[154:155], v[154:155], v[254:255]
	v_pk_fma_f32 v[252:253], v[156:157], v[156:157], v[252:253]
	v_pk_fma_f32 v[254:255], v[158:159], v[158:159], v[254:255]
	v_pk_add_f32 v[252:253], v[252:253], v[254:255]
	s_nop 0
	v_add_f32_e32 v183, v252, v253
	s_nop 1
	v_add_f32_dpp v183, v183, v183 quad_perm:[1,0,3,2] row_mask:0xf bank_mask:0xf bound_ctrl:1
	s_nop 1
	v_add_f32_dpp v183, v183, v183 quad_perm:[2,3,0,1] row_mask:0xf bank_mask:0xf bound_ctrl:1
	s_nop 1
	v_add_f32_dpp v183, v183, v183 row_half_mirror row_mask:0xf bank_mask:0xf bound_ctrl:1
	s_nop 1
	v_add_f32_dpp v183, v183, v183 row_mirror row_mask:0xf bank_mask:0xf bound_ctrl:1
	s_nop 1
	v_readlane_b32 s98, v183, 0
	v_readlane_b32 s99, v183, 16
	v_readlane_b32 s100, v183, 32
	v_readlane_b32 s101, v183, 48
	s_nop 1
	v_mov_b32_e32 v183, s98
	v_add_f32_e32 v183, s99, v183
	v_add_f32_e32 v183, s100, v183
	v_add_f32_e32 v183, s101, v183
	v_fmamk_f32 v183, v183, 0x3a800000, v182
	v_cmp_gt_f32_e32 vcc, 0x800000, v183
	v_mul_f32_e32 v181, 0x4b800000, v183
	s_nop 1
	v_cndmask_b32_e32 v183, v183, v181, vcc
	v_rsq_f32_e32 v183, v183
	s_nop 0
	v_mul_f32_e32 v181, 0x45800000, v183
	v_cndmask_b32_e32 v184, v183, v181, vcc
	v_mov_b32_e32 v185, v184
	v_cvt_pk_bf16_f32 v32, v144, v145
	v_cvt_pk_bf16_f32 v33, v146, v147
	v_cvt_pk_bf16_f32 v34, v148, v149
	v_cvt_pk_bf16_f32 v35, v150, v151
	v_cvt_pk_bf16_f32 v36, v152, v153
	v_cvt_pk_bf16_f32 v37, v154, v155
	v_cvt_pk_bf16_f32 v38, v156, v157
	v_cvt_pk_bf16_f32 v39, v158, v159
	v_add_u32_e32 v181, 0x2000000, v177
	global_store_dwordx4 v181, v[32:35], s[78:79]
	global_store_dwordx4 v181, v[36:39], s[78:79] offset:1024
	v_add_u32_e32 v236, 0x4000, v237
	s_mov_b64 exec, 1
	global_store_dword v236, v184, s[78:79]
	s_mov_b64 exec, -1
	s_waitcnt vmcnt(16)
	v_lshlrev_b32_e32 v144, 16, v48
	v_and_b32_e32 v145, 0xffff0000, v48
	v_lshlrev_b32_e32 v146, 16, v49
	v_and_b32_e32 v147, 0xffff0000, v49
	v_lshlrev_b32_e32 v148, 16, v50
	v_and_b32_e32 v149, 0xffff0000, v50
	v_lshlrev_b32_e32 v150, 16, v51
	v_and_b32_e32 v151, 0xffff0000, v51
	v_lshlrev_b32_e32 v152, 16, v52
	v_and_b32_e32 v153, 0xffff0000, v52
	v_lshlrev_b32_e32 v154, 16, v53
	v_and_b32_e32 v155, 0xffff0000, v53
	v_lshlrev_b32_e32 v156, 16, v54
	v_and_b32_e32 v157, 0xffff0000, v54
	v_lshlrev_b32_e32 v158, 16, v55
	v_and_b32_e32 v159, 0xffff0000, v55
	v_lshlrev_b32_e32 v160, 16, v56
	v_and_b32_e32 v161, 0xffff0000, v56
	v_lshlrev_b32_e32 v162, 16, v57
	v_and_b32_e32 v163, 0xffff0000, v57
	v_lshlrev_b32_e32 v164, 16, v58
	v_and_b32_e32 v165, 0xffff0000, v58
	v_lshlrev_b32_e32 v166, 16, v59
	v_and_b32_e32 v167, 0xffff0000, v59
	v_lshlrev_b32_e32 v168, 16, v60
	v_and_b32_e32 v169, 0xffff0000, v60
	v_lshlrev_b32_e32 v170, 16, v61
	v_and_b32_e32 v171, 0xffff0000, v61
	v_lshlrev_b32_e32 v172, 16, v62
	v_and_b32_e32 v173, 0xffff0000, v62
	v_lshlrev_b32_e32 v174, 16, v63
	v_and_b32_e32 v175, 0xffff0000, v63
	v_pk_mul_f32 v[252:253], v[160:161], v[160:161]
	v_pk_mul_f32 v[254:255], v[162:163], v[162:163]
	v_pk_fma_f32 v[252:253], v[164:165], v[164:165], v[252:253]
	v_pk_fma_f32 v[254:255], v[166:167], v[166:167], v[254:255]
	v_pk_fma_f32 v[252:253], v[168:169], v[168:169], v[252:253]
	v_pk_fma_f32 v[254:255], v[170:171], v[170:171], v[254:255]
	v_pk_fma_f32 v[252:253], v[172:173], v[172:173], v[252:253]
	v_pk_fma_f32 v[254:255], v[174:175], v[174:175], v[254:255]
	v_pk_add_f32 v[252:253], v[252:253], v[254:255]
	s_nop 0
	v_add_f32_e32 v183, v252, v253
	s_nop 1
	v_add_f32_dpp v183, v183, v183 quad_perm:[1,0,3,2] row_mask:0xf bank_mask:0xf bound_ctrl:1
	s_nop 1
	v_add_f32_dpp v183, v183, v183 quad_perm:[2,3,0,1] row_mask:0xf bank_mask:0xf bound_ctrl:1
	s_nop 1
	v_add_f32_dpp v183, v183, v183 row_half_mirror row_mask:0xf bank_mask:0xf bound_ctrl:1
	s_nop 1
	v_add_f32_dpp v183, v183, v183 row_mirror row_mask:0xf bank_mask:0xf bound_ctrl:1
	s_nop 1
	v_readlane_b32 s98, v183, 0
	v_readlane_b32 s99, v183, 16
	v_readlane_b32 s100, v183, 32
	v_readlane_b32 s101, v183, 48
	s_nop 1
	v_mov_b32_e32 v183, s98
	v_add_f32_e32 v183, s99, v183
	v_add_f32_e32 v183, s100, v183
	v_add_f32_e32 v183, s101, v183
	v_fmamk_f32 v183, v183, 0x3a800000, v182
	v_cmp_gt_f32_e32 vcc, 0x800000, v183
	v_mul_f32_e32 v181, 0x4b800000, v183
	s_nop 1
	v_cndmask_b32_e32 v183, v183, v181, vcc
	v_rsq_f32_e32 v183, v183
	s_nop 0
	v_mul_f32_e32 v181, 0x45800000, v183
	v_cndmask_b32_e32 v184, v183, v181, vcc
	v_mov_b32_e32 v185, v184
	v_pk_mul_f32 v[160:161], v[160:161], v[184:185]
	v_pk_mul_f32 v[162:163], v[162:163], v[184:185]
	v_pk_mul_f32 v[164:165], v[164:165], v[184:185]
	v_pk_mul_f32 v[166:167], v[166:167], v[184:185]
	v_pk_mul_f32 v[168:169], v[168:169], v[184:185]
	v_pk_mul_f32 v[170:171], v[170:171], v[184:185]
	v_pk_mul_f32 v[172:173], v[172:173], v[184:185]
	v_pk_mul_f32 v[174:175], v[174:175], v[184:185]
	v_pk_fma_f32 v[144:145], v[160:161], v[128:129], v[144:145]
	v_pk_fma_f32 v[146:147], v[162:163], v[130:131], v[146:147]
	v_pk_fma_f32 v[148:149], v[164:165], v[132:133], v[148:149]
	v_pk_fma_f32 v[150:151], v[166:167], v[134:135], v[150:151]
	v_pk_fma_f32 v[152:153], v[168:169], v[136:137], v[152:153]
	v_pk_fma_f32 v[154:155], v[170:171], v[138:139], v[154:155]
	v_pk_fma_f32 v[156:157], v[172:173], v[140:141], v[156:157]
	v_pk_fma_f32 v[158:159], v[174:175], v[142:143], v[158:159]
	v_pk_mul_f32 v[252:253], v[144:145], v[144:145]
	v_pk_mul_f32 v[254:255], v[146:147], v[146:147]
	v_pk_fma_f32 v[252:253], v[148:149], v[148:149], v[252:253]
	v_pk_fma_f32 v[254:255], v[150:151], v[150:151], v[254:255]
	v_pk_fma_f32 v[252:253], v[152:153], v[152:153], v[252:253]
	v_pk_fma_f32 v[254:255], v[154:155], v[154:155], v[254:255]
	v_pk_fma_f32 v[252:253], v[156:157], v[156:157], v[252:253]
	v_pk_fma_f32 v[254:255], v[158:159], v[158:159], v[254:255]
	v_pk_add_f32 v[252:253], v[252:253], v[254:255]
	s_nop 0
	v_add_f32_e32 v183, v252, v253
	s_nop 1
	v_add_f32_dpp v183, v183, v183 quad_perm:[1,0,3,2] row_mask:0xf bank_mask:0xf bound_ctrl:1
	s_nop 1
	v_add_f32_dpp v183, v183, v183 quad_perm:[2,3,0,1] row_mask:0xf bank_mask:0xf bound_ctrl:1
	s_nop 1
	v_add_f32_dpp v183, v183, v183 row_half_mirror row_mask:0xf bank_mask:0xf bound_ctrl:1
	s_nop 1
	v_add_f32_dpp v183, v183, v183 row_mirror row_mask:0xf bank_mask:0xf bound_ctrl:1
	s_nop 1
	v_readlane_b32 s98, v183, 0
	v_readlane_b32 s99, v183, 16
	v_readlane_b32 s100, v183, 32
	v_readlane_b32 s101, v183, 48
	s_nop 1
	v_mov_b32_e32 v183, s98
	v_add_f32_e32 v183, s99, v183
	v_add_f32_e32 v183, s100, v183
	v_add_f32_e32 v183, s101, v183
	v_fmamk_f32 v183, v183, 0x3a800000, v182
	v_cmp_gt_f32_e32 vcc, 0x800000, v183
	v_mul_f32_e32 v181, 0x4b800000, v183
	s_nop 1
	v_cndmask_b32_e32 v183, v183, v181, vcc
	v_rsq_f32_e32 v183, v183
	s_nop 0
	v_mul_f32_e32 v181, 0x45800000, v183
	v_cndmask_b32_e32 v184, v183, v181, vcc
	v_mov_b32_e32 v185, v184
	v_cvt_pk_bf16_f32 v48, v144, v145
	v_cvt_pk_bf16_f32 v49, v146, v147
	v_cvt_pk_bf16_f32 v50, v148, v149
	v_cvt_pk_bf16_f32 v51, v150, v151
	v_cvt_pk_bf16_f32 v52, v152, v153
	v_cvt_pk_bf16_f32 v53, v154, v155
	v_cvt_pk_bf16_f32 v54, v156, v157
	v_cvt_pk_bf16_f32 v55, v158, v159
	v_add_u32_e32 v181, 0x2400000, v177
	global_store_dwordx4 v181, v[48:51], s[78:79]
	global_store_dwordx4 v181, v[52:55], s[78:79] offset:1024
	v_add_u32_e32 v236, 0x6000, v237
	s_mov_b64 exec, 1
	global_store_dword v236, v184, s[78:79]
	s_mov_b64 exec, -1
	s_waitcnt vmcnt(12)
	v_lshlrev_b32_e32 v144, 16, v64
	v_and_b32_e32 v145, 0xffff0000, v64
	v_lshlrev_b32_e32 v146, 16, v65
	v_and_b32_e32 v147, 0xffff0000, v65
	v_lshlrev_b32_e32 v148, 16, v66
	v_and_b32_e32 v149, 0xffff0000, v66
	v_lshlrev_b32_e32 v150, 16, v67
	v_and_b32_e32 v151, 0xffff0000, v67
	v_lshlrev_b32_e32 v152, 16, v68
	v_and_b32_e32 v153, 0xffff0000, v68
	v_lshlrev_b32_e32 v154, 16, v69
	v_and_b32_e32 v155, 0xffff0000, v69
	v_lshlrev_b32_e32 v156, 16, v70
	v_and_b32_e32 v157, 0xffff0000, v70
	v_lshlrev_b32_e32 v158, 16, v71
	v_and_b32_e32 v159, 0xffff0000, v71
	v_lshlrev_b32_e32 v160, 16, v72
	v_and_b32_e32 v161, 0xffff0000, v72
	v_lshlrev_b32_e32 v162, 16, v73
	v_and_b32_e32 v163, 0xffff0000, v73
	v_lshlrev_b32_e32 v164, 16, v74
	v_and_b32_e32 v165, 0xffff0000, v74
	v_lshlrev_b32_e32 v166, 16, v75
	v_and_b32_e32 v167, 0xffff0000, v75
	v_lshlrev_b32_e32 v168, 16, v76
	v_and_b32_e32 v169, 0xffff0000, v76
	v_lshlrev_b32_e32 v170, 16, v77
	v_and_b32_e32 v171, 0xffff0000, v77
	v_lshlrev_b32_e32 v172, 16, v78
	v_and_b32_e32 v173, 0xffff0000, v78
	v_lshlrev_b32_e32 v174, 16, v79
	v_and_b32_e32 v175, 0xffff0000, v79
	v_pk_mul_f32 v[252:253], v[160:161], v[160:161]
	v_pk_mul_f32 v[254:255], v[162:163], v[162:163]
	v_pk_fma_f32 v[252:253], v[164:165], v[164:165], v[252:253]
	v_pk_fma_f32 v[254:255], v[166:167], v[166:167], v[254:255]
	v_pk_fma_f32 v[252:253], v[168:169], v[168:169], v[252:253]
	v_pk_fma_f32 v[254:255], v[170:171], v[170:171], v[254:255]
	v_pk_fma_f32 v[252:253], v[172:173], v[172:173], v[252:253]
	v_pk_fma_f32 v[254:255], v[174:175], v[174:175], v[254:255]
	v_pk_add_f32 v[252:253], v[252:253], v[254:255]
	s_nop 0
	v_add_f32_e32 v183, v252, v253
	s_nop 1
	v_add_f32_dpp v183, v183, v183 quad_perm:[1,0,3,2] row_mask:0xf bank_mask:0xf bound_ctrl:1
	s_nop 1
	v_add_f32_dpp v183, v183, v183 quad_perm:[2,3,0,1] row_mask:0xf bank_mask:0xf bound_ctrl:1
	s_nop 1
	v_add_f32_dpp v183, v183, v183 row_half_mirror row_mask:0xf bank_mask:0xf bound_ctrl:1
	s_nop 1
	v_add_f32_dpp v183, v183, v183 row_mirror row_mask:0xf bank_mask:0xf bound_ctrl:1
	s_nop 1
	v_readlane_b32 s98, v183, 0
	v_readlane_b32 s99, v183, 16
	v_readlane_b32 s100, v183, 32
	v_readlane_b32 s101, v183, 48
	s_nop 1
	v_mov_b32_e32 v183, s98
	v_add_f32_e32 v183, s99, v183
	v_add_f32_e32 v183, s100, v183
	v_add_f32_e32 v183, s101, v183
	v_fmamk_f32 v183, v183, 0x3a800000, v182
	v_cmp_gt_f32_e32 vcc, 0x800000, v183
	v_mul_f32_e32 v181, 0x4b800000, v183
	s_nop 1
	v_cndmask_b32_e32 v183, v183, v181, vcc
	v_rsq_f32_e32 v183, v183
	s_nop 0
	v_mul_f32_e32 v181, 0x45800000, v183
	v_cndmask_b32_e32 v184, v183, v181, vcc
	v_mov_b32_e32 v185, v184
	v_pk_mul_f32 v[160:161], v[160:161], v[184:185]
	v_pk_mul_f32 v[162:163], v[162:163], v[184:185]
	v_pk_mul_f32 v[164:165], v[164:165], v[184:185]
	v_pk_mul_f32 v[166:167], v[166:167], v[184:185]
	v_pk_mul_f32 v[168:169], v[168:169], v[184:185]
	v_pk_mul_f32 v[170:171], v[170:171], v[184:185]
	v_pk_mul_f32 v[172:173], v[172:173], v[184:185]
	v_pk_mul_f32 v[174:175], v[174:175], v[184:185]
	v_pk_fma_f32 v[144:145], v[160:161], v[128:129], v[144:145]
	v_pk_fma_f32 v[146:147], v[162:163], v[130:131], v[146:147]
	v_pk_fma_f32 v[148:149], v[164:165], v[132:133], v[148:149]
	v_pk_fma_f32 v[150:151], v[166:167], v[134:135], v[150:151]
	v_pk_fma_f32 v[152:153], v[168:169], v[136:137], v[152:153]
	v_pk_fma_f32 v[154:155], v[170:171], v[138:139], v[154:155]
	v_pk_fma_f32 v[156:157], v[172:173], v[140:141], v[156:157]
	v_pk_fma_f32 v[158:159], v[174:175], v[142:143], v[158:159]
	v_pk_mul_f32 v[252:253], v[144:145], v[144:145]
	v_pk_mul_f32 v[254:255], v[146:147], v[146:147]
	v_pk_fma_f32 v[252:253], v[148:149], v[148:149], v[252:253]
	v_pk_fma_f32 v[254:255], v[150:151], v[150:151], v[254:255]
	v_pk_fma_f32 v[252:253], v[152:153], v[152:153], v[252:253]
	v_pk_fma_f32 v[254:255], v[154:155], v[154:155], v[254:255]
	v_pk_fma_f32 v[252:253], v[156:157], v[156:157], v[252:253]
	v_pk_fma_f32 v[254:255], v[158:159], v[158:159], v[254:255]
	v_pk_add_f32 v[252:253], v[252:253], v[254:255]
	s_nop 0
	v_add_f32_e32 v183, v252, v253
	s_nop 1
	v_add_f32_dpp v183, v183, v183 quad_perm:[1,0,3,2] row_mask:0xf bank_mask:0xf bound_ctrl:1
	s_nop 1
	v_add_f32_dpp v183, v183, v183 quad_perm:[2,3,0,1] row_mask:0xf bank_mask:0xf bound_ctrl:1
	s_nop 1
	v_add_f32_dpp v183, v183, v183 row_half_mirror row_mask:0xf bank_mask:0xf bound_ctrl:1
	s_nop 1
	v_add_f32_dpp v183, v183, v183 row_mirror row_mask:0xf bank_mask:0xf bound_ctrl:1
	s_nop 1
	v_readlane_b32 s98, v183, 0
	v_readlane_b32 s99, v183, 16
	v_readlane_b32 s100, v183, 32
	v_readlane_b32 s101, v183, 48
	s_nop 1
	v_mov_b32_e32 v183, s98
	v_add_f32_e32 v183, s99, v183
	v_add_f32_e32 v183, s100, v183
	v_add_f32_e32 v183, s101, v183
	v_fmamk_f32 v183, v183, 0x3a800000, v182
	v_cmp_gt_f32_e32 vcc, 0x800000, v183
	v_mul_f32_e32 v181, 0x4b800000, v183
	s_nop 1
	v_cndmask_b32_e32 v183, v183, v181, vcc
	v_rsq_f32_e32 v183, v183
	s_nop 0
	v_mul_f32_e32 v181, 0x45800000, v183
	v_cndmask_b32_e32 v184, v183, v181, vcc
	v_mov_b32_e32 v185, v184
	v_cvt_pk_bf16_f32 v64, v144, v145
	v_cvt_pk_bf16_f32 v65, v146, v147
	v_cvt_pk_bf16_f32 v66, v148, v149
	v_cvt_pk_bf16_f32 v67, v150, v151
	v_cvt_pk_bf16_f32 v68, v152, v153
	v_cvt_pk_bf16_f32 v69, v154, v155
	v_cvt_pk_bf16_f32 v70, v156, v157
	v_cvt_pk_bf16_f32 v71, v158, v159
	v_add_u32_e32 v181, 0x2800000, v177
	global_store_dwordx4 v181, v[64:67], s[78:79]
	global_store_dwordx4 v181, v[68:71], s[78:79] offset:1024
	v_add_u32_e32 v236, 0x8000, v237
	s_mov_b64 exec, 1
	global_store_dword v236, v184, s[78:79]
	s_mov_b64 exec, -1
	s_waitcnt vmcnt(8)
	v_lshlrev_b32_e32 v144, 16, v80
	v_and_b32_e32 v145, 0xffff0000, v80
	v_lshlrev_b32_e32 v146, 16, v81
	v_and_b32_e32 v147, 0xffff0000, v81
	v_lshlrev_b32_e32 v148, 16, v82
	v_and_b32_e32 v149, 0xffff0000, v82
	v_lshlrev_b32_e32 v150, 16, v83
	v_and_b32_e32 v151, 0xffff0000, v83
	v_lshlrev_b32_e32 v152, 16, v84
	v_and_b32_e32 v153, 0xffff0000, v84
	v_lshlrev_b32_e32 v154, 16, v85
	v_and_b32_e32 v155, 0xffff0000, v85
	v_lshlrev_b32_e32 v156, 16, v86
	v_and_b32_e32 v157, 0xffff0000, v86
	v_lshlrev_b32_e32 v158, 16, v87
	v_and_b32_e32 v159, 0xffff0000, v87
	v_lshlrev_b32_e32 v160, 16, v88
	v_and_b32_e32 v161, 0xffff0000, v88
	v_lshlrev_b32_e32 v162, 16, v89
	v_and_b32_e32 v163, 0xffff0000, v89
	v_lshlrev_b32_e32 v164, 16, v90
	v_and_b32_e32 v165, 0xffff0000, v90
	v_lshlrev_b32_e32 v166, 16, v91
	v_and_b32_e32 v167, 0xffff0000, v91
	v_lshlrev_b32_e32 v168, 16, v92
	v_and_b32_e32 v169, 0xffff0000, v92
	v_lshlrev_b32_e32 v170, 16, v93
	v_and_b32_e32 v171, 0xffff0000, v93
	v_lshlrev_b32_e32 v172, 16, v94
	v_and_b32_e32 v173, 0xffff0000, v94
	v_lshlrev_b32_e32 v174, 16, v95
	v_and_b32_e32 v175, 0xffff0000, v95
	v_pk_mul_f32 v[252:253], v[160:161], v[160:161]
	v_pk_mul_f32 v[254:255], v[162:163], v[162:163]
	v_pk_fma_f32 v[252:253], v[164:165], v[164:165], v[252:253]
	v_pk_fma_f32 v[254:255], v[166:167], v[166:167], v[254:255]
	v_pk_fma_f32 v[252:253], v[168:169], v[168:169], v[252:253]
	v_pk_fma_f32 v[254:255], v[170:171], v[170:171], v[254:255]
	v_pk_fma_f32 v[252:253], v[172:173], v[172:173], v[252:253]
	v_pk_fma_f32 v[254:255], v[174:175], v[174:175], v[254:255]
	v_pk_add_f32 v[252:253], v[252:253], v[254:255]
	s_nop 0
	v_add_f32_e32 v183, v252, v253
	s_nop 1
	v_add_f32_dpp v183, v183, v183 quad_perm:[1,0,3,2] row_mask:0xf bank_mask:0xf bound_ctrl:1
	s_nop 1
	v_add_f32_dpp v183, v183, v183 quad_perm:[2,3,0,1] row_mask:0xf bank_mask:0xf bound_ctrl:1
	s_nop 1
	v_add_f32_dpp v183, v183, v183 row_half_mirror row_mask:0xf bank_mask:0xf bound_ctrl:1
	s_nop 1
	v_add_f32_dpp v183, v183, v183 row_mirror row_mask:0xf bank_mask:0xf bound_ctrl:1
	s_nop 1
	v_readlane_b32 s98, v183, 0
	v_readlane_b32 s99, v183, 16
	v_readlane_b32 s100, v183, 32
	v_readlane_b32 s101, v183, 48
	s_nop 1
	v_mov_b32_e32 v183, s98
	v_add_f32_e32 v183, s99, v183
	v_add_f32_e32 v183, s100, v183
	v_add_f32_e32 v183, s101, v183
	v_fmamk_f32 v183, v183, 0x3a800000, v182
	v_cmp_gt_f32_e32 vcc, 0x800000, v183
	v_mul_f32_e32 v181, 0x4b800000, v183
	s_nop 1
	v_cndmask_b32_e32 v183, v183, v181, vcc
	v_rsq_f32_e32 v183, v183
	s_nop 0
	v_mul_f32_e32 v181, 0x45800000, v183
	v_cndmask_b32_e32 v184, v183, v181, vcc
	v_mov_b32_e32 v185, v184
	v_pk_mul_f32 v[160:161], v[160:161], v[184:185]
	v_pk_mul_f32 v[162:163], v[162:163], v[184:185]
	v_pk_mul_f32 v[164:165], v[164:165], v[184:185]
	v_pk_mul_f32 v[166:167], v[166:167], v[184:185]
	v_pk_mul_f32 v[168:169], v[168:169], v[184:185]
	v_pk_mul_f32 v[170:171], v[170:171], v[184:185]
	v_pk_mul_f32 v[172:173], v[172:173], v[184:185]
	v_pk_mul_f32 v[174:175], v[174:175], v[184:185]
	v_pk_fma_f32 v[144:145], v[160:161], v[128:129], v[144:145]
	v_pk_fma_f32 v[146:147], v[162:163], v[130:131], v[146:147]
	v_pk_fma_f32 v[148:149], v[164:165], v[132:133], v[148:149]
	v_pk_fma_f32 v[150:151], v[166:167], v[134:135], v[150:151]
	v_pk_fma_f32 v[152:153], v[168:169], v[136:137], v[152:153]
	v_pk_fma_f32 v[154:155], v[170:171], v[138:139], v[154:155]
	v_pk_fma_f32 v[156:157], v[172:173], v[140:141], v[156:157]
	v_pk_fma_f32 v[158:159], v[174:175], v[142:143], v[158:159]
	v_pk_mul_f32 v[252:253], v[144:145], v[144:145]
	v_pk_mul_f32 v[254:255], v[146:147], v[146:147]
	v_pk_fma_f32 v[252:253], v[148:149], v[148:149], v[252:253]
	v_pk_fma_f32 v[254:255], v[150:151], v[150:151], v[254:255]
	v_pk_fma_f32 v[252:253], v[152:153], v[152:153], v[252:253]
	v_pk_fma_f32 v[254:255], v[154:155], v[154:155], v[254:255]
	v_pk_fma_f32 v[252:253], v[156:157], v[156:157], v[252:253]
	v_pk_fma_f32 v[254:255], v[158:159], v[158:159], v[254:255]
	v_pk_add_f32 v[252:253], v[252:253], v[254:255]
	s_nop 0
	v_add_f32_e32 v183, v252, v253
	s_nop 1
	v_add_f32_dpp v183, v183, v183 quad_perm:[1,0,3,2] row_mask:0xf bank_mask:0xf bound_ctrl:1
	s_nop 1
	v_add_f32_dpp v183, v183, v183 quad_perm:[2,3,0,1] row_mask:0xf bank_mask:0xf bound_ctrl:1
	s_nop 1
	v_add_f32_dpp v183, v183, v183 row_half_mirror row_mask:0xf bank_mask:0xf bound_ctrl:1
	s_nop 1
	v_add_f32_dpp v183, v183, v183 row_mirror row_mask:0xf bank_mask:0xf bound_ctrl:1
	s_nop 1
	v_readlane_b32 s98, v183, 0
	v_readlane_b32 s99, v183, 16
	v_readlane_b32 s100, v183, 32
	v_readlane_b32 s101, v183, 48
	s_nop 1
	v_mov_b32_e32 v183, s98
	v_add_f32_e32 v183, s99, v183
	v_add_f32_e32 v183, s100, v183
	v_add_f32_e32 v183, s101, v183
	v_fmamk_f32 v183, v183, 0x3a800000, v182
	v_cmp_gt_f32_e32 vcc, 0x800000, v183
	v_mul_f32_e32 v181, 0x4b800000, v183
	s_nop 1
	v_cndmask_b32_e32 v183, v183, v181, vcc
	v_rsq_f32_e32 v183, v183
	s_nop 0
	v_mul_f32_e32 v181, 0x45800000, v183
	v_cndmask_b32_e32 v184, v183, v181, vcc
	v_mov_b32_e32 v185, v184
	v_cvt_pk_bf16_f32 v80, v144, v145
	v_cvt_pk_bf16_f32 v81, v146, v147
	v_cvt_pk_bf16_f32 v82, v148, v149
	v_cvt_pk_bf16_f32 v83, v150, v151
	v_cvt_pk_bf16_f32 v84, v152, v153
	v_cvt_pk_bf16_f32 v85, v154, v155
	v_cvt_pk_bf16_f32 v86, v156, v157
	v_cvt_pk_bf16_f32 v87, v158, v159
	v_add_u32_e32 v181, 0x2c00000, v177
	global_store_dwordx4 v181, v[80:83], s[78:79]
	global_store_dwordx4 v181, v[84:87], s[78:79] offset:1024
	v_add_u32_e32 v236, 0xa000, v237
	s_mov_b64 exec, 1
	global_store_dword v236, v184, s[78:79]
	s_mov_b64 exec, -1
	s_waitcnt vmcnt(4)
	v_lshlrev_b32_e32 v144, 16, v96
	v_and_b32_e32 v145, 0xffff0000, v96
	v_lshlrev_b32_e32 v146, 16, v97
	v_and_b32_e32 v147, 0xffff0000, v97
	v_lshlrev_b32_e32 v148, 16, v98
	v_and_b32_e32 v149, 0xffff0000, v98
	v_lshlrev_b32_e32 v150, 16, v99
	v_and_b32_e32 v151, 0xffff0000, v99
	v_lshlrev_b32_e32 v152, 16, v100
	v_and_b32_e32 v153, 0xffff0000, v100
	v_lshlrev_b32_e32 v154, 16, v101
	v_and_b32_e32 v155, 0xffff0000, v101
	v_lshlrev_b32_e32 v156, 16, v102
	v_and_b32_e32 v157, 0xffff0000, v102
	v_lshlrev_b32_e32 v158, 16, v103
	v_and_b32_e32 v159, 0xffff0000, v103
	v_lshlrev_b32_e32 v160, 16, v104
	v_and_b32_e32 v161, 0xffff0000, v104
	v_lshlrev_b32_e32 v162, 16, v105
	v_and_b32_e32 v163, 0xffff0000, v105
	v_lshlrev_b32_e32 v164, 16, v106
	v_and_b32_e32 v165, 0xffff0000, v106
	v_lshlrev_b32_e32 v166, 16, v107
	v_and_b32_e32 v167, 0xffff0000, v107
	v_lshlrev_b32_e32 v168, 16, v108
	v_and_b32_e32 v169, 0xffff0000, v108
	v_lshlrev_b32_e32 v170, 16, v109
	v_and_b32_e32 v171, 0xffff0000, v109
	v_lshlrev_b32_e32 v172, 16, v110
	v_and_b32_e32 v173, 0xffff0000, v110
	v_lshlrev_b32_e32 v174, 16, v111
	v_and_b32_e32 v175, 0xffff0000, v111
	v_pk_mul_f32 v[252:253], v[160:161], v[160:161]
	v_pk_mul_f32 v[254:255], v[162:163], v[162:163]
	v_pk_fma_f32 v[252:253], v[164:165], v[164:165], v[252:253]
	v_pk_fma_f32 v[254:255], v[166:167], v[166:167], v[254:255]
	v_pk_fma_f32 v[252:253], v[168:169], v[168:169], v[252:253]
	v_pk_fma_f32 v[254:255], v[170:171], v[170:171], v[254:255]
	v_pk_fma_f32 v[252:253], v[172:173], v[172:173], v[252:253]
	v_pk_fma_f32 v[254:255], v[174:175], v[174:175], v[254:255]
	v_pk_add_f32 v[252:253], v[252:253], v[254:255]
	s_nop 0
	v_add_f32_e32 v183, v252, v253
	s_nop 1
	v_add_f32_dpp v183, v183, v183 quad_perm:[1,0,3,2] row_mask:0xf bank_mask:0xf bound_ctrl:1
	s_nop 1
	v_add_f32_dpp v183, v183, v183 quad_perm:[2,3,0,1] row_mask:0xf bank_mask:0xf bound_ctrl:1
	s_nop 1
	v_add_f32_dpp v183, v183, v183 row_half_mirror row_mask:0xf bank_mask:0xf bound_ctrl:1
	s_nop 1
	v_add_f32_dpp v183, v183, v183 row_mirror row_mask:0xf bank_mask:0xf bound_ctrl:1
	s_nop 1
	v_readlane_b32 s98, v183, 0
	v_readlane_b32 s99, v183, 16
	v_readlane_b32 s100, v183, 32
	v_readlane_b32 s101, v183, 48
	s_nop 1
	v_mov_b32_e32 v183, s98
	v_add_f32_e32 v183, s99, v183
	v_add_f32_e32 v183, s100, v183
	v_add_f32_e32 v183, s101, v183
	v_fmamk_f32 v183, v183, 0x3a800000, v182
	v_cmp_gt_f32_e32 vcc, 0x800000, v183
	v_mul_f32_e32 v181, 0x4b800000, v183
	s_nop 1
	v_cndmask_b32_e32 v183, v183, v181, vcc
	v_rsq_f32_e32 v183, v183
	s_nop 0
	v_mul_f32_e32 v181, 0x45800000, v183
	v_cndmask_b32_e32 v184, v183, v181, vcc
	v_mov_b32_e32 v185, v184
	v_pk_mul_f32 v[160:161], v[160:161], v[184:185]
	v_pk_mul_f32 v[162:163], v[162:163], v[184:185]
	v_pk_mul_f32 v[164:165], v[164:165], v[184:185]
	v_pk_mul_f32 v[166:167], v[166:167], v[184:185]
	v_pk_mul_f32 v[168:169], v[168:169], v[184:185]
	v_pk_mul_f32 v[170:171], v[170:171], v[184:185]
	v_pk_mul_f32 v[172:173], v[172:173], v[184:185]
	v_pk_mul_f32 v[174:175], v[174:175], v[184:185]
	v_pk_fma_f32 v[144:145], v[160:161], v[128:129], v[144:145]
	v_pk_fma_f32 v[146:147], v[162:163], v[130:131], v[146:147]
	v_pk_fma_f32 v[148:149], v[164:165], v[132:133], v[148:149]
	v_pk_fma_f32 v[150:151], v[166:167], v[134:135], v[150:151]
	v_pk_fma_f32 v[152:153], v[168:169], v[136:137], v[152:153]
	v_pk_fma_f32 v[154:155], v[170:171], v[138:139], v[154:155]
	v_pk_fma_f32 v[156:157], v[172:173], v[140:141], v[156:157]
	v_pk_fma_f32 v[158:159], v[174:175], v[142:143], v[158:159]
	v_pk_mul_f32 v[252:253], v[144:145], v[144:145]
	v_pk_mul_f32 v[254:255], v[146:147], v[146:147]
	v_pk_fma_f32 v[252:253], v[148:149], v[148:149], v[252:253]
	v_pk_fma_f32 v[254:255], v[150:151], v[150:151], v[254:255]
	v_pk_fma_f32 v[252:253], v[152:153], v[152:153], v[252:253]
	v_pk_fma_f32 v[254:255], v[154:155], v[154:155], v[254:255]
	v_pk_fma_f32 v[252:253], v[156:157], v[156:157], v[252:253]
	v_pk_fma_f32 v[254:255], v[158:159], v[158:159], v[254:255]
	v_pk_add_f32 v[252:253], v[252:253], v[254:255]
	s_nop 0
	v_add_f32_e32 v183, v252, v253
	s_nop 1
	v_add_f32_dpp v183, v183, v183 quad_perm:[1,0,3,2] row_mask:0xf bank_mask:0xf bound_ctrl:1
	s_nop 1
	v_add_f32_dpp v183, v183, v183 quad_perm:[2,3,0,1] row_mask:0xf bank_mask:0xf bound_ctrl:1
	s_nop 1
	v_add_f32_dpp v183, v183, v183 row_half_mirror row_mask:0xf bank_mask:0xf bound_ctrl:1
	s_nop 1
	v_add_f32_dpp v183, v183, v183 row_mirror row_mask:0xf bank_mask:0xf bound_ctrl:1
	s_nop 1
	v_readlane_b32 s98, v183, 0
	v_readlane_b32 s99, v183, 16
	v_readlane_b32 s100, v183, 32
	v_readlane_b32 s101, v183, 48
	s_nop 1
	v_mov_b32_e32 v183, s98
	v_add_f32_e32 v183, s99, v183
	v_add_f32_e32 v183, s100, v183
	v_add_f32_e32 v183, s101, v183
	v_fmamk_f32 v183, v183, 0x3a800000, v182
	v_cmp_gt_f32_e32 vcc, 0x800000, v183
	v_mul_f32_e32 v181, 0x4b800000, v183
	s_nop 1
	v_cndmask_b32_e32 v183, v183, v181, vcc
	v_rsq_f32_e32 v183, v183
	s_nop 0
	v_mul_f32_e32 v181, 0x45800000, v183
	v_cndmask_b32_e32 v184, v183, v181, vcc
	v_mov_b32_e32 v185, v184
	v_cvt_pk_bf16_f32 v96, v144, v145
	v_cvt_pk_bf16_f32 v97, v146, v147
	v_cvt_pk_bf16_f32 v98, v148, v149
	v_cvt_pk_bf16_f32 v99, v150, v151
	v_cvt_pk_bf16_f32 v100, v152, v153
	v_cvt_pk_bf16_f32 v101, v154, v155
	v_cvt_pk_bf16_f32 v102, v156, v157
	v_cvt_pk_bf16_f32 v103, v158, v159
	v_add_u32_e32 v181, 0x3000000, v177
	global_store_dwordx4 v181, v[96:99], s[78:79]
	global_store_dwordx4 v181, v[100:103], s[78:79] offset:1024
	v_add_u32_e32 v236, 0xc000, v237
	s_mov_b64 exec, 1
	global_store_dword v236, v184, s[78:79]
	s_mov_b64 exec, -1
	s_waitcnt vmcnt(0)
	v_lshlrev_b32_e32 v144, 16, v112
	v_and_b32_e32 v145, 0xffff0000, v112
	v_lshlrev_b32_e32 v146, 16, v113
	v_and_b32_e32 v147, 0xffff0000, v113
	v_lshlrev_b32_e32 v148, 16, v114
	v_and_b32_e32 v149, 0xffff0000, v114
	v_lshlrev_b32_e32 v150, 16, v115
	v_and_b32_e32 v151, 0xffff0000, v115
	v_lshlrev_b32_e32 v152, 16, v116
	v_and_b32_e32 v153, 0xffff0000, v116
	v_lshlrev_b32_e32 v154, 16, v117
	v_and_b32_e32 v155, 0xffff0000, v117
	v_lshlrev_b32_e32 v156, 16, v118
	v_and_b32_e32 v157, 0xffff0000, v118
	v_lshlrev_b32_e32 v158, 16, v119
	v_and_b32_e32 v159, 0xffff0000, v119
	v_lshlrev_b32_e32 v160, 16, v120
	v_and_b32_e32 v161, 0xffff0000, v120
	v_lshlrev_b32_e32 v162, 16, v121
	v_and_b32_e32 v163, 0xffff0000, v121
	v_lshlrev_b32_e32 v164, 16, v122
	v_and_b32_e32 v165, 0xffff0000, v122
	v_lshlrev_b32_e32 v166, 16, v123
	v_and_b32_e32 v167, 0xffff0000, v123
	v_lshlrev_b32_e32 v168, 16, v124
	v_and_b32_e32 v169, 0xffff0000, v124
	v_lshlrev_b32_e32 v170, 16, v125
	v_and_b32_e32 v171, 0xffff0000, v125
	v_lshlrev_b32_e32 v172, 16, v126
	v_and_b32_e32 v173, 0xffff0000, v126
	v_lshlrev_b32_e32 v174, 16, v127
	v_and_b32_e32 v175, 0xffff0000, v127
	v_pk_mul_f32 v[252:253], v[160:161], v[160:161]
	v_pk_mul_f32 v[254:255], v[162:163], v[162:163]
	v_pk_fma_f32 v[252:253], v[164:165], v[164:165], v[252:253]
	v_pk_fma_f32 v[254:255], v[166:167], v[166:167], v[254:255]
	v_pk_fma_f32 v[252:253], v[168:169], v[168:169], v[252:253]
	v_pk_fma_f32 v[254:255], v[170:171], v[170:171], v[254:255]
	v_pk_fma_f32 v[252:253], v[172:173], v[172:173], v[252:253]
	v_pk_fma_f32 v[254:255], v[174:175], v[174:175], v[254:255]
	v_pk_add_f32 v[252:253], v[252:253], v[254:255]
	s_nop 0
	v_add_f32_e32 v183, v252, v253
	s_nop 1
	v_add_f32_dpp v183, v183, v183 quad_perm:[1,0,3,2] row_mask:0xf bank_mask:0xf bound_ctrl:1
	s_nop 1
	v_add_f32_dpp v183, v183, v183 quad_perm:[2,3,0,1] row_mask:0xf bank_mask:0xf bound_ctrl:1
	s_nop 1
	v_add_f32_dpp v183, v183, v183 row_half_mirror row_mask:0xf bank_mask:0xf bound_ctrl:1
	s_nop 1
	v_add_f32_dpp v183, v183, v183 row_mirror row_mask:0xf bank_mask:0xf bound_ctrl:1
	s_nop 1
	v_readlane_b32 s98, v183, 0
	v_readlane_b32 s99, v183, 16
	v_readlane_b32 s100, v183, 32
	v_readlane_b32 s101, v183, 48
	s_nop 1
	v_mov_b32_e32 v183, s98
	v_add_f32_e32 v183, s99, v183
	v_add_f32_e32 v183, s100, v183
	v_add_f32_e32 v183, s101, v183
	v_fmamk_f32 v183, v183, 0x3a800000, v182
	v_cmp_gt_f32_e32 vcc, 0x800000, v183
	v_mul_f32_e32 v181, 0x4b800000, v183
	s_nop 1
	v_cndmask_b32_e32 v183, v183, v181, vcc
	v_rsq_f32_e32 v183, v183
	s_nop 0
	v_mul_f32_e32 v181, 0x45800000, v183
	v_cndmask_b32_e32 v184, v183, v181, vcc
	v_mov_b32_e32 v185, v184
	v_pk_mul_f32 v[160:161], v[160:161], v[184:185]
	v_pk_mul_f32 v[162:163], v[162:163], v[184:185]
	v_pk_mul_f32 v[164:165], v[164:165], v[184:185]
	v_pk_mul_f32 v[166:167], v[166:167], v[184:185]
	v_pk_mul_f32 v[168:169], v[168:169], v[184:185]
	v_pk_mul_f32 v[170:171], v[170:171], v[184:185]
	v_pk_mul_f32 v[172:173], v[172:173], v[184:185]
	v_pk_mul_f32 v[174:175], v[174:175], v[184:185]
	v_pk_fma_f32 v[144:145], v[160:161], v[128:129], v[144:145]
	v_pk_fma_f32 v[146:147], v[162:163], v[130:131], v[146:147]
	v_pk_fma_f32 v[148:149], v[164:165], v[132:133], v[148:149]
	v_pk_fma_f32 v[150:151], v[166:167], v[134:135], v[150:151]
	v_pk_fma_f32 v[152:153], v[168:169], v[136:137], v[152:153]
	v_pk_fma_f32 v[154:155], v[170:171], v[138:139], v[154:155]
	v_pk_fma_f32 v[156:157], v[172:173], v[140:141], v[156:157]
	v_pk_fma_f32 v[158:159], v[174:175], v[142:143], v[158:159]
	v_pk_mul_f32 v[252:253], v[144:145], v[144:145]
	v_pk_mul_f32 v[254:255], v[146:147], v[146:147]
	v_pk_fma_f32 v[252:253], v[148:149], v[148:149], v[252:253]
	v_pk_fma_f32 v[254:255], v[150:151], v[150:151], v[254:255]
	v_pk_fma_f32 v[252:253], v[152:153], v[152:153], v[252:253]
	v_pk_fma_f32 v[254:255], v[154:155], v[154:155], v[254:255]
	v_pk_fma_f32 v[252:253], v[156:157], v[156:157], v[252:253]
	v_pk_fma_f32 v[254:255], v[158:159], v[158:159], v[254:255]
	v_pk_add_f32 v[252:253], v[252:253], v[254:255]
	s_nop 0
	v_add_f32_e32 v183, v252, v253
	s_nop 1
	v_add_f32_dpp v183, v183, v183 quad_perm:[1,0,3,2] row_mask:0xf bank_mask:0xf bound_ctrl:1
	s_nop 1
	v_add_f32_dpp v183, v183, v183 quad_perm:[2,3,0,1] row_mask:0xf bank_mask:0xf bound_ctrl:1
	s_nop 1
	v_add_f32_dpp v183, v183, v183 row_half_mirror row_mask:0xf bank_mask:0xf bound_ctrl:1
	s_nop 1
	v_add_f32_dpp v183, v183, v183 row_mirror row_mask:0xf bank_mask:0xf bound_ctrl:1
	s_nop 1
	v_readlane_b32 s98, v183, 0
	v_readlane_b32 s99, v183, 16
	v_readlane_b32 s100, v183, 32
	v_readlane_b32 s101, v183, 48
	s_nop 1
	v_mov_b32_e32 v183, s98
	v_add_f32_e32 v183, s99, v183
	v_add_f32_e32 v183, s100, v183
	v_add_f32_e32 v183, s101, v183
	v_fmamk_f32 v183, v183, 0x3a800000, v182
	v_cmp_gt_f32_e32 vcc, 0x800000, v183
	v_mul_f32_e32 v181, 0x4b800000, v183
	s_nop 1
	v_cndmask_b32_e32 v183, v183, v181, vcc
	v_rsq_f32_e32 v183, v183
	s_nop 0
	v_mul_f32_e32 v181, 0x45800000, v183
	v_cndmask_b32_e32 v184, v183, v181, vcc
	v_mov_b32_e32 v185, v184
	v_cvt_pk_bf16_f32 v112, v144, v145
	v_cvt_pk_bf16_f32 v113, v146, v147
	v_cvt_pk_bf16_f32 v114, v148, v149
	v_cvt_pk_bf16_f32 v115, v150, v151
	v_cvt_pk_bf16_f32 v116, v152, v153
	v_cvt_pk_bf16_f32 v117, v154, v155
	v_cvt_pk_bf16_f32 v118, v156, v157
	v_cvt_pk_bf16_f32 v119, v158, v159
	v_add_u32_e32 v181, 0x3400000, v177
	global_store_dwordx4 v181, v[112:115], s[78:79]
	global_store_dwordx4 v181, v[116:119], s[78:79] offset:1024
	v_add_u32_e32 v236, 0xe000, v237
	s_mov_b64 exec, 1
	global_store_dword v236, v184, s[78:79]
	s_mov_b64 exec, -1
	v_readfirstlane_b32 s98, v179
	s_nop 3
	s_and_b32 s99, s98, 3
	s_cmp_lg_u32 s99, 0
	s_cbranch_scc1 .Lmyxupd_done_3
	v_lshrrev_b32_e32 v179, 2, v179
	v_lshlrev_b32_e32 v177, 4, v176
	v_lshl_add_u32 v177, v179, 11, v177
	v_lshlrev_b32_e32 v237, 2, v179
	v_add_u32_e32 v237, 0x10000, v237
	v_add_u32_e32 v181, 0x3800000, v177
	global_load_dwordx4 v[0:3], v181, s[78:79]
	global_load_dwordx4 v[4:7], v181, s[78:79] offset:1024
	v_lshl_add_u32 v183, v179, 12, v180
	v_add_u32_e32 v183, 0xbf00000, v183
	v_add_u32_e32 v181, 0x0, v183
	global_load_dwordx4 v[8:11], v181, s[78:79]
	global_load_dwordx4 v[12:15], v181, s[78:79] offset:16
	global_load_dwordx4 v[16:19], v181, s[78:79] offset:2048
	global_load_dwordx4 v[20:23], v181, s[78:79] offset:2064
	v_add_u32_e32 v181, 0x200000, v183
	global_load_dwordx4 v[24:27], v181, s[78:79]
	global_load_dwordx4 v[28:31], v181, s[78:79] offset:16
	global_load_dwordx4 v[32:35], v181, s[78:79] offset:2048
	global_load_dwordx4 v[36:39], v181, s[78:79] offset:2064
	v_add_u32_e32 v181, 0x400000, v183
	global_load_dwordx4 v[40:43], v181, s[78:79]
	global_load_dwordx4 v[44:47], v181, s[78:79] offset:16
	global_load_dwordx4 v[48:51], v181, s[78:79] offset:2048
	global_load_dwordx4 v[52:55], v181, s[78:79] offset:2064
	v_add_u32_e32 v181, 0x600000, v183
	global_load_dwordx4 v[56:59], v181, s[78:79]
	global_load_dwordx4 v[60:63], v181, s[78:79] offset:16
	global_load_dwordx4 v[64:67], v181, s[78:79] offset:2048
	global_load_dwordx4 v[68:71], v181, s[78:79] offset:2064
	v_add_u32_e32 v181, 0x800000, v183
	global_load_dwordx4 v[72:75], v181, s[78:79]
	global_load_dwordx4 v[76:79], v181, s[78:79] offset:16
	global_load_dwordx4 v[80:83], v181, s[78:79] offset:2048
	global_load_dwordx4 v[84:87], v181, s[78:79] offset:2064
	v_add_u32_e32 v181, 0xa00000, v183
	global_load_dwordx4 v[88:91], v181, s[78:79]
	global_load_dwordx4 v[92:95], v181, s[78:79] offset:16
	global_load_dwordx4 v[96:99], v181, s[78:79] offset:2048
	global_load_dwordx4 v[100:103], v181, s[78:79] offset:2064
	s_waitcnt vmcnt(20)
	v_pk_add_f32 v[160:161], v[8:9], 0 op_sel_hi:[1,0]
	v_pk_add_f32 v[162:163], v[10:11], 0 op_sel_hi:[1,0]
	v_pk_add_f32 v[164:165], v[12:13], 0 op_sel_hi:[1,0]
	v_pk_add_f32 v[166:167], v[14:15], 0 op_sel_hi:[1,0]
	v_pk_add_f32 v[168:169], v[16:17], 0 op_sel_hi:[1,0]
	v_pk_add_f32 v[170:171], v[18:19], 0 op_sel_hi:[1,0]
	v_pk_add_f32 v[172:173], v[20:21], 0 op_sel_hi:[1,0]
	v_pk_add_f32 v[174:175], v[22:23], 0 op_sel_hi:[1,0]
	s_waitcnt vmcnt(16)
	v_pk_add_f32 v[160:161], v[160:161], v[24:25]
	v_pk_add_f32 v[162:163], v[162:163], v[26:27]
	v_pk_add_f32 v[164:165], v[164:165], v[28:29]
	v_pk_add_f32 v[166:167], v[166:167], v[30:31]
	v_pk_add_f32 v[168:169], v[168:169], v[32:33]
	v_pk_add_f32 v[170:171], v[170:171], v[34:35]
	v_pk_add_f32 v[172:173], v[172:173], v[36:37]
	v_pk_add_f32 v[174:175], v[174:175], v[38:39]
	s_waitcnt vmcnt(12)
	v_pk_add_f32 v[160:161], v[160:161], v[40:41]
	v_pk_add_f32 v[162:163], v[162:163], v[42:43]
	v_pk_add_f32 v[164:165], v[164:165], v[44:45]
	v_pk_add_f32 v[166:167], v[166:167], v[46:47]
	v_pk_add_f32 v[168:169], v[168:169], v[48:49]
	v_pk_add_f32 v[170:171], v[170:171], v[50:51]
	v_pk_add_f32 v[172:173], v[172:173], v[52:53]
	v_pk_add_f32 v[174:175], v[174:175], v[54:55]
	s_waitcnt vmcnt(8)
	v_pk_add_f32 v[160:161], v[160:161], v[56:57]
	v_pk_add_f32 v[162:163], v[162:163], v[58:59]
	v_pk_add_f32 v[164:165], v[164:165], v[60:61]
	v_pk_add_f32 v[166:167], v[166:167], v[62:63]
	v_pk_add_f32 v[168:169], v[168:169], v[64:65]
	v_pk_add_f32 v[170:171], v[170:171], v[66:67]
	v_pk_add_f32 v[172:173], v[172:173], v[68:69]
	v_pk_add_f32 v[174:175], v[174:175], v[70:71]
	s_waitcnt vmcnt(4)
	v_pk_add_f32 v[160:161], v[160:161], v[72:73]
	v_pk_add_f32 v[162:163], v[162:163], v[74:75]
	v_pk_add_f32 v[164:165], v[164:165], v[76:77]
	v_pk_add_f32 v[166:167], v[166:167], v[78:79]
	v_pk_add_f32 v[168:169], v[168:169], v[80:81]
	v_pk_add_f32 v[170:171], v[170:171], v[82:83]
	v_pk_add_f32 v[172:173], v[172:173], v[84:85]
	v_pk_add_f32 v[174:175], v[174:175], v[86:87]
	s_waitcnt vmcnt(0)
	v_pk_add_f32 v[160:161], v[160:161], v[88:89]
	v_pk_add_f32 v[162:163], v[162:163], v[90:91]
	v_pk_add_f32 v[164:165], v[164:165], v[92:93]
	v_pk_add_f32 v[166:167], v[166:167], v[94:95]
	v_pk_add_f32 v[168:169], v[168:169], v[96:97]
	v_pk_add_f32 v[170:171], v[170:171], v[98:99]
	v_pk_add_f32 v[172:173], v[172:173], v[100:101]
	v_pk_add_f32 v[174:175], v[174:175], v[102:103]
	v_lshlrev_b32_e32 v144, 16, v0
	v_and_b32_e32 v145, 0xffff0000, v0
	v_lshlrev_b32_e32 v146, 16, v1
	v_and_b32_e32 v147, 0xffff0000, v1
	v_lshlrev_b32_e32 v148, 16, v2
	v_and_b32_e32 v149, 0xffff0000, v2
	v_lshlrev_b32_e32 v150, 16, v3
	v_and_b32_e32 v151, 0xffff0000, v3
	v_lshlrev_b32_e32 v152, 16, v4
	v_and_b32_e32 v153, 0xffff0000, v4
	v_lshlrev_b32_e32 v154, 16, v5
	v_and_b32_e32 v155, 0xffff0000, v5
	v_lshlrev_b32_e32 v156, 16, v6
	v_and_b32_e32 v157, 0xffff0000, v6
	v_lshlrev_b32_e32 v158, 16, v7
	v_and_b32_e32 v159, 0xffff0000, v7
	v_add_u32_e32 v181, 0xc00000, v183
	global_load_dwordx4 v[8:11], v181, s[78:79]
	global_load_dwordx4 v[12:15], v181, s[78:79] offset:16
	global_load_dwordx4 v[16:19], v181, s[78:79] offset:2048
	global_load_dwordx4 v[20:23], v181, s[78:79] offset:2064
	v_add_u32_e32 v181, 0xe00000, v183
	global_load_dwordx4 v[24:27], v181, s[78:79]
	global_load_dwordx4 v[28:31], v181, s[78:79] offset:16
	global_load_dwordx4 v[32:35], v181, s[78:79] offset:2048
	global_load_dwordx4 v[36:39], v181, s[78:79] offset:2064
	v_add_u32_e32 v181, 0x1000000, v183
	global_load_dwordx4 v[40:43], v181, s[78:79]
	global_load_dwordx4 v[44:47], v181, s[78:79] offset:16
	global_load_dwordx4 v[48:51], v181, s[78:79] offset:2048
	global_load_dwordx4 v[52:55], v181, s[78:79] offset:2064
	v_add_u32_e32 v181, 0x1200000, v183
	global_load_dwordx4 v[56:59], v181, s[78:79]
	global_load_dwordx4 v[60:63], v181, s[78:79] offset:16
	global_load_dwordx4 v[64:67], v181, s[78:79] offset:2048
	global_load_dwordx4 v[68:71], v181, s[78:79] offset:2064
	v_add_u32_e32 v181, 0x1400000, v183
	global_load_dwordx4 v[72:75], v181, s[78:79]
	global_load_dwordx4 v[76:79], v181, s[78:79] offset:16
	global_load_dwordx4 v[80:83], v181, s[78:79] offset:2048
	global_load_dwordx4 v[84:87], v181, s[78:79] offset:2064
	s_waitcnt vmcnt(16)
	v_pk_add_f32 v[160:161], v[160:161], v[8:9]
	v_pk_add_f32 v[162:163], v[162:163], v[10:11]
	v_pk_add_f32 v[164:165], v[164:165], v[12:13]
	v_pk_add_f32 v[166:167], v[166:167], v[14:15]
	v_pk_add_f32 v[168:169], v[168:169], v[16:17]
	v_pk_add_f32 v[170:171], v[170:171], v[18:19]
	v_pk_add_f32 v[172:173], v[172:173], v[20:21]
	v_pk_add_f32 v[174:175], v[174:175], v[22:23]
	s_waitcnt vmcnt(12)
	v_pk_add_f32 v[160:161], v[160:161], v[24:25]
	v_pk_add_f32 v[162:163], v[162:163], v[26:27]
	v_pk_add_f32 v[164:165], v[164:165], v[28:29]
	v_pk_add_f32 v[166:167], v[166:167], v[30:31]
	v_pk_add_f32 v[168:169], v[168:169], v[32:33]
	v_pk_add_f32 v[170:171], v[170:171], v[34:35]
	v_pk_add_f32 v[172:173], v[172:173], v[36:37]
	v_pk_add_f32 v[174:175], v[174:175], v[38:39]
	s_waitcnt vmcnt(8)
	v_pk_add_f32 v[160:161], v[160:161], v[40:41]
	v_pk_add_f32 v[162:163], v[162:163], v[42:43]
	v_pk_add_f32 v[164:165], v[164:165], v[44:45]
	v_pk_add_f32 v[166:167], v[166:167], v[46:47]
	v_pk_add_f32 v[168:169], v[168:169], v[48:49]
	v_pk_add_f32 v[170:171], v[170:171], v[50:51]
	v_pk_add_f32 v[172:173], v[172:173], v[52:53]
	v_pk_add_f32 v[174:175], v[174:175], v[54:55]
	s_waitcnt vmcnt(4)
	v_pk_add_f32 v[160:161], v[160:161], v[56:57]
	v_pk_add_f32 v[162:163], v[162:163], v[58:59]
	v_pk_add_f32 v[164:165], v[164:165], v[60:61]
	v_pk_add_f32 v[166:167], v[166:167], v[62:63]
	v_pk_add_f32 v[168:169], v[168:169], v[64:65]
	v_pk_add_f32 v[170:171], v[170:171], v[66:67]
	v_pk_add_f32 v[172:173], v[172:173], v[68:69]
	v_pk_add_f32 v[174:175], v[174:175], v[70:71]
	s_waitcnt vmcnt(0)
	v_pk_add_f32 v[160:161], v[160:161], v[72:73]
	v_pk_add_f32 v[162:163], v[162:163], v[74:75]
	v_pk_add_f32 v[164:165], v[164:165], v[76:77]
	v_pk_add_f32 v[166:167], v[166:167], v[78:79]
	v_pk_add_f32 v[168:169], v[168:169], v[80:81]
	v_pk_add_f32 v[170:171], v[170:171], v[82:83]
	v_pk_add_f32 v[172:173], v[172:173], v[84:85]
	v_pk_add_f32 v[174:175], v[174:175], v[86:87]
	v_pk_mul_f32 v[252:253], v[160:161], v[160:161]
	v_pk_mul_f32 v[254:255], v[162:163], v[162:163]
	v_pk_fma_f32 v[252:253], v[164:165], v[164:165], v[252:253]
	v_pk_fma_f32 v[254:255], v[166:167], v[166:167], v[254:255]
	v_pk_fma_f32 v[252:253], v[168:169], v[168:169], v[252:253]
	v_pk_fma_f32 v[254:255], v[170:171], v[170:171], v[254:255]
	v_pk_fma_f32 v[252:253], v[172:173], v[172:173], v[252:253]
	v_pk_fma_f32 v[254:255], v[174:175], v[174:175], v[254:255]
	v_pk_add_f32 v[252:253], v[252:253], v[254:255]
	s_nop 0
	v_add_f32_e32 v183, v252, v253
	s_nop 1
	v_add_f32_dpp v183, v183, v183 quad_perm:[1,0,3,2] row_mask:0xf bank_mask:0xf bound_ctrl:1
	s_nop 1
	v_add_f32_dpp v183, v183, v183 quad_perm:[2,3,0,1] row_mask:0xf bank_mask:0xf bound_ctrl:1
	s_nop 1
	v_add_f32_dpp v183, v183, v183 row_half_mirror row_mask:0xf bank_mask:0xf bound_ctrl:1
	s_nop 1
	v_add_f32_dpp v183, v183, v183 row_mirror row_mask:0xf bank_mask:0xf bound_ctrl:1
	s_nop 1
	v_readlane_b32 s98, v183, 0
	v_readlane_b32 s99, v183, 16
	v_readlane_b32 s100, v183, 32
	v_readlane_b32 s101, v183, 48
	s_nop 1
	v_mov_b32_e32 v183, s98
	v_add_f32_e32 v183, s99, v183
	v_add_f32_e32 v183, s100, v183
	v_add_f32_e32 v183, s101, v183
	v_fmamk_f32 v183, v183, 0x3a800000, v182
	v_cmp_gt_f32_e32 vcc, 0x800000, v183
	v_mul_f32_e32 v181, 0x4b800000, v183
	s_nop 1
	v_cndmask_b32_e32 v183, v183, v181, vcc
	v_rsq_f32_e32 v183, v183
	s_nop 0
	v_mul_f32_e32 v181, 0x45800000, v183
	v_cndmask_b32_e32 v184, v183, v181, vcc
	v_mov_b32_e32 v185, v184
	v_pk_mul_f32 v[160:161], v[160:161], v[184:185]
	v_pk_mul_f32 v[162:163], v[162:163], v[184:185]
	v_pk_mul_f32 v[164:165], v[164:165], v[184:185]
	v_pk_mul_f32 v[166:167], v[166:167], v[184:185]
	v_pk_mul_f32 v[168:169], v[168:169], v[184:185]
	v_pk_mul_f32 v[170:171], v[170:171], v[184:185]
	v_pk_mul_f32 v[172:173], v[172:173], v[184:185]
	v_pk_mul_f32 v[174:175], v[174:175], v[184:185]
	v_pk_fma_f32 v[144:145], v[160:161], v[128:129], v[144:145]
	v_pk_fma_f32 v[146:147], v[162:163], v[130:131], v[146:147]
	v_pk_fma_f32 v[148:149], v[164:165], v[132:133], v[148:149]
	v_pk_fma_f32 v[150:151], v[166:167], v[134:135], v[150:151]
	v_pk_fma_f32 v[152:153], v[168:169], v[136:137], v[152:153]
	v_pk_fma_f32 v[154:155], v[170:171], v[138:139], v[154:155]
	v_pk_fma_f32 v[156:157], v[172:173], v[140:141], v[156:157]
	v_pk_fma_f32 v[158:159], v[174:175], v[142:143], v[158:159]
	v_pk_mul_f32 v[252:253], v[144:145], v[144:145]
	v_pk_mul_f32 v[254:255], v[146:147], v[146:147]
	v_pk_fma_f32 v[252:253], v[148:149], v[148:149], v[252:253]
	v_pk_fma_f32 v[254:255], v[150:151], v[150:151], v[254:255]
	v_pk_fma_f32 v[252:253], v[152:153], v[152:153], v[252:253]
	v_pk_fma_f32 v[254:255], v[154:155], v[154:155], v[254:255]
	v_pk_fma_f32 v[252:253], v[156:157], v[156:157], v[252:253]
	v_pk_fma_f32 v[254:255], v[158:159], v[158:159], v[254:255]
	v_pk_add_f32 v[252:253], v[252:253], v[254:255]
	s_nop 0
	v_add_f32_e32 v183, v252, v253
	s_nop 1
	v_add_f32_dpp v183, v183, v183 quad_perm:[1,0,3,2] row_mask:0xf bank_mask:0xf bound_ctrl:1
	s_nop 1
	v_add_f32_dpp v183, v183, v183 quad_perm:[2,3,0,1] row_mask:0xf bank_mask:0xf bound_ctrl:1
	s_nop 1
	v_add_f32_dpp v183, v183, v183 row_half_mirror row_mask:0xf bank_mask:0xf bound_ctrl:1
	s_nop 1
	v_add_f32_dpp v183, v183, v183 row_mirror row_mask:0xf bank_mask:0xf bound_ctrl:1
	s_nop 1
	v_readlane_b32 s98, v183, 0
	v_readlane_b32 s99, v183, 16
	v_readlane_b32 s100, v183, 32
	v_readlane_b32 s101, v183, 48
	s_nop 1
	v_mov_b32_e32 v183, s98
	v_add_f32_e32 v183, s99, v183
	v_add_f32_e32 v183, s100, v183
	v_add_f32_e32 v183, s101, v183
	v_fmamk_f32 v183, v183, 0x3a800000, v182
	v_cmp_gt_f32_e32 vcc, 0x800000, v183
	v_mul_f32_e32 v181, 0x4b800000, v183
	s_nop 1
	v_cndmask_b32_e32 v183, v183, v181, vcc
	v_rsq_f32_e32 v183, v183
	s_nop 0
	v_mul_f32_e32 v181, 0x45800000, v183
	v_cndmask_b32_e32 v184, v183, v181, vcc
	v_mov_b32_e32 v185, v184
	v_cvt_pk_bf16_f32 v0, v144, v145
	v_cvt_pk_bf16_f32 v1, v146, v147
	v_cvt_pk_bf16_f32 v2, v148, v149
	v_cvt_pk_bf16_f32 v3, v150, v151
	v_cvt_pk_bf16_f32 v4, v152, v153
	v_cvt_pk_bf16_f32 v5, v154, v155
	v_cvt_pk_bf16_f32 v6, v156, v157
	v_cvt_pk_bf16_f32 v7, v158, v159
	v_add_u32_e32 v181, 0x3800000, v177
	global_store_dwordx4 v181, v[0:3], s[78:79]
	global_store_dwordx4 v181, v[4:7], s[78:79] offset:1024
	v_add_u32_e32 v236, 0x10000, v237
	s_mov_b64 exec, 1
	global_store_dword v236, v184, s[78:79]
	s_mov_b64 exec, -1

.LBB0_1863:
	v_readlane_b32 s0, v235, 52
	v_readlane_b32 s1, v235, 53
	s_and_b64 vcc, exec, s[0:1]
	s_waitcnt lgkmcnt(0)
	s_barrier
	v_mbcnt_lo_u32_b32 v0, -1, 0
	v_mbcnt_hi_u32_b32 v0, -1, v0
	s_cbranch_vccnz .LBB0_1883
	v_lshlrev_b32_e32 v2, 3, v0
	v_ashrrev_i32_e32 v3, 31, v2
	v_readlane_b32 s4, v235, 4
	v_lshlrev_b64 v[4:5], 1, v[2:3]
	v_lshlrev_b64 v[2:3], 2, v[2:3]
	v_readlane_b32 s14, v235, 14
	v_readlane_b32 s15, v235, 15
	v_lshl_add_u64 v[62:63], s[90:91], 0, v[2:3]
	v_readlane_b32 s5, v235, 5
	v_readlane_b32 s6, v235, 6
	v_readlane_b32 s7, v235, 7
	v_readlane_b32 s8, v235, 8
	v_readlane_b32 s9, v235, 9
	v_readlane_b32 s10, v235, 10
	v_readlane_b32 s11, v235, 11
	v_readlane_b32 s12, v235, 12
	v_readlane_b32 s13, v235, 13
	v_readlane_b32 s16, v235, 16
	v_readlane_b32 s17, v235, 17
	v_readlane_b32 s18, v235, 18
	v_readlane_b32 s19, v235, 19
	v_lshl_add_u64 v[2:3], s[14:15], 0, v[2:3]
	s_mov_b64 s[0:1], 0x2000
	v_lshl_add_u64 v[60:61], s[86:87], 0, v[4:5]
	v_lshl_add_u64 v[64:65], s[54:55], 0, v[4:5]
	v_lshl_add_u64 v[66:67], v[2:3], 0, s[0:1]
	s_mov_b32 s1, 0
	v_cmp_eq_u32_e64 s[16:17], 0, v0
	s_mov_b64 s[4:5], 0x200000
	s_mov_b64 s[6:7], 0x200800
	s_mov_b64 s[8:9], 0x400000
	s_mov_b64 s[10:11], 0x400800
	s_mov_b64 s[12:13], 0x600000
	s_mov_b64 s[14:15], 0x600800
	s_mov_b64 s[18:19], 0x800000
	s_mov_b32 s48, 0x800000
	s_mov_b64 s[20:21], 0x800800
	s_mov_b64 s[22:23], 0xa00000
	s_mov_b64 s[24:25], 0xa00800
	s_mov_b64 s[26:27], 0xc00000
	s_mov_b64 s[28:29], 0xc00800
	s_mov_b64 s[36:37], 0xe00000
	s_mov_b64 s[38:39], 0xe00800
	v_mov_b32_e32 v104, 0
	v_mov_b32_e32 v105, 0x358637bd
	v_readlane_b32 s42, v235, 61
	v_readlane_b32 s43, v235, 62
	v_mbcnt_lo_u32_b32 v176, -1, 0
	v_mbcnt_hi_u32_b32 v176, -1, v176
	v_readlane_b32 s98, v235, 49
	v_readlane_b32 s99, v235, 20
	v_readlane_b32 s100, v235, 14
	v_readlane_b32 s101, v235, 15
	s_nop 3
	s_lshr_b32 vcc_lo, s98, 3
	s_and_b32 vcc_hi, vcc_lo, 7
	s_lshr_b32 vcc_lo, vcc_lo, 3
	s_lshl_b32 vcc_lo, vcc_lo, 3
	s_add_i32 vcc_lo, vcc_lo, s99
	s_lshl_b32 s98, vcc_hi, 8
	s_add_i32 s98, s98, vcc_lo
	s_mov_b32 s99, s98
	v_mov_b32_e32 v183, s99
	v_lshlrev_b32_e32 v177, 4, v176
	s_lshl_b32 s99, s99, 11
	v_add_u32_e32 v177, s99, v177
	v_add_u32_e32 v178, 0x1800000, v177
	v_add_u32_e32 v179, 0x9e00000, v177
	v_lshlrev_b32_e32 v180, 5, v176
	v_add_u32_e32 v181, 0x2000, v180
	global_load_dwordx4 v[128:131], v181, s[100:101]
	global_load_dwordx4 v[132:135], v181, s[100:101] offset:16
	global_load_dwordx4 v[136:139], v181, s[100:101] offset:2048
	global_load_dwordx4 v[140:143], v181, s[100:101] offset:2064
	v_mov_b32_e32 v182, 0x358637bd
	global_load_dwordx4 v[0:3], v178, s[78:79]
	global_load_dwordx4 v[4:7], v178, s[78:79] offset:1024
	global_load_dwordx4 v[8:11], v179, s[78:79]
	global_load_dwordx4 v[12:15], v179, s[78:79] offset:1024
	v_add_u32_e32 v178, 0x400000, v178
	v_add_u32_e32 v179, 0x400000, v179
	global_load_dwordx4 v[16:19], v178, s[78:79]
	global_load_dwordx4 v[20:23], v178, s[78:79] offset:1024
	global_load_dwordx4 v[24:27], v179, s[78:79]
	global_load_dwordx4 v[28:31], v179, s[78:79] offset:1024
	v_add_u32_e32 v178, 0x400000, v178
	v_add_u32_e32 v179, 0x400000, v179
	global_load_dwordx4 v[32:35], v178, s[78:79]
	global_load_dwordx4 v[36:39], v178, s[78:79] offset:1024
	global_load_dwordx4 v[40:43], v179, s[78:79]
	global_load_dwordx4 v[44:47], v179, s[78:79] offset:1024
	v_add_u32_e32 v178, 0x400000, v178
	v_add_u32_e32 v179, 0x400000, v179
	global_load_dwordx4 v[48:51], v178, s[78:79]
	global_load_dwordx4 v[52:55], v178, s[78:79] offset:1024
	global_load_dwordx4 v[56:59], v179, s[78:79]
	global_load_dwordx4 v[60:63], v179, s[78:79] offset:1024
	v_add_u32_e32 v178, 0x400000, v178
	v_add_u32_e32 v179, 0x400000, v179
	global_load_dwordx4 v[64:67], v178, s[78:79]
	global_load_dwordx4 v[68:71], v178, s[78:79] offset:1024
	global_load_dwordx4 v[72:75], v179, s[78:79]
	global_load_dwordx4 v[76:79], v179, s[78:79] offset:1024
	v_add_u32_e32 v178, 0x400000, v178
	v_add_u32_e32 v179, 0x400000, v179
	global_load_dwordx4 v[80:83], v178, s[78:79]
	global_load_dwordx4 v[84:87], v178, s[78:79] offset:1024
	global_load_dwordx4 v[88:91], v179, s[78:79]
	global_load_dwordx4 v[92:95], v179, s[78:79] offset:1024
	v_add_u32_e32 v178, 0x400000, v178
	v_add_u32_e32 v179, 0x400000, v179
	global_load_dwordx4 v[96:99], v178, s[78:79]
	global_load_dwordx4 v[100:103], v178, s[78:79] offset:1024
	global_load_dwordx4 v[104:107], v179, s[78:79]
	global_load_dwordx4 v[108:111], v179, s[78:79] offset:1024
	v_add_u32_e32 v178, 0x400000, v178
	v_add_u32_e32 v179, 0x400000, v179
	global_load_dwordx4 v[112:115], v178, s[78:79]
	global_load_dwordx4 v[116:119], v178, s[78:79] offset:1024
	global_load_dwordx4 v[120:123], v179, s[78:79]
	global_load_dwordx4 v[124:127], v179, s[78:79] offset:1024
	v_lshlrev_b32_e32 v237, 2, v183
	v_add_u32_e32 v237, 0x10000, v237
	v_mov_b32_e32 v179, s98
	s_waitcnt vmcnt(28)
	v_lshlrev_b32_e32 v144, 16, v0
	v_and_b32_e32 v145, 0xffff0000, v0
	v_lshlrev_b32_e32 v146, 16, v1
	v_and_b32_e32 v147, 0xffff0000, v1
	v_lshlrev_b32_e32 v148, 16, v2
	v_and_b32_e32 v149, 0xffff0000, v2
	v_lshlrev_b32_e32 v150, 16, v3
	v_and_b32_e32 v151, 0xffff0000, v3
	v_lshlrev_b32_e32 v152, 16, v4
	v_and_b32_e32 v153, 0xffff0000, v4
	v_lshlrev_b32_e32 v154, 16, v5
	v_and_b32_e32 v155, 0xffff0000, v5
	v_lshlrev_b32_e32 v156, 16, v6
	v_and_b32_e32 v157, 0xffff0000, v6
	v_lshlrev_b32_e32 v158, 16, v7
	v_and_b32_e32 v159, 0xffff0000, v7
	v_lshlrev_b32_e32 v160, 16, v8
	v_and_b32_e32 v161, 0xffff0000, v8
	v_lshlrev_b32_e32 v162, 16, v9
	v_and_b32_e32 v163, 0xffff0000, v9
	v_lshlrev_b32_e32 v164, 16, v10
	v_and_b32_e32 v165, 0xffff0000, v10
	v_lshlrev_b32_e32 v166, 16, v11
	v_and_b32_e32 v167, 0xffff0000, v11
	v_lshlrev_b32_e32 v168, 16, v12
	v_and_b32_e32 v169, 0xffff0000, v12
	v_lshlrev_b32_e32 v170, 16, v13
	v_and_b32_e32 v171, 0xffff0000, v13
	v_lshlrev_b32_e32 v172, 16, v14
	v_and_b32_e32 v173, 0xffff0000, v14
	v_lshlrev_b32_e32 v174, 16, v15
	v_and_b32_e32 v175, 0xffff0000, v15
	v_pk_mul_f32 v[252:253], v[160:161], v[160:161]
	v_pk_mul_f32 v[254:255], v[162:163], v[162:163]
	v_pk_fma_f32 v[252:253], v[164:165], v[164:165], v[252:253]
	v_pk_fma_f32 v[254:255], v[166:167], v[166:167], v[254:255]
	v_pk_fma_f32 v[252:253], v[168:169], v[168:169], v[252:253]
	v_pk_fma_f32 v[254:255], v[170:171], v[170:171], v[254:255]
	v_pk_fma_f32 v[252:253], v[172:173], v[172:173], v[252:253]
	v_pk_fma_f32 v[254:255], v[174:175], v[174:175], v[254:255]
	v_pk_add_f32 v[252:253], v[252:253], v[254:255]
	s_nop 0
	v_add_f32_e32 v183, v252, v253
	s_nop 1
	v_add_f32_dpp v183, v183, v183 quad_perm:[1,0,3,2] row_mask:0xf bank_mask:0xf bound_ctrl:1
	s_nop 1
	v_add_f32_dpp v183, v183, v183 quad_perm:[2,3,0,1] row_mask:0xf bank_mask:0xf bound_ctrl:1
	s_nop 1
	v_add_f32_dpp v183, v183, v183 row_half_mirror row_mask:0xf bank_mask:0xf bound_ctrl:1
	s_nop 1
	v_add_f32_dpp v183, v183, v183 row_mirror row_mask:0xf bank_mask:0xf bound_ctrl:1
	s_nop 1
	v_readlane_b32 s98, v183, 0
	v_readlane_b32 s99, v183, 16
	v_readlane_b32 s100, v183, 32
	v_readlane_b32 s101, v183, 48
	s_nop 1
	v_mov_b32_e32 v183, s98
	v_add_f32_e32 v183, s99, v183
	v_add_f32_e32 v183, s100, v183
	v_add_f32_e32 v183, s101, v183
	v_fmamk_f32 v183, v183, 0x3a800000, v182
	v_cmp_gt_f32_e32 vcc, 0x800000, v183
	v_mul_f32_e32 v181, 0x4b800000, v183
	s_nop 1
	v_cndmask_b32_e32 v183, v183, v181, vcc
	v_rsq_f32_e32 v183, v183
	s_nop 0
	v_mul_f32_e32 v181, 0x45800000, v183
	v_cndmask_b32_e32 v184, v183, v181, vcc
	v_mov_b32_e32 v185, v184
	v_pk_mul_f32 v[160:161], v[160:161], v[184:185]
	v_pk_mul_f32 v[162:163], v[162:163], v[184:185]
	v_pk_mul_f32 v[164:165], v[164:165], v[184:185]
	v_pk_mul_f32 v[166:167], v[166:167], v[184:185]
	v_pk_mul_f32 v[168:169], v[168:169], v[184:185]
	v_pk_mul_f32 v[170:171], v[170:171], v[184:185]
	v_pk_mul_f32 v[172:173], v[172:173], v[184:185]
	v_pk_mul_f32 v[174:175], v[174:175], v[184:185]
	v_pk_fma_f32 v[144:145], v[160:161], v[128:129], v[144:145]
	v_pk_fma_f32 v[146:147], v[162:163], v[130:131], v[146:147]
	v_pk_fma_f32 v[148:149], v[164:165], v[132:133], v[148:149]
	v_pk_fma_f32 v[150:151], v[166:167], v[134:135], v[150:151]
	v_pk_fma_f32 v[152:153], v[168:169], v[136:137], v[152:153]
	v_pk_fma_f32 v[154:155], v[170:171], v[138:139], v[154:155]
	v_pk_fma_f32 v[156:157], v[172:173], v[140:141], v[156:157]
	v_pk_fma_f32 v[158:159], v[174:175], v[142:143], v[158:159]
	v_pk_mul_f32 v[252:253], v[144:145], v[144:145]
	v_pk_mul_f32 v[254:255], v[146:147], v[146:147]
	v_pk_fma_f32 v[252:253], v[148:149], v[148:149], v[252:253]
	v_pk_fma_f32 v[254:255], v[150:151], v[150:151], v[254:255]
	v_pk_fma_f32 v[252:253], v[152:153], v[152:153], v[252:253]
	v_pk_fma_f32 v[254:255], v[154:155], v[154:155], v[254:255]
	v_pk_fma_f32 v[252:253], v[156:157], v[156:157], v[252:253]
	v_pk_fma_f32 v[254:255], v[158:159], v[158:159], v[254:255]
	v_pk_add_f32 v[252:253], v[252:253], v[254:255]
	s_nop 0
	v_add_f32_e32 v183, v252, v253
	s_nop 1
	v_add_f32_dpp v183, v183, v183 quad_perm:[1,0,3,2] row_mask:0xf bank_mask:0xf bound_ctrl:1
	s_nop 1
	v_add_f32_dpp v183, v183, v183 quad_perm:[2,3,0,1] row_mask:0xf bank_mask:0xf bound_ctrl:1
	s_nop 1
	v_add_f32_dpp v183, v183, v183 row_half_mirror row_mask:0xf bank_mask:0xf bound_ctrl:1
	s_nop 1
	v_add_f32_dpp v183, v183, v183 row_mirror row_mask:0xf bank_mask:0xf bound_ctrl:1
	s_nop 1
	v_readlane_b32 s98, v183, 0
	v_readlane_b32 s99, v183, 16
	v_readlane_b32 s100, v183, 32
	v_readlane_b32 s101, v183, 48
	s_nop 1
	v_mov_b32_e32 v183, s98
	v_add_f32_e32 v183, s99, v183
	v_add_f32_e32 v183, s100, v183
	v_add_f32_e32 v183, s101, v183
	v_fmamk_f32 v183, v183, 0x3a800000, v182
	v_cmp_gt_f32_e32 vcc, 0x800000, v183
	v_mul_f32_e32 v181, 0x4b800000, v183
	s_nop 1
	v_cndmask_b32_e32 v183, v183, v181, vcc
	v_rsq_f32_e32 v183, v183
	s_nop 0
	v_mul_f32_e32 v181, 0x45800000, v183
	v_cndmask_b32_e32 v184, v183, v181, vcc
	v_mov_b32_e32 v185, v184
	v_cvt_pk_bf16_f32 v0, v144, v145
	v_cvt_pk_bf16_f32 v1, v146, v147
	v_cvt_pk_bf16_f32 v2, v148, v149
	v_cvt_pk_bf16_f32 v3, v150, v151
	v_cvt_pk_bf16_f32 v4, v152, v153
	v_cvt_pk_bf16_f32 v5, v154, v155
	v_cvt_pk_bf16_f32 v6, v156, v157
	v_cvt_pk_bf16_f32 v7, v158, v159
	v_add_u32_e32 v181, 0x1800000, v177
	global_store_dwordx4 v181, v[0:3], s[78:79]
	global_store_dwordx4 v181, v[4:7], s[78:79] offset:1024
	v_add_u32_e32 v236, 0x0, v237
	s_mov_b64 exec, 1
	global_store_dword v236, v184, s[78:79]
	s_mov_b64 exec, -1
	s_waitcnt vmcnt(24)
	v_lshlrev_b32_e32 v144, 16, v16
	v_and_b32_e32 v145, 0xffff0000, v16
	v_lshlrev_b32_e32 v146, 16, v17
	v_and_b32_e32 v147, 0xffff0000, v17
	v_lshlrev_b32_e32 v148, 16, v18
	v_and_b32_e32 v149, 0xffff0000, v18
	v_lshlrev_b32_e32 v150, 16, v19
	v_and_b32_e32 v151, 0xffff0000, v19
	v_lshlrev_b32_e32 v152, 16, v20
	v_and_b32_e32 v153, 0xffff0000, v20
	v_lshlrev_b32_e32 v154, 16, v21
	v_and_b32_e32 v155, 0xffff0000, v21
	v_lshlrev_b32_e32 v156, 16, v22
	v_and_b32_e32 v157, 0xffff0000, v22
	v_lshlrev_b32_e32 v158, 16, v23
	v_and_b32_e32 v159, 0xffff0000, v23
	v_lshlrev_b32_e32 v160, 16, v24
	v_and_b32_e32 v161, 0xffff0000, v24
	v_lshlrev_b32_e32 v162, 16, v25
	v_and_b32_e32 v163, 0xffff0000, v25
	v_lshlrev_b32_e32 v164, 16, v26
	v_and_b32_e32 v165, 0xffff0000, v26
	v_lshlrev_b32_e32 v166, 16, v27
	v_and_b32_e32 v167, 0xffff0000, v27
	v_lshlrev_b32_e32 v168, 16, v28
	v_and_b32_e32 v169, 0xffff0000, v28
	v_lshlrev_b32_e32 v170, 16, v29
	v_and_b32_e32 v171, 0xffff0000, v29
	v_lshlrev_b32_e32 v172, 16, v30
	v_and_b32_e32 v173, 0xffff0000, v30
	v_lshlrev_b32_e32 v174, 16, v31
	v_and_b32_e32 v175, 0xffff0000, v31
	v_pk_mul_f32 v[252:253], v[160:161], v[160:161]
	v_pk_mul_f32 v[254:255], v[162:163], v[162:163]
	v_pk_fma_f32 v[252:253], v[164:165], v[164:165], v[252:253]
	v_pk_fma_f32 v[254:255], v[166:167], v[166:167], v[254:255]
	v_pk_fma_f32 v[252:253], v[168:169], v[168:169], v[252:253]
	v_pk_fma_f32 v[254:255], v[170:171], v[170:171], v[254:255]
	v_pk_fma_f32 v[252:253], v[172:173], v[172:173], v[252:253]
	v_pk_fma_f32 v[254:255], v[174:175], v[174:175], v[254:255]
	v_pk_add_f32 v[252:253], v[252:253], v[254:255]
	s_nop 0
	v_add_f32_e32 v183, v252, v253
	s_nop 1
	v_add_f32_dpp v183, v183, v183 quad_perm:[1,0,3,2] row_mask:0xf bank_mask:0xf bound_ctrl:1
	s_nop 1
	v_add_f32_dpp v183, v183, v183 quad_perm:[2,3,0,1] row_mask:0xf bank_mask:0xf bound_ctrl:1
	s_nop 1
	v_add_f32_dpp v183, v183, v183 row_half_mirror row_mask:0xf bank_mask:0xf bound_ctrl:1
	s_nop 1
	v_add_f32_dpp v183, v183, v183 row_mirror row_mask:0xf bank_mask:0xf bound_ctrl:1
	s_nop 1
	v_readlane_b32 s98, v183, 0
	v_readlane_b32 s99, v183, 16
	v_readlane_b32 s100, v183, 32
	v_readlane_b32 s101, v183, 48
	s_nop 1
	v_mov_b32_e32 v183, s98
	v_add_f32_e32 v183, s99, v183
	v_add_f32_e32 v183, s100, v183
	v_add_f32_e32 v183, s101, v183
	v_fmamk_f32 v183, v183, 0x3a800000, v182
	v_cmp_gt_f32_e32 vcc, 0x800000, v183
	v_mul_f32_e32 v181, 0x4b800000, v183
	s_nop 1
	v_cndmask_b32_e32 v183, v183, v181, vcc
	v_rsq_f32_e32 v183, v183
	s_nop 0
	v_mul_f32_e32 v181, 0x45800000, v183
	v_cndmask_b32_e32 v184, v183, v181, vcc
	v_mov_b32_e32 v185, v184
	v_pk_mul_f32 v[160:161], v[160:161], v[184:185]
	v_pk_mul_f32 v[162:163], v[162:163], v[184:185]
	v_pk_mul_f32 v[164:165], v[164:165], v[184:185]
	v_pk_mul_f32 v[166:167], v[166:167], v[184:185]
	v_pk_mul_f32 v[168:169], v[168:169], v[184:185]
	v_pk_mul_f32 v[170:171], v[170:171], v[184:185]
	v_pk_mul_f32 v[172:173], v[172:173], v[184:185]
	v_pk_mul_f32 v[174:175], v[174:175], v[184:185]
	v_pk_fma_f32 v[144:145], v[160:161], v[128:129], v[144:145]
	v_pk_fma_f32 v[146:147], v[162:163], v[130:131], v[146:147]
	v_pk_fma_f32 v[148:149], v[164:165], v[132:133], v[148:149]
	v_pk_fma_f32 v[150:151], v[166:167], v[134:135], v[150:151]
	v_pk_fma_f32 v[152:153], v[168:169], v[136:137], v[152:153]
	v_pk_fma_f32 v[154:155], v[170:171], v[138:139], v[154:155]
	v_pk_fma_f32 v[156:157], v[172:173], v[140:141], v[156:157]
	v_pk_fma_f32 v[158:159], v[174:175], v[142:143], v[158:159]
	v_pk_mul_f32 v[252:253], v[144:145], v[144:145]
	v_pk_mul_f32 v[254:255], v[146:147], v[146:147]
	v_pk_fma_f32 v[252:253], v[148:149], v[148:149], v[252:253]
	v_pk_fma_f32 v[254:255], v[150:151], v[150:151], v[254:255]
	v_pk_fma_f32 v[252:253], v[152:153], v[152:153], v[252:253]
	v_pk_fma_f32 v[254:255], v[154:155], v[154:155], v[254:255]
	v_pk_fma_f32 v[252:253], v[156:157], v[156:157], v[252:253]
	v_pk_fma_f32 v[254:255], v[158:159], v[158:159], v[254:255]
	v_pk_add_f32 v[252:253], v[252:253], v[254:255]
	s_nop 0
	v_add_f32_e32 v183, v252, v253
	s_nop 1
	v_add_f32_dpp v183, v183, v183 quad_perm:[1,0,3,2] row_mask:0xf bank_mask:0xf bound_ctrl:1
	s_nop 1
	v_add_f32_dpp v183, v183, v183 quad_perm:[2,3,0,1] row_mask:0xf bank_mask:0xf bound_ctrl:1
	s_nop 1
	v_add_f32_dpp v183, v183, v183 row_half_mirror row_mask:0xf bank_mask:0xf bound_ctrl:1
	s_nop 1
	v_add_f32_dpp v183, v183, v183 row_mirror row_mask:0xf bank_mask:0xf bound_ctrl:1
	s_nop 1
	v_readlane_b32 s98, v183, 0
	v_readlane_b32 s99, v183, 16
	v_readlane_b32 s100, v183, 32
	v_readlane_b32 s101, v183, 48
	s_nop 1
	v_mov_b32_e32 v183, s98
	v_add_f32_e32 v183, s99, v183
	v_add_f32_e32 v183, s100, v183
	v_add_f32_e32 v183, s101, v183
	v_fmamk_f32 v183, v183, 0x3a800000, v182
	v_cmp_gt_f32_e32 vcc, 0x800000, v183
	v_mul_f32_e32 v181, 0x4b800000, v183
	s_nop 1
	v_cndmask_b32_e32 v183, v183, v181, vcc
	v_rsq_f32_e32 v183, v183
	s_nop 0
	v_mul_f32_e32 v181, 0x45800000, v183
	v_cndmask_b32_e32 v184, v183, v181, vcc
	v_mov_b32_e32 v185, v184
	v_cvt_pk_bf16_f32 v16, v144, v145
	v_cvt_pk_bf16_f32 v17, v146, v147
	v_cvt_pk_bf16_f32 v18, v148, v149
	v_cvt_pk_bf16_f32 v19, v150, v151
	v_cvt_pk_bf16_f32 v20, v152, v153
	v_cvt_pk_bf16_f32 v21, v154, v155
	v_cvt_pk_bf16_f32 v22, v156, v157
	v_cvt_pk_bf16_f32 v23, v158, v159
	v_add_u32_e32 v181, 0x1c00000, v177
	global_store_dwordx4 v181, v[16:19], s[78:79]
	global_store_dwordx4 v181, v[20:23], s[78:79] offset:1024
	v_add_u32_e32 v236, 0x2000, v237
	s_mov_b64 exec, 1
	global_store_dword v236, v184, s[78:79]
	s_mov_b64 exec, -1
	s_waitcnt vmcnt(20)
	v_lshlrev_b32_e32 v144, 16, v32
	v_and_b32_e32 v145, 0xffff0000, v32
	v_lshlrev_b32_e32 v146, 16, v33
	v_and_b32_e32 v147, 0xffff0000, v33
	v_lshlrev_b32_e32 v148, 16, v34
	v_and_b32_e32 v149, 0xffff0000, v34
	v_lshlrev_b32_e32 v150, 16, v35
	v_and_b32_e32 v151, 0xffff0000, v35
	v_lshlrev_b32_e32 v152, 16, v36
	v_and_b32_e32 v153, 0xffff0000, v36
	v_lshlrev_b32_e32 v154, 16, v37
	v_and_b32_e32 v155, 0xffff0000, v37
	v_lshlrev_b32_e32 v156, 16, v38
	v_and_b32_e32 v157, 0xffff0000, v38
	v_lshlrev_b32_e32 v158, 16, v39
	v_and_b32_e32 v159, 0xffff0000, v39
	v_lshlrev_b32_e32 v160, 16, v40
	v_and_b32_e32 v161, 0xffff0000, v40
	v_lshlrev_b32_e32 v162, 16, v41
	v_and_b32_e32 v163, 0xffff0000, v41
	v_lshlrev_b32_e32 v164, 16, v42
	v_and_b32_e32 v165, 0xffff0000, v42
	v_lshlrev_b32_e32 v166, 16, v43
	v_and_b32_e32 v167, 0xffff0000, v43
	v_lshlrev_b32_e32 v168, 16, v44
	v_and_b32_e32 v169, 0xffff0000, v44
	v_lshlrev_b32_e32 v170, 16, v45
	v_and_b32_e32 v171, 0xffff0000, v45
	v_lshlrev_b32_e32 v172, 16, v46
	v_and_b32_e32 v173, 0xffff0000, v46
	v_lshlrev_b32_e32 v174, 16, v47
	v_and_b32_e32 v175, 0xffff0000, v47
	v_pk_mul_f32 v[252:253], v[160:161], v[160:161]
	v_pk_mul_f32 v[254:255], v[162:163], v[162:163]
	v_pk_fma_f32 v[252:253], v[164:165], v[164:165], v[252:253]
	v_pk_fma_f32 v[254:255], v[166:167], v[166:167], v[254:255]
	v_pk_fma_f32 v[252:253], v[168:169], v[168:169], v[252:253]
	v_pk_fma_f32 v[254:255], v[170:171], v[170:171], v[254:255]
	v_pk_fma_f32 v[252:253], v[172:173], v[172:173], v[252:253]
	v_pk_fma_f32 v[254:255], v[174:175], v[174:175], v[254:255]
	v_pk_add_f32 v[252:253], v[252:253], v[254:255]
	s_nop 0
	v_add_f32_e32 v183, v252, v253
	s_nop 1
	v_add_f32_dpp v183, v183, v183 quad_perm:[1,0,3,2] row_mask:0xf bank_mask:0xf bound_ctrl:1
	s_nop 1
	v_add_f32_dpp v183, v183, v183 quad_perm:[2,3,0,1] row_mask:0xf bank_mask:0xf bound_ctrl:1
	s_nop 1
	v_add_f32_dpp v183, v183, v183 row_half_mirror row_mask:0xf bank_mask:0xf bound_ctrl:1
	s_nop 1
	v_add_f32_dpp v183, v183, v183 row_mirror row_mask:0xf bank_mask:0xf bound_ctrl:1
	s_nop 1
	v_readlane_b32 s98, v183, 0
	v_readlane_b32 s99, v183, 16
	v_readlane_b32 s100, v183, 32
	v_readlane_b32 s101, v183, 48
	s_nop 1
	v_mov_b32_e32 v183, s98
	v_add_f32_e32 v183, s99, v183
	v_add_f32_e32 v183, s100, v183
	v_add_f32_e32 v183, s101, v183
	v_fmamk_f32 v183, v183, 0x3a800000, v182
	v_cmp_gt_f32_e32 vcc, 0x800000, v183
	v_mul_f32_e32 v181, 0x4b800000, v183
	s_nop 1
	v_cndmask_b32_e32 v183, v183, v181, vcc
	v_rsq_f32_e32 v183, v183
	s_nop 0
	v_mul_f32_e32 v181, 0x45800000, v183
	v_cndmask_b32_e32 v184, v183, v181, vcc
	v_mov_b32_e32 v185, v184
	v_pk_mul_f32 v[160:161], v[160:161], v[184:185]
	v_pk_mul_f32 v[162:163], v[162:163], v[184:185]
	v_pk_mul_f32 v[164:165], v[164:165], v[184:185]
	v_pk_mul_f32 v[166:167], v[166:167], v[184:185]
	v_pk_mul_f32 v[168:169], v[168:169], v[184:185]
	v_pk_mul_f32 v[170:171], v[170:171], v[184:185]
	v_pk_mul_f32 v[172:173], v[172:173], v[184:185]
	v_pk_mul_f32 v[174:175], v[174:175], v[184:185]
	v_pk_fma_f32 v[144:145], v[160:161], v[128:129], v[144:145]
	v_pk_fma_f32 v[146:147], v[162:163], v[130:131], v[146:147]
	v_pk_fma_f32 v[148:149], v[164:165], v[132:133], v[148:149]
	v_pk_fma_f32 v[150:151], v[166:167], v[134:135], v[150:151]
	v_pk_fma_f32 v[152:153], v[168:169], v[136:137], v[152:153]
	v_pk_fma_f32 v[154:155], v[170:171], v[138:139], v[154:155]
	v_pk_fma_f32 v[156:157], v[172:173], v[140:141], v[156:157]
	v_pk_fma_f32 v[158:159], v[174:175], v[142:143], v[158:159]
	v_pk_mul_f32 v[252:253], v[144:145], v[144:145]
	v_pk_mul_f32 v[254:255], v[146:147], v[146:147]
	v_pk_fma_f32 v[252:253], v[148:149], v[148:149], v[252:253]
	v_pk_fma_f32 v[254:255], v[150:151], v[150:151], v[254:255]
	v_pk_fma_f32 v[252:253], v[152:153], v[152:153], v[252:253]
	v_pk_fma_f32 v[254:255], v[154:155], v[154:155], v[254:255]
	v_pk_fma_f32 v[252:253], v[156:157], v[156:157], v[252:253]
	v_pk_fma_f32 v[254:255], v[158:159], v[158:159], v[254:255]
	v_pk_add_f32 v[252:253], v[252:253], v[254:255]
	s_nop 0
	v_add_f32_e32 v183, v252, v253
	s_nop 1
	v_add_f32_dpp v183, v183, v183 quad_perm:[1,0,3,2] row_mask:0xf bank_mask:0xf bound_ctrl:1
	s_nop 1
	v_add_f32_dpp v183, v183, v183 quad_perm:[2,3,0,1] row_mask:0xf bank_mask:0xf bound_ctrl:1
	s_nop 1
	v_add_f32_dpp v183, v183, v183 row_half_mirror row_mask:0xf bank_mask:0xf bound_ctrl:1
	s_nop 1
	v_add_f32_dpp v183, v183, v183 row_mirror row_mask:0xf bank_mask:0xf bound_ctrl:1
	s_nop 1
	v_readlane_b32 s98, v183, 0
	v_readlane_b32 s99, v183, 16
	v_readlane_b32 s100, v183, 32
	v_readlane_b32 s101, v183, 48
	s_nop 1
	v_mov_b32_e32 v183, s98
	v_add_f32_e32 v183, s99, v183
	v_add_f32_e32 v183, s100, v183
	v_add_f32_e32 v183, s101, v183
	v_fmamk_f32 v183, v183, 0x3a800000, v182
	v_cmp_gt_f32_e32 vcc, 0x800000, v183
	v_mul_f32_e32 v181, 0x4b800000, v183
	s_nop 1
	v_cndmask_b32_e32 v183, v183, v181, vcc
	v_rsq_f32_e32 v183, v183
	s_nop 0
	v_mul_f32_e32 v181, 0x45800000, v183
	v_cndmask_b32_e32 v184, v183, v181, vcc
	v_mov_b32_e32 v185, v184
	v_cvt_pk_bf16_f32 v32, v144, v145
	v_cvt_pk_bf16_f32 v33, v146, v147
	v_cvt_pk_bf16_f32 v34, v148, v149
	v_cvt_pk_bf16_f32 v35, v150, v151
	v_cvt_pk_bf16_f32 v36, v152, v153
	v_cvt_pk_bf16_f32 v37, v154, v155
	v_cvt_pk_bf16_f32 v38, v156, v157
	v_cvt_pk_bf16_f32 v39, v158, v159
	v_add_u32_e32 v181, 0x2000000, v177
	global_store_dwordx4 v181, v[32:35], s[78:79]
	global_store_dwordx4 v181, v[36:39], s[78:79] offset:1024
	v_add_u32_e32 v236, 0x4000, v237
	s_mov_b64 exec, 1
	global_store_dword v236, v184, s[78:79]
	s_mov_b64 exec, -1
	s_waitcnt vmcnt(16)
	v_lshlrev_b32_e32 v144, 16, v48
	v_and_b32_e32 v145, 0xffff0000, v48
	v_lshlrev_b32_e32 v146, 16, v49
	v_and_b32_e32 v147, 0xffff0000, v49
	v_lshlrev_b32_e32 v148, 16, v50
	v_and_b32_e32 v149, 0xffff0000, v50
	v_lshlrev_b32_e32 v150, 16, v51
	v_and_b32_e32 v151, 0xffff0000, v51
	v_lshlrev_b32_e32 v152, 16, v52
	v_and_b32_e32 v153, 0xffff0000, v52
	v_lshlrev_b32_e32 v154, 16, v53
	v_and_b32_e32 v155, 0xffff0000, v53
	v_lshlrev_b32_e32 v156, 16, v54
	v_and_b32_e32 v157, 0xffff0000, v54
	v_lshlrev_b32_e32 v158, 16, v55
	v_and_b32_e32 v159, 0xffff0000, v55
	v_lshlrev_b32_e32 v160, 16, v56
	v_and_b32_e32 v161, 0xffff0000, v56
	v_lshlrev_b32_e32 v162, 16, v57
	v_and_b32_e32 v163, 0xffff0000, v57
	v_lshlrev_b32_e32 v164, 16, v58
	v_and_b32_e32 v165, 0xffff0000, v58
	v_lshlrev_b32_e32 v166, 16, v59
	v_and_b32_e32 v167, 0xffff0000, v59
	v_lshlrev_b32_e32 v168, 16, v60
	v_and_b32_e32 v169, 0xffff0000, v60
	v_lshlrev_b32_e32 v170, 16, v61
	v_and_b32_e32 v171, 0xffff0000, v61
	v_lshlrev_b32_e32 v172, 16, v62
	v_and_b32_e32 v173, 0xffff0000, v62
	v_lshlrev_b32_e32 v174, 16, v63
	v_and_b32_e32 v175, 0xffff0000, v63
	v_pk_mul_f32 v[252:253], v[160:161], v[160:161]
	v_pk_mul_f32 v[254:255], v[162:163], v[162:163]
	v_pk_fma_f32 v[252:253], v[164:165], v[164:165], v[252:253]
	v_pk_fma_f32 v[254:255], v[166:167], v[166:167], v[254:255]
	v_pk_fma_f32 v[252:253], v[168:169], v[168:169], v[252:253]
	v_pk_fma_f32 v[254:255], v[170:171], v[170:171], v[254:255]
	v_pk_fma_f32 v[252:253], v[172:173], v[172:173], v[252:253]
	v_pk_fma_f32 v[254:255], v[174:175], v[174:175], v[254:255]
	v_pk_add_f32 v[252:253], v[252:253], v[254:255]
	s_nop 0
	v_add_f32_e32 v183, v252, v253
	s_nop 1
	v_add_f32_dpp v183, v183, v183 quad_perm:[1,0,3,2] row_mask:0xf bank_mask:0xf bound_ctrl:1
	s_nop 1
	v_add_f32_dpp v183, v183, v183 quad_perm:[2,3,0,1] row_mask:0xf bank_mask:0xf bound_ctrl:1
	s_nop 1
	v_add_f32_dpp v183, v183, v183 row_half_mirror row_mask:0xf bank_mask:0xf bound_ctrl:1
	s_nop 1
	v_add_f32_dpp v183, v183, v183 row_mirror row_mask:0xf bank_mask:0xf bound_ctrl:1
	s_nop 1
	v_readlane_b32 s98, v183, 0
	v_readlane_b32 s99, v183, 16
	v_readlane_b32 s100, v183, 32
	v_readlane_b32 s101, v183, 48
	s_nop 1
	v_mov_b32_e32 v183, s98
	v_add_f32_e32 v183, s99, v183
	v_add_f32_e32 v183, s100, v183
	v_add_f32_e32 v183, s101, v183
	v_fmamk_f32 v183, v183, 0x3a800000, v182
	v_cmp_gt_f32_e32 vcc, 0x800000, v183
	v_mul_f32_e32 v181, 0x4b800000, v183
	s_nop 1
	v_cndmask_b32_e32 v183, v183, v181, vcc
	v_rsq_f32_e32 v183, v183
	s_nop 0
	v_mul_f32_e32 v181, 0x45800000, v183
	v_cndmask_b32_e32 v184, v183, v181, vcc
	v_mov_b32_e32 v185, v184
	v_pk_mul_f32 v[160:161], v[160:161], v[184:185]
	v_pk_mul_f32 v[162:163], v[162:163], v[184:185]
	v_pk_mul_f32 v[164:165], v[164:165], v[184:185]
	v_pk_mul_f32 v[166:167], v[166:167], v[184:185]
	v_pk_mul_f32 v[168:169], v[168:169], v[184:185]
	v_pk_mul_f32 v[170:171], v[170:171], v[184:185]
	v_pk_mul_f32 v[172:173], v[172:173], v[184:185]
	v_pk_mul_f32 v[174:175], v[174:175], v[184:185]
	v_pk_fma_f32 v[144:145], v[160:161], v[128:129], v[144:145]
	v_pk_fma_f32 v[146:147], v[162:163], v[130:131], v[146:147]
	v_pk_fma_f32 v[148:149], v[164:165], v[132:133], v[148:149]
	v_pk_fma_f32 v[150:151], v[166:167], v[134:135], v[150:151]
	v_pk_fma_f32 v[152:153], v[168:169], v[136:137], v[152:153]
	v_pk_fma_f32 v[154:155], v[170:171], v[138:139], v[154:155]
	v_pk_fma_f32 v[156:157], v[172:173], v[140:141], v[156:157]
	v_pk_fma_f32 v[158:159], v[174:175], v[142:143], v[158:159]
	v_pk_mul_f32 v[252:253], v[144:145], v[144:145]
	v_pk_mul_f32 v[254:255], v[146:147], v[146:147]
	v_pk_fma_f32 v[252:253], v[148:149], v[148:149], v[252:253]
	v_pk_fma_f32 v[254:255], v[150:151], v[150:151], v[254:255]
	v_pk_fma_f32 v[252:253], v[152:153], v[152:153], v[252:253]
	v_pk_fma_f32 v[254:255], v[154:155], v[154:155], v[254:255]
	v_pk_fma_f32 v[252:253], v[156:157], v[156:157], v[252:253]
	v_pk_fma_f32 v[254:255], v[158:159], v[158:159], v[254:255]
	v_pk_add_f32 v[252:253], v[252:253], v[254:255]
	s_nop 0
	v_add_f32_e32 v183, v252, v253
	s_nop 1
	v_add_f32_dpp v183, v183, v183 quad_perm:[1,0,3,2] row_mask:0xf bank_mask:0xf bound_ctrl:1
	s_nop 1
	v_add_f32_dpp v183, v183, v183 quad_perm:[2,3,0,1] row_mask:0xf bank_mask:0xf bound_ctrl:1
	s_nop 1
	v_add_f32_dpp v183, v183, v183 row_half_mirror row_mask:0xf bank_mask:0xf bound_ctrl:1
	s_nop 1
	v_add_f32_dpp v183, v183, v183 row_mirror row_mask:0xf bank_mask:0xf bound_ctrl:1
	s_nop 1
	v_readlane_b32 s98, v183, 0
	v_readlane_b32 s99, v183, 16
	v_readlane_b32 s100, v183, 32
	v_readlane_b32 s101, v183, 48
	s_nop 1
	v_mov_b32_e32 v183, s98
	v_add_f32_e32 v183, s99, v183
	v_add_f32_e32 v183, s100, v183
	v_add_f32_e32 v183, s101, v183
	v_fmamk_f32 v183, v183, 0x3a800000, v182
	v_cmp_gt_f32_e32 vcc, 0x800000, v183
	v_mul_f32_e32 v181, 0x4b800000, v183
	s_nop 1
	v_cndmask_b32_e32 v183, v183, v181, vcc
	v_rsq_f32_e32 v183, v183
	s_nop 0
	v_mul_f32_e32 v181, 0x45800000, v183
	v_cndmask_b32_e32 v184, v183, v181, vcc
	v_mov_b32_e32 v185, v184
	v_cvt_pk_bf16_f32 v48, v144, v145
	v_cvt_pk_bf16_f32 v49, v146, v147
	v_cvt_pk_bf16_f32 v50, v148, v149
	v_cvt_pk_bf16_f32 v51, v150, v151
	v_cvt_pk_bf16_f32 v52, v152, v153
	v_cvt_pk_bf16_f32 v53, v154, v155
	v_cvt_pk_bf16_f32 v54, v156, v157
	v_cvt_pk_bf16_f32 v55, v158, v159
	v_add_u32_e32 v181, 0x2400000, v177
	global_store_dwordx4 v181, v[48:51], s[78:79]
	global_store_dwordx4 v181, v[52:55], s[78:79] offset:1024
	v_add_u32_e32 v236, 0x6000, v237
	s_mov_b64 exec, 1
	global_store_dword v236, v184, s[78:79]
	s_mov_b64 exec, -1
	s_waitcnt vmcnt(12)
	v_lshlrev_b32_e32 v144, 16, v64
	v_and_b32_e32 v145, 0xffff0000, v64
	v_lshlrev_b32_e32 v146, 16, v65
	v_and_b32_e32 v147, 0xffff0000, v65
	v_lshlrev_b32_e32 v148, 16, v66
	v_and_b32_e32 v149, 0xffff0000, v66
	v_lshlrev_b32_e32 v150, 16, v67
	v_and_b32_e32 v151, 0xffff0000, v67
	v_lshlrev_b32_e32 v152, 16, v68
	v_and_b32_e32 v153, 0xffff0000, v68
	v_lshlrev_b32_e32 v154, 16, v69
	v_and_b32_e32 v155, 0xffff0000, v69
	v_lshlrev_b32_e32 v156, 16, v70
	v_and_b32_e32 v157, 0xffff0000, v70
	v_lshlrev_b32_e32 v158, 16, v71
	v_and_b32_e32 v159, 0xffff0000, v71
	v_lshlrev_b32_e32 v160, 16, v72
	v_and_b32_e32 v161, 0xffff0000, v72
	v_lshlrev_b32_e32 v162, 16, v73
	v_and_b32_e32 v163, 0xffff0000, v73
	v_lshlrev_b32_e32 v164, 16, v74
	v_and_b32_e32 v165, 0xffff0000, v74
	v_lshlrev_b32_e32 v166, 16, v75
	v_and_b32_e32 v167, 0xffff0000, v75
	v_lshlrev_b32_e32 v168, 16, v76
	v_and_b32_e32 v169, 0xffff0000, v76
	v_lshlrev_b32_e32 v170, 16, v77
	v_and_b32_e32 v171, 0xffff0000, v77
	v_lshlrev_b32_e32 v172, 16, v78
	v_and_b32_e32 v173, 0xffff0000, v78
	v_lshlrev_b32_e32 v174, 16, v79
	v_and_b32_e32 v175, 0xffff0000, v79
	v_pk_mul_f32 v[252:253], v[160:161], v[160:161]
	v_pk_mul_f32 v[254:255], v[162:163], v[162:163]
	v_pk_fma_f32 v[252:253], v[164:165], v[164:165], v[252:253]
	v_pk_fma_f32 v[254:255], v[166:167], v[166:167], v[254:255]
	v_pk_fma_f32 v[252:253], v[168:169], v[168:169], v[252:253]
	v_pk_fma_f32 v[254:255], v[170:171], v[170:171], v[254:255]
	v_pk_fma_f32 v[252:253], v[172:173], v[172:173], v[252:253]
	v_pk_fma_f32 v[254:255], v[174:175], v[174:175], v[254:255]
	v_pk_add_f32 v[252:253], v[252:253], v[254:255]
	s_nop 0
	v_add_f32_e32 v183, v252, v253
	s_nop 1
	v_add_f32_dpp v183, v183, v183 quad_perm:[1,0,3,2] row_mask:0xf bank_mask:0xf bound_ctrl:1
	s_nop 1
	v_add_f32_dpp v183, v183, v183 quad_perm:[2,3,0,1] row_mask:0xf bank_mask:0xf bound_ctrl:1
	s_nop 1
	v_add_f32_dpp v183, v183, v183 row_half_mirror row_mask:0xf bank_mask:0xf bound_ctrl:1
	s_nop 1
	v_add_f32_dpp v183, v183, v183 row_mirror row_mask:0xf bank_mask:0xf bound_ctrl:1
	s_nop 1
	v_readlane_b32 s98, v183, 0
	v_readlane_b32 s99, v183, 16
	v_readlane_b32 s100, v183, 32
	v_readlane_b32 s101, v183, 48
	s_nop 1
	v_mov_b32_e32 v183, s98
	v_add_f32_e32 v183, s99, v183
	v_add_f32_e32 v183, s100, v183
	v_add_f32_e32 v183, s101, v183
	v_fmamk_f32 v183, v183, 0x3a800000, v182
	v_cmp_gt_f32_e32 vcc, 0x800000, v183
	v_mul_f32_e32 v181, 0x4b800000, v183
	s_nop 1
	v_cndmask_b32_e32 v183, v183, v181, vcc
	v_rsq_f32_e32 v183, v183
	s_nop 0
	v_mul_f32_e32 v181, 0x45800000, v183
	v_cndmask_b32_e32 v184, v183, v181, vcc
	v_mov_b32_e32 v185, v184
	v_pk_mul_f32 v[160:161], v[160:161], v[184:185]
	v_pk_mul_f32 v[162:163], v[162:163], v[184:185]
	v_pk_mul_f32 v[164:165], v[164:165], v[184:185]
	v_pk_mul_f32 v[166:167], v[166:167], v[184:185]
	v_pk_mul_f32 v[168:169], v[168:169], v[184:185]
	v_pk_mul_f32 v[170:171], v[170:171], v[184:185]
	v_pk_mul_f32 v[172:173], v[172:173], v[184:185]
	v_pk_mul_f32 v[174:175], v[174:175], v[184:185]
	v_pk_fma_f32 v[144:145], v[160:161], v[128:129], v[144:145]
	v_pk_fma_f32 v[146:147], v[162:163], v[130:131], v[146:147]
	v_pk_fma_f32 v[148:149], v[164:165], v[132:133], v[148:149]
	v_pk_fma_f32 v[150:151], v[166:167], v[134:135], v[150:151]
	v_pk_fma_f32 v[152:153], v[168:169], v[136:137], v[152:153]
	v_pk_fma_f32 v[154:155], v[170:171], v[138:139], v[154:155]
	v_pk_fma_f32 v[156:157], v[172:173], v[140:141], v[156:157]
	v_pk_fma_f32 v[158:159], v[174:175], v[142:143], v[158:159]
	v_pk_mul_f32 v[252:253], v[144:145], v[144:145]
	v_pk_mul_f32 v[254:255], v[146:147], v[146:147]
	v_pk_fma_f32 v[252:253], v[148:149], v[148:149], v[252:253]
	v_pk_fma_f32 v[254:255], v[150:151], v[150:151], v[254:255]
	v_pk_fma_f32 v[252:253], v[152:153], v[152:153], v[252:253]
	v_pk_fma_f32 v[254:255], v[154:155], v[154:155], v[254:255]
	v_pk_fma_f32 v[252:253], v[156:157], v[156:157], v[252:253]
	v_pk_fma_f32 v[254:255], v[158:159], v[158:159], v[254:255]
	v_pk_add_f32 v[252:253], v[252:253], v[254:255]
	s_nop 0
	v_add_f32_e32 v183, v252, v253
	s_nop 1
	v_add_f32_dpp v183, v183, v183 quad_perm:[1,0,3,2] row_mask:0xf bank_mask:0xf bound_ctrl:1
	s_nop 1
	v_add_f32_dpp v183, v183, v183 quad_perm:[2,3,0,1] row_mask:0xf bank_mask:0xf bound_ctrl:1
	s_nop 1
	v_add_f32_dpp v183, v183, v183 row_half_mirror row_mask:0xf bank_mask:0xf bound_ctrl:1
	s_nop 1
	v_add_f32_dpp v183, v183, v183 row_mirror row_mask:0xf bank_mask:0xf bound_ctrl:1
	s_nop 1
	v_readlane_b32 s98, v183, 0
	v_readlane_b32 s99, v183, 16
	v_readlane_b32 s100, v183, 32
	v_readlane_b32 s101, v183, 48
	s_nop 1
	v_mov_b32_e32 v183, s98
	v_add_f32_e32 v183, s99, v183
	v_add_f32_e32 v183, s100, v183
	v_add_f32_e32 v183, s101, v183
	v_fmamk_f32 v183, v183, 0x3a800000, v182
	v_cmp_gt_f32_e32 vcc, 0x800000, v183
	v_mul_f32_e32 v181, 0x4b800000, v183
	s_nop 1
	v_cndmask_b32_e32 v183, v183, v181, vcc
	v_rsq_f32_e32 v183, v183
	s_nop 0
	v_mul_f32_e32 v181, 0x45800000, v183
	v_cndmask_b32_e32 v184, v183, v181, vcc
	v_mov_b32_e32 v185, v184
	v_cvt_pk_bf16_f32 v64, v144, v145
	v_cvt_pk_bf16_f32 v65, v146, v147
	v_cvt_pk_bf16_f32 v66, v148, v149
	v_cvt_pk_bf16_f32 v67, v150, v151
	v_cvt_pk_bf16_f32 v68, v152, v153
	v_cvt_pk_bf16_f32 v69, v154, v155
	v_cvt_pk_bf16_f32 v70, v156, v157
	v_cvt_pk_bf16_f32 v71, v158, v159
	v_add_u32_e32 v181, 0x2800000, v177
	global_store_dwordx4 v181, v[64:67], s[78:79]
	global_store_dwordx4 v181, v[68:71], s[78:79] offset:1024
	v_add_u32_e32 v236, 0x8000, v237
	s_mov_b64 exec, 1
	global_store_dword v236, v184, s[78:79]
	s_mov_b64 exec, -1
	s_waitcnt vmcnt(8)
	v_lshlrev_b32_e32 v144, 16, v80
	v_and_b32_e32 v145, 0xffff0000, v80
	v_lshlrev_b32_e32 v146, 16, v81
	v_and_b32_e32 v147, 0xffff0000, v81
	v_lshlrev_b32_e32 v148, 16, v82
	v_and_b32_e32 v149, 0xffff0000, v82
	v_lshlrev_b32_e32 v150, 16, v83
	v_and_b32_e32 v151, 0xffff0000, v83
	v_lshlrev_b32_e32 v152, 16, v84
	v_and_b32_e32 v153, 0xffff0000, v84
	v_lshlrev_b32_e32 v154, 16, v85
	v_and_b32_e32 v155, 0xffff0000, v85
	v_lshlrev_b32_e32 v156, 16, v86
	v_and_b32_e32 v157, 0xffff0000, v86
	v_lshlrev_b32_e32 v158, 16, v87
	v_and_b32_e32 v159, 0xffff0000, v87
	v_lshlrev_b32_e32 v160, 16, v88
	v_and_b32_e32 v161, 0xffff0000, v88
	v_lshlrev_b32_e32 v162, 16, v89
	v_and_b32_e32 v163, 0xffff0000, v89
	v_lshlrev_b32_e32 v164, 16, v90
	v_and_b32_e32 v165, 0xffff0000, v90
	v_lshlrev_b32_e32 v166, 16, v91
	v_and_b32_e32 v167, 0xffff0000, v91
	v_lshlrev_b32_e32 v168, 16, v92
	v_and_b32_e32 v169, 0xffff0000, v92
	v_lshlrev_b32_e32 v170, 16, v93
	v_and_b32_e32 v171, 0xffff0000, v93
	v_lshlrev_b32_e32 v172, 16, v94
	v_and_b32_e32 v173, 0xffff0000, v94
	v_lshlrev_b32_e32 v174, 16, v95
	v_and_b32_e32 v175, 0xffff0000, v95
	v_pk_mul_f32 v[252:253], v[160:161], v[160:161]
	v_pk_mul_f32 v[254:255], v[162:163], v[162:163]
	v_pk_fma_f32 v[252:253], v[164:165], v[164:165], v[252:253]
	v_pk_fma_f32 v[254:255], v[166:167], v[166:167], v[254:255]
	v_pk_fma_f32 v[252:253], v[168:169], v[168:169], v[252:253]
	v_pk_fma_f32 v[254:255], v[170:171], v[170:171], v[254:255]
	v_pk_fma_f32 v[252:253], v[172:173], v[172:173], v[252:253]
	v_pk_fma_f32 v[254:255], v[174:175], v[174:175], v[254:255]
	v_pk_add_f32 v[252:253], v[252:253], v[254:255]
	s_nop 0
	v_add_f32_e32 v183, v252, v253
	s_nop 1
	v_add_f32_dpp v183, v183, v183 quad_perm:[1,0,3,2] row_mask:0xf bank_mask:0xf bound_ctrl:1
	s_nop 1
	v_add_f32_dpp v183, v183, v183 quad_perm:[2,3,0,1] row_mask:0xf bank_mask:0xf bound_ctrl:1
	s_nop 1
	v_add_f32_dpp v183, v183, v183 row_half_mirror row_mask:0xf bank_mask:0xf bound_ctrl:1
	s_nop 1
	v_add_f32_dpp v183, v183, v183 row_mirror row_mask:0xf bank_mask:0xf bound_ctrl:1
	s_nop 1
	v_readlane_b32 s98, v183, 0
	v_readlane_b32 s99, v183, 16
	v_readlane_b32 s100, v183, 32
	v_readlane_b32 s101, v183, 48
	s_nop 1
	v_mov_b32_e32 v183, s98
	v_add_f32_e32 v183, s99, v183
	v_add_f32_e32 v183, s100, v183
	v_add_f32_e32 v183, s101, v183
	v_fmamk_f32 v183, v183, 0x3a800000, v182
	v_cmp_gt_f32_e32 vcc, 0x800000, v183
	v_mul_f32_e32 v181, 0x4b800000, v183
	s_nop 1
	v_cndmask_b32_e32 v183, v183, v181, vcc
	v_rsq_f32_e32 v183, v183
	s_nop 0
	v_mul_f32_e32 v181, 0x45800000, v183
	v_cndmask_b32_e32 v184, v183, v181, vcc
	v_mov_b32_e32 v185, v184
	v_pk_mul_f32 v[160:161], v[160:161], v[184:185]
	v_pk_mul_f32 v[162:163], v[162:163], v[184:185]
	v_pk_mul_f32 v[164:165], v[164:165], v[184:185]
	v_pk_mul_f32 v[166:167], v[166:167], v[184:185]
	v_pk_mul_f32 v[168:169], v[168:169], v[184:185]
	v_pk_mul_f32 v[170:171], v[170:171], v[184:185]
	v_pk_mul_f32 v[172:173], v[172:173], v[184:185]
	v_pk_mul_f32 v[174:175], v[174:175], v[184:185]
	v_pk_fma_f32 v[144:145], v[160:161], v[128:129], v[144:145]
	v_pk_fma_f32 v[146:147], v[162:163], v[130:131], v[146:147]
	v_pk_fma_f32 v[148:149], v[164:165], v[132:133], v[148:149]
	v_pk_fma_f32 v[150:151], v[166:167], v[134:135], v[150:151]
	v_pk_fma_f32 v[152:153], v[168:169], v[136:137], v[152:153]
	v_pk_fma_f32 v[154:155], v[170:171], v[138:139], v[154:155]
	v_pk_fma_f32 v[156:157], v[172:173], v[140:141], v[156:157]
	v_pk_fma_f32 v[158:159], v[174:175], v[142:143], v[158:159]
	v_pk_mul_f32 v[252:253], v[144:145], v[144:145]
	v_pk_mul_f32 v[254:255], v[146:147], v[146:147]
	v_pk_fma_f32 v[252:253], v[148:149], v[148:149], v[252:253]
	v_pk_fma_f32 v[254:255], v[150:151], v[150:151], v[254:255]
	v_pk_fma_f32 v[252:253], v[152:153], v[152:153], v[252:253]
	v_pk_fma_f32 v[254:255], v[154:155], v[154:155], v[254:255]
	v_pk_fma_f32 v[252:253], v[156:157], v[156:157], v[252:253]
	v_pk_fma_f32 v[254:255], v[158:159], v[158:159], v[254:255]
	v_pk_add_f32 v[252:253], v[252:253], v[254:255]
	s_nop 0
	v_add_f32_e32 v183, v252, v253
	s_nop 1
	v_add_f32_dpp v183, v183, v183 quad_perm:[1,0,3,2] row_mask:0xf bank_mask:0xf bound_ctrl:1
	s_nop 1
	v_add_f32_dpp v183, v183, v183 quad_perm:[2,3,0,1] row_mask:0xf bank_mask:0xf bound_ctrl:1
	s_nop 1
	v_add_f32_dpp v183, v183, v183 row_half_mirror row_mask:0xf bank_mask:0xf bound_ctrl:1
	s_nop 1
	v_add_f32_dpp v183, v183, v183 row_mirror row_mask:0xf bank_mask:0xf bound_ctrl:1
	s_nop 1
	v_readlane_b32 s98, v183, 0
	v_readlane_b32 s99, v183, 16
	v_readlane_b32 s100, v183, 32
	v_readlane_b32 s101, v183, 48
	s_nop 1
	v_mov_b32_e32 v183, s98
	v_add_f32_e32 v183, s99, v183
	v_add_f32_e32 v183, s100, v183
	v_add_f32_e32 v183, s101, v183
	v_fmamk_f32 v183, v183, 0x3a800000, v182
	v_cmp_gt_f32_e32 vcc, 0x800000, v183
	v_mul_f32_e32 v181, 0x4b800000, v183
	s_nop 1
	v_cndmask_b32_e32 v183, v183, v181, vcc
	v_rsq_f32_e32 v183, v183
	s_nop 0
	v_mul_f32_e32 v181, 0x45800000, v183
	v_cndmask_b32_e32 v184, v183, v181, vcc
	v_mov_b32_e32 v185, v184
	v_cvt_pk_bf16_f32 v80, v144, v145
	v_cvt_pk_bf16_f32 v81, v146, v147
	v_cvt_pk_bf16_f32 v82, v148, v149
	v_cvt_pk_bf16_f32 v83, v150, v151
	v_cvt_pk_bf16_f32 v84, v152, v153
	v_cvt_pk_bf16_f32 v85, v154, v155
	v_cvt_pk_bf16_f32 v86, v156, v157
	v_cvt_pk_bf16_f32 v87, v158, v159
	v_add_u32_e32 v181, 0x2c00000, v177
	global_store_dwordx4 v181, v[80:83], s[78:79]
	global_store_dwordx4 v181, v[84:87], s[78:79] offset:1024
	v_add_u32_e32 v236, 0xa000, v237
	s_mov_b64 exec, 1
	global_store_dword v236, v184, s[78:79]
	s_mov_b64 exec, -1
	s_waitcnt vmcnt(4)
	v_lshlrev_b32_e32 v144, 16, v96
	v_and_b32_e32 v145, 0xffff0000, v96
	v_lshlrev_b32_e32 v146, 16, v97
	v_and_b32_e32 v147, 0xffff0000, v97
	v_lshlrev_b32_e32 v148, 16, v98
	v_and_b32_e32 v149, 0xffff0000, v98
	v_lshlrev_b32_e32 v150, 16, v99
	v_and_b32_e32 v151, 0xffff0000, v99
	v_lshlrev_b32_e32 v152, 16, v100
	v_and_b32_e32 v153, 0xffff0000, v100
	v_lshlrev_b32_e32 v154, 16, v101
	v_and_b32_e32 v155, 0xffff0000, v101
	v_lshlrev_b32_e32 v156, 16, v102
	v_and_b32_e32 v157, 0xffff0000, v102
	v_lshlrev_b32_e32 v158, 16, v103
	v_and_b32_e32 v159, 0xffff0000, v103
	v_lshlrev_b32_e32 v160, 16, v104
	v_and_b32_e32 v161, 0xffff0000, v104
	v_lshlrev_b32_e32 v162, 16, v105
	v_and_b32_e32 v163, 0xffff0000, v105
	v_lshlrev_b32_e32 v164, 16, v106
	v_and_b32_e32 v165, 0xffff0000, v106
	v_lshlrev_b32_e32 v166, 16, v107
	v_and_b32_e32 v167, 0xffff0000, v107
	v_lshlrev_b32_e32 v168, 16, v108
	v_and_b32_e32 v169, 0xffff0000, v108
	v_lshlrev_b32_e32 v170, 16, v109
	v_and_b32_e32 v171, 0xffff0000, v109
	v_lshlrev_b32_e32 v172, 16, v110
	v_and_b32_e32 v173, 0xffff0000, v110
	v_lshlrev_b32_e32 v174, 16, v111
	v_and_b32_e32 v175, 0xffff0000, v111
	v_pk_mul_f32 v[252:253], v[160:161], v[160:161]
	v_pk_mul_f32 v[254:255], v[162:163], v[162:163]
	v_pk_fma_f32 v[252:253], v[164:165], v[164:165], v[252:253]
	v_pk_fma_f32 v[254:255], v[166:167], v[166:167], v[254:255]
	v_pk_fma_f32 v[252:253], v[168:169], v[168:169], v[252:253]
	v_pk_fma_f32 v[254:255], v[170:171], v[170:171], v[254:255]
	v_pk_fma_f32 v[252:253], v[172:173], v[172:173], v[252:253]
	v_pk_fma_f32 v[254:255], v[174:175], v[174:175], v[254:255]
	v_pk_add_f32 v[252:253], v[252:253], v[254:255]
	s_nop 0
	v_add_f32_e32 v183, v252, v253
	s_nop 1
	v_add_f32_dpp v183, v183, v183 quad_perm:[1,0,3,2] row_mask:0xf bank_mask:0xf bound_ctrl:1
	s_nop 1
	v_add_f32_dpp v183, v183, v183 quad_perm:[2,3,0,1] row_mask:0xf bank_mask:0xf bound_ctrl:1
	s_nop 1
	v_add_f32_dpp v183, v183, v183 row_half_mirror row_mask:0xf bank_mask:0xf bound_ctrl:1
	s_nop 1
	v_add_f32_dpp v183, v183, v183 row_mirror row_mask:0xf bank_mask:0xf bound_ctrl:1
	s_nop 1
	v_readlane_b32 s98, v183, 0
	v_readlane_b32 s99, v183, 16
	v_readlane_b32 s100, v183, 32
	v_readlane_b32 s101, v183, 48
	s_nop 1
	v_mov_b32_e32 v183, s98
	v_add_f32_e32 v183, s99, v183
	v_add_f32_e32 v183, s100, v183
	v_add_f32_e32 v183, s101, v183
	v_fmamk_f32 v183, v183, 0x3a800000, v182
	v_cmp_gt_f32_e32 vcc, 0x800000, v183
	v_mul_f32_e32 v181, 0x4b800000, v183
	s_nop 1
	v_cndmask_b32_e32 v183, v183, v181, vcc
	v_rsq_f32_e32 v183, v183
	s_nop 0
	v_mul_f32_e32 v181, 0x45800000, v183
	v_cndmask_b32_e32 v184, v183, v181, vcc
	v_mov_b32_e32 v185, v184
	v_pk_mul_f32 v[160:161], v[160:161], v[184:185]
	v_pk_mul_f32 v[162:163], v[162:163], v[184:185]
	v_pk_mul_f32 v[164:165], v[164:165], v[184:185]
	v_pk_mul_f32 v[166:167], v[166:167], v[184:185]
	v_pk_mul_f32 v[168:169], v[168:169], v[184:185]
	v_pk_mul_f32 v[170:171], v[170:171], v[184:185]
	v_pk_mul_f32 v[172:173], v[172:173], v[184:185]
	v_pk_mul_f32 v[174:175], v[174:175], v[184:185]
	v_pk_fma_f32 v[144:145], v[160:161], v[128:129], v[144:145]
	v_pk_fma_f32 v[146:147], v[162:163], v[130:131], v[146:147]
	v_pk_fma_f32 v[148:149], v[164:165], v[132:133], v[148:149]
	v_pk_fma_f32 v[150:151], v[166:167], v[134:135], v[150:151]
	v_pk_fma_f32 v[152:153], v[168:169], v[136:137], v[152:153]
	v_pk_fma_f32 v[154:155], v[170:171], v[138:139], v[154:155]
	v_pk_fma_f32 v[156:157], v[172:173], v[140:141], v[156:157]
	v_pk_fma_f32 v[158:159], v[174:175], v[142:143], v[158:159]
	v_pk_mul_f32 v[252:253], v[144:145], v[144:145]
	v_pk_mul_f32 v[254:255], v[146:147], v[146:147]
	v_pk_fma_f32 v[252:253], v[148:149], v[148:149], v[252:253]
	v_pk_fma_f32 v[254:255], v[150:151], v[150:151], v[254:255]
	v_pk_fma_f32 v[252:253], v[152:153], v[152:153], v[252:253]
	v_pk_fma_f32 v[254:255], v[154:155], v[154:155], v[254:255]
	v_pk_fma_f32 v[252:253], v[156:157], v[156:157], v[252:253]
	v_pk_fma_f32 v[254:255], v[158:159], v[158:159], v[254:255]
	v_pk_add_f32 v[252:253], v[252:253], v[254:255]
	s_nop 0
	v_add_f32_e32 v183, v252, v253
	s_nop 1
	v_add_f32_dpp v183, v183, v183 quad_perm:[1,0,3,2] row_mask:0xf bank_mask:0xf bound_ctrl:1
	s_nop 1
	v_add_f32_dpp v183, v183, v183 quad_perm:[2,3,0,1] row_mask:0xf bank_mask:0xf bound_ctrl:1
	s_nop 1
	v_add_f32_dpp v183, v183, v183 row_half_mirror row_mask:0xf bank_mask:0xf bound_ctrl:1
	s_nop 1
	v_add_f32_dpp v183, v183, v183 row_mirror row_mask:0xf bank_mask:0xf bound_ctrl:1
	s_nop 1
	v_readlane_b32 s98, v183, 0
	v_readlane_b32 s99, v183, 16
	v_readlane_b32 s100, v183, 32
	v_readlane_b32 s101, v183, 48
	s_nop 1
	v_mov_b32_e32 v183, s98
	v_add_f32_e32 v183, s99, v183
	v_add_f32_e32 v183, s100, v183
	v_add_f32_e32 v183, s101, v183
	v_fmamk_f32 v183, v183, 0x3a800000, v182
	v_cmp_gt_f32_e32 vcc, 0x800000, v183
	v_mul_f32_e32 v181, 0x4b800000, v183
	s_nop 1
	v_cndmask_b32_e32 v183, v183, v181, vcc
	v_rsq_f32_e32 v183, v183
	s_nop 0
	v_mul_f32_e32 v181, 0x45800000, v183
	v_cndmask_b32_e32 v184, v183, v181, vcc
	v_mov_b32_e32 v185, v184
	v_cvt_pk_bf16_f32 v96, v144, v145
	v_cvt_pk_bf16_f32 v97, v146, v147
	v_cvt_pk_bf16_f32 v98, v148, v149
	v_cvt_pk_bf16_f32 v99, v150, v151
	v_cvt_pk_bf16_f32 v100, v152, v153
	v_cvt_pk_bf16_f32 v101, v154, v155
	v_cvt_pk_bf16_f32 v102, v156, v157
	v_cvt_pk_bf16_f32 v103, v158, v159
	v_add_u32_e32 v181, 0x3000000, v177
	global_store_dwordx4 v181, v[96:99], s[78:79]
	global_store_dwordx4 v181, v[100:103], s[78:79] offset:1024
	v_add_u32_e32 v236, 0xc000, v237
	s_mov_b64 exec, 1
	global_store_dword v236, v184, s[78:79]
	s_mov_b64 exec, -1
	s_waitcnt vmcnt(0)
	v_lshlrev_b32_e32 v144, 16, v112
	v_and_b32_e32 v145, 0xffff0000, v112
	v_lshlrev_b32_e32 v146, 16, v113
	v_and_b32_e32 v147, 0xffff0000, v113
	v_lshlrev_b32_e32 v148, 16, v114
	v_and_b32_e32 v149, 0xffff0000, v114
	v_lshlrev_b32_e32 v150, 16, v115
	v_and_b32_e32 v151, 0xffff0000, v115
	v_lshlrev_b32_e32 v152, 16, v116
	v_and_b32_e32 v153, 0xffff0000, v116
	v_lshlrev_b32_e32 v154, 16, v117
	v_and_b32_e32 v155, 0xffff0000, v117
	v_lshlrev_b32_e32 v156, 16, v118
	v_and_b32_e32 v157, 0xffff0000, v118
	v_lshlrev_b32_e32 v158, 16, v119
	v_and_b32_e32 v159, 0xffff0000, v119
	v_lshlrev_b32_e32 v160, 16, v120
	v_and_b32_e32 v161, 0xffff0000, v120
	v_lshlrev_b32_e32 v162, 16, v121
	v_and_b32_e32 v163, 0xffff0000, v121
	v_lshlrev_b32_e32 v164, 16, v122
	v_and_b32_e32 v165, 0xffff0000, v122
	v_lshlrev_b32_e32 v166, 16, v123
	v_and_b32_e32 v167, 0xffff0000, v123
	v_lshlrev_b32_e32 v168, 16, v124
	v_and_b32_e32 v169, 0xffff0000, v124
	v_lshlrev_b32_e32 v170, 16, v125
	v_and_b32_e32 v171, 0xffff0000, v125
	v_lshlrev_b32_e32 v172, 16, v126
	v_and_b32_e32 v173, 0xffff0000, v126
	v_lshlrev_b32_e32 v174, 16, v127
	v_and_b32_e32 v175, 0xffff0000, v127
	v_pk_mul_f32 v[252:253], v[160:161], v[160:161]
	v_pk_mul_f32 v[254:255], v[162:163], v[162:163]
	v_pk_fma_f32 v[252:253], v[164:165], v[164:165], v[252:253]
	v_pk_fma_f32 v[254:255], v[166:167], v[166:167], v[254:255]
	v_pk_fma_f32 v[252:253], v[168:169], v[168:169], v[252:253]
	v_pk_fma_f32 v[254:255], v[170:171], v[170:171], v[254:255]
	v_pk_fma_f32 v[252:253], v[172:173], v[172:173], v[252:253]
	v_pk_fma_f32 v[254:255], v[174:175], v[174:175], v[254:255]
	v_pk_add_f32 v[252:253], v[252:253], v[254:255]
	s_nop 0
	v_add_f32_e32 v183, v252, v253
	s_nop 1
	v_add_f32_dpp v183, v183, v183 quad_perm:[1,0,3,2] row_mask:0xf bank_mask:0xf bound_ctrl:1
	s_nop 1
	v_add_f32_dpp v183, v183, v183 quad_perm:[2,3,0,1] row_mask:0xf bank_mask:0xf bound_ctrl:1
	s_nop 1
	v_add_f32_dpp v183, v183, v183 row_half_mirror row_mask:0xf bank_mask:0xf bound_ctrl:1
	s_nop 1
	v_add_f32_dpp v183, v183, v183 row_mirror row_mask:0xf bank_mask:0xf bound_ctrl:1
	s_nop 1
	v_readlane_b32 s98, v183, 0
	v_readlane_b32 s99, v183, 16
	v_readlane_b32 s100, v183, 32
	v_readlane_b32 s101, v183, 48
	s_nop 1
	v_mov_b32_e32 v183, s98
	v_add_f32_e32 v183, s99, v183
	v_add_f32_e32 v183, s100, v183
	v_add_f32_e32 v183, s101, v183
	v_fmamk_f32 v183, v183, 0x3a800000, v182
	v_cmp_gt_f32_e32 vcc, 0x800000, v183
	v_mul_f32_e32 v181, 0x4b800000, v183
	s_nop 1
	v_cndmask_b32_e32 v183, v183, v181, vcc
	v_rsq_f32_e32 v183, v183
	s_nop 0
	v_mul_f32_e32 v181, 0x45800000, v183
	v_cndmask_b32_e32 v184, v183, v181, vcc
	v_mov_b32_e32 v185, v184
	v_pk_mul_f32 v[160:161], v[160:161], v[184:185]
	v_pk_mul_f32 v[162:163], v[162:163], v[184:185]
	v_pk_mul_f32 v[164:165], v[164:165], v[184:185]
	v_pk_mul_f32 v[166:167], v[166:167], v[184:185]
	v_pk_mul_f32 v[168:169], v[168:169], v[184:185]
	v_pk_mul_f32 v[170:171], v[170:171], v[184:185]
	v_pk_mul_f32 v[172:173], v[172:173], v[184:185]
	v_pk_mul_f32 v[174:175], v[174:175], v[184:185]
	v_pk_fma_f32 v[144:145], v[160:161], v[128:129], v[144:145]
	v_pk_fma_f32 v[146:147], v[162:163], v[130:131], v[146:147]
	v_pk_fma_f32 v[148:149], v[164:165], v[132:133], v[148:149]
	v_pk_fma_f32 v[150:151], v[166:167], v[134:135], v[150:151]
	v_pk_fma_f32 v[152:153], v[168:169], v[136:137], v[152:153]
	v_pk_fma_f32 v[154:155], v[170:171], v[138:139], v[154:155]
	v_pk_fma_f32 v[156:157], v[172:173], v[140:141], v[156:157]
	v_pk_fma_f32 v[158:159], v[174:175], v[142:143], v[158:159]
	v_pk_mul_f32 v[252:253], v[144:145], v[144:145]
	v_pk_mul_f32 v[254:255], v[146:147], v[146:147]
	v_pk_fma_f32 v[252:253], v[148:149], v[148:149], v[252:253]
	v_pk_fma_f32 v[254:255], v[150:151], v[150:151], v[254:255]
	v_pk_fma_f32 v[252:253], v[152:153], v[152:153], v[252:253]
	v_pk_fma_f32 v[254:255], v[154:155], v[154:155], v[254:255]
	v_pk_fma_f32 v[252:253], v[156:157], v[156:157], v[252:253]
	v_pk_fma_f32 v[254:255], v[158:159], v[158:159], v[254:255]
	v_pk_add_f32 v[252:253], v[252:253], v[254:255]
	s_nop 0
	v_add_f32_e32 v183, v252, v253
	s_nop 1
	v_add_f32_dpp v183, v183, v183 quad_perm:[1,0,3,2] row_mask:0xf bank_mask:0xf bound_ctrl:1
	s_nop 1
	v_add_f32_dpp v183, v183, v183 quad_perm:[2,3,0,1] row_mask:0xf bank_mask:0xf bound_ctrl:1
	s_nop 1
	v_add_f32_dpp v183, v183, v183 row_half_mirror row_mask:0xf bank_mask:0xf bound_ctrl:1
	s_nop 1
	v_add_f32_dpp v183, v183, v183 row_mirror row_mask:0xf bank_mask:0xf bound_ctrl:1
	s_nop 1
	v_readlane_b32 s98, v183, 0
	v_readlane_b32 s99, v183, 16
	v_readlane_b32 s100, v183, 32
	v_readlane_b32 s101, v183, 48
	s_nop 1
	v_mov_b32_e32 v183, s98
	v_add_f32_e32 v183, s99, v183
	v_add_f32_e32 v183, s100, v183
	v_add_f32_e32 v183, s101, v183
	v_fmamk_f32 v183, v183, 0x3a800000, v182
	v_cmp_gt_f32_e32 vcc, 0x800000, v183
	v_mul_f32_e32 v181, 0x4b800000, v183
	s_nop 1
	v_cndmask_b32_e32 v183, v183, v181, vcc
	v_rsq_f32_e32 v183, v183
	s_nop 0
	v_mul_f32_e32 v181, 0x45800000, v183
	v_cndmask_b32_e32 v184, v183, v181, vcc
	v_mov_b32_e32 v185, v184
	v_cvt_pk_bf16_f32 v112, v144, v145
	v_cvt_pk_bf16_f32 v113, v146, v147
	v_cvt_pk_bf16_f32 v114, v148, v149
	v_cvt_pk_bf16_f32 v115, v150, v151
	v_cvt_pk_bf16_f32 v116, v152, v153
	v_cvt_pk_bf16_f32 v117, v154, v155
	v_cvt_pk_bf16_f32 v118, v156, v157
	v_cvt_pk_bf16_f32 v119, v158, v159
	v_add_u32_e32 v181, 0x3400000, v177
	global_store_dwordx4 v181, v[112:115], s[78:79]
	global_store_dwordx4 v181, v[116:119], s[78:79] offset:1024
	v_add_u32_e32 v236, 0xe000, v237
	s_mov_b64 exec, 1
	global_store_dword v236, v184, s[78:79]
	s_mov_b64 exec, -1
	v_readfirstlane_b32 s98, v179
	s_nop 3
	s_and_b32 s99, s98, 3
	s_cmp_lg_u32 s99, 0
	s_cbranch_scc1 .Lmyxupd_done_4
	v_lshrrev_b32_e32 v179, 2, v179
	v_lshlrev_b32_e32 v177, 4, v176
	v_lshl_add_u32 v177, v179, 11, v177
	v_lshlrev_b32_e32 v237, 2, v179
	v_add_u32_e32 v237, 0x10000, v237
	v_add_u32_e32 v181, 0x3800000, v177
	global_load_dwordx4 v[0:3], v181, s[78:79]
	global_load_dwordx4 v[4:7], v181, s[78:79] offset:1024
	v_lshl_add_u32 v183, v179, 12, v180
	v_add_u32_e32 v183, 0xbf00000, v183
	v_add_u32_e32 v181, 0x0, v183
	global_load_dwordx4 v[8:11], v181, s[78:79]
	global_load_dwordx4 v[12:15], v181, s[78:79] offset:16
	global_load_dwordx4 v[16:19], v181, s[78:79] offset:2048
	global_load_dwordx4 v[20:23], v181, s[78:79] offset:2064
	v_add_u32_e32 v181, 0x200000, v183
	global_load_dwordx4 v[24:27], v181, s[78:79]
	global_load_dwordx4 v[28:31], v181, s[78:79] offset:16
	global_load_dwordx4 v[32:35], v181, s[78:79] offset:2048
	global_load_dwordx4 v[36:39], v181, s[78:79] offset:2064
	v_add_u32_e32 v181, 0x400000, v183
	global_load_dwordx4 v[40:43], v181, s[78:79]
	global_load_dwordx4 v[44:47], v181, s[78:79] offset:16
	global_load_dwordx4 v[48:51], v181, s[78:79] offset:2048
	global_load_dwordx4 v[52:55], v181, s[78:79] offset:2064
	v_add_u32_e32 v181, 0x600000, v183
	global_load_dwordx4 v[56:59], v181, s[78:79]
	global_load_dwordx4 v[60:63], v181, s[78:79] offset:16
	global_load_dwordx4 v[64:67], v181, s[78:79] offset:2048
	global_load_dwordx4 v[68:71], v181, s[78:79] offset:2064
	v_add_u32_e32 v181, 0x800000, v183
	global_load_dwordx4 v[72:75], v181, s[78:79]
	global_load_dwordx4 v[76:79], v181, s[78:79] offset:16
	global_load_dwordx4 v[80:83], v181, s[78:79] offset:2048
	global_load_dwordx4 v[84:87], v181, s[78:79] offset:2064
	v_add_u32_e32 v181, 0xa00000, v183
	global_load_dwordx4 v[88:91], v181, s[78:79]
	global_load_dwordx4 v[92:95], v181, s[78:79] offset:16
	global_load_dwordx4 v[96:99], v181, s[78:79] offset:2048
	global_load_dwordx4 v[100:103], v181, s[78:79] offset:2064
	s_waitcnt vmcnt(20)
	v_pk_add_f32 v[160:161], v[8:9], 0 op_sel_hi:[1,0]
	v_pk_add_f32 v[162:163], v[10:11], 0 op_sel_hi:[1,0]
	v_pk_add_f32 v[164:165], v[12:13], 0 op_sel_hi:[1,0]
	v_pk_add_f32 v[166:167], v[14:15], 0 op_sel_hi:[1,0]
	v_pk_add_f32 v[168:169], v[16:17], 0 op_sel_hi:[1,0]
	v_pk_add_f32 v[170:171], v[18:19], 0 op_sel_hi:[1,0]
	v_pk_add_f32 v[172:173], v[20:21], 0 op_sel_hi:[1,0]
	v_pk_add_f32 v[174:175], v[22:23], 0 op_sel_hi:[1,0]
	s_waitcnt vmcnt(16)
	v_pk_add_f32 v[160:161], v[160:161], v[24:25]
	v_pk_add_f32 v[162:163], v[162:163], v[26:27]
	v_pk_add_f32 v[164:165], v[164:165], v[28:29]
	v_pk_add_f32 v[166:167], v[166:167], v[30:31]
	v_pk_add_f32 v[168:169], v[168:169], v[32:33]
	v_pk_add_f32 v[170:171], v[170:171], v[34:35]
	v_pk_add_f32 v[172:173], v[172:173], v[36:37]
	v_pk_add_f32 v[174:175], v[174:175], v[38:39]
	s_waitcnt vmcnt(12)
	v_pk_add_f32 v[160:161], v[160:161], v[40:41]
	v_pk_add_f32 v[162:163], v[162:163], v[42:43]
	v_pk_add_f32 v[164:165], v[164:165], v[44:45]
	v_pk_add_f32 v[166:167], v[166:167], v[46:47]
	v_pk_add_f32 v[168:169], v[168:169], v[48:49]
	v_pk_add_f32 v[170:171], v[170:171], v[50:51]
	v_pk_add_f32 v[172:173], v[172:173], v[52:53]
	v_pk_add_f32 v[174:175], v[174:175], v[54:55]
	s_waitcnt vmcnt(8)
	v_pk_add_f32 v[160:161], v[160:161], v[56:57]
	v_pk_add_f32 v[162:163], v[162:163], v[58:59]
	v_pk_add_f32 v[164:165], v[164:165], v[60:61]
	v_pk_add_f32 v[166:167], v[166:167], v[62:63]
	v_pk_add_f32 v[168:169], v[168:169], v[64:65]
	v_pk_add_f32 v[170:171], v[170:171], v[66:67]
	v_pk_add_f32 v[172:173], v[172:173], v[68:69]
	v_pk_add_f32 v[174:175], v[174:175], v[70:71]
	s_waitcnt vmcnt(4)
	v_pk_add_f32 v[160:161], v[160:161], v[72:73]
	v_pk_add_f32 v[162:163], v[162:163], v[74:75]
	v_pk_add_f32 v[164:165], v[164:165], v[76:77]
	v_pk_add_f32 v[166:167], v[166:167], v[78:79]
	v_pk_add_f32 v[168:169], v[168:169], v[80:81]
	v_pk_add_f32 v[170:171], v[170:171], v[82:83]
	v_pk_add_f32 v[172:173], v[172:173], v[84:85]
	v_pk_add_f32 v[174:175], v[174:175], v[86:87]
	s_waitcnt vmcnt(0)
	v_pk_add_f32 v[160:161], v[160:161], v[88:89]
	v_pk_add_f32 v[162:163], v[162:163], v[90:91]
	v_pk_add_f32 v[164:165], v[164:165], v[92:93]
	v_pk_add_f32 v[166:167], v[166:167], v[94:95]
	v_pk_add_f32 v[168:169], v[168:169], v[96:97]
	v_pk_add_f32 v[170:171], v[170:171], v[98:99]
	v_pk_add_f32 v[172:173], v[172:173], v[100:101]
	v_pk_add_f32 v[174:175], v[174:175], v[102:103]
	v_lshlrev_b32_e32 v144, 16, v0
	v_and_b32_e32 v145, 0xffff0000, v0
	v_lshlrev_b32_e32 v146, 16, v1
	v_and_b32_e32 v147, 0xffff0000, v1
	v_lshlrev_b32_e32 v148, 16, v2
	v_and_b32_e32 v149, 0xffff0000, v2
	v_lshlrev_b32_e32 v150, 16, v3
	v_and_b32_e32 v151, 0xffff0000, v3
	v_lshlrev_b32_e32 v152, 16, v4
	v_and_b32_e32 v153, 0xffff0000, v4
	v_lshlrev_b32_e32 v154, 16, v5
	v_and_b32_e32 v155, 0xffff0000, v5
	v_lshlrev_b32_e32 v156, 16, v6
	v_and_b32_e32 v157, 0xffff0000, v6
	v_lshlrev_b32_e32 v158, 16, v7
	v_and_b32_e32 v159, 0xffff0000, v7
	v_add_u32_e32 v181, 0xc00000, v183
	global_load_dwordx4 v[8:11], v181, s[78:79]
	global_load_dwordx4 v[12:15], v181, s[78:79] offset:16
	global_load_dwordx4 v[16:19], v181, s[78:79] offset:2048
	global_load_dwordx4 v[20:23], v181, s[78:79] offset:2064
	v_add_u32_e32 v181, 0xe00000, v183
	global_load_dwordx4 v[24:27], v181, s[78:79]
	global_load_dwordx4 v[28:31], v181, s[78:79] offset:16
	global_load_dwordx4 v[32:35], v181, s[78:79] offset:2048
	global_load_dwordx4 v[36:39], v181, s[78:79] offset:2064
	s_waitcnt vmcnt(4)
	v_pk_add_f32 v[160:161], v[160:161], v[8:9]
	v_pk_add_f32 v[162:163], v[162:163], v[10:11]
	v_pk_add_f32 v[164:165], v[164:165], v[12:13]
	v_pk_add_f32 v[166:167], v[166:167], v[14:15]
	v_pk_add_f32 v[168:169], v[168:169], v[16:17]
	v_pk_add_f32 v[170:171], v[170:171], v[18:19]
	v_pk_add_f32 v[172:173], v[172:173], v[20:21]
	v_pk_add_f32 v[174:175], v[174:175], v[22:23]
	s_waitcnt vmcnt(0)
	v_pk_add_f32 v[160:161], v[160:161], v[24:25]
	v_pk_add_f32 v[162:163], v[162:163], v[26:27]
	v_pk_add_f32 v[164:165], v[164:165], v[28:29]
	v_pk_add_f32 v[166:167], v[166:167], v[30:31]
	v_pk_add_f32 v[168:169], v[168:169], v[32:33]
	v_pk_add_f32 v[170:171], v[170:171], v[34:35]
	v_pk_add_f32 v[172:173], v[172:173], v[36:37]
	v_pk_add_f32 v[174:175], v[174:175], v[38:39]
	v_pk_mul_f32 v[252:253], v[160:161], v[160:161]
	v_pk_mul_f32 v[254:255], v[162:163], v[162:163]
	v_pk_fma_f32 v[252:253], v[164:165], v[164:165], v[252:253]
	v_pk_fma_f32 v[254:255], v[166:167], v[166:167], v[254:255]
	v_pk_fma_f32 v[252:253], v[168:169], v[168:169], v[252:253]
	v_pk_fma_f32 v[254:255], v[170:171], v[170:171], v[254:255]
	v_pk_fma_f32 v[252:253], v[172:173], v[172:173], v[252:253]
	v_pk_fma_f32 v[254:255], v[174:175], v[174:175], v[254:255]
	v_pk_add_f32 v[252:253], v[252:253], v[254:255]
	s_nop 0
	v_add_f32_e32 v183, v252, v253
	s_nop 1
	v_add_f32_dpp v183, v183, v183 quad_perm:[1,0,3,2] row_mask:0xf bank_mask:0xf bound_ctrl:1
	s_nop 1
	v_add_f32_dpp v183, v183, v183 quad_perm:[2,3,0,1] row_mask:0xf bank_mask:0xf bound_ctrl:1
	s_nop 1
	v_add_f32_dpp v183, v183, v183 row_half_mirror row_mask:0xf bank_mask:0xf bound_ctrl:1
	s_nop 1
	v_add_f32_dpp v183, v183, v183 row_mirror row_mask:0xf bank_mask:0xf bound_ctrl:1
	s_nop 1
	v_readlane_b32 s98, v183, 0
	v_readlane_b32 s99, v183, 16
	v_readlane_b32 s100, v183, 32
	v_readlane_b32 s101, v183, 48
	s_nop 1
	v_mov_b32_e32 v183, s98
	v_add_f32_e32 v183, s99, v183
	v_add_f32_e32 v183, s100, v183
	v_add_f32_e32 v183, s101, v183
	v_fmamk_f32 v183, v183, 0x3a800000, v182
	v_cmp_gt_f32_e32 vcc, 0x800000, v183
	v_mul_f32_e32 v181, 0x4b800000, v183
	s_nop 1
	v_cndmask_b32_e32 v183, v183, v181, vcc
	v_rsq_f32_e32 v183, v183
	s_nop 0
	v_mul_f32_e32 v181, 0x45800000, v183
	v_cndmask_b32_e32 v184, v183, v181, vcc
	v_mov_b32_e32 v185, v184
	v_pk_mul_f32 v[160:161], v[160:161], v[184:185]
	v_pk_mul_f32 v[162:163], v[162:163], v[184:185]
	v_pk_mul_f32 v[164:165], v[164:165], v[184:185]
	v_pk_mul_f32 v[166:167], v[166:167], v[184:185]
	v_pk_mul_f32 v[168:169], v[168:169], v[184:185]
	v_pk_mul_f32 v[170:171], v[170:171], v[184:185]
	v_pk_mul_f32 v[172:173], v[172:173], v[184:185]
	v_pk_mul_f32 v[174:175], v[174:175], v[184:185]
	v_pk_fma_f32 v[144:145], v[160:161], v[128:129], v[144:145]
	v_pk_fma_f32 v[146:147], v[162:163], v[130:131], v[146:147]
	v_pk_fma_f32 v[148:149], v[164:165], v[132:133], v[148:149]
	v_pk_fma_f32 v[150:151], v[166:167], v[134:135], v[150:151]
	v_pk_fma_f32 v[152:153], v[168:169], v[136:137], v[152:153]
	v_pk_fma_f32 v[154:155], v[170:171], v[138:139], v[154:155]
	v_pk_fma_f32 v[156:157], v[172:173], v[140:141], v[156:157]
	v_pk_fma_f32 v[158:159], v[174:175], v[142:143], v[158:159]
	v_pk_mul_f32 v[252:253], v[144:145], v[144:145]
	v_pk_mul_f32 v[254:255], v[146:147], v[146:147]
	v_pk_fma_f32 v[252:253], v[148:149], v[148:149], v[252:253]
	v_pk_fma_f32 v[254:255], v[150:151], v[150:151], v[254:255]
	v_pk_fma_f32 v[252:253], v[152:153], v[152:153], v[252:253]
	v_pk_fma_f32 v[254:255], v[154:155], v[154:155], v[254:255]
	v_pk_fma_f32 v[252:253], v[156:157], v[156:157], v[252:253]
	v_pk_fma_f32 v[254:255], v[158:159], v[158:159], v[254:255]
	v_pk_add_f32 v[252:253], v[252:253], v[254:255]
	s_nop 0
	v_add_f32_e32 v183, v252, v253
	s_nop 1
	v_add_f32_dpp v183, v183, v183 quad_perm:[1,0,3,2] row_mask:0xf bank_mask:0xf bound_ctrl:1
	s_nop 1
	v_add_f32_dpp v183, v183, v183 quad_perm:[2,3,0,1] row_mask:0xf bank_mask:0xf bound_ctrl:1
	s_nop 1
	v_add_f32_dpp v183, v183, v183 row_half_mirror row_mask:0xf bank_mask:0xf bound_ctrl:1
	s_nop 1
	v_add_f32_dpp v183, v183, v183 row_mirror row_mask:0xf bank_mask:0xf bound_ctrl:1
	s_nop 1
	v_readlane_b32 s98, v183, 0
	v_readlane_b32 s99, v183, 16
	v_readlane_b32 s100, v183, 32
	v_readlane_b32 s101, v183, 48
	s_nop 1
	v_mov_b32_e32 v183, s98
	v_add_f32_e32 v183, s99, v183
	v_add_f32_e32 v183, s100, v183
	v_add_f32_e32 v183, s101, v183
	v_fmamk_f32 v183, v183, 0x3a800000, v182
	v_cmp_gt_f32_e32 vcc, 0x800000, v183
	v_mul_f32_e32 v181, 0x4b800000, v183
	s_nop 1
	v_cndmask_b32_e32 v183, v183, v181, vcc
	v_rsq_f32_e32 v183, v183
	s_nop 0
	v_mul_f32_e32 v181, 0x45800000, v183
	v_cndmask_b32_e32 v184, v183, v181, vcc
	v_mov_b32_e32 v185, v184
	v_cvt_pk_bf16_f32 v0, v144, v145
	v_cvt_pk_bf16_f32 v1, v146, v147
	v_cvt_pk_bf16_f32 v2, v148, v149
	v_cvt_pk_bf16_f32 v3, v150, v151
	v_cvt_pk_bf16_f32 v4, v152, v153
	v_cvt_pk_bf16_f32 v5, v154, v155
	v_cvt_pk_bf16_f32 v6, v156, v157
	v_cvt_pk_bf16_f32 v7, v158, v159
	v_add_u32_e32 v181, 0x3800000, v177
	global_store_dwordx4 v181, v[0:3], s[78:79]
	global_store_dwordx4 v181, v[4:7], s[78:79] offset:1024
	v_add_u32_e32 v236, 0x10000, v237
	s_mov_b64 exec, 1
	global_store_dword v236, v184, s[78:79]
	s_mov_b64 exec, -1

.LBB0_2139:
	v_readlane_b32 s0, v235, 52
	v_readlane_b32 s1, v235, 53
	s_and_b64 vcc, exec, s[0:1]
	s_waitcnt lgkmcnt(0)
	s_barrier
	v_mbcnt_lo_u32_b32 v0, -1, 0
	v_mbcnt_hi_u32_b32 v0, -1, v0
	s_cbranch_vccnz .LBB0_2159
	v_lshlrev_b32_e32 v2, 3, v0
	v_readlane_b32 s4, v235, 4
	v_ashrrev_i32_e32 v3, 31, v2
	v_readlane_b32 s6, v235, 6
	v_readlane_b32 s7, v235, 7
	v_lshlrev_b64 v[4:5], 1, v[2:3]
	v_lshlrev_b64 v[2:3], 2, v[2:3]
	v_readlane_b32 s5, v235, 5
	v_readlane_b32 s10, v235, 10
	v_readlane_b32 s11, v235, 11
	v_readlane_b32 s18, v235, 18
	v_readlane_b32 s19, v235, 19
	v_readlane_b32 s6, v235, 61
	v_lshl_add_u64 v[154:155], s[90:91], 0, v[2:3]
	v_readlane_b32 s8, v235, 8
	v_lshl_add_u64 v[2:3], s[18:19], 0, v[2:3]
	s_mov_b64 s[0:1], 0x2000
	v_readlane_b32 s4, v235, 0
	v_readlane_b32 s7, v235, 62
	s_mov_b32 s10, s6
	s_ashr_i32 s11, s6, 31
	v_readlane_b32 s9, v235, 9
	v_lshl_add_u64 v[158:159], v[2:3], 0, s[0:1]
	s_lshl_b32 s4, s4, 4
	s_add_i32 s0, s6, 0xffffc000
	s_lshl_b64 s[6:7], s[10:11], 2
	s_mov_b32 s8, s10
	v_readlane_b32 s12, v235, 12
	v_readlane_b32 s13, v235, 13
	v_readlane_b32 s14, v235, 14
	v_readlane_b32 s15, v235, 15
	v_readlane_b32 s16, v235, 16
	v_readlane_b32 s17, v235, 17
	v_readlane_b32 s5, v235, 1
	s_add_u32 s80, s6, 0x10000
	v_writelane_b32 v235, s8, 61
	s_addc_u32 s12, s7, 0
	s_ashr_i32 s5, s4, 31
	v_writelane_b32 v235, s9, 62
	s_lshl_b64 s[8:9], s[10:11], 11
	v_lshl_add_u64 v[152:153], s[86:87], 0, v[4:5]
	v_lshl_add_u64 v[156:157], s[54:55], 0, v[4:5]
	s_mov_b32 s1, 0
	v_cmp_eq_u32_e64 s[16:17], 0, v0
	s_lshl_b64 s[6:7], s[4:5], 2
	v_lshl_add_u64 v[160:161], s[8:9], 0, v[4:5]
	s_lshl_b64 s[8:9], s[4:5], 11
	s_mov_b64 s[20:21], 0x600000
	s_mov_b64 s[22:23], 0x600800
	s_mov_b64 s[24:25], 0x800000
	s_mov_b32 s5, 0x800000
	s_mov_b64 s[26:27], 0x800800
	s_mov_b64 s[28:29], 0xa00000
	s_mov_b64 s[36:37], 0xa00800
	s_mov_b64 s[38:39], 0xc00000
	s_mov_b64 s[40:41], 0xc00800
	s_mov_b64 s[42:43], 0xe00000
	s_mov_b64 s[44:45], 0xe00800
	s_mov_b64 s[46:47], 0x1000000
	s_mov_b32 s13, 0x1000000
	s_mov_b64 s[48:49], 0x1000800
	s_mov_b64 s[50:51], 0x1200000
	s_mov_b32 s14, 0x1200000
	s_mov_b64 s[10:11], 0x1200800
	s_mov_b64 s[82:83], 0x1400000
	s_mov_b32 s15, 0x1400000
	s_mov_b64 s[90:91], 0x1400800
	v_mov_b32_e32 v215, 0
	v_mov_b32_e32 v216, 0x358637bd
	v_mbcnt_lo_u32_b32 v176, -1, 0
	v_mbcnt_hi_u32_b32 v176, -1, v176
	v_readlane_b32 s98, v235, 49
	v_readlane_b32 s99, v235, 20
	v_readlane_b32 s100, v235, 18
	v_readlane_b32 s101, v235, 19
	s_nop 3
	s_lshr_b32 vcc_lo, s98, 3
	s_and_b32 vcc_hi, vcc_lo, 7
	s_lshr_b32 vcc_lo, vcc_lo, 3
	s_lshl_b32 vcc_lo, vcc_lo, 3
	s_add_i32 vcc_lo, vcc_lo, s99
	s_lshl_b32 s98, vcc_hi, 8
	s_add_i32 s98, s98, vcc_lo
	s_mov_b32 s99, s98
	v_mov_b32_e32 v183, s99
	v_lshlrev_b32_e32 v177, 4, v176
	s_lshl_b32 s99, s99, 11
	v_add_u32_e32 v177, s99, v177
	v_add_u32_e32 v178, 0x1800000, v177
	v_add_u32_e32 v179, 0x9e00000, v177
	v_lshlrev_b32_e32 v180, 5, v176
	v_add_u32_e32 v181, 0x2000, v180
	global_load_dwordx4 v[128:131], v181, s[100:101]
	global_load_dwordx4 v[132:135], v181, s[100:101] offset:16
	global_load_dwordx4 v[136:139], v181, s[100:101] offset:2048
	global_load_dwordx4 v[140:143], v181, s[100:101] offset:2064
	v_mov_b32_e32 v182, 0x358637bd
	global_load_dwordx4 v[0:3], v178, s[78:79]
	global_load_dwordx4 v[4:7], v178, s[78:79] offset:1024
	global_load_dwordx4 v[8:11], v179, s[78:79]
	global_load_dwordx4 v[12:15], v179, s[78:79] offset:1024
	v_add_u32_e32 v178, 0x400000, v178
	v_add_u32_e32 v179, 0x400000, v179
	global_load_dwordx4 v[16:19], v178, s[78:79]
	global_load_dwordx4 v[20:23], v178, s[78:79] offset:1024
	global_load_dwordx4 v[24:27], v179, s[78:79]
	global_load_dwordx4 v[28:31], v179, s[78:79] offset:1024
	v_add_u32_e32 v178, 0x400000, v178
	v_add_u32_e32 v179, 0x400000, v179
	global_load_dwordx4 v[32:35], v178, s[78:79]
	global_load_dwordx4 v[36:39], v178, s[78:79] offset:1024
	global_load_dwordx4 v[40:43], v179, s[78:79]
	global_load_dwordx4 v[44:47], v179, s[78:79] offset:1024
	v_add_u32_e32 v178, 0x400000, v178
	v_add_u32_e32 v179, 0x400000, v179
	global_load_dwordx4 v[48:51], v178, s[78:79]
	global_load_dwordx4 v[52:55], v178, s[78:79] offset:1024
	global_load_dwordx4 v[56:59], v179, s[78:79]
	global_load_dwordx4 v[60:63], v179, s[78:79] offset:1024
	v_add_u32_e32 v178, 0x400000, v178
	v_add_u32_e32 v179, 0x400000, v179
	global_load_dwordx4 v[64:67], v178, s[78:79]
	global_load_dwordx4 v[68:71], v178, s[78:79] offset:1024
	global_load_dwordx4 v[72:75], v179, s[78:79]
	global_load_dwordx4 v[76:79], v179, s[78:79] offset:1024
	v_add_u32_e32 v178, 0x400000, v178
	v_add_u32_e32 v179, 0x400000, v179
	global_load_dwordx4 v[80:83], v178, s[78:79]
	global_load_dwordx4 v[84:87], v178, s[78:79] offset:1024
	global_load_dwordx4 v[88:91], v179, s[78:79]
	global_load_dwordx4 v[92:95], v179, s[78:79] offset:1024
	v_add_u32_e32 v178, 0x400000, v178
	v_add_u32_e32 v179, 0x400000, v179
	global_load_dwordx4 v[96:99], v178, s[78:79]
	global_load_dwordx4 v[100:103], v178, s[78:79] offset:1024
	global_load_dwordx4 v[104:107], v179, s[78:79]
	global_load_dwordx4 v[108:111], v179, s[78:79] offset:1024
	v_add_u32_e32 v178, 0x400000, v178
	v_add_u32_e32 v179, 0x400000, v179
	global_load_dwordx4 v[112:115], v178, s[78:79]
	global_load_dwordx4 v[116:119], v178, s[78:79] offset:1024
	global_load_dwordx4 v[120:123], v179, s[78:79]
	global_load_dwordx4 v[124:127], v179, s[78:79] offset:1024
	v_lshlrev_b32_e32 v237, 2, v183
	v_add_u32_e32 v237, 0x10000, v237
	v_mov_b32_e32 v179, s98
	s_waitcnt vmcnt(28)
	v_lshlrev_b32_e32 v144, 16, v0
	v_and_b32_e32 v145, 0xffff0000, v0
	v_lshlrev_b32_e32 v146, 16, v1
	v_and_b32_e32 v147, 0xffff0000, v1
	v_lshlrev_b32_e32 v148, 16, v2
	v_and_b32_e32 v149, 0xffff0000, v2
	v_lshlrev_b32_e32 v150, 16, v3
	v_and_b32_e32 v151, 0xffff0000, v3
	v_lshlrev_b32_e32 v152, 16, v4
	v_and_b32_e32 v153, 0xffff0000, v4
	v_lshlrev_b32_e32 v154, 16, v5
	v_and_b32_e32 v155, 0xffff0000, v5
	v_lshlrev_b32_e32 v156, 16, v6
	v_and_b32_e32 v157, 0xffff0000, v6
	v_lshlrev_b32_e32 v158, 16, v7
	v_and_b32_e32 v159, 0xffff0000, v7
	v_lshlrev_b32_e32 v160, 16, v8
	v_and_b32_e32 v161, 0xffff0000, v8
	v_lshlrev_b32_e32 v162, 16, v9
	v_and_b32_e32 v163, 0xffff0000, v9
	v_lshlrev_b32_e32 v164, 16, v10
	v_and_b32_e32 v165, 0xffff0000, v10
	v_lshlrev_b32_e32 v166, 16, v11
	v_and_b32_e32 v167, 0xffff0000, v11
	v_lshlrev_b32_e32 v168, 16, v12
	v_and_b32_e32 v169, 0xffff0000, v12
	v_lshlrev_b32_e32 v170, 16, v13
	v_and_b32_e32 v171, 0xffff0000, v13
	v_lshlrev_b32_e32 v172, 16, v14
	v_and_b32_e32 v173, 0xffff0000, v14
	v_lshlrev_b32_e32 v174, 16, v15
	v_and_b32_e32 v175, 0xffff0000, v15
	v_pk_mul_f32 v[252:253], v[160:161], v[160:161]
	v_pk_mul_f32 v[254:255], v[162:163], v[162:163]
	v_pk_fma_f32 v[252:253], v[164:165], v[164:165], v[252:253]
	v_pk_fma_f32 v[254:255], v[166:167], v[166:167], v[254:255]
	v_pk_fma_f32 v[252:253], v[168:169], v[168:169], v[252:253]
	v_pk_fma_f32 v[254:255], v[170:171], v[170:171], v[254:255]
	v_pk_fma_f32 v[252:253], v[172:173], v[172:173], v[252:253]
	v_pk_fma_f32 v[254:255], v[174:175], v[174:175], v[254:255]
	v_pk_add_f32 v[252:253], v[252:253], v[254:255]
	s_nop 0
	v_add_f32_e32 v183, v252, v253
	s_nop 1
	v_add_f32_dpp v183, v183, v183 quad_perm:[1,0,3,2] row_mask:0xf bank_mask:0xf bound_ctrl:1
	s_nop 1
	v_add_f32_dpp v183, v183, v183 quad_perm:[2,3,0,1] row_mask:0xf bank_mask:0xf bound_ctrl:1
	s_nop 1
	v_add_f32_dpp v183, v183, v183 row_half_mirror row_mask:0xf bank_mask:0xf bound_ctrl:1
	s_nop 1
	v_add_f32_dpp v183, v183, v183 row_mirror row_mask:0xf bank_mask:0xf bound_ctrl:1
	s_nop 1
	v_readlane_b32 s98, v183, 0
	v_readlane_b32 s99, v183, 16
	v_readlane_b32 s100, v183, 32
	v_readlane_b32 s101, v183, 48
	s_nop 1
	v_mov_b32_e32 v183, s98
	v_add_f32_e32 v183, s99, v183
	v_add_f32_e32 v183, s100, v183
	v_add_f32_e32 v183, s101, v183
	v_fmamk_f32 v183, v183, 0x3a800000, v182
	v_cmp_gt_f32_e32 vcc, 0x800000, v183
	v_mul_f32_e32 v181, 0x4b800000, v183
	s_nop 1
	v_cndmask_b32_e32 v183, v183, v181, vcc
	v_rsq_f32_e32 v183, v183
	s_nop 0
	v_mul_f32_e32 v181, 0x45800000, v183
	v_cndmask_b32_e32 v184, v183, v181, vcc
	v_mov_b32_e32 v185, v184
	v_pk_mul_f32 v[160:161], v[160:161], v[184:185]
	v_pk_mul_f32 v[162:163], v[162:163], v[184:185]
	v_pk_mul_f32 v[164:165], v[164:165], v[184:185]
	v_pk_mul_f32 v[166:167], v[166:167], v[184:185]
	v_pk_mul_f32 v[168:169], v[168:169], v[184:185]
	v_pk_mul_f32 v[170:171], v[170:171], v[184:185]
	v_pk_mul_f32 v[172:173], v[172:173], v[184:185]
	v_pk_mul_f32 v[174:175], v[174:175], v[184:185]
	v_pk_fma_f32 v[144:145], v[160:161], v[128:129], v[144:145]
	v_pk_fma_f32 v[146:147], v[162:163], v[130:131], v[146:147]
	v_pk_fma_f32 v[148:149], v[164:165], v[132:133], v[148:149]
	v_pk_fma_f32 v[150:151], v[166:167], v[134:135], v[150:151]
	v_pk_fma_f32 v[152:153], v[168:169], v[136:137], v[152:153]
	v_pk_fma_f32 v[154:155], v[170:171], v[138:139], v[154:155]
	v_pk_fma_f32 v[156:157], v[172:173], v[140:141], v[156:157]
	v_pk_fma_f32 v[158:159], v[174:175], v[142:143], v[158:159]
	v_pk_mul_f32 v[252:253], v[144:145], v[144:145]
	v_pk_mul_f32 v[254:255], v[146:147], v[146:147]
	v_pk_fma_f32 v[252:253], v[148:149], v[148:149], v[252:253]
	v_pk_fma_f32 v[254:255], v[150:151], v[150:151], v[254:255]
	v_pk_fma_f32 v[252:253], v[152:153], v[152:153], v[252:253]
	v_pk_fma_f32 v[254:255], v[154:155], v[154:155], v[254:255]
	v_pk_fma_f32 v[252:253], v[156:157], v[156:157], v[252:253]
	v_pk_fma_f32 v[254:255], v[158:159], v[158:159], v[254:255]
	v_pk_add_f32 v[252:253], v[252:253], v[254:255]
	s_nop 0
	v_add_f32_e32 v183, v252, v253
	s_nop 1
	v_add_f32_dpp v183, v183, v183 quad_perm:[1,0,3,2] row_mask:0xf bank_mask:0xf bound_ctrl:1
	s_nop 1
	v_add_f32_dpp v183, v183, v183 quad_perm:[2,3,0,1] row_mask:0xf bank_mask:0xf bound_ctrl:1
	s_nop 1
	v_add_f32_dpp v183, v183, v183 row_half_mirror row_mask:0xf bank_mask:0xf bound_ctrl:1
	s_nop 1
	v_add_f32_dpp v183, v183, v183 row_mirror row_mask:0xf bank_mask:0xf bound_ctrl:1
	s_nop 1
	v_readlane_b32 s98, v183, 0
	v_readlane_b32 s99, v183, 16
	v_readlane_b32 s100, v183, 32
	v_readlane_b32 s101, v183, 48
	s_nop 1
	v_mov_b32_e32 v183, s98
	v_add_f32_e32 v183, s99, v183
	v_add_f32_e32 v183, s100, v183
	v_add_f32_e32 v183, s101, v183
	v_fmamk_f32 v183, v183, 0x3a800000, v182
	v_cmp_gt_f32_e32 vcc, 0x800000, v183
	v_mul_f32_e32 v181, 0x4b800000, v183
	s_nop 1
	v_cndmask_b32_e32 v183, v183, v181, vcc
	v_rsq_f32_e32 v183, v183
	s_nop 0
	v_mul_f32_e32 v181, 0x45800000, v183
	v_cndmask_b32_e32 v184, v183, v181, vcc
	v_mov_b32_e32 v185, v184
	v_cvt_pk_bf16_f32 v0, v144, v145
	v_cvt_pk_bf16_f32 v1, v146, v147
	v_cvt_pk_bf16_f32 v2, v148, v149
	v_cvt_pk_bf16_f32 v3, v150, v151
	v_cvt_pk_bf16_f32 v4, v152, v153
	v_cvt_pk_bf16_f32 v5, v154, v155
	v_cvt_pk_bf16_f32 v6, v156, v157
	v_cvt_pk_bf16_f32 v7, v158, v159
	v_add_u32_e32 v181, 0x1800000, v177
	global_store_dwordx4 v181, v[0:3], s[78:79]
	global_store_dwordx4 v181, v[4:7], s[78:79] offset:1024
	v_add_u32_e32 v236, 0x0, v237
	s_mov_b64 exec, 1
	global_store_dword v236, v184, s[78:79]
	s_mov_b64 exec, -1
	s_waitcnt vmcnt(24)
	v_lshlrev_b32_e32 v144, 16, v16
	v_and_b32_e32 v145, 0xffff0000, v16
	v_lshlrev_b32_e32 v146, 16, v17
	v_and_b32_e32 v147, 0xffff0000, v17
	v_lshlrev_b32_e32 v148, 16, v18
	v_and_b32_e32 v149, 0xffff0000, v18
	v_lshlrev_b32_e32 v150, 16, v19
	v_and_b32_e32 v151, 0xffff0000, v19
	v_lshlrev_b32_e32 v152, 16, v20
	v_and_b32_e32 v153, 0xffff0000, v20
	v_lshlrev_b32_e32 v154, 16, v21
	v_and_b32_e32 v155, 0xffff0000, v21
	v_lshlrev_b32_e32 v156, 16, v22
	v_and_b32_e32 v157, 0xffff0000, v22
	v_lshlrev_b32_e32 v158, 16, v23
	v_and_b32_e32 v159, 0xffff0000, v23
	v_lshlrev_b32_e32 v160, 16, v24
	v_and_b32_e32 v161, 0xffff0000, v24
	v_lshlrev_b32_e32 v162, 16, v25
	v_and_b32_e32 v163, 0xffff0000, v25
	v_lshlrev_b32_e32 v164, 16, v26
	v_and_b32_e32 v165, 0xffff0000, v26
	v_lshlrev_b32_e32 v166, 16, v27
	v_and_b32_e32 v167, 0xffff0000, v27
	v_lshlrev_b32_e32 v168, 16, v28
	v_and_b32_e32 v169, 0xffff0000, v28
	v_lshlrev_b32_e32 v170, 16, v29
	v_and_b32_e32 v171, 0xffff0000, v29
	v_lshlrev_b32_e32 v172, 16, v30
	v_and_b32_e32 v173, 0xffff0000, v30
	v_lshlrev_b32_e32 v174, 16, v31
	v_and_b32_e32 v175, 0xffff0000, v31
	v_pk_mul_f32 v[252:253], v[160:161], v[160:161]
	v_pk_mul_f32 v[254:255], v[162:163], v[162:163]
	v_pk_fma_f32 v[252:253], v[164:165], v[164:165], v[252:253]
	v_pk_fma_f32 v[254:255], v[166:167], v[166:167], v[254:255]
	v_pk_fma_f32 v[252:253], v[168:169], v[168:169], v[252:253]
	v_pk_fma_f32 v[254:255], v[170:171], v[170:171], v[254:255]
	v_pk_fma_f32 v[252:253], v[172:173], v[172:173], v[252:253]
	v_pk_fma_f32 v[254:255], v[174:175], v[174:175], v[254:255]
	v_pk_add_f32 v[252:253], v[252:253], v[254:255]
	s_nop 0
	v_add_f32_e32 v183, v252, v253
	s_nop 1
	v_add_f32_dpp v183, v183, v183 quad_perm:[1,0,3,2] row_mask:0xf bank_mask:0xf bound_ctrl:1
	s_nop 1
	v_add_f32_dpp v183, v183, v183 quad_perm:[2,3,0,1] row_mask:0xf bank_mask:0xf bound_ctrl:1
	s_nop 1
	v_add_f32_dpp v183, v183, v183 row_half_mirror row_mask:0xf bank_mask:0xf bound_ctrl:1
	s_nop 1
	v_add_f32_dpp v183, v183, v183 row_mirror row_mask:0xf bank_mask:0xf bound_ctrl:1
	s_nop 1
	v_readlane_b32 s98, v183, 0
	v_readlane_b32 s99, v183, 16
	v_readlane_b32 s100, v183, 32
	v_readlane_b32 s101, v183, 48
	s_nop 1
	v_mov_b32_e32 v183, s98
	v_add_f32_e32 v183, s99, v183
	v_add_f32_e32 v183, s100, v183
	v_add_f32_e32 v183, s101, v183
	v_fmamk_f32 v183, v183, 0x3a800000, v182
	v_cmp_gt_f32_e32 vcc, 0x800000, v183
	v_mul_f32_e32 v181, 0x4b800000, v183
	s_nop 1
	v_cndmask_b32_e32 v183, v183, v181, vcc
	v_rsq_f32_e32 v183, v183
	s_nop 0
	v_mul_f32_e32 v181, 0x45800000, v183
	v_cndmask_b32_e32 v184, v183, v181, vcc
	v_mov_b32_e32 v185, v184
	v_pk_mul_f32 v[160:161], v[160:161], v[184:185]
	v_pk_mul_f32 v[162:163], v[162:163], v[184:185]
	v_pk_mul_f32 v[164:165], v[164:165], v[184:185]
	v_pk_mul_f32 v[166:167], v[166:167], v[184:185]
	v_pk_mul_f32 v[168:169], v[168:169], v[184:185]
	v_pk_mul_f32 v[170:171], v[170:171], v[184:185]
	v_pk_mul_f32 v[172:173], v[172:173], v[184:185]
	v_pk_mul_f32 v[174:175], v[174:175], v[184:185]
	v_pk_fma_f32 v[144:145], v[160:161], v[128:129], v[144:145]
	v_pk_fma_f32 v[146:147], v[162:163], v[130:131], v[146:147]
	v_pk_fma_f32 v[148:149], v[164:165], v[132:133], v[148:149]
	v_pk_fma_f32 v[150:151], v[166:167], v[134:135], v[150:151]
	v_pk_fma_f32 v[152:153], v[168:169], v[136:137], v[152:153]
	v_pk_fma_f32 v[154:155], v[170:171], v[138:139], v[154:155]
	v_pk_fma_f32 v[156:157], v[172:173], v[140:141], v[156:157]
	v_pk_fma_f32 v[158:159], v[174:175], v[142:143], v[158:159]
	v_pk_mul_f32 v[252:253], v[144:145], v[144:145]
	v_pk_mul_f32 v[254:255], v[146:147], v[146:147]
	v_pk_fma_f32 v[252:253], v[148:149], v[148:149], v[252:253]
	v_pk_fma_f32 v[254:255], v[150:151], v[150:151], v[254:255]
	v_pk_fma_f32 v[252:253], v[152:153], v[152:153], v[252:253]
	v_pk_fma_f32 v[254:255], v[154:155], v[154:155], v[254:255]
	v_pk_fma_f32 v[252:253], v[156:157], v[156:157], v[252:253]
	v_pk_fma_f32 v[254:255], v[158:159], v[158:159], v[254:255]
	v_pk_add_f32 v[252:253], v[252:253], v[254:255]
	s_nop 0
	v_add_f32_e32 v183, v252, v253
	s_nop 1
	v_add_f32_dpp v183, v183, v183 quad_perm:[1,0,3,2] row_mask:0xf bank_mask:0xf bound_ctrl:1
	s_nop 1
	v_add_f32_dpp v183, v183, v183 quad_perm:[2,3,0,1] row_mask:0xf bank_mask:0xf bound_ctrl:1
	s_nop 1
	v_add_f32_dpp v183, v183, v183 row_half_mirror row_mask:0xf bank_mask:0xf bound_ctrl:1
	s_nop 1
	v_add_f32_dpp v183, v183, v183 row_mirror row_mask:0xf bank_mask:0xf bound_ctrl:1
	s_nop 1
	v_readlane_b32 s98, v183, 0
	v_readlane_b32 s99, v183, 16
	v_readlane_b32 s100, v183, 32
	v_readlane_b32 s101, v183, 48
	s_nop 1
	v_mov_b32_e32 v183, s98
	v_add_f32_e32 v183, s99, v183
	v_add_f32_e32 v183, s100, v183
	v_add_f32_e32 v183, s101, v183
	v_fmamk_f32 v183, v183, 0x3a800000, v182
	v_cmp_gt_f32_e32 vcc, 0x800000, v183
	v_mul_f32_e32 v181, 0x4b800000, v183
	s_nop 1
	v_cndmask_b32_e32 v183, v183, v181, vcc
	v_rsq_f32_e32 v183, v183
	s_nop 0
	v_mul_f32_e32 v181, 0x45800000, v183
	v_cndmask_b32_e32 v184, v183, v181, vcc
	v_mov_b32_e32 v185, v184
	v_cvt_pk_bf16_f32 v16, v144, v145
	v_cvt_pk_bf16_f32 v17, v146, v147
	v_cvt_pk_bf16_f32 v18, v148, v149
	v_cvt_pk_bf16_f32 v19, v150, v151
	v_cvt_pk_bf16_f32 v20, v152, v153
	v_cvt_pk_bf16_f32 v21, v154, v155
	v_cvt_pk_bf16_f32 v22, v156, v157
	v_cvt_pk_bf16_f32 v23, v158, v159
	v_add_u32_e32 v181, 0x1c00000, v177
	global_store_dwordx4 v181, v[16:19], s[78:79]
	global_store_dwordx4 v181, v[20:23], s[78:79] offset:1024
	v_add_u32_e32 v236, 0x2000, v237
	s_mov_b64 exec, 1
	global_store_dword v236, v184, s[78:79]
	s_mov_b64 exec, -1
	s_waitcnt vmcnt(20)
	v_lshlrev_b32_e32 v144, 16, v32
	v_and_b32_e32 v145, 0xffff0000, v32
	v_lshlrev_b32_e32 v146, 16, v33
	v_and_b32_e32 v147, 0xffff0000, v33
	v_lshlrev_b32_e32 v148, 16, v34
	v_and_b32_e32 v149, 0xffff0000, v34
	v_lshlrev_b32_e32 v150, 16, v35
	v_and_b32_e32 v151, 0xffff0000, v35
	v_lshlrev_b32_e32 v152, 16, v36
	v_and_b32_e32 v153, 0xffff0000, v36
	v_lshlrev_b32_e32 v154, 16, v37
	v_and_b32_e32 v155, 0xffff0000, v37
	v_lshlrev_b32_e32 v156, 16, v38
	v_and_b32_e32 v157, 0xffff0000, v38
	v_lshlrev_b32_e32 v158, 16, v39
	v_and_b32_e32 v159, 0xffff0000, v39
	v_lshlrev_b32_e32 v160, 16, v40
	v_and_b32_e32 v161, 0xffff0000, v40
	v_lshlrev_b32_e32 v162, 16, v41
	v_and_b32_e32 v163, 0xffff0000, v41
	v_lshlrev_b32_e32 v164, 16, v42
	v_and_b32_e32 v165, 0xffff0000, v42
	v_lshlrev_b32_e32 v166, 16, v43
	v_and_b32_e32 v167, 0xffff0000, v43
	v_lshlrev_b32_e32 v168, 16, v44
	v_and_b32_e32 v169, 0xffff0000, v44
	v_lshlrev_b32_e32 v170, 16, v45
	v_and_b32_e32 v171, 0xffff0000, v45
	v_lshlrev_b32_e32 v172, 16, v46
	v_and_b32_e32 v173, 0xffff0000, v46
	v_lshlrev_b32_e32 v174, 16, v47
	v_and_b32_e32 v175, 0xffff0000, v47
	v_pk_mul_f32 v[252:253], v[160:161], v[160:161]
	v_pk_mul_f32 v[254:255], v[162:163], v[162:163]
	v_pk_fma_f32 v[252:253], v[164:165], v[164:165], v[252:253]
	v_pk_fma_f32 v[254:255], v[166:167], v[166:167], v[254:255]
	v_pk_fma_f32 v[252:253], v[168:169], v[168:169], v[252:253]
	v_pk_fma_f32 v[254:255], v[170:171], v[170:171], v[254:255]
	v_pk_fma_f32 v[252:253], v[172:173], v[172:173], v[252:253]
	v_pk_fma_f32 v[254:255], v[174:175], v[174:175], v[254:255]
	v_pk_add_f32 v[252:253], v[252:253], v[254:255]
	s_nop 0
	v_add_f32_e32 v183, v252, v253
	s_nop 1
	v_add_f32_dpp v183, v183, v183 quad_perm:[1,0,3,2] row_mask:0xf bank_mask:0xf bound_ctrl:1
	s_nop 1
	v_add_f32_dpp v183, v183, v183 quad_perm:[2,3,0,1] row_mask:0xf bank_mask:0xf bound_ctrl:1
	s_nop 1
	v_add_f32_dpp v183, v183, v183 row_half_mirror row_mask:0xf bank_mask:0xf bound_ctrl:1
	s_nop 1
	v_add_f32_dpp v183, v183, v183 row_mirror row_mask:0xf bank_mask:0xf bound_ctrl:1
	s_nop 1
	v_readlane_b32 s98, v183, 0
	v_readlane_b32 s99, v183, 16
	v_readlane_b32 s100, v183, 32
	v_readlane_b32 s101, v183, 48
	s_nop 1
	v_mov_b32_e32 v183, s98
	v_add_f32_e32 v183, s99, v183
	v_add_f32_e32 v183, s100, v183
	v_add_f32_e32 v183, s101, v183
	v_fmamk_f32 v183, v183, 0x3a800000, v182
	v_cmp_gt_f32_e32 vcc, 0x800000, v183
	v_mul_f32_e32 v181, 0x4b800000, v183
	s_nop 1
	v_cndmask_b32_e32 v183, v183, v181, vcc
	v_rsq_f32_e32 v183, v183
	s_nop 0
	v_mul_f32_e32 v181, 0x45800000, v183
	v_cndmask_b32_e32 v184, v183, v181, vcc
	v_mov_b32_e32 v185, v184
	v_pk_mul_f32 v[160:161], v[160:161], v[184:185]
	v_pk_mul_f32 v[162:163], v[162:163], v[184:185]
	v_pk_mul_f32 v[164:165], v[164:165], v[184:185]
	v_pk_mul_f32 v[166:167], v[166:167], v[184:185]
	v_pk_mul_f32 v[168:169], v[168:169], v[184:185]
	v_pk_mul_f32 v[170:171], v[170:171], v[184:185]
	v_pk_mul_f32 v[172:173], v[172:173], v[184:185]
	v_pk_mul_f32 v[174:175], v[174:175], v[184:185]
	v_pk_fma_f32 v[144:145], v[160:161], v[128:129], v[144:145]
	v_pk_fma_f32 v[146:147], v[162:163], v[130:131], v[146:147]
	v_pk_fma_f32 v[148:149], v[164:165], v[132:133], v[148:149]
	v_pk_fma_f32 v[150:151], v[166:167], v[134:135], v[150:151]
	v_pk_fma_f32 v[152:153], v[168:169], v[136:137], v[152:153]
	v_pk_fma_f32 v[154:155], v[170:171], v[138:139], v[154:155]
	v_pk_fma_f32 v[156:157], v[172:173], v[140:141], v[156:157]
	v_pk_fma_f32 v[158:159], v[174:175], v[142:143], v[158:159]
	v_pk_mul_f32 v[252:253], v[144:145], v[144:145]
	v_pk_mul_f32 v[254:255], v[146:147], v[146:147]
	v_pk_fma_f32 v[252:253], v[148:149], v[148:149], v[252:253]
	v_pk_fma_f32 v[254:255], v[150:151], v[150:151], v[254:255]
	v_pk_fma_f32 v[252:253], v[152:153], v[152:153], v[252:253]
	v_pk_fma_f32 v[254:255], v[154:155], v[154:155], v[254:255]
	v_pk_fma_f32 v[252:253], v[156:157], v[156:157], v[252:253]
	v_pk_fma_f32 v[254:255], v[158:159], v[158:159], v[254:255]
	v_pk_add_f32 v[252:253], v[252:253], v[254:255]
	s_nop 0
	v_add_f32_e32 v183, v252, v253
	s_nop 1
	v_add_f32_dpp v183, v183, v183 quad_perm:[1,0,3,2] row_mask:0xf bank_mask:0xf bound_ctrl:1
	s_nop 1
	v_add_f32_dpp v183, v183, v183 quad_perm:[2,3,0,1] row_mask:0xf bank_mask:0xf bound_ctrl:1
	s_nop 1
	v_add_f32_dpp v183, v183, v183 row_half_mirror row_mask:0xf bank_mask:0xf bound_ctrl:1
	s_nop 1
	v_add_f32_dpp v183, v183, v183 row_mirror row_mask:0xf bank_mask:0xf bound_ctrl:1
	s_nop 1
	v_readlane_b32 s98, v183, 0
	v_readlane_b32 s99, v183, 16
	v_readlane_b32 s100, v183, 32
	v_readlane_b32 s101, v183, 48
	s_nop 1
	v_mov_b32_e32 v183, s98
	v_add_f32_e32 v183, s99, v183
	v_add_f32_e32 v183, s100, v183
	v_add_f32_e32 v183, s101, v183
	v_fmamk_f32 v183, v183, 0x3a800000, v182
	v_cmp_gt_f32_e32 vcc, 0x800000, v183
	v_mul_f32_e32 v181, 0x4b800000, v183
	s_nop 1
	v_cndmask_b32_e32 v183, v183, v181, vcc
	v_rsq_f32_e32 v183, v183
	s_nop 0
	v_mul_f32_e32 v181, 0x45800000, v183
	v_cndmask_b32_e32 v184, v183, v181, vcc
	v_mov_b32_e32 v185, v184
	v_cvt_pk_bf16_f32 v32, v144, v145
	v_cvt_pk_bf16_f32 v33, v146, v147
	v_cvt_pk_bf16_f32 v34, v148, v149
	v_cvt_pk_bf16_f32 v35, v150, v151
	v_cvt_pk_bf16_f32 v36, v152, v153
	v_cvt_pk_bf16_f32 v37, v154, v155
	v_cvt_pk_bf16_f32 v38, v156, v157
	v_cvt_pk_bf16_f32 v39, v158, v159
	v_add_u32_e32 v181, 0x2000000, v177
	global_store_dwordx4 v181, v[32:35], s[78:79]
	global_store_dwordx4 v181, v[36:39], s[78:79] offset:1024
	v_add_u32_e32 v236, 0x4000, v237
	s_mov_b64 exec, 1
	global_store_dword v236, v184, s[78:79]
	s_mov_b64 exec, -1
	s_waitcnt vmcnt(16)
	v_lshlrev_b32_e32 v144, 16, v48
	v_and_b32_e32 v145, 0xffff0000, v48
	v_lshlrev_b32_e32 v146, 16, v49
	v_and_b32_e32 v147, 0xffff0000, v49
	v_lshlrev_b32_e32 v148, 16, v50
	v_and_b32_e32 v149, 0xffff0000, v50
	v_lshlrev_b32_e32 v150, 16, v51
	v_and_b32_e32 v151, 0xffff0000, v51
	v_lshlrev_b32_e32 v152, 16, v52
	v_and_b32_e32 v153, 0xffff0000, v52
	v_lshlrev_b32_e32 v154, 16, v53
	v_and_b32_e32 v155, 0xffff0000, v53
	v_lshlrev_b32_e32 v156, 16, v54
	v_and_b32_e32 v157, 0xffff0000, v54
	v_lshlrev_b32_e32 v158, 16, v55
	v_and_b32_e32 v159, 0xffff0000, v55
	v_lshlrev_b32_e32 v160, 16, v56
	v_and_b32_e32 v161, 0xffff0000, v56
	v_lshlrev_b32_e32 v162, 16, v57
	v_and_b32_e32 v163, 0xffff0000, v57
	v_lshlrev_b32_e32 v164, 16, v58
	v_and_b32_e32 v165, 0xffff0000, v58
	v_lshlrev_b32_e32 v166, 16, v59
	v_and_b32_e32 v167, 0xffff0000, v59
	v_lshlrev_b32_e32 v168, 16, v60
	v_and_b32_e32 v169, 0xffff0000, v60
	v_lshlrev_b32_e32 v170, 16, v61
	v_and_b32_e32 v171, 0xffff0000, v61
	v_lshlrev_b32_e32 v172, 16, v62
	v_and_b32_e32 v173, 0xffff0000, v62
	v_lshlrev_b32_e32 v174, 16, v63
	v_and_b32_e32 v175, 0xffff0000, v63
	v_pk_mul_f32 v[252:253], v[160:161], v[160:161]
	v_pk_mul_f32 v[254:255], v[162:163], v[162:163]
	v_pk_fma_f32 v[252:253], v[164:165], v[164:165], v[252:253]
	v_pk_fma_f32 v[254:255], v[166:167], v[166:167], v[254:255]
	v_pk_fma_f32 v[252:253], v[168:169], v[168:169], v[252:253]
	v_pk_fma_f32 v[254:255], v[170:171], v[170:171], v[254:255]
	v_pk_fma_f32 v[252:253], v[172:173], v[172:173], v[252:253]
	v_pk_fma_f32 v[254:255], v[174:175], v[174:175], v[254:255]
	v_pk_add_f32 v[252:253], v[252:253], v[254:255]
	s_nop 0
	v_add_f32_e32 v183, v252, v253
	s_nop 1
	v_add_f32_dpp v183, v183, v183 quad_perm:[1,0,3,2] row_mask:0xf bank_mask:0xf bound_ctrl:1
	s_nop 1
	v_add_f32_dpp v183, v183, v183 quad_perm:[2,3,0,1] row_mask:0xf bank_mask:0xf bound_ctrl:1
	s_nop 1
	v_add_f32_dpp v183, v183, v183 row_half_mirror row_mask:0xf bank_mask:0xf bound_ctrl:1
	s_nop 1
	v_add_f32_dpp v183, v183, v183 row_mirror row_mask:0xf bank_mask:0xf bound_ctrl:1
	s_nop 1
	v_readlane_b32 s98, v183, 0
	v_readlane_b32 s99, v183, 16
	v_readlane_b32 s100, v183, 32
	v_readlane_b32 s101, v183, 48
	s_nop 1
	v_mov_b32_e32 v183, s98
	v_add_f32_e32 v183, s99, v183
	v_add_f32_e32 v183, s100, v183
	v_add_f32_e32 v183, s101, v183
	v_fmamk_f32 v183, v183, 0x3a800000, v182
	v_cmp_gt_f32_e32 vcc, 0x800000, v183
	v_mul_f32_e32 v181, 0x4b800000, v183
	s_nop 1
	v_cndmask_b32_e32 v183, v183, v181, vcc
	v_rsq_f32_e32 v183, v183
	s_nop 0
	v_mul_f32_e32 v181, 0x45800000, v183
	v_cndmask_b32_e32 v184, v183, v181, vcc
	v_mov_b32_e32 v185, v184
	v_pk_mul_f32 v[160:161], v[160:161], v[184:185]
	v_pk_mul_f32 v[162:163], v[162:163], v[184:185]
	v_pk_mul_f32 v[164:165], v[164:165], v[184:185]
	v_pk_mul_f32 v[166:167], v[166:167], v[184:185]
	v_pk_mul_f32 v[168:169], v[168:169], v[184:185]
	v_pk_mul_f32 v[170:171], v[170:171], v[184:185]
	v_pk_mul_f32 v[172:173], v[172:173], v[184:185]
	v_pk_mul_f32 v[174:175], v[174:175], v[184:185]
	v_pk_fma_f32 v[144:145], v[160:161], v[128:129], v[144:145]
	v_pk_fma_f32 v[146:147], v[162:163], v[130:131], v[146:147]
	v_pk_fma_f32 v[148:149], v[164:165], v[132:133], v[148:149]
	v_pk_fma_f32 v[150:151], v[166:167], v[134:135], v[150:151]
	v_pk_fma_f32 v[152:153], v[168:169], v[136:137], v[152:153]
	v_pk_fma_f32 v[154:155], v[170:171], v[138:139], v[154:155]
	v_pk_fma_f32 v[156:157], v[172:173], v[140:141], v[156:157]
	v_pk_fma_f32 v[158:159], v[174:175], v[142:143], v[158:159]
	v_pk_mul_f32 v[252:253], v[144:145], v[144:145]
	v_pk_mul_f32 v[254:255], v[146:147], v[146:147]
	v_pk_fma_f32 v[252:253], v[148:149], v[148:149], v[252:253]
	v_pk_fma_f32 v[254:255], v[150:151], v[150:151], v[254:255]
	v_pk_fma_f32 v[252:253], v[152:153], v[152:153], v[252:253]
	v_pk_fma_f32 v[254:255], v[154:155], v[154:155], v[254:255]
	v_pk_fma_f32 v[252:253], v[156:157], v[156:157], v[252:253]
	v_pk_fma_f32 v[254:255], v[158:159], v[158:159], v[254:255]
	v_pk_add_f32 v[252:253], v[252:253], v[254:255]
	s_nop 0
	v_add_f32_e32 v183, v252, v253
	s_nop 1
	v_add_f32_dpp v183, v183, v183 quad_perm:[1,0,3,2] row_mask:0xf bank_mask:0xf bound_ctrl:1
	s_nop 1
	v_add_f32_dpp v183, v183, v183 quad_perm:[2,3,0,1] row_mask:0xf bank_mask:0xf bound_ctrl:1
	s_nop 1
	v_add_f32_dpp v183, v183, v183 row_half_mirror row_mask:0xf bank_mask:0xf bound_ctrl:1
	s_nop 1
	v_add_f32_dpp v183, v183, v183 row_mirror row_mask:0xf bank_mask:0xf bound_ctrl:1
	s_nop 1
	v_readlane_b32 s98, v183, 0
	v_readlane_b32 s99, v183, 16
	v_readlane_b32 s100, v183, 32
	v_readlane_b32 s101, v183, 48
	s_nop 1
	v_mov_b32_e32 v183, s98
	v_add_f32_e32 v183, s99, v183
	v_add_f32_e32 v183, s100, v183
	v_add_f32_e32 v183, s101, v183
	v_fmamk_f32 v183, v183, 0x3a800000, v182
	v_cmp_gt_f32_e32 vcc, 0x800000, v183
	v_mul_f32_e32 v181, 0x4b800000, v183
	s_nop 1
	v_cndmask_b32_e32 v183, v183, v181, vcc
	v_rsq_f32_e32 v183, v183
	s_nop 0
	v_mul_f32_e32 v181, 0x45800000, v183
	v_cndmask_b32_e32 v184, v183, v181, vcc
	v_mov_b32_e32 v185, v184
	v_cvt_pk_bf16_f32 v48, v144, v145
	v_cvt_pk_bf16_f32 v49, v146, v147
	v_cvt_pk_bf16_f32 v50, v148, v149
	v_cvt_pk_bf16_f32 v51, v150, v151
	v_cvt_pk_bf16_f32 v52, v152, v153
	v_cvt_pk_bf16_f32 v53, v154, v155
	v_cvt_pk_bf16_f32 v54, v156, v157
	v_cvt_pk_bf16_f32 v55, v158, v159
	v_add_u32_e32 v181, 0x2400000, v177
	global_store_dwordx4 v181, v[48:51], s[78:79]
	global_store_dwordx4 v181, v[52:55], s[78:79] offset:1024
	v_add_u32_e32 v236, 0x6000, v237
	s_mov_b64 exec, 1
	global_store_dword v236, v184, s[78:79]
	s_mov_b64 exec, -1
	s_waitcnt vmcnt(12)
	v_lshlrev_b32_e32 v144, 16, v64
	v_and_b32_e32 v145, 0xffff0000, v64
	v_lshlrev_b32_e32 v146, 16, v65
	v_and_b32_e32 v147, 0xffff0000, v65
	v_lshlrev_b32_e32 v148, 16, v66
	v_and_b32_e32 v149, 0xffff0000, v66
	v_lshlrev_b32_e32 v150, 16, v67
	v_and_b32_e32 v151, 0xffff0000, v67
	v_lshlrev_b32_e32 v152, 16, v68
	v_and_b32_e32 v153, 0xffff0000, v68
	v_lshlrev_b32_e32 v154, 16, v69
	v_and_b32_e32 v155, 0xffff0000, v69
	v_lshlrev_b32_e32 v156, 16, v70
	v_and_b32_e32 v157, 0xffff0000, v70
	v_lshlrev_b32_e32 v158, 16, v71
	v_and_b32_e32 v159, 0xffff0000, v71
	v_lshlrev_b32_e32 v160, 16, v72
	v_and_b32_e32 v161, 0xffff0000, v72
	v_lshlrev_b32_e32 v162, 16, v73
	v_and_b32_e32 v163, 0xffff0000, v73
	v_lshlrev_b32_e32 v164, 16, v74
	v_and_b32_e32 v165, 0xffff0000, v74
	v_lshlrev_b32_e32 v166, 16, v75
	v_and_b32_e32 v167, 0xffff0000, v75
	v_lshlrev_b32_e32 v168, 16, v76
	v_and_b32_e32 v169, 0xffff0000, v76
	v_lshlrev_b32_e32 v170, 16, v77
	v_and_b32_e32 v171, 0xffff0000, v77
	v_lshlrev_b32_e32 v172, 16, v78
	v_and_b32_e32 v173, 0xffff0000, v78
	v_lshlrev_b32_e32 v174, 16, v79
	v_and_b32_e32 v175, 0xffff0000, v79
	v_pk_mul_f32 v[252:253], v[160:161], v[160:161]
	v_pk_mul_f32 v[254:255], v[162:163], v[162:163]
	v_pk_fma_f32 v[252:253], v[164:165], v[164:165], v[252:253]
	v_pk_fma_f32 v[254:255], v[166:167], v[166:167], v[254:255]
	v_pk_fma_f32 v[252:253], v[168:169], v[168:169], v[252:253]
	v_pk_fma_f32 v[254:255], v[170:171], v[170:171], v[254:255]
	v_pk_fma_f32 v[252:253], v[172:173], v[172:173], v[252:253]
	v_pk_fma_f32 v[254:255], v[174:175], v[174:175], v[254:255]
	v_pk_add_f32 v[252:253], v[252:253], v[254:255]
	s_nop 0
	v_add_f32_e32 v183, v252, v253
	s_nop 1
	v_add_f32_dpp v183, v183, v183 quad_perm:[1,0,3,2] row_mask:0xf bank_mask:0xf bound_ctrl:1
	s_nop 1
	v_add_f32_dpp v183, v183, v183 quad_perm:[2,3,0,1] row_mask:0xf bank_mask:0xf bound_ctrl:1
	s_nop 1
	v_add_f32_dpp v183, v183, v183 row_half_mirror row_mask:0xf bank_mask:0xf bound_ctrl:1
	s_nop 1
	v_add_f32_dpp v183, v183, v183 row_mirror row_mask:0xf bank_mask:0xf bound_ctrl:1
	s_nop 1
	v_readlane_b32 s98, v183, 0
	v_readlane_b32 s99, v183, 16
	v_readlane_b32 s100, v183, 32
	v_readlane_b32 s101, v183, 48
	s_nop 1
	v_mov_b32_e32 v183, s98
	v_add_f32_e32 v183, s99, v183
	v_add_f32_e32 v183, s100, v183
	v_add_f32_e32 v183, s101, v183
	v_fmamk_f32 v183, v183, 0x3a800000, v182
	v_cmp_gt_f32_e32 vcc, 0x800000, v183
	v_mul_f32_e32 v181, 0x4b800000, v183
	s_nop 1
	v_cndmask_b32_e32 v183, v183, v181, vcc
	v_rsq_f32_e32 v183, v183
	s_nop 0
	v_mul_f32_e32 v181, 0x45800000, v183
	v_cndmask_b32_e32 v184, v183, v181, vcc
	v_mov_b32_e32 v185, v184
	v_pk_mul_f32 v[160:161], v[160:161], v[184:185]
	v_pk_mul_f32 v[162:163], v[162:163], v[184:185]
	v_pk_mul_f32 v[164:165], v[164:165], v[184:185]
	v_pk_mul_f32 v[166:167], v[166:167], v[184:185]
	v_pk_mul_f32 v[168:169], v[168:169], v[184:185]
	v_pk_mul_f32 v[170:171], v[170:171], v[184:185]
	v_pk_mul_f32 v[172:173], v[172:173], v[184:185]
	v_pk_mul_f32 v[174:175], v[174:175], v[184:185]
	v_pk_fma_f32 v[144:145], v[160:161], v[128:129], v[144:145]
	v_pk_fma_f32 v[146:147], v[162:163], v[130:131], v[146:147]
	v_pk_fma_f32 v[148:149], v[164:165], v[132:133], v[148:149]
	v_pk_fma_f32 v[150:151], v[166:167], v[134:135], v[150:151]
	v_pk_fma_f32 v[152:153], v[168:169], v[136:137], v[152:153]
	v_pk_fma_f32 v[154:155], v[170:171], v[138:139], v[154:155]
	v_pk_fma_f32 v[156:157], v[172:173], v[140:141], v[156:157]
	v_pk_fma_f32 v[158:159], v[174:175], v[142:143], v[158:159]
	v_pk_mul_f32 v[252:253], v[144:145], v[144:145]
	v_pk_mul_f32 v[254:255], v[146:147], v[146:147]
	v_pk_fma_f32 v[252:253], v[148:149], v[148:149], v[252:253]
	v_pk_fma_f32 v[254:255], v[150:151], v[150:151], v[254:255]
	v_pk_fma_f32 v[252:253], v[152:153], v[152:153], v[252:253]
	v_pk_fma_f32 v[254:255], v[154:155], v[154:155], v[254:255]
	v_pk_fma_f32 v[252:253], v[156:157], v[156:157], v[252:253]
	v_pk_fma_f32 v[254:255], v[158:159], v[158:159], v[254:255]
	v_pk_add_f32 v[252:253], v[252:253], v[254:255]
	s_nop 0
	v_add_f32_e32 v183, v252, v253
	s_nop 1
	v_add_f32_dpp v183, v183, v183 quad_perm:[1,0,3,2] row_mask:0xf bank_mask:0xf bound_ctrl:1
	s_nop 1
	v_add_f32_dpp v183, v183, v183 quad_perm:[2,3,0,1] row_mask:0xf bank_mask:0xf bound_ctrl:1
	s_nop 1
	v_add_f32_dpp v183, v183, v183 row_half_mirror row_mask:0xf bank_mask:0xf bound_ctrl:1
	s_nop 1
	v_add_f32_dpp v183, v183, v183 row_mirror row_mask:0xf bank_mask:0xf bound_ctrl:1
	s_nop 1
	v_readlane_b32 s98, v183, 0
	v_readlane_b32 s99, v183, 16
	v_readlane_b32 s100, v183, 32
	v_readlane_b32 s101, v183, 48
	s_nop 1
	v_mov_b32_e32 v183, s98
	v_add_f32_e32 v183, s99, v183
	v_add_f32_e32 v183, s100, v183
	v_add_f32_e32 v183, s101, v183
	v_fmamk_f32 v183, v183, 0x3a800000, v182
	v_cmp_gt_f32_e32 vcc, 0x800000, v183
	v_mul_f32_e32 v181, 0x4b800000, v183
	s_nop 1
	v_cndmask_b32_e32 v183, v183, v181, vcc
	v_rsq_f32_e32 v183, v183
	s_nop 0
	v_mul_f32_e32 v181, 0x45800000, v183
	v_cndmask_b32_e32 v184, v183, v181, vcc
	v_mov_b32_e32 v185, v184
	v_cvt_pk_bf16_f32 v64, v144, v145
	v_cvt_pk_bf16_f32 v65, v146, v147
	v_cvt_pk_bf16_f32 v66, v148, v149
	v_cvt_pk_bf16_f32 v67, v150, v151
	v_cvt_pk_bf16_f32 v68, v152, v153
	v_cvt_pk_bf16_f32 v69, v154, v155
	v_cvt_pk_bf16_f32 v70, v156, v157
	v_cvt_pk_bf16_f32 v71, v158, v159
	v_add_u32_e32 v181, 0x2800000, v177
	global_store_dwordx4 v181, v[64:67], s[78:79]
	global_store_dwordx4 v181, v[68:71], s[78:79] offset:1024
	v_add_u32_e32 v236, 0x8000, v237
	s_mov_b64 exec, 1
	global_store_dword v236, v184, s[78:79]
	s_mov_b64 exec, -1
	s_waitcnt vmcnt(8)
	v_lshlrev_b32_e32 v144, 16, v80
	v_and_b32_e32 v145, 0xffff0000, v80
	v_lshlrev_b32_e32 v146, 16, v81
	v_and_b32_e32 v147, 0xffff0000, v81
	v_lshlrev_b32_e32 v148, 16, v82
	v_and_b32_e32 v149, 0xffff0000, v82
	v_lshlrev_b32_e32 v150, 16, v83
	v_and_b32_e32 v151, 0xffff0000, v83
	v_lshlrev_b32_e32 v152, 16, v84
	v_and_b32_e32 v153, 0xffff0000, v84
	v_lshlrev_b32_e32 v154, 16, v85
	v_and_b32_e32 v155, 0xffff0000, v85
	v_lshlrev_b32_e32 v156, 16, v86
	v_and_b32_e32 v157, 0xffff0000, v86
	v_lshlrev_b32_e32 v158, 16, v87
	v_and_b32_e32 v159, 0xffff0000, v87
	v_lshlrev_b32_e32 v160, 16, v88
	v_and_b32_e32 v161, 0xffff0000, v88
	v_lshlrev_b32_e32 v162, 16, v89
	v_and_b32_e32 v163, 0xffff0000, v89
	v_lshlrev_b32_e32 v164, 16, v90
	v_and_b32_e32 v165, 0xffff0000, v90
	v_lshlrev_b32_e32 v166, 16, v91
	v_and_b32_e32 v167, 0xffff0000, v91
	v_lshlrev_b32_e32 v168, 16, v92
	v_and_b32_e32 v169, 0xffff0000, v92
	v_lshlrev_b32_e32 v170, 16, v93
	v_and_b32_e32 v171, 0xffff0000, v93
	v_lshlrev_b32_e32 v172, 16, v94
	v_and_b32_e32 v173, 0xffff0000, v94
	v_lshlrev_b32_e32 v174, 16, v95
	v_and_b32_e32 v175, 0xffff0000, v95
	v_pk_mul_f32 v[252:253], v[160:161], v[160:161]
	v_pk_mul_f32 v[254:255], v[162:163], v[162:163]
	v_pk_fma_f32 v[252:253], v[164:165], v[164:165], v[252:253]
	v_pk_fma_f32 v[254:255], v[166:167], v[166:167], v[254:255]
	v_pk_fma_f32 v[252:253], v[168:169], v[168:169], v[252:253]
	v_pk_fma_f32 v[254:255], v[170:171], v[170:171], v[254:255]
	v_pk_fma_f32 v[252:253], v[172:173], v[172:173], v[252:253]
	v_pk_fma_f32 v[254:255], v[174:175], v[174:175], v[254:255]
	v_pk_add_f32 v[252:253], v[252:253], v[254:255]
	s_nop 0
	v_add_f32_e32 v183, v252, v253
	s_nop 1
	v_add_f32_dpp v183, v183, v183 quad_perm:[1,0,3,2] row_mask:0xf bank_mask:0xf bound_ctrl:1
	s_nop 1
	v_add_f32_dpp v183, v183, v183 quad_perm:[2,3,0,1] row_mask:0xf bank_mask:0xf bound_ctrl:1
	s_nop 1
	v_add_f32_dpp v183, v183, v183 row_half_mirror row_mask:0xf bank_mask:0xf bound_ctrl:1
	s_nop 1
	v_add_f32_dpp v183, v183, v183 row_mirror row_mask:0xf bank_mask:0xf bound_ctrl:1
	s_nop 1
	v_readlane_b32 s98, v183, 0
	v_readlane_b32 s99, v183, 16
	v_readlane_b32 s100, v183, 32
	v_readlane_b32 s101, v183, 48
	s_nop 1
	v_mov_b32_e32 v183, s98
	v_add_f32_e32 v183, s99, v183
	v_add_f32_e32 v183, s100, v183
	v_add_f32_e32 v183, s101, v183
	v_fmamk_f32 v183, v183, 0x3a800000, v182
	v_cmp_gt_f32_e32 vcc, 0x800000, v183
	v_mul_f32_e32 v181, 0x4b800000, v183
	s_nop 1
	v_cndmask_b32_e32 v183, v183, v181, vcc
	v_rsq_f32_e32 v183, v183
	s_nop 0
	v_mul_f32_e32 v181, 0x45800000, v183
	v_cndmask_b32_e32 v184, v183, v181, vcc
	v_mov_b32_e32 v185, v184
	v_pk_mul_f32 v[160:161], v[160:161], v[184:185]
	v_pk_mul_f32 v[162:163], v[162:163], v[184:185]
	v_pk_mul_f32 v[164:165], v[164:165], v[184:185]
	v_pk_mul_f32 v[166:167], v[166:167], v[184:185]
	v_pk_mul_f32 v[168:169], v[168:169], v[184:185]
	v_pk_mul_f32 v[170:171], v[170:171], v[184:185]
	v_pk_mul_f32 v[172:173], v[172:173], v[184:185]
	v_pk_mul_f32 v[174:175], v[174:175], v[184:185]
	v_pk_fma_f32 v[144:145], v[160:161], v[128:129], v[144:145]
	v_pk_fma_f32 v[146:147], v[162:163], v[130:131], v[146:147]
	v_pk_fma_f32 v[148:149], v[164:165], v[132:133], v[148:149]
	v_pk_fma_f32 v[150:151], v[166:167], v[134:135], v[150:151]
	v_pk_fma_f32 v[152:153], v[168:169], v[136:137], v[152:153]
	v_pk_fma_f32 v[154:155], v[170:171], v[138:139], v[154:155]
	v_pk_fma_f32 v[156:157], v[172:173], v[140:141], v[156:157]
	v_pk_fma_f32 v[158:159], v[174:175], v[142:143], v[158:159]
	v_pk_mul_f32 v[252:253], v[144:145], v[144:145]
	v_pk_mul_f32 v[254:255], v[146:147], v[146:147]
	v_pk_fma_f32 v[252:253], v[148:149], v[148:149], v[252:253]
	v_pk_fma_f32 v[254:255], v[150:151], v[150:151], v[254:255]
	v_pk_fma_f32 v[252:253], v[152:153], v[152:153], v[252:253]
	v_pk_fma_f32 v[254:255], v[154:155], v[154:155], v[254:255]
	v_pk_fma_f32 v[252:253], v[156:157], v[156:157], v[252:253]
	v_pk_fma_f32 v[254:255], v[158:159], v[158:159], v[254:255]
	v_pk_add_f32 v[252:253], v[252:253], v[254:255]
	s_nop 0
	v_add_f32_e32 v183, v252, v253
	s_nop 1
	v_add_f32_dpp v183, v183, v183 quad_perm:[1,0,3,2] row_mask:0xf bank_mask:0xf bound_ctrl:1
	s_nop 1
	v_add_f32_dpp v183, v183, v183 quad_perm:[2,3,0,1] row_mask:0xf bank_mask:0xf bound_ctrl:1
	s_nop 1
	v_add_f32_dpp v183, v183, v183 row_half_mirror row_mask:0xf bank_mask:0xf bound_ctrl:1
	s_nop 1
	v_add_f32_dpp v183, v183, v183 row_mirror row_mask:0xf bank_mask:0xf bound_ctrl:1
	s_nop 1
	v_readlane_b32 s98, v183, 0
	v_readlane_b32 s99, v183, 16
	v_readlane_b32 s100, v183, 32
	v_readlane_b32 s101, v183, 48
	s_nop 1
	v_mov_b32_e32 v183, s98
	v_add_f32_e32 v183, s99, v183
	v_add_f32_e32 v183, s100, v183
	v_add_f32_e32 v183, s101, v183
	v_fmamk_f32 v183, v183, 0x3a800000, v182
	v_cmp_gt_f32_e32 vcc, 0x800000, v183
	v_mul_f32_e32 v181, 0x4b800000, v183
	s_nop 1
	v_cndmask_b32_e32 v183, v183, v181, vcc
	v_rsq_f32_e32 v183, v183
	s_nop 0
	v_mul_f32_e32 v181, 0x45800000, v183
	v_cndmask_b32_e32 v184, v183, v181, vcc
	v_mov_b32_e32 v185, v184
	v_cvt_pk_bf16_f32 v80, v144, v145
	v_cvt_pk_bf16_f32 v81, v146, v147
	v_cvt_pk_bf16_f32 v82, v148, v149
	v_cvt_pk_bf16_f32 v83, v150, v151
	v_cvt_pk_bf16_f32 v84, v152, v153
	v_cvt_pk_bf16_f32 v85, v154, v155
	v_cvt_pk_bf16_f32 v86, v156, v157
	v_cvt_pk_bf16_f32 v87, v158, v159
	v_add_u32_e32 v181, 0x2c00000, v177
	global_store_dwordx4 v181, v[80:83], s[78:79]
	global_store_dwordx4 v181, v[84:87], s[78:79] offset:1024
	v_add_u32_e32 v236, 0xa000, v237
	s_mov_b64 exec, 1
	global_store_dword v236, v184, s[78:79]
	s_mov_b64 exec, -1
	s_waitcnt vmcnt(4)
	v_lshlrev_b32_e32 v144, 16, v96
	v_and_b32_e32 v145, 0xffff0000, v96
	v_lshlrev_b32_e32 v146, 16, v97
	v_and_b32_e32 v147, 0xffff0000, v97
	v_lshlrev_b32_e32 v148, 16, v98
	v_and_b32_e32 v149, 0xffff0000, v98
	v_lshlrev_b32_e32 v150, 16, v99
	v_and_b32_e32 v151, 0xffff0000, v99
	v_lshlrev_b32_e32 v152, 16, v100
	v_and_b32_e32 v153, 0xffff0000, v100
	v_lshlrev_b32_e32 v154, 16, v101
	v_and_b32_e32 v155, 0xffff0000, v101
	v_lshlrev_b32_e32 v156, 16, v102
	v_and_b32_e32 v157, 0xffff0000, v102
	v_lshlrev_b32_e32 v158, 16, v103
	v_and_b32_e32 v159, 0xffff0000, v103
	v_lshlrev_b32_e32 v160, 16, v104
	v_and_b32_e32 v161, 0xffff0000, v104
	v_lshlrev_b32_e32 v162, 16, v105
	v_and_b32_e32 v163, 0xffff0000, v105
	v_lshlrev_b32_e32 v164, 16, v106
	v_and_b32_e32 v165, 0xffff0000, v106
	v_lshlrev_b32_e32 v166, 16, v107
	v_and_b32_e32 v167, 0xffff0000, v107
	v_lshlrev_b32_e32 v168, 16, v108
	v_and_b32_e32 v169, 0xffff0000, v108
	v_lshlrev_b32_e32 v170, 16, v109
	v_and_b32_e32 v171, 0xffff0000, v109
	v_lshlrev_b32_e32 v172, 16, v110
	v_and_b32_e32 v173, 0xffff0000, v110
	v_lshlrev_b32_e32 v174, 16, v111
	v_and_b32_e32 v175, 0xffff0000, v111
	v_pk_mul_f32 v[252:253], v[160:161], v[160:161]
	v_pk_mul_f32 v[254:255], v[162:163], v[162:163]
	v_pk_fma_f32 v[252:253], v[164:165], v[164:165], v[252:253]
	v_pk_fma_f32 v[254:255], v[166:167], v[166:167], v[254:255]
	v_pk_fma_f32 v[252:253], v[168:169], v[168:169], v[252:253]
	v_pk_fma_f32 v[254:255], v[170:171], v[170:171], v[254:255]
	v_pk_fma_f32 v[252:253], v[172:173], v[172:173], v[252:253]
	v_pk_fma_f32 v[254:255], v[174:175], v[174:175], v[254:255]
	v_pk_add_f32 v[252:253], v[252:253], v[254:255]
	s_nop 0
	v_add_f32_e32 v183, v252, v253
	s_nop 1
	v_add_f32_dpp v183, v183, v183 quad_perm:[1,0,3,2] row_mask:0xf bank_mask:0xf bound_ctrl:1
	s_nop 1
	v_add_f32_dpp v183, v183, v183 quad_perm:[2,3,0,1] row_mask:0xf bank_mask:0xf bound_ctrl:1
	s_nop 1
	v_add_f32_dpp v183, v183, v183 row_half_mirror row_mask:0xf bank_mask:0xf bound_ctrl:1
	s_nop 1
	v_add_f32_dpp v183, v183, v183 row_mirror row_mask:0xf bank_mask:0xf bound_ctrl:1
	s_nop 1
	v_readlane_b32 s98, v183, 0
	v_readlane_b32 s99, v183, 16
	v_readlane_b32 s100, v183, 32
	v_readlane_b32 s101, v183, 48
	s_nop 1
	v_mov_b32_e32 v183, s98
	v_add_f32_e32 v183, s99, v183
	v_add_f32_e32 v183, s100, v183
	v_add_f32_e32 v183, s101, v183
	v_fmamk_f32 v183, v183, 0x3a800000, v182
	v_cmp_gt_f32_e32 vcc, 0x800000, v183
	v_mul_f32_e32 v181, 0x4b800000, v183
	s_nop 1
	v_cndmask_b32_e32 v183, v183, v181, vcc
	v_rsq_f32_e32 v183, v183
	s_nop 0
	v_mul_f32_e32 v181, 0x45800000, v183
	v_cndmask_b32_e32 v184, v183, v181, vcc
	v_mov_b32_e32 v185, v184
	v_pk_mul_f32 v[160:161], v[160:161], v[184:185]
	v_pk_mul_f32 v[162:163], v[162:163], v[184:185]
	v_pk_mul_f32 v[164:165], v[164:165], v[184:185]
	v_pk_mul_f32 v[166:167], v[166:167], v[184:185]
	v_pk_mul_f32 v[168:169], v[168:169], v[184:185]
	v_pk_mul_f32 v[170:171], v[170:171], v[184:185]
	v_pk_mul_f32 v[172:173], v[172:173], v[184:185]
	v_pk_mul_f32 v[174:175], v[174:175], v[184:185]
	v_pk_fma_f32 v[144:145], v[160:161], v[128:129], v[144:145]
	v_pk_fma_f32 v[146:147], v[162:163], v[130:131], v[146:147]
	v_pk_fma_f32 v[148:149], v[164:165], v[132:133], v[148:149]
	v_pk_fma_f32 v[150:151], v[166:167], v[134:135], v[150:151]
	v_pk_fma_f32 v[152:153], v[168:169], v[136:137], v[152:153]
	v_pk_fma_f32 v[154:155], v[170:171], v[138:139], v[154:155]
	v_pk_fma_f32 v[156:157], v[172:173], v[140:141], v[156:157]
	v_pk_fma_f32 v[158:159], v[174:175], v[142:143], v[158:159]
	v_pk_mul_f32 v[252:253], v[144:145], v[144:145]
	v_pk_mul_f32 v[254:255], v[146:147], v[146:147]
	v_pk_fma_f32 v[252:253], v[148:149], v[148:149], v[252:253]
	v_pk_fma_f32 v[254:255], v[150:151], v[150:151], v[254:255]
	v_pk_fma_f32 v[252:253], v[152:153], v[152:153], v[252:253]
	v_pk_fma_f32 v[254:255], v[154:155], v[154:155], v[254:255]
	v_pk_fma_f32 v[252:253], v[156:157], v[156:157], v[252:253]
	v_pk_fma_f32 v[254:255], v[158:159], v[158:159], v[254:255]
	v_pk_add_f32 v[252:253], v[252:253], v[254:255]
	s_nop 0
	v_add_f32_e32 v183, v252, v253
	s_nop 1
	v_add_f32_dpp v183, v183, v183 quad_perm:[1,0,3,2] row_mask:0xf bank_mask:0xf bound_ctrl:1
	s_nop 1
	v_add_f32_dpp v183, v183, v183 quad_perm:[2,3,0,1] row_mask:0xf bank_mask:0xf bound_ctrl:1
	s_nop 1
	v_add_f32_dpp v183, v183, v183 row_half_mirror row_mask:0xf bank_mask:0xf bound_ctrl:1
	s_nop 1
	v_add_f32_dpp v183, v183, v183 row_mirror row_mask:0xf bank_mask:0xf bound_ctrl:1
	s_nop 1
	v_readlane_b32 s98, v183, 0
	v_readlane_b32 s99, v183, 16
	v_readlane_b32 s100, v183, 32
	v_readlane_b32 s101, v183, 48
	s_nop 1
	v_mov_b32_e32 v183, s98
	v_add_f32_e32 v183, s99, v183
	v_add_f32_e32 v183, s100, v183
	v_add_f32_e32 v183, s101, v183
	v_fmamk_f32 v183, v183, 0x3a800000, v182
	v_cmp_gt_f32_e32 vcc, 0x800000, v183
	v_mul_f32_e32 v181, 0x4b800000, v183
	s_nop 1
	v_cndmask_b32_e32 v183, v183, v181, vcc
	v_rsq_f32_e32 v183, v183
	s_nop 0
	v_mul_f32_e32 v181, 0x45800000, v183
	v_cndmask_b32_e32 v184, v183, v181, vcc
	v_mov_b32_e32 v185, v184
	v_cvt_pk_bf16_f32 v96, v144, v145
	v_cvt_pk_bf16_f32 v97, v146, v147
	v_cvt_pk_bf16_f32 v98, v148, v149
	v_cvt_pk_bf16_f32 v99, v150, v151
	v_cvt_pk_bf16_f32 v100, v152, v153
	v_cvt_pk_bf16_f32 v101, v154, v155
	v_cvt_pk_bf16_f32 v102, v156, v157
	v_cvt_pk_bf16_f32 v103, v158, v159
	v_add_u32_e32 v181, 0x3000000, v177
	global_store_dwordx4 v181, v[96:99], s[78:79]
	global_store_dwordx4 v181, v[100:103], s[78:79] offset:1024
	v_add_u32_e32 v236, 0xc000, v237
	s_mov_b64 exec, 1
	global_store_dword v236, v184, s[78:79]
	s_mov_b64 exec, -1
	s_waitcnt vmcnt(0)
	v_lshlrev_b32_e32 v144, 16, v112
	v_and_b32_e32 v145, 0xffff0000, v112
	v_lshlrev_b32_e32 v146, 16, v113
	v_and_b32_e32 v147, 0xffff0000, v113
	v_lshlrev_b32_e32 v148, 16, v114
	v_and_b32_e32 v149, 0xffff0000, v114
	v_lshlrev_b32_e32 v150, 16, v115
	v_and_b32_e32 v151, 0xffff0000, v115
	v_lshlrev_b32_e32 v152, 16, v116
	v_and_b32_e32 v153, 0xffff0000, v116
	v_lshlrev_b32_e32 v154, 16, v117
	v_and_b32_e32 v155, 0xffff0000, v117
	v_lshlrev_b32_e32 v156, 16, v118
	v_and_b32_e32 v157, 0xffff0000, v118
	v_lshlrev_b32_e32 v158, 16, v119
	v_and_b32_e32 v159, 0xffff0000, v119
	v_lshlrev_b32_e32 v160, 16, v120
	v_and_b32_e32 v161, 0xffff0000, v120
	v_lshlrev_b32_e32 v162, 16, v121
	v_and_b32_e32 v163, 0xffff0000, v121
	v_lshlrev_b32_e32 v164, 16, v122
	v_and_b32_e32 v165, 0xffff0000, v122
	v_lshlrev_b32_e32 v166, 16, v123
	v_and_b32_e32 v167, 0xffff0000, v123
	v_lshlrev_b32_e32 v168, 16, v124
	v_and_b32_e32 v169, 0xffff0000, v124
	v_lshlrev_b32_e32 v170, 16, v125
	v_and_b32_e32 v171, 0xffff0000, v125
	v_lshlrev_b32_e32 v172, 16, v126
	v_and_b32_e32 v173, 0xffff0000, v126
	v_lshlrev_b32_e32 v174, 16, v127
	v_and_b32_e32 v175, 0xffff0000, v127
	v_pk_mul_f32 v[252:253], v[160:161], v[160:161]
	v_pk_mul_f32 v[254:255], v[162:163], v[162:163]
	v_pk_fma_f32 v[252:253], v[164:165], v[164:165], v[252:253]
	v_pk_fma_f32 v[254:255], v[166:167], v[166:167], v[254:255]
	v_pk_fma_f32 v[252:253], v[168:169], v[168:169], v[252:253]
	v_pk_fma_f32 v[254:255], v[170:171], v[170:171], v[254:255]
	v_pk_fma_f32 v[252:253], v[172:173], v[172:173], v[252:253]
	v_pk_fma_f32 v[254:255], v[174:175], v[174:175], v[254:255]
	v_pk_add_f32 v[252:253], v[252:253], v[254:255]
	s_nop 0
	v_add_f32_e32 v183, v252, v253
	s_nop 1
	v_add_f32_dpp v183, v183, v183 quad_perm:[1,0,3,2] row_mask:0xf bank_mask:0xf bound_ctrl:1
	s_nop 1
	v_add_f32_dpp v183, v183, v183 quad_perm:[2,3,0,1] row_mask:0xf bank_mask:0xf bound_ctrl:1
	s_nop 1
	v_add_f32_dpp v183, v183, v183 row_half_mirror row_mask:0xf bank_mask:0xf bound_ctrl:1
	s_nop 1
	v_add_f32_dpp v183, v183, v183 row_mirror row_mask:0xf bank_mask:0xf bound_ctrl:1
	s_nop 1
	v_readlane_b32 s98, v183, 0
	v_readlane_b32 s99, v183, 16
	v_readlane_b32 s100, v183, 32
	v_readlane_b32 s101, v183, 48
	s_nop 1
	v_mov_b32_e32 v183, s98
	v_add_f32_e32 v183, s99, v183
	v_add_f32_e32 v183, s100, v183
	v_add_f32_e32 v183, s101, v183
	v_fmamk_f32 v183, v183, 0x3a800000, v182
	v_cmp_gt_f32_e32 vcc, 0x800000, v183
	v_mul_f32_e32 v181, 0x4b800000, v183
	s_nop 1
	v_cndmask_b32_e32 v183, v183, v181, vcc
	v_rsq_f32_e32 v183, v183
	s_nop 0
	v_mul_f32_e32 v181, 0x45800000, v183
	v_cndmask_b32_e32 v184, v183, v181, vcc
	v_mov_b32_e32 v185, v184
	v_pk_mul_f32 v[160:161], v[160:161], v[184:185]
	v_pk_mul_f32 v[162:163], v[162:163], v[184:185]
	v_pk_mul_f32 v[164:165], v[164:165], v[184:185]
	v_pk_mul_f32 v[166:167], v[166:167], v[184:185]
	v_pk_mul_f32 v[168:169], v[168:169], v[184:185]
	v_pk_mul_f32 v[170:171], v[170:171], v[184:185]
	v_pk_mul_f32 v[172:173], v[172:173], v[184:185]
	v_pk_mul_f32 v[174:175], v[174:175], v[184:185]
	v_pk_fma_f32 v[144:145], v[160:161], v[128:129], v[144:145]
	v_pk_fma_f32 v[146:147], v[162:163], v[130:131], v[146:147]
	v_pk_fma_f32 v[148:149], v[164:165], v[132:133], v[148:149]
	v_pk_fma_f32 v[150:151], v[166:167], v[134:135], v[150:151]
	v_pk_fma_f32 v[152:153], v[168:169], v[136:137], v[152:153]
	v_pk_fma_f32 v[154:155], v[170:171], v[138:139], v[154:155]
	v_pk_fma_f32 v[156:157], v[172:173], v[140:141], v[156:157]
	v_pk_fma_f32 v[158:159], v[174:175], v[142:143], v[158:159]
	v_pk_mul_f32 v[252:253], v[144:145], v[144:145]
	v_pk_mul_f32 v[254:255], v[146:147], v[146:147]
	v_pk_fma_f32 v[252:253], v[148:149], v[148:149], v[252:253]
	v_pk_fma_f32 v[254:255], v[150:151], v[150:151], v[254:255]
	v_pk_fma_f32 v[252:253], v[152:153], v[152:153], v[252:253]
	v_pk_fma_f32 v[254:255], v[154:155], v[154:155], v[254:255]
	v_pk_fma_f32 v[252:253], v[156:157], v[156:157], v[252:253]
	v_pk_fma_f32 v[254:255], v[158:159], v[158:159], v[254:255]
	v_pk_add_f32 v[252:253], v[252:253], v[254:255]
	s_nop 0
	v_add_f32_e32 v183, v252, v253
	s_nop 1
	v_add_f32_dpp v183, v183, v183 quad_perm:[1,0,3,2] row_mask:0xf bank_mask:0xf bound_ctrl:1
	s_nop 1
	v_add_f32_dpp v183, v183, v183 quad_perm:[2,3,0,1] row_mask:0xf bank_mask:0xf bound_ctrl:1
	s_nop 1
	v_add_f32_dpp v183, v183, v183 row_half_mirror row_mask:0xf bank_mask:0xf bound_ctrl:1
	s_nop 1
	v_add_f32_dpp v183, v183, v183 row_mirror row_mask:0xf bank_mask:0xf bound_ctrl:1
	s_nop 1
	v_readlane_b32 s98, v183, 0
	v_readlane_b32 s99, v183, 16
	v_readlane_b32 s100, v183, 32
	v_readlane_b32 s101, v183, 48
	s_nop 1
	v_mov_b32_e32 v183, s98
	v_add_f32_e32 v183, s99, v183
	v_add_f32_e32 v183, s100, v183
	v_add_f32_e32 v183, s101, v183
	v_fmamk_f32 v183, v183, 0x3a800000, v182
	v_cmp_gt_f32_e32 vcc, 0x800000, v183
	v_mul_f32_e32 v181, 0x4b800000, v183
	s_nop 1
	v_cndmask_b32_e32 v183, v183, v181, vcc
	v_rsq_f32_e32 v183, v183
	s_nop 0
	v_mul_f32_e32 v181, 0x45800000, v183
	v_cndmask_b32_e32 v184, v183, v181, vcc
	v_mov_b32_e32 v185, v184
	v_cvt_pk_bf16_f32 v112, v144, v145
	v_cvt_pk_bf16_f32 v113, v146, v147
	v_cvt_pk_bf16_f32 v114, v148, v149
	v_cvt_pk_bf16_f32 v115, v150, v151
	v_cvt_pk_bf16_f32 v116, v152, v153
	v_cvt_pk_bf16_f32 v117, v154, v155
	v_cvt_pk_bf16_f32 v118, v156, v157
	v_cvt_pk_bf16_f32 v119, v158, v159
	v_add_u32_e32 v181, 0x3400000, v177
	global_store_dwordx4 v181, v[112:115], s[78:79]
	global_store_dwordx4 v181, v[116:119], s[78:79] offset:1024
	v_add_u32_e32 v236, 0xe000, v237
	s_mov_b64 exec, 1
	global_store_dword v236, v184, s[78:79]
	s_mov_b64 exec, -1
	v_readfirstlane_b32 s98, v179
	s_nop 3
	s_and_b32 s99, s98, 3
	s_cmp_lg_u32 s99, 0
	s_cbranch_scc1 .Lmyxupd_done_5
	v_lshrrev_b32_e32 v179, 2, v179
	v_lshlrev_b32_e32 v177, 4, v176
	v_lshl_add_u32 v177, v179, 11, v177
	v_lshlrev_b32_e32 v237, 2, v179
	v_add_u32_e32 v237, 0x10000, v237
	v_add_u32_e32 v181, 0x3800000, v177
	global_load_dwordx4 v[0:3], v181, s[78:79]
	global_load_dwordx4 v[4:7], v181, s[78:79] offset:1024
	v_lshl_add_u32 v183, v179, 12, v180
	v_add_u32_e32 v183, 0xbf00000, v183
	v_add_u32_e32 v181, 0x0, v183
	global_load_dwordx4 v[8:11], v181, s[78:79]
	global_load_dwordx4 v[12:15], v181, s[78:79] offset:16
	global_load_dwordx4 v[16:19], v181, s[78:79] offset:2048
	global_load_dwordx4 v[20:23], v181, s[78:79] offset:2064
	v_add_u32_e32 v181, 0x200000, v183
	global_load_dwordx4 v[24:27], v181, s[78:79]
	global_load_dwordx4 v[28:31], v181, s[78:79] offset:16
	global_load_dwordx4 v[32:35], v181, s[78:79] offset:2048
	global_load_dwordx4 v[36:39], v181, s[78:79] offset:2064
	v_add_u32_e32 v181, 0x400000, v183
	global_load_dwordx4 v[40:43], v181, s[78:79]
	global_load_dwordx4 v[44:47], v181, s[78:79] offset:16
	global_load_dwordx4 v[48:51], v181, s[78:79] offset:2048
	global_load_dwordx4 v[52:55], v181, s[78:79] offset:2064
	v_add_u32_e32 v181, 0x600000, v183
	global_load_dwordx4 v[56:59], v181, s[78:79]
	global_load_dwordx4 v[60:63], v181, s[78:79] offset:16
	global_load_dwordx4 v[64:67], v181, s[78:79] offset:2048
	global_load_dwordx4 v[68:71], v181, s[78:79] offset:2064
	v_add_u32_e32 v181, 0x800000, v183
	global_load_dwordx4 v[72:75], v181, s[78:79]
	global_load_dwordx4 v[76:79], v181, s[78:79] offset:16
	global_load_dwordx4 v[80:83], v181, s[78:79] offset:2048
	global_load_dwordx4 v[84:87], v181, s[78:79] offset:2064
	v_add_u32_e32 v181, 0xa00000, v183
	global_load_dwordx4 v[88:91], v181, s[78:79]
	global_load_dwordx4 v[92:95], v181, s[78:79] offset:16
	global_load_dwordx4 v[96:99], v181, s[78:79] offset:2048
	global_load_dwordx4 v[100:103], v181, s[78:79] offset:2064
	s_waitcnt vmcnt(20)
	v_pk_add_f32 v[160:161], v[8:9], 0 op_sel_hi:[1,0]
	v_pk_add_f32 v[162:163], v[10:11], 0 op_sel_hi:[1,0]
	v_pk_add_f32 v[164:165], v[12:13], 0 op_sel_hi:[1,0]
	v_pk_add_f32 v[166:167], v[14:15], 0 op_sel_hi:[1,0]
	v_pk_add_f32 v[168:169], v[16:17], 0 op_sel_hi:[1,0]
	v_pk_add_f32 v[170:171], v[18:19], 0 op_sel_hi:[1,0]
	v_pk_add_f32 v[172:173], v[20:21], 0 op_sel_hi:[1,0]
	v_pk_add_f32 v[174:175], v[22:23], 0 op_sel_hi:[1,0]
	s_waitcnt vmcnt(16)
	v_pk_add_f32 v[160:161], v[160:161], v[24:25]
	v_pk_add_f32 v[162:163], v[162:163], v[26:27]
	v_pk_add_f32 v[164:165], v[164:165], v[28:29]
	v_pk_add_f32 v[166:167], v[166:167], v[30:31]
	v_pk_add_f32 v[168:169], v[168:169], v[32:33]
	v_pk_add_f32 v[170:171], v[170:171], v[34:35]
	v_pk_add_f32 v[172:173], v[172:173], v[36:37]
	v_pk_add_f32 v[174:175], v[174:175], v[38:39]
	s_waitcnt vmcnt(12)
	v_pk_add_f32 v[160:161], v[160:161], v[40:41]
	v_pk_add_f32 v[162:163], v[162:163], v[42:43]
	v_pk_add_f32 v[164:165], v[164:165], v[44:45]
	v_pk_add_f32 v[166:167], v[166:167], v[46:47]
	v_pk_add_f32 v[168:169], v[168:169], v[48:49]
	v_pk_add_f32 v[170:171], v[170:171], v[50:51]
	v_pk_add_f32 v[172:173], v[172:173], v[52:53]
	v_pk_add_f32 v[174:175], v[174:175], v[54:55]
	s_waitcnt vmcnt(8)
	v_pk_add_f32 v[160:161], v[160:161], v[56:57]
	v_pk_add_f32 v[162:163], v[162:163], v[58:59]
	v_pk_add_f32 v[164:165], v[164:165], v[60:61]
	v_pk_add_f32 v[166:167], v[166:167], v[62:63]
	v_pk_add_f32 v[168:169], v[168:169], v[64:65]
	v_pk_add_f32 v[170:171], v[170:171], v[66:67]
	v_pk_add_f32 v[172:173], v[172:173], v[68:69]
	v_pk_add_f32 v[174:175], v[174:175], v[70:71]
	s_waitcnt vmcnt(4)
	v_pk_add_f32 v[160:161], v[160:161], v[72:73]
	v_pk_add_f32 v[162:163], v[162:163], v[74:75]
	v_pk_add_f32 v[164:165], v[164:165], v[76:77]
	v_pk_add_f32 v[166:167], v[166:167], v[78:79]
	v_pk_add_f32 v[168:169], v[168:169], v[80:81]
	v_pk_add_f32 v[170:171], v[170:171], v[82:83]
	v_pk_add_f32 v[172:173], v[172:173], v[84:85]
	v_pk_add_f32 v[174:175], v[174:175], v[86:87]
	s_waitcnt vmcnt(0)
	v_pk_add_f32 v[160:161], v[160:161], v[88:89]
	v_pk_add_f32 v[162:163], v[162:163], v[90:91]
	v_pk_add_f32 v[164:165], v[164:165], v[92:93]
	v_pk_add_f32 v[166:167], v[166:167], v[94:95]
	v_pk_add_f32 v[168:169], v[168:169], v[96:97]
	v_pk_add_f32 v[170:171], v[170:171], v[98:99]
	v_pk_add_f32 v[172:173], v[172:173], v[100:101]
	v_pk_add_f32 v[174:175], v[174:175], v[102:103]
	v_lshlrev_b32_e32 v144, 16, v0
	v_and_b32_e32 v145, 0xffff0000, v0
	v_lshlrev_b32_e32 v146, 16, v1
	v_and_b32_e32 v147, 0xffff0000, v1
	v_lshlrev_b32_e32 v148, 16, v2
	v_and_b32_e32 v149, 0xffff0000, v2
	v_lshlrev_b32_e32 v150, 16, v3
	v_and_b32_e32 v151, 0xffff0000, v3
	v_lshlrev_b32_e32 v152, 16, v4
	v_and_b32_e32 v153, 0xffff0000, v4
	v_lshlrev_b32_e32 v154, 16, v5
	v_and_b32_e32 v155, 0xffff0000, v5
	v_lshlrev_b32_e32 v156, 16, v6
	v_and_b32_e32 v157, 0xffff0000, v6
	v_lshlrev_b32_e32 v158, 16, v7
	v_and_b32_e32 v159, 0xffff0000, v7
	v_add_u32_e32 v181, 0xc00000, v183
	global_load_dwordx4 v[8:11], v181, s[78:79]
	global_load_dwordx4 v[12:15], v181, s[78:79] offset:16
	global_load_dwordx4 v[16:19], v181, s[78:79] offset:2048
	global_load_dwordx4 v[20:23], v181, s[78:79] offset:2064
	v_add_u32_e32 v181, 0xe00000, v183
	global_load_dwordx4 v[24:27], v181, s[78:79]
	global_load_dwordx4 v[28:31], v181, s[78:79] offset:16
	global_load_dwordx4 v[32:35], v181, s[78:79] offset:2048
	global_load_dwordx4 v[36:39], v181, s[78:79] offset:2064
	v_add_u32_e32 v181, 0x1000000, v183
	global_load_dwordx4 v[40:43], v181, s[78:79]
	global_load_dwordx4 v[44:47], v181, s[78:79] offset:16
	global_load_dwordx4 v[48:51], v181, s[78:79] offset:2048
	global_load_dwordx4 v[52:55], v181, s[78:79] offset:2064
	v_add_u32_e32 v181, 0x1200000, v183
	global_load_dwordx4 v[56:59], v181, s[78:79]
	global_load_dwordx4 v[60:63], v181, s[78:79] offset:16
	global_load_dwordx4 v[64:67], v181, s[78:79] offset:2048
	global_load_dwordx4 v[68:71], v181, s[78:79] offset:2064
	v_add_u32_e32 v181, 0x1400000, v183
	global_load_dwordx4 v[72:75], v181, s[78:79]
	global_load_dwordx4 v[76:79], v181, s[78:79] offset:16
	global_load_dwordx4 v[80:83], v181, s[78:79] offset:2048
	global_load_dwordx4 v[84:87], v181, s[78:79] offset:2064
	s_waitcnt vmcnt(16)
	v_pk_add_f32 v[160:161], v[160:161], v[8:9]
	v_pk_add_f32 v[162:163], v[162:163], v[10:11]
	v_pk_add_f32 v[164:165], v[164:165], v[12:13]
	v_pk_add_f32 v[166:167], v[166:167], v[14:15]
	v_pk_add_f32 v[168:169], v[168:169], v[16:17]
	v_pk_add_f32 v[170:171], v[170:171], v[18:19]
	v_pk_add_f32 v[172:173], v[172:173], v[20:21]
	v_pk_add_f32 v[174:175], v[174:175], v[22:23]
	s_waitcnt vmcnt(12)
	v_pk_add_f32 v[160:161], v[160:161], v[24:25]
	v_pk_add_f32 v[162:163], v[162:163], v[26:27]
	v_pk_add_f32 v[164:165], v[164:165], v[28:29]
	v_pk_add_f32 v[166:167], v[166:167], v[30:31]
	v_pk_add_f32 v[168:169], v[168:169], v[32:33]
	v_pk_add_f32 v[170:171], v[170:171], v[34:35]
	v_pk_add_f32 v[172:173], v[172:173], v[36:37]
	v_pk_add_f32 v[174:175], v[174:175], v[38:39]
	s_waitcnt vmcnt(8)
	v_pk_add_f32 v[160:161], v[160:161], v[40:41]
	v_pk_add_f32 v[162:163], v[162:163], v[42:43]
	v_pk_add_f32 v[164:165], v[164:165], v[44:45]
	v_pk_add_f32 v[166:167], v[166:167], v[46:47]
	v_pk_add_f32 v[168:169], v[168:169], v[48:49]
	v_pk_add_f32 v[170:171], v[170:171], v[50:51]
	v_pk_add_f32 v[172:173], v[172:173], v[52:53]
	v_pk_add_f32 v[174:175], v[174:175], v[54:55]
	s_waitcnt vmcnt(4)
	v_pk_add_f32 v[160:161], v[160:161], v[56:57]
	v_pk_add_f32 v[162:163], v[162:163], v[58:59]
	v_pk_add_f32 v[164:165], v[164:165], v[60:61]
	v_pk_add_f32 v[166:167], v[166:167], v[62:63]
	v_pk_add_f32 v[168:169], v[168:169], v[64:65]
	v_pk_add_f32 v[170:171], v[170:171], v[66:67]
	v_pk_add_f32 v[172:173], v[172:173], v[68:69]
	v_pk_add_f32 v[174:175], v[174:175], v[70:71]
	s_waitcnt vmcnt(0)
	v_pk_add_f32 v[160:161], v[160:161], v[72:73]
	v_pk_add_f32 v[162:163], v[162:163], v[74:75]
	v_pk_add_f32 v[164:165], v[164:165], v[76:77]
	v_pk_add_f32 v[166:167], v[166:167], v[78:79]
	v_pk_add_f32 v[168:169], v[168:169], v[80:81]
	v_pk_add_f32 v[170:171], v[170:171], v[82:83]
	v_pk_add_f32 v[172:173], v[172:173], v[84:85]
	v_pk_add_f32 v[174:175], v[174:175], v[86:87]
	v_pk_mul_f32 v[252:253], v[160:161], v[160:161]
	v_pk_mul_f32 v[254:255], v[162:163], v[162:163]
	v_pk_fma_f32 v[252:253], v[164:165], v[164:165], v[252:253]
	v_pk_fma_f32 v[254:255], v[166:167], v[166:167], v[254:255]
	v_pk_fma_f32 v[252:253], v[168:169], v[168:169], v[252:253]
	v_pk_fma_f32 v[254:255], v[170:171], v[170:171], v[254:255]
	v_pk_fma_f32 v[252:253], v[172:173], v[172:173], v[252:253]
	v_pk_fma_f32 v[254:255], v[174:175], v[174:175], v[254:255]
	v_pk_add_f32 v[252:253], v[252:253], v[254:255]
	s_nop 0
	v_add_f32_e32 v183, v252, v253
	s_nop 1
	v_add_f32_dpp v183, v183, v183 quad_perm:[1,0,3,2] row_mask:0xf bank_mask:0xf bound_ctrl:1
	s_nop 1
	v_add_f32_dpp v183, v183, v183 quad_perm:[2,3,0,1] row_mask:0xf bank_mask:0xf bound_ctrl:1
	s_nop 1
	v_add_f32_dpp v183, v183, v183 row_half_mirror row_mask:0xf bank_mask:0xf bound_ctrl:1
	s_nop 1
	v_add_f32_dpp v183, v183, v183 row_mirror row_mask:0xf bank_mask:0xf bound_ctrl:1
	s_nop 1
	v_readlane_b32 s98, v183, 0
	v_readlane_b32 s99, v183, 16
	v_readlane_b32 s100, v183, 32
	v_readlane_b32 s101, v183, 48
	s_nop 1
	v_mov_b32_e32 v183, s98
	v_add_f32_e32 v183, s99, v183
	v_add_f32_e32 v183, s100, v183
	v_add_f32_e32 v183, s101, v183
	v_fmamk_f32 v183, v183, 0x3a800000, v182
	v_cmp_gt_f32_e32 vcc, 0x800000, v183
	v_mul_f32_e32 v181, 0x4b800000, v183
	s_nop 1
	v_cndmask_b32_e32 v183, v183, v181, vcc
	v_rsq_f32_e32 v183, v183
	s_nop 0
	v_mul_f32_e32 v181, 0x45800000, v183
	v_cndmask_b32_e32 v184, v183, v181, vcc
	v_mov_b32_e32 v185, v184
	v_pk_mul_f32 v[160:161], v[160:161], v[184:185]
	v_pk_mul_f32 v[162:163], v[162:163], v[184:185]
	v_pk_mul_f32 v[164:165], v[164:165], v[184:185]
	v_pk_mul_f32 v[166:167], v[166:167], v[184:185]
	v_pk_mul_f32 v[168:169], v[168:169], v[184:185]
	v_pk_mul_f32 v[170:171], v[170:171], v[184:185]
	v_pk_mul_f32 v[172:173], v[172:173], v[184:185]
	v_pk_mul_f32 v[174:175], v[174:175], v[184:185]
	v_pk_fma_f32 v[144:145], v[160:161], v[128:129], v[144:145]
	v_pk_fma_f32 v[146:147], v[162:163], v[130:131], v[146:147]
	v_pk_fma_f32 v[148:149], v[164:165], v[132:133], v[148:149]
	v_pk_fma_f32 v[150:151], v[166:167], v[134:135], v[150:151]
	v_pk_fma_f32 v[152:153], v[168:169], v[136:137], v[152:153]
	v_pk_fma_f32 v[154:155], v[170:171], v[138:139], v[154:155]
	v_pk_fma_f32 v[156:157], v[172:173], v[140:141], v[156:157]
	v_pk_fma_f32 v[158:159], v[174:175], v[142:143], v[158:159]
	v_pk_mul_f32 v[252:253], v[144:145], v[144:145]
	v_pk_mul_f32 v[254:255], v[146:147], v[146:147]
	v_pk_fma_f32 v[252:253], v[148:149], v[148:149], v[252:253]
	v_pk_fma_f32 v[254:255], v[150:151], v[150:151], v[254:255]
	v_pk_fma_f32 v[252:253], v[152:153], v[152:153], v[252:253]
	v_pk_fma_f32 v[254:255], v[154:155], v[154:155], v[254:255]
	v_pk_fma_f32 v[252:253], v[156:157], v[156:157], v[252:253]
	v_pk_fma_f32 v[254:255], v[158:159], v[158:159], v[254:255]
	v_pk_add_f32 v[252:253], v[252:253], v[254:255]
	s_nop 0
	v_add_f32_e32 v183, v252, v253
	s_nop 1
	v_add_f32_dpp v183, v183, v183 quad_perm:[1,0,3,2] row_mask:0xf bank_mask:0xf bound_ctrl:1
	s_nop 1
	v_add_f32_dpp v183, v183, v183 quad_perm:[2,3,0,1] row_mask:0xf bank_mask:0xf bound_ctrl:1
	s_nop 1
	v_add_f32_dpp v183, v183, v183 row_half_mirror row_mask:0xf bank_mask:0xf bound_ctrl:1
	s_nop 1
	v_add_f32_dpp v183, v183, v183 row_mirror row_mask:0xf bank_mask:0xf bound_ctrl:1
	s_nop 1
	v_readlane_b32 s98, v183, 0
	v_readlane_b32 s99, v183, 16
	v_readlane_b32 s100, v183, 32
	v_readlane_b32 s101, v183, 48
	s_nop 1
	v_mov_b32_e32 v183, s98
	v_add_f32_e32 v183, s99, v183
	v_add_f32_e32 v183, s100, v183
	v_add_f32_e32 v183, s101, v183
	v_fmamk_f32 v183, v183, 0x3a800000, v182
	v_cmp_gt_f32_e32 vcc, 0x800000, v183
	v_mul_f32_e32 v181, 0x4b800000, v183
	s_nop 1
	v_cndmask_b32_e32 v183, v183, v181, vcc
	v_rsq_f32_e32 v183, v183
	s_nop 0
	v_mul_f32_e32 v181, 0x45800000, v183
	v_cndmask_b32_e32 v184, v183, v181, vcc
	v_mov_b32_e32 v185, v184
	v_cvt_pk_bf16_f32 v0, v144, v145
	v_cvt_pk_bf16_f32 v1, v146, v147
	v_cvt_pk_bf16_f32 v2, v148, v149
	v_cvt_pk_bf16_f32 v3, v150, v151
	v_cvt_pk_bf16_f32 v4, v152, v153
	v_cvt_pk_bf16_f32 v5, v154, v155
	v_cvt_pk_bf16_f32 v6, v156, v157
	v_cvt_pk_bf16_f32 v7, v158, v159
	v_add_u32_e32 v181, 0x3800000, v177
	global_store_dwordx4 v181, v[0:3], s[78:79]
	global_store_dwordx4 v181, v[4:7], s[78:79] offset:1024
	v_add_u32_e32 v236, 0x10000, v237
	s_mov_b64 exec, 1
	global_store_dword v236, v184, s[78:79]
	s_mov_b64 exec, -1

.LBB0_2573:
	v_readlane_b32 s0, v235, 52
	v_readlane_b32 s1, v235, 53
	s_and_b64 vcc, exec, s[0:1]
	s_waitcnt lgkmcnt(0)
	s_barrier
	v_mbcnt_lo_u32_b32 v0, -1, 0
	v_mbcnt_hi_u32_b32 v0, -1, v0
	s_cbranch_vccnz .LBB0_2593
	v_lshlrev_b32_e32 v2, 3, v0
	v_ashrrev_i32_e32 v3, 31, v2
	v_readlane_b32 s4, v235, 4
	v_lshlrev_b64 v[4:5], 1, v[2:3]
	v_lshlrev_b64 v[2:3], 2, v[2:3]
	v_readlane_b32 s14, v235, 14
	v_readlane_b32 s15, v235, 15
	v_lshl_add_u64 v[62:63], s[90:91], 0, v[2:3]
	v_readlane_b32 s5, v235, 5
	v_readlane_b32 s6, v235, 6
	v_readlane_b32 s7, v235, 7
	v_readlane_b32 s8, v235, 8
	v_readlane_b32 s9, v235, 9
	v_readlane_b32 s10, v235, 10
	v_readlane_b32 s11, v235, 11
	v_readlane_b32 s12, v235, 12
	v_readlane_b32 s13, v235, 13
	v_readlane_b32 s16, v235, 16
	v_readlane_b32 s17, v235, 17
	v_readlane_b32 s18, v235, 18
	v_readlane_b32 s19, v235, 19
	v_lshl_add_u64 v[2:3], s[14:15], 0, v[2:3]
	s_mov_b64 s[0:1], 0x3000
	v_lshl_add_u64 v[60:61], s[86:87], 0, v[4:5]
	v_lshl_add_u64 v[64:65], s[54:55], 0, v[4:5]
	v_lshl_add_u64 v[66:67], v[2:3], 0, s[0:1]
	s_mov_b32 s1, 0
	v_cmp_eq_u32_e64 s[4:5], 0, v0
	s_mov_b64 s[6:7], 0x200000
	s_mov_b64 s[8:9], 0x200800
	s_mov_b64 s[10:11], 0x400000
	s_mov_b64 s[12:13], 0x400800
	s_mov_b64 s[14:15], 0x600000
	s_mov_b64 s[16:17], 0x600800
	s_mov_b64 s[18:19], 0x800000
	s_mov_b32 s48, 0x800000
	s_mov_b64 s[20:21], 0x800800
	s_mov_b64 s[22:23], 0xa00000
	s_mov_b64 s[24:25], 0xa00800
	s_mov_b64 s[26:27], 0xc00000
	s_mov_b64 s[28:29], 0xc00800
	s_mov_b64 s[30:31], 0xe00000
	s_mov_b64 s[36:37], 0xe00800
	v_mov_b32_e32 v104, 0
	v_mov_b32_e32 v105, 0x358637bd
	v_readlane_b32 s38, v235, 61
	v_readlane_b32 s39, v235, 62
	v_mbcnt_lo_u32_b32 v176, -1, 0
	v_mbcnt_hi_u32_b32 v176, -1, v176
	v_readlane_b32 s98, v235, 49
	v_readlane_b32 s99, v235, 20
	v_readlane_b32 s100, v235, 14
	v_readlane_b32 s101, v235, 15
	s_nop 3
	s_lshr_b32 vcc_lo, s98, 3
	s_and_b32 vcc_hi, vcc_lo, 7
	s_lshr_b32 vcc_lo, vcc_lo, 3
	s_lshl_b32 vcc_lo, vcc_lo, 3
	s_add_i32 vcc_lo, vcc_lo, s99
	s_lshl_b32 s98, vcc_hi, 8
	s_add_i32 s98, s98, vcc_lo
	s_mov_b32 s99, s98
	v_mov_b32_e32 v183, s99
	v_lshlrev_b32_e32 v177, 4, v176
	s_lshl_b32 s99, s99, 11
	v_add_u32_e32 v177, s99, v177
	v_add_u32_e32 v178, 0x1800000, v177
	v_add_u32_e32 v179, 0x9e00000, v177
	v_lshlrev_b32_e32 v180, 5, v176
	v_add_u32_e32 v181, 0x3000, v180
	global_load_dwordx4 v[128:131], v181, s[100:101]
	global_load_dwordx4 v[132:135], v181, s[100:101] offset:16
	global_load_dwordx4 v[136:139], v181, s[100:101] offset:2048
	global_load_dwordx4 v[140:143], v181, s[100:101] offset:2064
	v_mov_b32_e32 v182, 0x358637bd
	global_load_dwordx4 v[0:3], v178, s[78:79]
	global_load_dwordx4 v[4:7], v178, s[78:79] offset:1024
	global_load_dwordx4 v[8:11], v179, s[78:79]
	global_load_dwordx4 v[12:15], v179, s[78:79] offset:1024
	v_add_u32_e32 v178, 0x400000, v178
	v_add_u32_e32 v179, 0x400000, v179
	global_load_dwordx4 v[16:19], v178, s[78:79]
	global_load_dwordx4 v[20:23], v178, s[78:79] offset:1024
	global_load_dwordx4 v[24:27], v179, s[78:79]
	global_load_dwordx4 v[28:31], v179, s[78:79] offset:1024
	v_add_u32_e32 v178, 0x400000, v178
	v_add_u32_e32 v179, 0x400000, v179
	global_load_dwordx4 v[32:35], v178, s[78:79]
	global_load_dwordx4 v[36:39], v178, s[78:79] offset:1024
	global_load_dwordx4 v[40:43], v179, s[78:79]
	global_load_dwordx4 v[44:47], v179, s[78:79] offset:1024
	v_add_u32_e32 v178, 0x400000, v178
	v_add_u32_e32 v179, 0x400000, v179
	global_load_dwordx4 v[48:51], v178, s[78:79]
	global_load_dwordx4 v[52:55], v178, s[78:79] offset:1024
	global_load_dwordx4 v[56:59], v179, s[78:79]
	global_load_dwordx4 v[60:63], v179, s[78:79] offset:1024
	v_add_u32_e32 v178, 0x400000, v178
	v_add_u32_e32 v179, 0x400000, v179
	global_load_dwordx4 v[64:67], v178, s[78:79]
	global_load_dwordx4 v[68:71], v178, s[78:79] offset:1024
	global_load_dwordx4 v[72:75], v179, s[78:79]
	global_load_dwordx4 v[76:79], v179, s[78:79] offset:1024
	v_add_u32_e32 v178, 0x400000, v178
	v_add_u32_e32 v179, 0x400000, v179
	global_load_dwordx4 v[80:83], v178, s[78:79]
	global_load_dwordx4 v[84:87], v178, s[78:79] offset:1024
	global_load_dwordx4 v[88:91], v179, s[78:79]
	global_load_dwordx4 v[92:95], v179, s[78:79] offset:1024
	v_add_u32_e32 v178, 0x400000, v178
	v_add_u32_e32 v179, 0x400000, v179
	global_load_dwordx4 v[96:99], v178, s[78:79]
	global_load_dwordx4 v[100:103], v178, s[78:79] offset:1024
	global_load_dwordx4 v[104:107], v179, s[78:79]
	global_load_dwordx4 v[108:111], v179, s[78:79] offset:1024
	v_add_u32_e32 v178, 0x400000, v178
	v_add_u32_e32 v179, 0x400000, v179
	global_load_dwordx4 v[112:115], v178, s[78:79]
	global_load_dwordx4 v[116:119], v178, s[78:79] offset:1024
	global_load_dwordx4 v[120:123], v179, s[78:79]
	global_load_dwordx4 v[124:127], v179, s[78:79] offset:1024
	v_lshlrev_b32_e32 v237, 2, v183
	v_add_u32_e32 v237, 0x10000, v237
	v_mov_b32_e32 v179, s98
	s_waitcnt vmcnt(28)
	v_lshlrev_b32_e32 v144, 16, v0
	v_and_b32_e32 v145, 0xffff0000, v0
	v_lshlrev_b32_e32 v146, 16, v1
	v_and_b32_e32 v147, 0xffff0000, v1
	v_lshlrev_b32_e32 v148, 16, v2
	v_and_b32_e32 v149, 0xffff0000, v2
	v_lshlrev_b32_e32 v150, 16, v3
	v_and_b32_e32 v151, 0xffff0000, v3
	v_lshlrev_b32_e32 v152, 16, v4
	v_and_b32_e32 v153, 0xffff0000, v4
	v_lshlrev_b32_e32 v154, 16, v5
	v_and_b32_e32 v155, 0xffff0000, v5
	v_lshlrev_b32_e32 v156, 16, v6
	v_and_b32_e32 v157, 0xffff0000, v6
	v_lshlrev_b32_e32 v158, 16, v7
	v_and_b32_e32 v159, 0xffff0000, v7
	v_lshlrev_b32_e32 v160, 16, v8
	v_and_b32_e32 v161, 0xffff0000, v8
	v_lshlrev_b32_e32 v162, 16, v9
	v_and_b32_e32 v163, 0xffff0000, v9
	v_lshlrev_b32_e32 v164, 16, v10
	v_and_b32_e32 v165, 0xffff0000, v10
	v_lshlrev_b32_e32 v166, 16, v11
	v_and_b32_e32 v167, 0xffff0000, v11
	v_lshlrev_b32_e32 v168, 16, v12
	v_and_b32_e32 v169, 0xffff0000, v12
	v_lshlrev_b32_e32 v170, 16, v13
	v_and_b32_e32 v171, 0xffff0000, v13
	v_lshlrev_b32_e32 v172, 16, v14
	v_and_b32_e32 v173, 0xffff0000, v14
	v_lshlrev_b32_e32 v174, 16, v15
	v_and_b32_e32 v175, 0xffff0000, v15
	v_pk_mul_f32 v[252:253], v[160:161], v[160:161]
	v_pk_mul_f32 v[254:255], v[162:163], v[162:163]
	v_pk_fma_f32 v[252:253], v[164:165], v[164:165], v[252:253]
	v_pk_fma_f32 v[254:255], v[166:167], v[166:167], v[254:255]
	v_pk_fma_f32 v[252:253], v[168:169], v[168:169], v[252:253]
	v_pk_fma_f32 v[254:255], v[170:171], v[170:171], v[254:255]
	v_pk_fma_f32 v[252:253], v[172:173], v[172:173], v[252:253]
	v_pk_fma_f32 v[254:255], v[174:175], v[174:175], v[254:255]
	v_pk_add_f32 v[252:253], v[252:253], v[254:255]
	s_nop 0
	v_add_f32_e32 v183, v252, v253
	s_nop 1
	v_add_f32_dpp v183, v183, v183 quad_perm:[1,0,3,2] row_mask:0xf bank_mask:0xf bound_ctrl:1
	s_nop 1
	v_add_f32_dpp v183, v183, v183 quad_perm:[2,3,0,1] row_mask:0xf bank_mask:0xf bound_ctrl:1
	s_nop 1
	v_add_f32_dpp v183, v183, v183 row_half_mirror row_mask:0xf bank_mask:0xf bound_ctrl:1
	s_nop 1
	v_add_f32_dpp v183, v183, v183 row_mirror row_mask:0xf bank_mask:0xf bound_ctrl:1
	s_nop 1
	v_readlane_b32 s98, v183, 0
	v_readlane_b32 s99, v183, 16
	v_readlane_b32 s100, v183, 32
	v_readlane_b32 s101, v183, 48
	s_nop 1
	v_mov_b32_e32 v183, s98
	v_add_f32_e32 v183, s99, v183
	v_add_f32_e32 v183, s100, v183
	v_add_f32_e32 v183, s101, v183
	v_fmamk_f32 v183, v183, 0x3a800000, v182
	v_cmp_gt_f32_e32 vcc, 0x800000, v183
	v_mul_f32_e32 v181, 0x4b800000, v183
	s_nop 1
	v_cndmask_b32_e32 v183, v183, v181, vcc
	v_rsq_f32_e32 v183, v183
	s_nop 0
	v_mul_f32_e32 v181, 0x45800000, v183
	v_cndmask_b32_e32 v184, v183, v181, vcc
	v_mov_b32_e32 v185, v184
	v_pk_mul_f32 v[160:161], v[160:161], v[184:185]
	v_pk_mul_f32 v[162:163], v[162:163], v[184:185]
	v_pk_mul_f32 v[164:165], v[164:165], v[184:185]
	v_pk_mul_f32 v[166:167], v[166:167], v[184:185]
	v_pk_mul_f32 v[168:169], v[168:169], v[184:185]
	v_pk_mul_f32 v[170:171], v[170:171], v[184:185]
	v_pk_mul_f32 v[172:173], v[172:173], v[184:185]
	v_pk_mul_f32 v[174:175], v[174:175], v[184:185]
	v_pk_fma_f32 v[144:145], v[160:161], v[128:129], v[144:145]
	v_pk_fma_f32 v[146:147], v[162:163], v[130:131], v[146:147]
	v_pk_fma_f32 v[148:149], v[164:165], v[132:133], v[148:149]
	v_pk_fma_f32 v[150:151], v[166:167], v[134:135], v[150:151]
	v_pk_fma_f32 v[152:153], v[168:169], v[136:137], v[152:153]
	v_pk_fma_f32 v[154:155], v[170:171], v[138:139], v[154:155]
	v_pk_fma_f32 v[156:157], v[172:173], v[140:141], v[156:157]
	v_pk_fma_f32 v[158:159], v[174:175], v[142:143], v[158:159]
	v_pk_mul_f32 v[252:253], v[144:145], v[144:145]
	v_pk_mul_f32 v[254:255], v[146:147], v[146:147]
	v_pk_fma_f32 v[252:253], v[148:149], v[148:149], v[252:253]
	v_pk_fma_f32 v[254:255], v[150:151], v[150:151], v[254:255]
	v_pk_fma_f32 v[252:253], v[152:153], v[152:153], v[252:253]
	v_pk_fma_f32 v[254:255], v[154:155], v[154:155], v[254:255]
	v_pk_fma_f32 v[252:253], v[156:157], v[156:157], v[252:253]
	v_pk_fma_f32 v[254:255], v[158:159], v[158:159], v[254:255]
	v_pk_add_f32 v[252:253], v[252:253], v[254:255]
	s_nop 0
	v_add_f32_e32 v183, v252, v253
	s_nop 1
	v_add_f32_dpp v183, v183, v183 quad_perm:[1,0,3,2] row_mask:0xf bank_mask:0xf bound_ctrl:1
	s_nop 1
	v_add_f32_dpp v183, v183, v183 quad_perm:[2,3,0,1] row_mask:0xf bank_mask:0xf bound_ctrl:1
	s_nop 1
	v_add_f32_dpp v183, v183, v183 row_half_mirror row_mask:0xf bank_mask:0xf bound_ctrl:1
	s_nop 1
	v_add_f32_dpp v183, v183, v183 row_mirror row_mask:0xf bank_mask:0xf bound_ctrl:1
	s_nop 1
	v_readlane_b32 s98, v183, 0
	v_readlane_b32 s99, v183, 16
	v_readlane_b32 s100, v183, 32
	v_readlane_b32 s101, v183, 48
	s_nop 1
	v_mov_b32_e32 v183, s98
	v_add_f32_e32 v183, s99, v183
	v_add_f32_e32 v183, s100, v183
	v_add_f32_e32 v183, s101, v183
	v_fmamk_f32 v183, v183, 0x3a800000, v182
	v_cmp_gt_f32_e32 vcc, 0x800000, v183
	v_mul_f32_e32 v181, 0x4b800000, v183
	s_nop 1
	v_cndmask_b32_e32 v183, v183, v181, vcc
	v_rsq_f32_e32 v183, v183
	s_nop 0
	v_mul_f32_e32 v181, 0x45800000, v183
	v_cndmask_b32_e32 v184, v183, v181, vcc
	v_mov_b32_e32 v185, v184
	v_cvt_pk_bf16_f32 v0, v144, v145
	v_cvt_pk_bf16_f32 v1, v146, v147
	v_cvt_pk_bf16_f32 v2, v148, v149
	v_cvt_pk_bf16_f32 v3, v150, v151
	v_cvt_pk_bf16_f32 v4, v152, v153
	v_cvt_pk_bf16_f32 v5, v154, v155
	v_cvt_pk_bf16_f32 v6, v156, v157
	v_cvt_pk_bf16_f32 v7, v158, v159
	v_add_u32_e32 v181, 0x1800000, v177
	global_store_dwordx4 v181, v[0:3], s[78:79]
	global_store_dwordx4 v181, v[4:7], s[78:79] offset:1024
	v_add_u32_e32 v236, 0x0, v237
	s_mov_b64 exec, 1
	global_store_dword v236, v184, s[78:79]
	s_mov_b64 exec, -1
	s_waitcnt vmcnt(24)
	v_lshlrev_b32_e32 v144, 16, v16
	v_and_b32_e32 v145, 0xffff0000, v16
	v_lshlrev_b32_e32 v146, 16, v17
	v_and_b32_e32 v147, 0xffff0000, v17
	v_lshlrev_b32_e32 v148, 16, v18
	v_and_b32_e32 v149, 0xffff0000, v18
	v_lshlrev_b32_e32 v150, 16, v19
	v_and_b32_e32 v151, 0xffff0000, v19
	v_lshlrev_b32_e32 v152, 16, v20
	v_and_b32_e32 v153, 0xffff0000, v20
	v_lshlrev_b32_e32 v154, 16, v21
	v_and_b32_e32 v155, 0xffff0000, v21
	v_lshlrev_b32_e32 v156, 16, v22
	v_and_b32_e32 v157, 0xffff0000, v22
	v_lshlrev_b32_e32 v158, 16, v23
	v_and_b32_e32 v159, 0xffff0000, v23
	v_lshlrev_b32_e32 v160, 16, v24
	v_and_b32_e32 v161, 0xffff0000, v24
	v_lshlrev_b32_e32 v162, 16, v25
	v_and_b32_e32 v163, 0xffff0000, v25
	v_lshlrev_b32_e32 v164, 16, v26
	v_and_b32_e32 v165, 0xffff0000, v26
	v_lshlrev_b32_e32 v166, 16, v27
	v_and_b32_e32 v167, 0xffff0000, v27
	v_lshlrev_b32_e32 v168, 16, v28
	v_and_b32_e32 v169, 0xffff0000, v28
	v_lshlrev_b32_e32 v170, 16, v29
	v_and_b32_e32 v171, 0xffff0000, v29
	v_lshlrev_b32_e32 v172, 16, v30
	v_and_b32_e32 v173, 0xffff0000, v30
	v_lshlrev_b32_e32 v174, 16, v31
	v_and_b32_e32 v175, 0xffff0000, v31
	v_pk_mul_f32 v[252:253], v[160:161], v[160:161]
	v_pk_mul_f32 v[254:255], v[162:163], v[162:163]
	v_pk_fma_f32 v[252:253], v[164:165], v[164:165], v[252:253]
	v_pk_fma_f32 v[254:255], v[166:167], v[166:167], v[254:255]
	v_pk_fma_f32 v[252:253], v[168:169], v[168:169], v[252:253]
	v_pk_fma_f32 v[254:255], v[170:171], v[170:171], v[254:255]
	v_pk_fma_f32 v[252:253], v[172:173], v[172:173], v[252:253]
	v_pk_fma_f32 v[254:255], v[174:175], v[174:175], v[254:255]
	v_pk_add_f32 v[252:253], v[252:253], v[254:255]
	s_nop 0
	v_add_f32_e32 v183, v252, v253
	s_nop 1
	v_add_f32_dpp v183, v183, v183 quad_perm:[1,0,3,2] row_mask:0xf bank_mask:0xf bound_ctrl:1
	s_nop 1
	v_add_f32_dpp v183, v183, v183 quad_perm:[2,3,0,1] row_mask:0xf bank_mask:0xf bound_ctrl:1
	s_nop 1
	v_add_f32_dpp v183, v183, v183 row_half_mirror row_mask:0xf bank_mask:0xf bound_ctrl:1
	s_nop 1
	v_add_f32_dpp v183, v183, v183 row_mirror row_mask:0xf bank_mask:0xf bound_ctrl:1
	s_nop 1
	v_readlane_b32 s98, v183, 0
	v_readlane_b32 s99, v183, 16
	v_readlane_b32 s100, v183, 32
	v_readlane_b32 s101, v183, 48
	s_nop 1
	v_mov_b32_e32 v183, s98
	v_add_f32_e32 v183, s99, v183
	v_add_f32_e32 v183, s100, v183
	v_add_f32_e32 v183, s101, v183
	v_fmamk_f32 v183, v183, 0x3a800000, v182
	v_cmp_gt_f32_e32 vcc, 0x800000, v183
	v_mul_f32_e32 v181, 0x4b800000, v183
	s_nop 1
	v_cndmask_b32_e32 v183, v183, v181, vcc
	v_rsq_f32_e32 v183, v183
	s_nop 0
	v_mul_f32_e32 v181, 0x45800000, v183
	v_cndmask_b32_e32 v184, v183, v181, vcc
	v_mov_b32_e32 v185, v184
	v_pk_mul_f32 v[160:161], v[160:161], v[184:185]
	v_pk_mul_f32 v[162:163], v[162:163], v[184:185]
	v_pk_mul_f32 v[164:165], v[164:165], v[184:185]
	v_pk_mul_f32 v[166:167], v[166:167], v[184:185]
	v_pk_mul_f32 v[168:169], v[168:169], v[184:185]
	v_pk_mul_f32 v[170:171], v[170:171], v[184:185]
	v_pk_mul_f32 v[172:173], v[172:173], v[184:185]
	v_pk_mul_f32 v[174:175], v[174:175], v[184:185]
	v_pk_fma_f32 v[144:145], v[160:161], v[128:129], v[144:145]
	v_pk_fma_f32 v[146:147], v[162:163], v[130:131], v[146:147]
	v_pk_fma_f32 v[148:149], v[164:165], v[132:133], v[148:149]
	v_pk_fma_f32 v[150:151], v[166:167], v[134:135], v[150:151]
	v_pk_fma_f32 v[152:153], v[168:169], v[136:137], v[152:153]
	v_pk_fma_f32 v[154:155], v[170:171], v[138:139], v[154:155]
	v_pk_fma_f32 v[156:157], v[172:173], v[140:141], v[156:157]
	v_pk_fma_f32 v[158:159], v[174:175], v[142:143], v[158:159]
	v_pk_mul_f32 v[252:253], v[144:145], v[144:145]
	v_pk_mul_f32 v[254:255], v[146:147], v[146:147]
	v_pk_fma_f32 v[252:253], v[148:149], v[148:149], v[252:253]
	v_pk_fma_f32 v[254:255], v[150:151], v[150:151], v[254:255]
	v_pk_fma_f32 v[252:253], v[152:153], v[152:153], v[252:253]
	v_pk_fma_f32 v[254:255], v[154:155], v[154:155], v[254:255]
	v_pk_fma_f32 v[252:253], v[156:157], v[156:157], v[252:253]
	v_pk_fma_f32 v[254:255], v[158:159], v[158:159], v[254:255]
	v_pk_add_f32 v[252:253], v[252:253], v[254:255]
	s_nop 0
	v_add_f32_e32 v183, v252, v253
	s_nop 1
	v_add_f32_dpp v183, v183, v183 quad_perm:[1,0,3,2] row_mask:0xf bank_mask:0xf bound_ctrl:1
	s_nop 1
	v_add_f32_dpp v183, v183, v183 quad_perm:[2,3,0,1] row_mask:0xf bank_mask:0xf bound_ctrl:1
	s_nop 1
	v_add_f32_dpp v183, v183, v183 row_half_mirror row_mask:0xf bank_mask:0xf bound_ctrl:1
	s_nop 1
	v_add_f32_dpp v183, v183, v183 row_mirror row_mask:0xf bank_mask:0xf bound_ctrl:1
	s_nop 1
	v_readlane_b32 s98, v183, 0
	v_readlane_b32 s99, v183, 16
	v_readlane_b32 s100, v183, 32
	v_readlane_b32 s101, v183, 48
	s_nop 1
	v_mov_b32_e32 v183, s98
	v_add_f32_e32 v183, s99, v183
	v_add_f32_e32 v183, s100, v183
	v_add_f32_e32 v183, s101, v183
	v_fmamk_f32 v183, v183, 0x3a800000, v182
	v_cmp_gt_f32_e32 vcc, 0x800000, v183
	v_mul_f32_e32 v181, 0x4b800000, v183
	s_nop 1
	v_cndmask_b32_e32 v183, v183, v181, vcc
	v_rsq_f32_e32 v183, v183
	s_nop 0
	v_mul_f32_e32 v181, 0x45800000, v183
	v_cndmask_b32_e32 v184, v183, v181, vcc
	v_mov_b32_e32 v185, v184
	v_cvt_pk_bf16_f32 v16, v144, v145
	v_cvt_pk_bf16_f32 v17, v146, v147
	v_cvt_pk_bf16_f32 v18, v148, v149
	v_cvt_pk_bf16_f32 v19, v150, v151
	v_cvt_pk_bf16_f32 v20, v152, v153
	v_cvt_pk_bf16_f32 v21, v154, v155
	v_cvt_pk_bf16_f32 v22, v156, v157
	v_cvt_pk_bf16_f32 v23, v158, v159
	v_add_u32_e32 v181, 0x1c00000, v177
	global_store_dwordx4 v181, v[16:19], s[78:79]
	global_store_dwordx4 v181, v[20:23], s[78:79] offset:1024
	v_add_u32_e32 v236, 0x2000, v237
	s_mov_b64 exec, 1
	global_store_dword v236, v184, s[78:79]
	s_mov_b64 exec, -1
	s_waitcnt vmcnt(20)
	v_lshlrev_b32_e32 v144, 16, v32
	v_and_b32_e32 v145, 0xffff0000, v32
	v_lshlrev_b32_e32 v146, 16, v33
	v_and_b32_e32 v147, 0xffff0000, v33
	v_lshlrev_b32_e32 v148, 16, v34
	v_and_b32_e32 v149, 0xffff0000, v34
	v_lshlrev_b32_e32 v150, 16, v35
	v_and_b32_e32 v151, 0xffff0000, v35
	v_lshlrev_b32_e32 v152, 16, v36
	v_and_b32_e32 v153, 0xffff0000, v36
	v_lshlrev_b32_e32 v154, 16, v37
	v_and_b32_e32 v155, 0xffff0000, v37
	v_lshlrev_b32_e32 v156, 16, v38
	v_and_b32_e32 v157, 0xffff0000, v38
	v_lshlrev_b32_e32 v158, 16, v39
	v_and_b32_e32 v159, 0xffff0000, v39
	v_lshlrev_b32_e32 v160, 16, v40
	v_and_b32_e32 v161, 0xffff0000, v40
	v_lshlrev_b32_e32 v162, 16, v41
	v_and_b32_e32 v163, 0xffff0000, v41
	v_lshlrev_b32_e32 v164, 16, v42
	v_and_b32_e32 v165, 0xffff0000, v42
	v_lshlrev_b32_e32 v166, 16, v43
	v_and_b32_e32 v167, 0xffff0000, v43
	v_lshlrev_b32_e32 v168, 16, v44
	v_and_b32_e32 v169, 0xffff0000, v44
	v_lshlrev_b32_e32 v170, 16, v45
	v_and_b32_e32 v171, 0xffff0000, v45
	v_lshlrev_b32_e32 v172, 16, v46
	v_and_b32_e32 v173, 0xffff0000, v46
	v_lshlrev_b32_e32 v174, 16, v47
	v_and_b32_e32 v175, 0xffff0000, v47
	v_pk_mul_f32 v[252:253], v[160:161], v[160:161]
	v_pk_mul_f32 v[254:255], v[162:163], v[162:163]
	v_pk_fma_f32 v[252:253], v[164:165], v[164:165], v[252:253]
	v_pk_fma_f32 v[254:255], v[166:167], v[166:167], v[254:255]
	v_pk_fma_f32 v[252:253], v[168:169], v[168:169], v[252:253]
	v_pk_fma_f32 v[254:255], v[170:171], v[170:171], v[254:255]
	v_pk_fma_f32 v[252:253], v[172:173], v[172:173], v[252:253]
	v_pk_fma_f32 v[254:255], v[174:175], v[174:175], v[254:255]
	v_pk_add_f32 v[252:253], v[252:253], v[254:255]
	s_nop 0
	v_add_f32_e32 v183, v252, v253
	s_nop 1
	v_add_f32_dpp v183, v183, v183 quad_perm:[1,0,3,2] row_mask:0xf bank_mask:0xf bound_ctrl:1
	s_nop 1
	v_add_f32_dpp v183, v183, v183 quad_perm:[2,3,0,1] row_mask:0xf bank_mask:0xf bound_ctrl:1
	s_nop 1
	v_add_f32_dpp v183, v183, v183 row_half_mirror row_mask:0xf bank_mask:0xf bound_ctrl:1
	s_nop 1
	v_add_f32_dpp v183, v183, v183 row_mirror row_mask:0xf bank_mask:0xf bound_ctrl:1
	s_nop 1
	v_readlane_b32 s98, v183, 0
	v_readlane_b32 s99, v183, 16
	v_readlane_b32 s100, v183, 32
	v_readlane_b32 s101, v183, 48
	s_nop 1
	v_mov_b32_e32 v183, s98
	v_add_f32_e32 v183, s99, v183
	v_add_f32_e32 v183, s100, v183
	v_add_f32_e32 v183, s101, v183
	v_fmamk_f32 v183, v183, 0x3a800000, v182
	v_cmp_gt_f32_e32 vcc, 0x800000, v183
	v_mul_f32_e32 v181, 0x4b800000, v183
	s_nop 1
	v_cndmask_b32_e32 v183, v183, v181, vcc
	v_rsq_f32_e32 v183, v183
	s_nop 0
	v_mul_f32_e32 v181, 0x45800000, v183
	v_cndmask_b32_e32 v184, v183, v181, vcc
	v_mov_b32_e32 v185, v184
	v_pk_mul_f32 v[160:161], v[160:161], v[184:185]
	v_pk_mul_f32 v[162:163], v[162:163], v[184:185]
	v_pk_mul_f32 v[164:165], v[164:165], v[184:185]
	v_pk_mul_f32 v[166:167], v[166:167], v[184:185]
	v_pk_mul_f32 v[168:169], v[168:169], v[184:185]
	v_pk_mul_f32 v[170:171], v[170:171], v[184:185]
	v_pk_mul_f32 v[172:173], v[172:173], v[184:185]
	v_pk_mul_f32 v[174:175], v[174:175], v[184:185]
	v_pk_fma_f32 v[144:145], v[160:161], v[128:129], v[144:145]
	v_pk_fma_f32 v[146:147], v[162:163], v[130:131], v[146:147]
	v_pk_fma_f32 v[148:149], v[164:165], v[132:133], v[148:149]
	v_pk_fma_f32 v[150:151], v[166:167], v[134:135], v[150:151]
	v_pk_fma_f32 v[152:153], v[168:169], v[136:137], v[152:153]
	v_pk_fma_f32 v[154:155], v[170:171], v[138:139], v[154:155]
	v_pk_fma_f32 v[156:157], v[172:173], v[140:141], v[156:157]
	v_pk_fma_f32 v[158:159], v[174:175], v[142:143], v[158:159]
	v_pk_mul_f32 v[252:253], v[144:145], v[144:145]
	v_pk_mul_f32 v[254:255], v[146:147], v[146:147]
	v_pk_fma_f32 v[252:253], v[148:149], v[148:149], v[252:253]
	v_pk_fma_f32 v[254:255], v[150:151], v[150:151], v[254:255]
	v_pk_fma_f32 v[252:253], v[152:153], v[152:153], v[252:253]
	v_pk_fma_f32 v[254:255], v[154:155], v[154:155], v[254:255]
	v_pk_fma_f32 v[252:253], v[156:157], v[156:157], v[252:253]
	v_pk_fma_f32 v[254:255], v[158:159], v[158:159], v[254:255]
	v_pk_add_f32 v[252:253], v[252:253], v[254:255]
	s_nop 0
	v_add_f32_e32 v183, v252, v253
	s_nop 1
	v_add_f32_dpp v183, v183, v183 quad_perm:[1,0,3,2] row_mask:0xf bank_mask:0xf bound_ctrl:1
	s_nop 1
	v_add_f32_dpp v183, v183, v183 quad_perm:[2,3,0,1] row_mask:0xf bank_mask:0xf bound_ctrl:1
	s_nop 1
	v_add_f32_dpp v183, v183, v183 row_half_mirror row_mask:0xf bank_mask:0xf bound_ctrl:1
	s_nop 1
	v_add_f32_dpp v183, v183, v183 row_mirror row_mask:0xf bank_mask:0xf bound_ctrl:1
	s_nop 1
	v_readlane_b32 s98, v183, 0
	v_readlane_b32 s99, v183, 16
	v_readlane_b32 s100, v183, 32
	v_readlane_b32 s101, v183, 48
	s_nop 1
	v_mov_b32_e32 v183, s98
	v_add_f32_e32 v183, s99, v183
	v_add_f32_e32 v183, s100, v183
	v_add_f32_e32 v183, s101, v183
	v_fmamk_f32 v183, v183, 0x3a800000, v182
	v_cmp_gt_f32_e32 vcc, 0x800000, v183
	v_mul_f32_e32 v181, 0x4b800000, v183
	s_nop 1
	v_cndmask_b32_e32 v183, v183, v181, vcc
	v_rsq_f32_e32 v183, v183
	s_nop 0
	v_mul_f32_e32 v181, 0x45800000, v183
	v_cndmask_b32_e32 v184, v183, v181, vcc
	v_mov_b32_e32 v185, v184
	v_cvt_pk_bf16_f32 v32, v144, v145
	v_cvt_pk_bf16_f32 v33, v146, v147
	v_cvt_pk_bf16_f32 v34, v148, v149
	v_cvt_pk_bf16_f32 v35, v150, v151
	v_cvt_pk_bf16_f32 v36, v152, v153
	v_cvt_pk_bf16_f32 v37, v154, v155
	v_cvt_pk_bf16_f32 v38, v156, v157
	v_cvt_pk_bf16_f32 v39, v158, v159
	v_add_u32_e32 v181, 0x2000000, v177
	global_store_dwordx4 v181, v[32:35], s[78:79]
	global_store_dwordx4 v181, v[36:39], s[78:79] offset:1024
	v_add_u32_e32 v236, 0x4000, v237
	s_mov_b64 exec, 1
	global_store_dword v236, v184, s[78:79]
	s_mov_b64 exec, -1
	s_waitcnt vmcnt(16)
	v_lshlrev_b32_e32 v144, 16, v48
	v_and_b32_e32 v145, 0xffff0000, v48
	v_lshlrev_b32_e32 v146, 16, v49
	v_and_b32_e32 v147, 0xffff0000, v49
	v_lshlrev_b32_e32 v148, 16, v50
	v_and_b32_e32 v149, 0xffff0000, v50
	v_lshlrev_b32_e32 v150, 16, v51
	v_and_b32_e32 v151, 0xffff0000, v51
	v_lshlrev_b32_e32 v152, 16, v52
	v_and_b32_e32 v153, 0xffff0000, v52
	v_lshlrev_b32_e32 v154, 16, v53
	v_and_b32_e32 v155, 0xffff0000, v53
	v_lshlrev_b32_e32 v156, 16, v54
	v_and_b32_e32 v157, 0xffff0000, v54
	v_lshlrev_b32_e32 v158, 16, v55
	v_and_b32_e32 v159, 0xffff0000, v55
	v_lshlrev_b32_e32 v160, 16, v56
	v_and_b32_e32 v161, 0xffff0000, v56
	v_lshlrev_b32_e32 v162, 16, v57
	v_and_b32_e32 v163, 0xffff0000, v57
	v_lshlrev_b32_e32 v164, 16, v58
	v_and_b32_e32 v165, 0xffff0000, v58
	v_lshlrev_b32_e32 v166, 16, v59
	v_and_b32_e32 v167, 0xffff0000, v59
	v_lshlrev_b32_e32 v168, 16, v60
	v_and_b32_e32 v169, 0xffff0000, v60
	v_lshlrev_b32_e32 v170, 16, v61
	v_and_b32_e32 v171, 0xffff0000, v61
	v_lshlrev_b32_e32 v172, 16, v62
	v_and_b32_e32 v173, 0xffff0000, v62
	v_lshlrev_b32_e32 v174, 16, v63
	v_and_b32_e32 v175, 0xffff0000, v63
	v_pk_mul_f32 v[252:253], v[160:161], v[160:161]
	v_pk_mul_f32 v[254:255], v[162:163], v[162:163]
	v_pk_fma_f32 v[252:253], v[164:165], v[164:165], v[252:253]
	v_pk_fma_f32 v[254:255], v[166:167], v[166:167], v[254:255]
	v_pk_fma_f32 v[252:253], v[168:169], v[168:169], v[252:253]
	v_pk_fma_f32 v[254:255], v[170:171], v[170:171], v[254:255]
	v_pk_fma_f32 v[252:253], v[172:173], v[172:173], v[252:253]
	v_pk_fma_f32 v[254:255], v[174:175], v[174:175], v[254:255]
	v_pk_add_f32 v[252:253], v[252:253], v[254:255]
	s_nop 0
	v_add_f32_e32 v183, v252, v253
	s_nop 1
	v_add_f32_dpp v183, v183, v183 quad_perm:[1,0,3,2] row_mask:0xf bank_mask:0xf bound_ctrl:1
	s_nop 1
	v_add_f32_dpp v183, v183, v183 quad_perm:[2,3,0,1] row_mask:0xf bank_mask:0xf bound_ctrl:1
	s_nop 1
	v_add_f32_dpp v183, v183, v183 row_half_mirror row_mask:0xf bank_mask:0xf bound_ctrl:1
	s_nop 1
	v_add_f32_dpp v183, v183, v183 row_mirror row_mask:0xf bank_mask:0xf bound_ctrl:1
	s_nop 1
	v_readlane_b32 s98, v183, 0
	v_readlane_b32 s99, v183, 16
	v_readlane_b32 s100, v183, 32
	v_readlane_b32 s101, v183, 48
	s_nop 1
	v_mov_b32_e32 v183, s98
	v_add_f32_e32 v183, s99, v183
	v_add_f32_e32 v183, s100, v183
	v_add_f32_e32 v183, s101, v183
	v_fmamk_f32 v183, v183, 0x3a800000, v182
	v_cmp_gt_f32_e32 vcc, 0x800000, v183
	v_mul_f32_e32 v181, 0x4b800000, v183
	s_nop 1
	v_cndmask_b32_e32 v183, v183, v181, vcc
	v_rsq_f32_e32 v183, v183
	s_nop 0
	v_mul_f32_e32 v181, 0x45800000, v183
	v_cndmask_b32_e32 v184, v183, v181, vcc
	v_mov_b32_e32 v185, v184
	v_pk_mul_f32 v[160:161], v[160:161], v[184:185]
	v_pk_mul_f32 v[162:163], v[162:163], v[184:185]
	v_pk_mul_f32 v[164:165], v[164:165], v[184:185]
	v_pk_mul_f32 v[166:167], v[166:167], v[184:185]
	v_pk_mul_f32 v[168:169], v[168:169], v[184:185]
	v_pk_mul_f32 v[170:171], v[170:171], v[184:185]
	v_pk_mul_f32 v[172:173], v[172:173], v[184:185]
	v_pk_mul_f32 v[174:175], v[174:175], v[184:185]
	v_pk_fma_f32 v[144:145], v[160:161], v[128:129], v[144:145]
	v_pk_fma_f32 v[146:147], v[162:163], v[130:131], v[146:147]
	v_pk_fma_f32 v[148:149], v[164:165], v[132:133], v[148:149]
	v_pk_fma_f32 v[150:151], v[166:167], v[134:135], v[150:151]
	v_pk_fma_f32 v[152:153], v[168:169], v[136:137], v[152:153]
	v_pk_fma_f32 v[154:155], v[170:171], v[138:139], v[154:155]
	v_pk_fma_f32 v[156:157], v[172:173], v[140:141], v[156:157]
	v_pk_fma_f32 v[158:159], v[174:175], v[142:143], v[158:159]
	v_pk_mul_f32 v[252:253], v[144:145], v[144:145]
	v_pk_mul_f32 v[254:255], v[146:147], v[146:147]
	v_pk_fma_f32 v[252:253], v[148:149], v[148:149], v[252:253]
	v_pk_fma_f32 v[254:255], v[150:151], v[150:151], v[254:255]
	v_pk_fma_f32 v[252:253], v[152:153], v[152:153], v[252:253]
	v_pk_fma_f32 v[254:255], v[154:155], v[154:155], v[254:255]
	v_pk_fma_f32 v[252:253], v[156:157], v[156:157], v[252:253]
	v_pk_fma_f32 v[254:255], v[158:159], v[158:159], v[254:255]
	v_pk_add_f32 v[252:253], v[252:253], v[254:255]
	s_nop 0
	v_add_f32_e32 v183, v252, v253
	s_nop 1
	v_add_f32_dpp v183, v183, v183 quad_perm:[1,0,3,2] row_mask:0xf bank_mask:0xf bound_ctrl:1
	s_nop 1
	v_add_f32_dpp v183, v183, v183 quad_perm:[2,3,0,1] row_mask:0xf bank_mask:0xf bound_ctrl:1
	s_nop 1
	v_add_f32_dpp v183, v183, v183 row_half_mirror row_mask:0xf bank_mask:0xf bound_ctrl:1
	s_nop 1
	v_add_f32_dpp v183, v183, v183 row_mirror row_mask:0xf bank_mask:0xf bound_ctrl:1
	s_nop 1
	v_readlane_b32 s98, v183, 0
	v_readlane_b32 s99, v183, 16
	v_readlane_b32 s100, v183, 32
	v_readlane_b32 s101, v183, 48
	s_nop 1
	v_mov_b32_e32 v183, s98
	v_add_f32_e32 v183, s99, v183
	v_add_f32_e32 v183, s100, v183
	v_add_f32_e32 v183, s101, v183
	v_fmamk_f32 v183, v183, 0x3a800000, v182
	v_cmp_gt_f32_e32 vcc, 0x800000, v183
	v_mul_f32_e32 v181, 0x4b800000, v183
	s_nop 1
	v_cndmask_b32_e32 v183, v183, v181, vcc
	v_rsq_f32_e32 v183, v183
	s_nop 0
	v_mul_f32_e32 v181, 0x45800000, v183
	v_cndmask_b32_e32 v184, v183, v181, vcc
	v_mov_b32_e32 v185, v184
	v_cvt_pk_bf16_f32 v48, v144, v145
	v_cvt_pk_bf16_f32 v49, v146, v147
	v_cvt_pk_bf16_f32 v50, v148, v149
	v_cvt_pk_bf16_f32 v51, v150, v151
	v_cvt_pk_bf16_f32 v52, v152, v153
	v_cvt_pk_bf16_f32 v53, v154, v155
	v_cvt_pk_bf16_f32 v54, v156, v157
	v_cvt_pk_bf16_f32 v55, v158, v159
	v_add_u32_e32 v181, 0x2400000, v177
	global_store_dwordx4 v181, v[48:51], s[78:79]
	global_store_dwordx4 v181, v[52:55], s[78:79] offset:1024
	v_add_u32_e32 v236, 0x6000, v237
	s_mov_b64 exec, 1
	global_store_dword v236, v184, s[78:79]
	s_mov_b64 exec, -1
	s_waitcnt vmcnt(12)
	v_lshlrev_b32_e32 v144, 16, v64
	v_and_b32_e32 v145, 0xffff0000, v64
	v_lshlrev_b32_e32 v146, 16, v65
	v_and_b32_e32 v147, 0xffff0000, v65
	v_lshlrev_b32_e32 v148, 16, v66
	v_and_b32_e32 v149, 0xffff0000, v66
	v_lshlrev_b32_e32 v150, 16, v67
	v_and_b32_e32 v151, 0xffff0000, v67
	v_lshlrev_b32_e32 v152, 16, v68
	v_and_b32_e32 v153, 0xffff0000, v68
	v_lshlrev_b32_e32 v154, 16, v69
	v_and_b32_e32 v155, 0xffff0000, v69
	v_lshlrev_b32_e32 v156, 16, v70
	v_and_b32_e32 v157, 0xffff0000, v70
	v_lshlrev_b32_e32 v158, 16, v71
	v_and_b32_e32 v159, 0xffff0000, v71
	v_lshlrev_b32_e32 v160, 16, v72
	v_and_b32_e32 v161, 0xffff0000, v72
	v_lshlrev_b32_e32 v162, 16, v73
	v_and_b32_e32 v163, 0xffff0000, v73
	v_lshlrev_b32_e32 v164, 16, v74
	v_and_b32_e32 v165, 0xffff0000, v74
	v_lshlrev_b32_e32 v166, 16, v75
	v_and_b32_e32 v167, 0xffff0000, v75
	v_lshlrev_b32_e32 v168, 16, v76
	v_and_b32_e32 v169, 0xffff0000, v76
	v_lshlrev_b32_e32 v170, 16, v77
	v_and_b32_e32 v171, 0xffff0000, v77
	v_lshlrev_b32_e32 v172, 16, v78
	v_and_b32_e32 v173, 0xffff0000, v78
	v_lshlrev_b32_e32 v174, 16, v79
	v_and_b32_e32 v175, 0xffff0000, v79
	v_pk_mul_f32 v[252:253], v[160:161], v[160:161]
	v_pk_mul_f32 v[254:255], v[162:163], v[162:163]
	v_pk_fma_f32 v[252:253], v[164:165], v[164:165], v[252:253]
	v_pk_fma_f32 v[254:255], v[166:167], v[166:167], v[254:255]
	v_pk_fma_f32 v[252:253], v[168:169], v[168:169], v[252:253]
	v_pk_fma_f32 v[254:255], v[170:171], v[170:171], v[254:255]
	v_pk_fma_f32 v[252:253], v[172:173], v[172:173], v[252:253]
	v_pk_fma_f32 v[254:255], v[174:175], v[174:175], v[254:255]
	v_pk_add_f32 v[252:253], v[252:253], v[254:255]
	s_nop 0
	v_add_f32_e32 v183, v252, v253
	s_nop 1
	v_add_f32_dpp v183, v183, v183 quad_perm:[1,0,3,2] row_mask:0xf bank_mask:0xf bound_ctrl:1
	s_nop 1
	v_add_f32_dpp v183, v183, v183 quad_perm:[2,3,0,1] row_mask:0xf bank_mask:0xf bound_ctrl:1
	s_nop 1
	v_add_f32_dpp v183, v183, v183 row_half_mirror row_mask:0xf bank_mask:0xf bound_ctrl:1
	s_nop 1
	v_add_f32_dpp v183, v183, v183 row_mirror row_mask:0xf bank_mask:0xf bound_ctrl:1
	s_nop 1
	v_readlane_b32 s98, v183, 0
	v_readlane_b32 s99, v183, 16
	v_readlane_b32 s100, v183, 32
	v_readlane_b32 s101, v183, 48
	s_nop 1
	v_mov_b32_e32 v183, s98
	v_add_f32_e32 v183, s99, v183
	v_add_f32_e32 v183, s100, v183
	v_add_f32_e32 v183, s101, v183
	v_fmamk_f32 v183, v183, 0x3a800000, v182
	v_cmp_gt_f32_e32 vcc, 0x800000, v183
	v_mul_f32_e32 v181, 0x4b800000, v183
	s_nop 1
	v_cndmask_b32_e32 v183, v183, v181, vcc
	v_rsq_f32_e32 v183, v183
	s_nop 0
	v_mul_f32_e32 v181, 0x45800000, v183
	v_cndmask_b32_e32 v184, v183, v181, vcc
	v_mov_b32_e32 v185, v184
	v_pk_mul_f32 v[160:161], v[160:161], v[184:185]
	v_pk_mul_f32 v[162:163], v[162:163], v[184:185]
	v_pk_mul_f32 v[164:165], v[164:165], v[184:185]
	v_pk_mul_f32 v[166:167], v[166:167], v[184:185]
	v_pk_mul_f32 v[168:169], v[168:169], v[184:185]
	v_pk_mul_f32 v[170:171], v[170:171], v[184:185]
	v_pk_mul_f32 v[172:173], v[172:173], v[184:185]
	v_pk_mul_f32 v[174:175], v[174:175], v[184:185]
	v_pk_fma_f32 v[144:145], v[160:161], v[128:129], v[144:145]
	v_pk_fma_f32 v[146:147], v[162:163], v[130:131], v[146:147]
	v_pk_fma_f32 v[148:149], v[164:165], v[132:133], v[148:149]
	v_pk_fma_f32 v[150:151], v[166:167], v[134:135], v[150:151]
	v_pk_fma_f32 v[152:153], v[168:169], v[136:137], v[152:153]
	v_pk_fma_f32 v[154:155], v[170:171], v[138:139], v[154:155]
	v_pk_fma_f32 v[156:157], v[172:173], v[140:141], v[156:157]
	v_pk_fma_f32 v[158:159], v[174:175], v[142:143], v[158:159]
	v_pk_mul_f32 v[252:253], v[144:145], v[144:145]
	v_pk_mul_f32 v[254:255], v[146:147], v[146:147]
	v_pk_fma_f32 v[252:253], v[148:149], v[148:149], v[252:253]
	v_pk_fma_f32 v[254:255], v[150:151], v[150:151], v[254:255]
	v_pk_fma_f32 v[252:253], v[152:153], v[152:153], v[252:253]
	v_pk_fma_f32 v[254:255], v[154:155], v[154:155], v[254:255]
	v_pk_fma_f32 v[252:253], v[156:157], v[156:157], v[252:253]
	v_pk_fma_f32 v[254:255], v[158:159], v[158:159], v[254:255]
	v_pk_add_f32 v[252:253], v[252:253], v[254:255]
	s_nop 0
	v_add_f32_e32 v183, v252, v253
	s_nop 1
	v_add_f32_dpp v183, v183, v183 quad_perm:[1,0,3,2] row_mask:0xf bank_mask:0xf bound_ctrl:1
	s_nop 1
	v_add_f32_dpp v183, v183, v183 quad_perm:[2,3,0,1] row_mask:0xf bank_mask:0xf bound_ctrl:1
	s_nop 1
	v_add_f32_dpp v183, v183, v183 row_half_mirror row_mask:0xf bank_mask:0xf bound_ctrl:1
	s_nop 1
	v_add_f32_dpp v183, v183, v183 row_mirror row_mask:0xf bank_mask:0xf bound_ctrl:1
	s_nop 1
	v_readlane_b32 s98, v183, 0
	v_readlane_b32 s99, v183, 16
	v_readlane_b32 s100, v183, 32
	v_readlane_b32 s101, v183, 48
	s_nop 1
	v_mov_b32_e32 v183, s98
	v_add_f32_e32 v183, s99, v183
	v_add_f32_e32 v183, s100, v183
	v_add_f32_e32 v183, s101, v183
	v_fmamk_f32 v183, v183, 0x3a800000, v182
	v_cmp_gt_f32_e32 vcc, 0x800000, v183
	v_mul_f32_e32 v181, 0x4b800000, v183
	s_nop 1
	v_cndmask_b32_e32 v183, v183, v181, vcc
	v_rsq_f32_e32 v183, v183
	s_nop 0
	v_mul_f32_e32 v181, 0x45800000, v183
	v_cndmask_b32_e32 v184, v183, v181, vcc
	v_mov_b32_e32 v185, v184
	v_cvt_pk_bf16_f32 v64, v144, v145
	v_cvt_pk_bf16_f32 v65, v146, v147
	v_cvt_pk_bf16_f32 v66, v148, v149
	v_cvt_pk_bf16_f32 v67, v150, v151
	v_cvt_pk_bf16_f32 v68, v152, v153
	v_cvt_pk_bf16_f32 v69, v154, v155
	v_cvt_pk_bf16_f32 v70, v156, v157
	v_cvt_pk_bf16_f32 v71, v158, v159
	v_add_u32_e32 v181, 0x2800000, v177
	global_store_dwordx4 v181, v[64:67], s[78:79]
	global_store_dwordx4 v181, v[68:71], s[78:79] offset:1024
	v_add_u32_e32 v236, 0x8000, v237
	s_mov_b64 exec, 1
	global_store_dword v236, v184, s[78:79]
	s_mov_b64 exec, -1
	s_waitcnt vmcnt(8)
	v_lshlrev_b32_e32 v144, 16, v80
	v_and_b32_e32 v145, 0xffff0000, v80
	v_lshlrev_b32_e32 v146, 16, v81
	v_and_b32_e32 v147, 0xffff0000, v81
	v_lshlrev_b32_e32 v148, 16, v82
	v_and_b32_e32 v149, 0xffff0000, v82
	v_lshlrev_b32_e32 v150, 16, v83
	v_and_b32_e32 v151, 0xffff0000, v83
	v_lshlrev_b32_e32 v152, 16, v84
	v_and_b32_e32 v153, 0xffff0000, v84
	v_lshlrev_b32_e32 v154, 16, v85
	v_and_b32_e32 v155, 0xffff0000, v85
	v_lshlrev_b32_e32 v156, 16, v86
	v_and_b32_e32 v157, 0xffff0000, v86
	v_lshlrev_b32_e32 v158, 16, v87
	v_and_b32_e32 v159, 0xffff0000, v87
	v_lshlrev_b32_e32 v160, 16, v88
	v_and_b32_e32 v161, 0xffff0000, v88
	v_lshlrev_b32_e32 v162, 16, v89
	v_and_b32_e32 v163, 0xffff0000, v89
	v_lshlrev_b32_e32 v164, 16, v90
	v_and_b32_e32 v165, 0xffff0000, v90
	v_lshlrev_b32_e32 v166, 16, v91
	v_and_b32_e32 v167, 0xffff0000, v91
	v_lshlrev_b32_e32 v168, 16, v92
	v_and_b32_e32 v169, 0xffff0000, v92
	v_lshlrev_b32_e32 v170, 16, v93
	v_and_b32_e32 v171, 0xffff0000, v93
	v_lshlrev_b32_e32 v172, 16, v94
	v_and_b32_e32 v173, 0xffff0000, v94
	v_lshlrev_b32_e32 v174, 16, v95
	v_and_b32_e32 v175, 0xffff0000, v95
	v_pk_mul_f32 v[252:253], v[160:161], v[160:161]
	v_pk_mul_f32 v[254:255], v[162:163], v[162:163]
	v_pk_fma_f32 v[252:253], v[164:165], v[164:165], v[252:253]
	v_pk_fma_f32 v[254:255], v[166:167], v[166:167], v[254:255]
	v_pk_fma_f32 v[252:253], v[168:169], v[168:169], v[252:253]
	v_pk_fma_f32 v[254:255], v[170:171], v[170:171], v[254:255]
	v_pk_fma_f32 v[252:253], v[172:173], v[172:173], v[252:253]
	v_pk_fma_f32 v[254:255], v[174:175], v[174:175], v[254:255]
	v_pk_add_f32 v[252:253], v[252:253], v[254:255]
	s_nop 0
	v_add_f32_e32 v183, v252, v253
	s_nop 1
	v_add_f32_dpp v183, v183, v183 quad_perm:[1,0,3,2] row_mask:0xf bank_mask:0xf bound_ctrl:1
	s_nop 1
	v_add_f32_dpp v183, v183, v183 quad_perm:[2,3,0,1] row_mask:0xf bank_mask:0xf bound_ctrl:1
	s_nop 1
	v_add_f32_dpp v183, v183, v183 row_half_mirror row_mask:0xf bank_mask:0xf bound_ctrl:1
	s_nop 1
	v_add_f32_dpp v183, v183, v183 row_mirror row_mask:0xf bank_mask:0xf bound_ctrl:1
	s_nop 1
	v_readlane_b32 s98, v183, 0
	v_readlane_b32 s99, v183, 16
	v_readlane_b32 s100, v183, 32
	v_readlane_b32 s101, v183, 48
	s_nop 1
	v_mov_b32_e32 v183, s98
	v_add_f32_e32 v183, s99, v183
	v_add_f32_e32 v183, s100, v183
	v_add_f32_e32 v183, s101, v183
	v_fmamk_f32 v183, v183, 0x3a800000, v182
	v_cmp_gt_f32_e32 vcc, 0x800000, v183
	v_mul_f32_e32 v181, 0x4b800000, v183
	s_nop 1
	v_cndmask_b32_e32 v183, v183, v181, vcc
	v_rsq_f32_e32 v183, v183
	s_nop 0
	v_mul_f32_e32 v181, 0x45800000, v183
	v_cndmask_b32_e32 v184, v183, v181, vcc
	v_mov_b32_e32 v185, v184
	v_pk_mul_f32 v[160:161], v[160:161], v[184:185]
	v_pk_mul_f32 v[162:163], v[162:163], v[184:185]
	v_pk_mul_f32 v[164:165], v[164:165], v[184:185]
	v_pk_mul_f32 v[166:167], v[166:167], v[184:185]
	v_pk_mul_f32 v[168:169], v[168:169], v[184:185]
	v_pk_mul_f32 v[170:171], v[170:171], v[184:185]
	v_pk_mul_f32 v[172:173], v[172:173], v[184:185]
	v_pk_mul_f32 v[174:175], v[174:175], v[184:185]
	v_pk_fma_f32 v[144:145], v[160:161], v[128:129], v[144:145]
	v_pk_fma_f32 v[146:147], v[162:163], v[130:131], v[146:147]
	v_pk_fma_f32 v[148:149], v[164:165], v[132:133], v[148:149]
	v_pk_fma_f32 v[150:151], v[166:167], v[134:135], v[150:151]
	v_pk_fma_f32 v[152:153], v[168:169], v[136:137], v[152:153]
	v_pk_fma_f32 v[154:155], v[170:171], v[138:139], v[154:155]
	v_pk_fma_f32 v[156:157], v[172:173], v[140:141], v[156:157]
	v_pk_fma_f32 v[158:159], v[174:175], v[142:143], v[158:159]
	v_pk_mul_f32 v[252:253], v[144:145], v[144:145]
	v_pk_mul_f32 v[254:255], v[146:147], v[146:147]
	v_pk_fma_f32 v[252:253], v[148:149], v[148:149], v[252:253]
	v_pk_fma_f32 v[254:255], v[150:151], v[150:151], v[254:255]
	v_pk_fma_f32 v[252:253], v[152:153], v[152:153], v[252:253]
	v_pk_fma_f32 v[254:255], v[154:155], v[154:155], v[254:255]
	v_pk_fma_f32 v[252:253], v[156:157], v[156:157], v[252:253]
	v_pk_fma_f32 v[254:255], v[158:159], v[158:159], v[254:255]
	v_pk_add_f32 v[252:253], v[252:253], v[254:255]
	s_nop 0
	v_add_f32_e32 v183, v252, v253
	s_nop 1
	v_add_f32_dpp v183, v183, v183 quad_perm:[1,0,3,2] row_mask:0xf bank_mask:0xf bound_ctrl:1
	s_nop 1
	v_add_f32_dpp v183, v183, v183 quad_perm:[2,3,0,1] row_mask:0xf bank_mask:0xf bound_ctrl:1
	s_nop 1
	v_add_f32_dpp v183, v183, v183 row_half_mirror row_mask:0xf bank_mask:0xf bound_ctrl:1
	s_nop 1
	v_add_f32_dpp v183, v183, v183 row_mirror row_mask:0xf bank_mask:0xf bound_ctrl:1
	s_nop 1
	v_readlane_b32 s98, v183, 0
	v_readlane_b32 s99, v183, 16
	v_readlane_b32 s100, v183, 32
	v_readlane_b32 s101, v183, 48
	s_nop 1
	v_mov_b32_e32 v183, s98
	v_add_f32_e32 v183, s99, v183
	v_add_f32_e32 v183, s100, v183
	v_add_f32_e32 v183, s101, v183
	v_fmamk_f32 v183, v183, 0x3a800000, v182
	v_cmp_gt_f32_e32 vcc, 0x800000, v183
	v_mul_f32_e32 v181, 0x4b800000, v183
	s_nop 1
	v_cndmask_b32_e32 v183, v183, v181, vcc
	v_rsq_f32_e32 v183, v183
	s_nop 0
	v_mul_f32_e32 v181, 0x45800000, v183
	v_cndmask_b32_e32 v184, v183, v181, vcc
	v_mov_b32_e32 v185, v184
	v_cvt_pk_bf16_f32 v80, v144, v145
	v_cvt_pk_bf16_f32 v81, v146, v147
	v_cvt_pk_bf16_f32 v82, v148, v149
	v_cvt_pk_bf16_f32 v83, v150, v151
	v_cvt_pk_bf16_f32 v84, v152, v153
	v_cvt_pk_bf16_f32 v85, v154, v155
	v_cvt_pk_bf16_f32 v86, v156, v157
	v_cvt_pk_bf16_f32 v87, v158, v159
	v_add_u32_e32 v181, 0x2c00000, v177
	global_store_dwordx4 v181, v[80:83], s[78:79]
	global_store_dwordx4 v181, v[84:87], s[78:79] offset:1024
	v_add_u32_e32 v236, 0xa000, v237
	s_mov_b64 exec, 1
	global_store_dword v236, v184, s[78:79]
	s_mov_b64 exec, -1
	s_waitcnt vmcnt(4)
	v_lshlrev_b32_e32 v144, 16, v96
	v_and_b32_e32 v145, 0xffff0000, v96
	v_lshlrev_b32_e32 v146, 16, v97
	v_and_b32_e32 v147, 0xffff0000, v97
	v_lshlrev_b32_e32 v148, 16, v98
	v_and_b32_e32 v149, 0xffff0000, v98
	v_lshlrev_b32_e32 v150, 16, v99
	v_and_b32_e32 v151, 0xffff0000, v99
	v_lshlrev_b32_e32 v152, 16, v100
	v_and_b32_e32 v153, 0xffff0000, v100
	v_lshlrev_b32_e32 v154, 16, v101
	v_and_b32_e32 v155, 0xffff0000, v101
	v_lshlrev_b32_e32 v156, 16, v102
	v_and_b32_e32 v157, 0xffff0000, v102
	v_lshlrev_b32_e32 v158, 16, v103
	v_and_b32_e32 v159, 0xffff0000, v103
	v_lshlrev_b32_e32 v160, 16, v104
	v_and_b32_e32 v161, 0xffff0000, v104
	v_lshlrev_b32_e32 v162, 16, v105
	v_and_b32_e32 v163, 0xffff0000, v105
	v_lshlrev_b32_e32 v164, 16, v106
	v_and_b32_e32 v165, 0xffff0000, v106
	v_lshlrev_b32_e32 v166, 16, v107
	v_and_b32_e32 v167, 0xffff0000, v107
	v_lshlrev_b32_e32 v168, 16, v108
	v_and_b32_e32 v169, 0xffff0000, v108
	v_lshlrev_b32_e32 v170, 16, v109
	v_and_b32_e32 v171, 0xffff0000, v109
	v_lshlrev_b32_e32 v172, 16, v110
	v_and_b32_e32 v173, 0xffff0000, v110
	v_lshlrev_b32_e32 v174, 16, v111
	v_and_b32_e32 v175, 0xffff0000, v111
	v_pk_mul_f32 v[252:253], v[160:161], v[160:161]
	v_pk_mul_f32 v[254:255], v[162:163], v[162:163]
	v_pk_fma_f32 v[252:253], v[164:165], v[164:165], v[252:253]
	v_pk_fma_f32 v[254:255], v[166:167], v[166:167], v[254:255]
	v_pk_fma_f32 v[252:253], v[168:169], v[168:169], v[252:253]
	v_pk_fma_f32 v[254:255], v[170:171], v[170:171], v[254:255]
	v_pk_fma_f32 v[252:253], v[172:173], v[172:173], v[252:253]
	v_pk_fma_f32 v[254:255], v[174:175], v[174:175], v[254:255]
	v_pk_add_f32 v[252:253], v[252:253], v[254:255]
	s_nop 0
	v_add_f32_e32 v183, v252, v253
	s_nop 1
	v_add_f32_dpp v183, v183, v183 quad_perm:[1,0,3,2] row_mask:0xf bank_mask:0xf bound_ctrl:1
	s_nop 1
	v_add_f32_dpp v183, v183, v183 quad_perm:[2,3,0,1] row_mask:0xf bank_mask:0xf bound_ctrl:1
	s_nop 1
	v_add_f32_dpp v183, v183, v183 row_half_mirror row_mask:0xf bank_mask:0xf bound_ctrl:1
	s_nop 1
	v_add_f32_dpp v183, v183, v183 row_mirror row_mask:0xf bank_mask:0xf bound_ctrl:1
	s_nop 1
	v_readlane_b32 s98, v183, 0
	v_readlane_b32 s99, v183, 16
	v_readlane_b32 s100, v183, 32
	v_readlane_b32 s101, v183, 48
	s_nop 1
	v_mov_b32_e32 v183, s98
	v_add_f32_e32 v183, s99, v183
	v_add_f32_e32 v183, s100, v183
	v_add_f32_e32 v183, s101, v183
	v_fmamk_f32 v183, v183, 0x3a800000, v182
	v_cmp_gt_f32_e32 vcc, 0x800000, v183
	v_mul_f32_e32 v181, 0x4b800000, v183
	s_nop 1
	v_cndmask_b32_e32 v183, v183, v181, vcc
	v_rsq_f32_e32 v183, v183
	s_nop 0
	v_mul_f32_e32 v181, 0x45800000, v183
	v_cndmask_b32_e32 v184, v183, v181, vcc
	v_mov_b32_e32 v185, v184
	v_pk_mul_f32 v[160:161], v[160:161], v[184:185]
	v_pk_mul_f32 v[162:163], v[162:163], v[184:185]
	v_pk_mul_f32 v[164:165], v[164:165], v[184:185]
	v_pk_mul_f32 v[166:167], v[166:167], v[184:185]
	v_pk_mul_f32 v[168:169], v[168:169], v[184:185]
	v_pk_mul_f32 v[170:171], v[170:171], v[184:185]
	v_pk_mul_f32 v[172:173], v[172:173], v[184:185]
	v_pk_mul_f32 v[174:175], v[174:175], v[184:185]
	v_pk_fma_f32 v[144:145], v[160:161], v[128:129], v[144:145]
	v_pk_fma_f32 v[146:147], v[162:163], v[130:131], v[146:147]
	v_pk_fma_f32 v[148:149], v[164:165], v[132:133], v[148:149]
	v_pk_fma_f32 v[150:151], v[166:167], v[134:135], v[150:151]
	v_pk_fma_f32 v[152:153], v[168:169], v[136:137], v[152:153]
	v_pk_fma_f32 v[154:155], v[170:171], v[138:139], v[154:155]
	v_pk_fma_f32 v[156:157], v[172:173], v[140:141], v[156:157]
	v_pk_fma_f32 v[158:159], v[174:175], v[142:143], v[158:159]
	v_pk_mul_f32 v[252:253], v[144:145], v[144:145]
	v_pk_mul_f32 v[254:255], v[146:147], v[146:147]
	v_pk_fma_f32 v[252:253], v[148:149], v[148:149], v[252:253]
	v_pk_fma_f32 v[254:255], v[150:151], v[150:151], v[254:255]
	v_pk_fma_f32 v[252:253], v[152:153], v[152:153], v[252:253]
	v_pk_fma_f32 v[254:255], v[154:155], v[154:155], v[254:255]
	v_pk_fma_f32 v[252:253], v[156:157], v[156:157], v[252:253]
	v_pk_fma_f32 v[254:255], v[158:159], v[158:159], v[254:255]
	v_pk_add_f32 v[252:253], v[252:253], v[254:255]
	s_nop 0
	v_add_f32_e32 v183, v252, v253
	s_nop 1
	v_add_f32_dpp v183, v183, v183 quad_perm:[1,0,3,2] row_mask:0xf bank_mask:0xf bound_ctrl:1
	s_nop 1
	v_add_f32_dpp v183, v183, v183 quad_perm:[2,3,0,1] row_mask:0xf bank_mask:0xf bound_ctrl:1
	s_nop 1
	v_add_f32_dpp v183, v183, v183 row_half_mirror row_mask:0xf bank_mask:0xf bound_ctrl:1
	s_nop 1
	v_add_f32_dpp v183, v183, v183 row_mirror row_mask:0xf bank_mask:0xf bound_ctrl:1
	s_nop 1
	v_readlane_b32 s98, v183, 0
	v_readlane_b32 s99, v183, 16
	v_readlane_b32 s100, v183, 32
	v_readlane_b32 s101, v183, 48
	s_nop 1
	v_mov_b32_e32 v183, s98
	v_add_f32_e32 v183, s99, v183
	v_add_f32_e32 v183, s100, v183
	v_add_f32_e32 v183, s101, v183
	v_fmamk_f32 v183, v183, 0x3a800000, v182
	v_cmp_gt_f32_e32 vcc, 0x800000, v183
	v_mul_f32_e32 v181, 0x4b800000, v183
	s_nop 1
	v_cndmask_b32_e32 v183, v183, v181, vcc
	v_rsq_f32_e32 v183, v183
	s_nop 0
	v_mul_f32_e32 v181, 0x45800000, v183
	v_cndmask_b32_e32 v184, v183, v181, vcc
	v_mov_b32_e32 v185, v184
	v_cvt_pk_bf16_f32 v96, v144, v145
	v_cvt_pk_bf16_f32 v97, v146, v147
	v_cvt_pk_bf16_f32 v98, v148, v149
	v_cvt_pk_bf16_f32 v99, v150, v151
	v_cvt_pk_bf16_f32 v100, v152, v153
	v_cvt_pk_bf16_f32 v101, v154, v155
	v_cvt_pk_bf16_f32 v102, v156, v157
	v_cvt_pk_bf16_f32 v103, v158, v159
	v_add_u32_e32 v181, 0x3000000, v177
	global_store_dwordx4 v181, v[96:99], s[78:79]
	global_store_dwordx4 v181, v[100:103], s[78:79] offset:1024
	v_add_u32_e32 v236, 0xc000, v237
	s_mov_b64 exec, 1
	global_store_dword v236, v184, s[78:79]
	s_mov_b64 exec, -1
	s_waitcnt vmcnt(0)
	v_lshlrev_b32_e32 v144, 16, v112
	v_and_b32_e32 v145, 0xffff0000, v112
	v_lshlrev_b32_e32 v146, 16, v113
	v_and_b32_e32 v147, 0xffff0000, v113
	v_lshlrev_b32_e32 v148, 16, v114
	v_and_b32_e32 v149, 0xffff0000, v114
	v_lshlrev_b32_e32 v150, 16, v115
	v_and_b32_e32 v151, 0xffff0000, v115
	v_lshlrev_b32_e32 v152, 16, v116
	v_and_b32_e32 v153, 0xffff0000, v116
	v_lshlrev_b32_e32 v154, 16, v117
	v_and_b32_e32 v155, 0xffff0000, v117
	v_lshlrev_b32_e32 v156, 16, v118
	v_and_b32_e32 v157, 0xffff0000, v118
	v_lshlrev_b32_e32 v158, 16, v119
	v_and_b32_e32 v159, 0xffff0000, v119
	v_lshlrev_b32_e32 v160, 16, v120
	v_and_b32_e32 v161, 0xffff0000, v120
	v_lshlrev_b32_e32 v162, 16, v121
	v_and_b32_e32 v163, 0xffff0000, v121
	v_lshlrev_b32_e32 v164, 16, v122
	v_and_b32_e32 v165, 0xffff0000, v122
	v_lshlrev_b32_e32 v166, 16, v123
	v_and_b32_e32 v167, 0xffff0000, v123
	v_lshlrev_b32_e32 v168, 16, v124
	v_and_b32_e32 v169, 0xffff0000, v124
	v_lshlrev_b32_e32 v170, 16, v125
	v_and_b32_e32 v171, 0xffff0000, v125
	v_lshlrev_b32_e32 v172, 16, v126
	v_and_b32_e32 v173, 0xffff0000, v126
	v_lshlrev_b32_e32 v174, 16, v127
	v_and_b32_e32 v175, 0xffff0000, v127
	v_pk_mul_f32 v[252:253], v[160:161], v[160:161]
	v_pk_mul_f32 v[254:255], v[162:163], v[162:163]
	v_pk_fma_f32 v[252:253], v[164:165], v[164:165], v[252:253]
	v_pk_fma_f32 v[254:255], v[166:167], v[166:167], v[254:255]
	v_pk_fma_f32 v[252:253], v[168:169], v[168:169], v[252:253]
	v_pk_fma_f32 v[254:255], v[170:171], v[170:171], v[254:255]
	v_pk_fma_f32 v[252:253], v[172:173], v[172:173], v[252:253]
	v_pk_fma_f32 v[254:255], v[174:175], v[174:175], v[254:255]
	v_pk_add_f32 v[252:253], v[252:253], v[254:255]
	s_nop 0
	v_add_f32_e32 v183, v252, v253
	s_nop 1
	v_add_f32_dpp v183, v183, v183 quad_perm:[1,0,3,2] row_mask:0xf bank_mask:0xf bound_ctrl:1
	s_nop 1
	v_add_f32_dpp v183, v183, v183 quad_perm:[2,3,0,1] row_mask:0xf bank_mask:0xf bound_ctrl:1
	s_nop 1
	v_add_f32_dpp v183, v183, v183 row_half_mirror row_mask:0xf bank_mask:0xf bound_ctrl:1
	s_nop 1
	v_add_f32_dpp v183, v183, v183 row_mirror row_mask:0xf bank_mask:0xf bound_ctrl:1
	s_nop 1
	v_readlane_b32 s98, v183, 0
	v_readlane_b32 s99, v183, 16
	v_readlane_b32 s100, v183, 32
	v_readlane_b32 s101, v183, 48
	s_nop 1
	v_mov_b32_e32 v183, s98
	v_add_f32_e32 v183, s99, v183
	v_add_f32_e32 v183, s100, v183
	v_add_f32_e32 v183, s101, v183
	v_fmamk_f32 v183, v183, 0x3a800000, v182
	v_cmp_gt_f32_e32 vcc, 0x800000, v183
	v_mul_f32_e32 v181, 0x4b800000, v183
	s_nop 1
	v_cndmask_b32_e32 v183, v183, v181, vcc
	v_rsq_f32_e32 v183, v183
	s_nop 0
	v_mul_f32_e32 v181, 0x45800000, v183
	v_cndmask_b32_e32 v184, v183, v181, vcc
	v_mov_b32_e32 v185, v184
	v_pk_mul_f32 v[160:161], v[160:161], v[184:185]
	v_pk_mul_f32 v[162:163], v[162:163], v[184:185]
	v_pk_mul_f32 v[164:165], v[164:165], v[184:185]
	v_pk_mul_f32 v[166:167], v[166:167], v[184:185]
	v_pk_mul_f32 v[168:169], v[168:169], v[184:185]
	v_pk_mul_f32 v[170:171], v[170:171], v[184:185]
	v_pk_mul_f32 v[172:173], v[172:173], v[184:185]
	v_pk_mul_f32 v[174:175], v[174:175], v[184:185]
	v_pk_fma_f32 v[144:145], v[160:161], v[128:129], v[144:145]
	v_pk_fma_f32 v[146:147], v[162:163], v[130:131], v[146:147]
	v_pk_fma_f32 v[148:149], v[164:165], v[132:133], v[148:149]
	v_pk_fma_f32 v[150:151], v[166:167], v[134:135], v[150:151]
	v_pk_fma_f32 v[152:153], v[168:169], v[136:137], v[152:153]
	v_pk_fma_f32 v[154:155], v[170:171], v[138:139], v[154:155]
	v_pk_fma_f32 v[156:157], v[172:173], v[140:141], v[156:157]
	v_pk_fma_f32 v[158:159], v[174:175], v[142:143], v[158:159]
	v_pk_mul_f32 v[252:253], v[144:145], v[144:145]
	v_pk_mul_f32 v[254:255], v[146:147], v[146:147]
	v_pk_fma_f32 v[252:253], v[148:149], v[148:149], v[252:253]
	v_pk_fma_f32 v[254:255], v[150:151], v[150:151], v[254:255]
	v_pk_fma_f32 v[252:253], v[152:153], v[152:153], v[252:253]
	v_pk_fma_f32 v[254:255], v[154:155], v[154:155], v[254:255]
	v_pk_fma_f32 v[252:253], v[156:157], v[156:157], v[252:253]
	v_pk_fma_f32 v[254:255], v[158:159], v[158:159], v[254:255]
	v_pk_add_f32 v[252:253], v[252:253], v[254:255]
	s_nop 0
	v_add_f32_e32 v183, v252, v253
	s_nop 1
	v_add_f32_dpp v183, v183, v183 quad_perm:[1,0,3,2] row_mask:0xf bank_mask:0xf bound_ctrl:1
	s_nop 1
	v_add_f32_dpp v183, v183, v183 quad_perm:[2,3,0,1] row_mask:0xf bank_mask:0xf bound_ctrl:1
	s_nop 1
	v_add_f32_dpp v183, v183, v183 row_half_mirror row_mask:0xf bank_mask:0xf bound_ctrl:1
	s_nop 1
	v_add_f32_dpp v183, v183, v183 row_mirror row_mask:0xf bank_mask:0xf bound_ctrl:1
	s_nop 1
	v_readlane_b32 s98, v183, 0
	v_readlane_b32 s99, v183, 16
	v_readlane_b32 s100, v183, 32
	v_readlane_b32 s101, v183, 48
	s_nop 1
	v_mov_b32_e32 v183, s98
	v_add_f32_e32 v183, s99, v183
	v_add_f32_e32 v183, s100, v183
	v_add_f32_e32 v183, s101, v183
	v_fmamk_f32 v183, v183, 0x3a800000, v182
	v_cmp_gt_f32_e32 vcc, 0x800000, v183
	v_mul_f32_e32 v181, 0x4b800000, v183
	s_nop 1
	v_cndmask_b32_e32 v183, v183, v181, vcc
	v_rsq_f32_e32 v183, v183
	s_nop 0
	v_mul_f32_e32 v181, 0x45800000, v183
	v_cndmask_b32_e32 v184, v183, v181, vcc
	v_mov_b32_e32 v185, v184
	v_cvt_pk_bf16_f32 v112, v144, v145
	v_cvt_pk_bf16_f32 v113, v146, v147
	v_cvt_pk_bf16_f32 v114, v148, v149
	v_cvt_pk_bf16_f32 v115, v150, v151
	v_cvt_pk_bf16_f32 v116, v152, v153
	v_cvt_pk_bf16_f32 v117, v154, v155
	v_cvt_pk_bf16_f32 v118, v156, v157
	v_cvt_pk_bf16_f32 v119, v158, v159
	v_add_u32_e32 v181, 0x3400000, v177
	global_store_dwordx4 v181, v[112:115], s[78:79]
	global_store_dwordx4 v181, v[116:119], s[78:79] offset:1024
	v_add_u32_e32 v236, 0xe000, v237
	s_mov_b64 exec, 1
	global_store_dword v236, v184, s[78:79]
	s_mov_b64 exec, -1
	v_readfirstlane_b32 s98, v179
	s_nop 3
	s_and_b32 s99, s98, 3
	s_cmp_lg_u32 s99, 0
	s_cbranch_scc1 .Lmyxupd_done_6
	v_lshrrev_b32_e32 v179, 2, v179
	v_lshlrev_b32_e32 v177, 4, v176
	v_lshl_add_u32 v177, v179, 11, v177
	v_lshlrev_b32_e32 v237, 2, v179
	v_add_u32_e32 v237, 0x10000, v237
	v_add_u32_e32 v181, 0x3800000, v177
	global_load_dwordx4 v[0:3], v181, s[78:79]
	global_load_dwordx4 v[4:7], v181, s[78:79] offset:1024
	v_lshl_add_u32 v183, v179, 12, v180
	v_add_u32_e32 v183, 0xbf00000, v183
	v_add_u32_e32 v181, 0x0, v183
	global_load_dwordx4 v[8:11], v181, s[78:79]
	global_load_dwordx4 v[12:15], v181, s[78:79] offset:16
	global_load_dwordx4 v[16:19], v181, s[78:79] offset:2048
	global_load_dwordx4 v[20:23], v181, s[78:79] offset:2064
	v_add_u32_e32 v181, 0x200000, v183
	global_load_dwordx4 v[24:27], v181, s[78:79]
	global_load_dwordx4 v[28:31], v181, s[78:79] offset:16
	global_load_dwordx4 v[32:35], v181, s[78:79] offset:2048
	global_load_dwordx4 v[36:39], v181, s[78:79] offset:2064
	v_add_u32_e32 v181, 0x400000, v183
	global_load_dwordx4 v[40:43], v181, s[78:79]
	global_load_dwordx4 v[44:47], v181, s[78:79] offset:16
	global_load_dwordx4 v[48:51], v181, s[78:79] offset:2048
	global_load_dwordx4 v[52:55], v181, s[78:79] offset:2064
	v_add_u32_e32 v181, 0x600000, v183
	global_load_dwordx4 v[56:59], v181, s[78:79]
	global_load_dwordx4 v[60:63], v181, s[78:79] offset:16
	global_load_dwordx4 v[64:67], v181, s[78:79] offset:2048
	global_load_dwordx4 v[68:71], v181, s[78:79] offset:2064
	v_add_u32_e32 v181, 0x800000, v183
	global_load_dwordx4 v[72:75], v181, s[78:79]
	global_load_dwordx4 v[76:79], v181, s[78:79] offset:16
	global_load_dwordx4 v[80:83], v181, s[78:79] offset:2048
	global_load_dwordx4 v[84:87], v181, s[78:79] offset:2064
	v_add_u32_e32 v181, 0xa00000, v183
	global_load_dwordx4 v[88:91], v181, s[78:79]
	global_load_dwordx4 v[92:95], v181, s[78:79] offset:16
	global_load_dwordx4 v[96:99], v181, s[78:79] offset:2048
	global_load_dwordx4 v[100:103], v181, s[78:79] offset:2064
	s_waitcnt vmcnt(20)
	v_pk_add_f32 v[160:161], v[8:9], 0 op_sel_hi:[1,0]
	v_pk_add_f32 v[162:163], v[10:11], 0 op_sel_hi:[1,0]
	v_pk_add_f32 v[164:165], v[12:13], 0 op_sel_hi:[1,0]
	v_pk_add_f32 v[166:167], v[14:15], 0 op_sel_hi:[1,0]
	v_pk_add_f32 v[168:169], v[16:17], 0 op_sel_hi:[1,0]
	v_pk_add_f32 v[170:171], v[18:19], 0 op_sel_hi:[1,0]
	v_pk_add_f32 v[172:173], v[20:21], 0 op_sel_hi:[1,0]
	v_pk_add_f32 v[174:175], v[22:23], 0 op_sel_hi:[1,0]
	s_waitcnt vmcnt(16)
	v_pk_add_f32 v[160:161], v[160:161], v[24:25]
	v_pk_add_f32 v[162:163], v[162:163], v[26:27]
	v_pk_add_f32 v[164:165], v[164:165], v[28:29]
	v_pk_add_f32 v[166:167], v[166:167], v[30:31]
	v_pk_add_f32 v[168:169], v[168:169], v[32:33]
	v_pk_add_f32 v[170:171], v[170:171], v[34:35]
	v_pk_add_f32 v[172:173], v[172:173], v[36:37]
	v_pk_add_f32 v[174:175], v[174:175], v[38:39]
	s_waitcnt vmcnt(12)
	v_pk_add_f32 v[160:161], v[160:161], v[40:41]
	v_pk_add_f32 v[162:163], v[162:163], v[42:43]
	v_pk_add_f32 v[164:165], v[164:165], v[44:45]
	v_pk_add_f32 v[166:167], v[166:167], v[46:47]
	v_pk_add_f32 v[168:169], v[168:169], v[48:49]
	v_pk_add_f32 v[170:171], v[170:171], v[50:51]
	v_pk_add_f32 v[172:173], v[172:173], v[52:53]
	v_pk_add_f32 v[174:175], v[174:175], v[54:55]
	s_waitcnt vmcnt(8)
	v_pk_add_f32 v[160:161], v[160:161], v[56:57]
	v_pk_add_f32 v[162:163], v[162:163], v[58:59]
	v_pk_add_f32 v[164:165], v[164:165], v[60:61]
	v_pk_add_f32 v[166:167], v[166:167], v[62:63]
	v_pk_add_f32 v[168:169], v[168:169], v[64:65]
	v_pk_add_f32 v[170:171], v[170:171], v[66:67]
	v_pk_add_f32 v[172:173], v[172:173], v[68:69]
	v_pk_add_f32 v[174:175], v[174:175], v[70:71]
	s_waitcnt vmcnt(4)
	v_pk_add_f32 v[160:161], v[160:161], v[72:73]
	v_pk_add_f32 v[162:163], v[162:163], v[74:75]
	v_pk_add_f32 v[164:165], v[164:165], v[76:77]
	v_pk_add_f32 v[166:167], v[166:167], v[78:79]
	v_pk_add_f32 v[168:169], v[168:169], v[80:81]
	v_pk_add_f32 v[170:171], v[170:171], v[82:83]
	v_pk_add_f32 v[172:173], v[172:173], v[84:85]
	v_pk_add_f32 v[174:175], v[174:175], v[86:87]
	s_waitcnt vmcnt(0)
	v_pk_add_f32 v[160:161], v[160:161], v[88:89]
	v_pk_add_f32 v[162:163], v[162:163], v[90:91]
	v_pk_add_f32 v[164:165], v[164:165], v[92:93]
	v_pk_add_f32 v[166:167], v[166:167], v[94:95]
	v_pk_add_f32 v[168:169], v[168:169], v[96:97]
	v_pk_add_f32 v[170:171], v[170:171], v[98:99]
	v_pk_add_f32 v[172:173], v[172:173], v[100:101]
	v_pk_add_f32 v[174:175], v[174:175], v[102:103]
	v_lshlrev_b32_e32 v144, 16, v0
	v_and_b32_e32 v145, 0xffff0000, v0
	v_lshlrev_b32_e32 v146, 16, v1
	v_and_b32_e32 v147, 0xffff0000, v1
	v_lshlrev_b32_e32 v148, 16, v2
	v_and_b32_e32 v149, 0xffff0000, v2
	v_lshlrev_b32_e32 v150, 16, v3
	v_and_b32_e32 v151, 0xffff0000, v3
	v_lshlrev_b32_e32 v152, 16, v4
	v_and_b32_e32 v153, 0xffff0000, v4
	v_lshlrev_b32_e32 v154, 16, v5
	v_and_b32_e32 v155, 0xffff0000, v5
	v_lshlrev_b32_e32 v156, 16, v6
	v_and_b32_e32 v157, 0xffff0000, v6
	v_lshlrev_b32_e32 v158, 16, v7
	v_and_b32_e32 v159, 0xffff0000, v7
	v_add_u32_e32 v181, 0xc00000, v183
	global_load_dwordx4 v[8:11], v181, s[78:79]
	global_load_dwordx4 v[12:15], v181, s[78:79] offset:16
	global_load_dwordx4 v[16:19], v181, s[78:79] offset:2048
	global_load_dwordx4 v[20:23], v181, s[78:79] offset:2064
	v_add_u32_e32 v181, 0xe00000, v183
	global_load_dwordx4 v[24:27], v181, s[78:79]
	global_load_dwordx4 v[28:31], v181, s[78:79] offset:16
	global_load_dwordx4 v[32:35], v181, s[78:79] offset:2048
	global_load_dwordx4 v[36:39], v181, s[78:79] offset:2064
	s_waitcnt vmcnt(4)
	v_pk_add_f32 v[160:161], v[160:161], v[8:9]
	v_pk_add_f32 v[162:163], v[162:163], v[10:11]
	v_pk_add_f32 v[164:165], v[164:165], v[12:13]
	v_pk_add_f32 v[166:167], v[166:167], v[14:15]
	v_pk_add_f32 v[168:169], v[168:169], v[16:17]
	v_pk_add_f32 v[170:171], v[170:171], v[18:19]
	v_pk_add_f32 v[172:173], v[172:173], v[20:21]
	v_pk_add_f32 v[174:175], v[174:175], v[22:23]
	s_waitcnt vmcnt(0)
	v_pk_add_f32 v[160:161], v[160:161], v[24:25]
	v_pk_add_f32 v[162:163], v[162:163], v[26:27]
	v_pk_add_f32 v[164:165], v[164:165], v[28:29]
	v_pk_add_f32 v[166:167], v[166:167], v[30:31]
	v_pk_add_f32 v[168:169], v[168:169], v[32:33]
	v_pk_add_f32 v[170:171], v[170:171], v[34:35]
	v_pk_add_f32 v[172:173], v[172:173], v[36:37]
	v_pk_add_f32 v[174:175], v[174:175], v[38:39]
	v_pk_mul_f32 v[252:253], v[160:161], v[160:161]
	v_pk_mul_f32 v[254:255], v[162:163], v[162:163]
	v_pk_fma_f32 v[252:253], v[164:165], v[164:165], v[252:253]
	v_pk_fma_f32 v[254:255], v[166:167], v[166:167], v[254:255]
	v_pk_fma_f32 v[252:253], v[168:169], v[168:169], v[252:253]
	v_pk_fma_f32 v[254:255], v[170:171], v[170:171], v[254:255]
	v_pk_fma_f32 v[252:253], v[172:173], v[172:173], v[252:253]
	v_pk_fma_f32 v[254:255], v[174:175], v[174:175], v[254:255]
	v_pk_add_f32 v[252:253], v[252:253], v[254:255]
	s_nop 0
	v_add_f32_e32 v183, v252, v253
	s_nop 1
	v_add_f32_dpp v183, v183, v183 quad_perm:[1,0,3,2] row_mask:0xf bank_mask:0xf bound_ctrl:1
	s_nop 1
	v_add_f32_dpp v183, v183, v183 quad_perm:[2,3,0,1] row_mask:0xf bank_mask:0xf bound_ctrl:1
	s_nop 1
	v_add_f32_dpp v183, v183, v183 row_half_mirror row_mask:0xf bank_mask:0xf bound_ctrl:1
	s_nop 1
	v_add_f32_dpp v183, v183, v183 row_mirror row_mask:0xf bank_mask:0xf bound_ctrl:1
	s_nop 1
	v_readlane_b32 s98, v183, 0
	v_readlane_b32 s99, v183, 16
	v_readlane_b32 s100, v183, 32
	v_readlane_b32 s101, v183, 48
	s_nop 1
	v_mov_b32_e32 v183, s98
	v_add_f32_e32 v183, s99, v183
	v_add_f32_e32 v183, s100, v183
	v_add_f32_e32 v183, s101, v183
	v_fmamk_f32 v183, v183, 0x3a800000, v182
	v_cmp_gt_f32_e32 vcc, 0x800000, v183
	v_mul_f32_e32 v181, 0x4b800000, v183
	s_nop 1
	v_cndmask_b32_e32 v183, v183, v181, vcc
	v_rsq_f32_e32 v183, v183
	s_nop 0
	v_mul_f32_e32 v181, 0x45800000, v183
	v_cndmask_b32_e32 v184, v183, v181, vcc
	v_mov_b32_e32 v185, v184
	v_pk_mul_f32 v[160:161], v[160:161], v[184:185]
	v_pk_mul_f32 v[162:163], v[162:163], v[184:185]
	v_pk_mul_f32 v[164:165], v[164:165], v[184:185]
	v_pk_mul_f32 v[166:167], v[166:167], v[184:185]
	v_pk_mul_f32 v[168:169], v[168:169], v[184:185]
	v_pk_mul_f32 v[170:171], v[170:171], v[184:185]
	v_pk_mul_f32 v[172:173], v[172:173], v[184:185]
	v_pk_mul_f32 v[174:175], v[174:175], v[184:185]
	v_pk_fma_f32 v[144:145], v[160:161], v[128:129], v[144:145]
	v_pk_fma_f32 v[146:147], v[162:163], v[130:131], v[146:147]
	v_pk_fma_f32 v[148:149], v[164:165], v[132:133], v[148:149]
	v_pk_fma_f32 v[150:151], v[166:167], v[134:135], v[150:151]
	v_pk_fma_f32 v[152:153], v[168:169], v[136:137], v[152:153]
	v_pk_fma_f32 v[154:155], v[170:171], v[138:139], v[154:155]
	v_pk_fma_f32 v[156:157], v[172:173], v[140:141], v[156:157]
	v_pk_fma_f32 v[158:159], v[174:175], v[142:143], v[158:159]
	v_pk_mul_f32 v[252:253], v[144:145], v[144:145]
	v_pk_mul_f32 v[254:255], v[146:147], v[146:147]
	v_pk_fma_f32 v[252:253], v[148:149], v[148:149], v[252:253]
	v_pk_fma_f32 v[254:255], v[150:151], v[150:151], v[254:255]
	v_pk_fma_f32 v[252:253], v[152:153], v[152:153], v[252:253]
	v_pk_fma_f32 v[254:255], v[154:155], v[154:155], v[254:255]
	v_pk_fma_f32 v[252:253], v[156:157], v[156:157], v[252:253]
	v_pk_fma_f32 v[254:255], v[158:159], v[158:159], v[254:255]
	v_pk_add_f32 v[252:253], v[252:253], v[254:255]
	s_nop 0
	v_add_f32_e32 v183, v252, v253
	s_nop 1
	v_add_f32_dpp v183, v183, v183 quad_perm:[1,0,3,2] row_mask:0xf bank_mask:0xf bound_ctrl:1
	s_nop 1
	v_add_f32_dpp v183, v183, v183 quad_perm:[2,3,0,1] row_mask:0xf bank_mask:0xf bound_ctrl:1
	s_nop 1
	v_add_f32_dpp v183, v183, v183 row_half_mirror row_mask:0xf bank_mask:0xf bound_ctrl:1
	s_nop 1
	v_add_f32_dpp v183, v183, v183 row_mirror row_mask:0xf bank_mask:0xf bound_ctrl:1
	s_nop 1
	v_readlane_b32 s98, v183, 0
	v_readlane_b32 s99, v183, 16
	v_readlane_b32 s100, v183, 32
	v_readlane_b32 s101, v183, 48
	s_nop 1
	v_mov_b32_e32 v183, s98
	v_add_f32_e32 v183, s99, v183
	v_add_f32_e32 v183, s100, v183
	v_add_f32_e32 v183, s101, v183
	v_fmamk_f32 v183, v183, 0x3a800000, v182
	v_cmp_gt_f32_e32 vcc, 0x800000, v183
	v_mul_f32_e32 v181, 0x4b800000, v183
	s_nop 1
	v_cndmask_b32_e32 v183, v183, v181, vcc
	v_rsq_f32_e32 v183, v183
	s_nop 0
	v_mul_f32_e32 v181, 0x45800000, v183
	v_cndmask_b32_e32 v184, v183, v181, vcc
	v_mov_b32_e32 v185, v184
	v_cvt_pk_bf16_f32 v0, v144, v145
	v_cvt_pk_bf16_f32 v1, v146, v147
	v_cvt_pk_bf16_f32 v2, v148, v149
	v_cvt_pk_bf16_f32 v3, v150, v151
	v_cvt_pk_bf16_f32 v4, v152, v153
	v_cvt_pk_bf16_f32 v5, v154, v155
	v_cvt_pk_bf16_f32 v6, v156, v157
	v_cvt_pk_bf16_f32 v7, v158, v159
	v_add_u32_e32 v181, 0x3800000, v177
	global_store_dwordx4 v181, v[0:3], s[78:79]
	global_store_dwordx4 v181, v[4:7], s[78:79] offset:1024
	v_add_u32_e32 v236, 0x10000, v237
	s_mov_b64 exec, 1
	global_store_dword v236, v184, s[78:79]
	s_mov_b64 exec, -1

.LBB0_2849:
	v_readlane_b32 s0, v235, 52
	v_readlane_b32 s1, v235, 53
	s_and_b64 vcc, exec, s[0:1]
	s_waitcnt lgkmcnt(0)
	s_barrier
	v_mbcnt_lo_u32_b32 v0, -1, 0
	v_mbcnt_hi_u32_b32 v0, -1, v0
	s_cbranch_vccnz .LBB0_2864
	v_lshlrev_b32_e32 v0, 3, v0
	v_ashrrev_i32_e32 v1, 31, v0
	v_readlane_b32 s0, v235, 4
	v_lshlrev_b64 v[2:3], 1, v[0:1]
	v_lshlrev_b64 v[0:1], 2, v[0:1]
	v_readlane_b32 s1, v235, 5
	v_readlane_b32 s14, v235, 18
	v_readlane_b32 s15, v235, 19
	s_mov_b64 s[0:1], 0x3000
	v_readlane_b32 s2, v235, 6
	v_lshl_add_u64 v[4:5], s[14:15], 0, v[0:1]
	v_readlane_b32 s4, v235, 8
	v_readlane_b32 s5, v235, 9
	v_lshl_add_u64 v[50:51], v[4:5], 0, s[0:1]
	v_readlane_b32 s0, v235, 0
	s_ashr_i32 s25, s24, 31
	s_lshl_b32 s0, s0, 4
	s_add_i32 s2, s24, 0xffffc000
	s_lshl_b64 s[4:5], s[24:25], 11
	s_add_u32 s4, s78, s4
	v_readlane_b32 s1, v235, 1
	s_addc_u32 s5, s79, s5
	v_lshl_add_u64 v[44:45], s[86:87], 0, v[2:3]
	v_lshl_add_u64 v[48:49], s[54:55], 0, v[2:3]
	v_readlane_b32 s6, v235, 10
	v_readlane_b32 s7, v235, 11
	v_lshl_add_u64 v[2:3], s[4:5], 0, v[2:3]
	s_mov_b64 s[4:5], 0x9e00000
	s_ashr_i32 s1, s0, 31
	v_lshl_add_u64 v[56:57], v[2:3], 0, s[4:5]
	s_lshl_b64 s[4:5], s[0:1], 11
	s_lshl_b64 s[6:7], s[24:25], 12
	s_add_u32 s6, s76, s6
	s_addc_u32 s7, s77, s7
	v_lshl_add_u64 v[46:47], s[90:91], 0, v[0:1]
	v_readlane_b32 s3, v235, 7
	v_readlane_b32 s8, v235, 12
	v_readlane_b32 s9, v235, 13
	v_readlane_b32 s10, v235, 14
	v_readlane_b32 s11, v235, 15
	v_readlane_b32 s12, v235, 16
	v_readlane_b32 s13, v235, 17
	v_lshl_add_u64 v[52:53], s[74:75], 0, v[0:1]
	v_lshl_add_u64 v[54:55], s[76:77], 0, v[0:1]
	v_lshl_add_u64 v[0:1], s[6:7], 0, v[0:1]
	s_mov_b64 s[6:7], 0x810
	v_lshl_add_u64 v[58:59], v[0:1], 0, s[6:7]
	s_lshl_b64 s[6:7], s[0:1], 12
	s_mov_b32 s3, 0
	s_mov_b64 s[8:9], 0x200000
	s_mov_b64 s[10:11], 0x200800
	s_mov_b64 s[12:13], 0x400000
	s_mov_b64 s[14:15], 0x400800
	s_mov_b64 s[16:17], 0x600000
	s_mov_b64 s[18:19], 0x600800
	s_mov_b64 s[20:21], 0x800000
	s_mov_b32 s1, 0x800000
	s_mov_b64 s[22:23], 0x800800
	s_mov_b64 s[24:25], 0xa00000
	s_mov_b64 s[26:27], 0xa00800
	s_mov_b64 s[28:29], 0xc00000
	s_mov_b64 s[30:31], 0xc00800
	s_mov_b64 s[34:35], 0xe00000
	s_mov_b64 s[36:37], 0xe00800
	s_mov_b64 s[38:39], 0x1000000
	s_mov_b32 s60, 0x1000000
	s_mov_b64 s[40:41], 0x1000800
	s_mov_b64 s[42:43], 0x1200000
	s_mov_b32 s61, 0x1200000
	s_mov_b64 s[44:45], 0x1200800
	s_mov_b64 s[46:47], 0x1400000
	s_mov_b32 s62, 0x1400000
	s_mov_b64 s[48:49], 0x1400800
	v_mov_b32_e32 v100, 0x358637bd
	v_mbcnt_lo_u32_b32 v176, -1, 0
	v_mbcnt_hi_u32_b32 v176, -1, v176
	v_readlane_b32 s98, v235, 49
	v_readlane_b32 s99, v235, 20
	v_readlane_b32 s100, v235, 18
	v_readlane_b32 s101, v235, 19
	s_nop 3
	s_lshr_b32 vcc_lo, s98, 3
	s_and_b32 vcc_hi, vcc_lo, 7
	s_lshr_b32 vcc_lo, vcc_lo, 3
	s_lshl_b32 vcc_lo, vcc_lo, 3
	s_add_i32 vcc_lo, vcc_lo, s99
	s_lshl_b32 s98, vcc_hi, 8
	s_add_i32 s98, s98, vcc_lo
	s_mov_b32 s99, s98
	v_mov_b32_e32 v183, s99
	v_lshlrev_b32_e32 v177, 4, v176
	s_lshl_b32 s99, s99, 11
	v_add_u32_e32 v177, s99, v177
	v_add_u32_e32 v178, 0x1800000, v177
	v_add_u32_e32 v179, 0x9e00000, v177
	v_lshlrev_b32_e32 v180, 5, v176
	v_add_u32_e32 v181, 0x3000, v180
	global_load_dwordx4 v[128:131], v181, s[100:101]
	global_load_dwordx4 v[132:135], v181, s[100:101] offset:16
	global_load_dwordx4 v[136:139], v181, s[100:101] offset:2048
	global_load_dwordx4 v[140:143], v181, s[100:101] offset:2064
	global_load_dwordx4 v[236:239], v180, s[74:75]
	global_load_dwordx4 v[240:243], v180, s[74:75] offset:16
	global_load_dwordx4 v[244:247], v180, s[74:75] offset:2048
	global_load_dwordx4 v[248:251], v180, s[74:75] offset:2064
	v_mov_b32_e32 v182, 0x358637bd
	global_load_dwordx4 v[0:3], v178, s[78:79]
	global_load_dwordx4 v[4:7], v178, s[78:79] offset:1024
	global_load_dwordx4 v[8:11], v179, s[78:79]
	global_load_dwordx4 v[12:15], v179, s[78:79] offset:1024
	v_add_u32_e32 v178, 0x400000, v178
	v_add_u32_e32 v179, 0x400000, v179
	global_load_dwordx4 v[16:19], v178, s[78:79]
	global_load_dwordx4 v[20:23], v178, s[78:79] offset:1024
	global_load_dwordx4 v[24:27], v179, s[78:79]
	global_load_dwordx4 v[28:31], v179, s[78:79] offset:1024
	v_add_u32_e32 v178, 0x400000, v178
	v_add_u32_e32 v179, 0x400000, v179
	global_load_dwordx4 v[32:35], v178, s[78:79]
	global_load_dwordx4 v[36:39], v178, s[78:79] offset:1024
	global_load_dwordx4 v[40:43], v179, s[78:79]
	global_load_dwordx4 v[44:47], v179, s[78:79] offset:1024
	v_add_u32_e32 v178, 0x400000, v178
	v_add_u32_e32 v179, 0x400000, v179
	global_load_dwordx4 v[48:51], v178, s[78:79]
	global_load_dwordx4 v[52:55], v178, s[78:79] offset:1024
	global_load_dwordx4 v[56:59], v179, s[78:79]
	global_load_dwordx4 v[60:63], v179, s[78:79] offset:1024
	v_add_u32_e32 v178, 0x400000, v178
	v_add_u32_e32 v179, 0x400000, v179
	global_load_dwordx4 v[64:67], v178, s[78:79]
	global_load_dwordx4 v[68:71], v178, s[78:79] offset:1024
	global_load_dwordx4 v[72:75], v179, s[78:79]
	global_load_dwordx4 v[76:79], v179, s[78:79] offset:1024
	v_add_u32_e32 v178, 0x400000, v178
	v_add_u32_e32 v179, 0x400000, v179
	global_load_dwordx4 v[80:83], v178, s[78:79]
	global_load_dwordx4 v[84:87], v178, s[78:79] offset:1024
	global_load_dwordx4 v[88:91], v179, s[78:79]
	global_load_dwordx4 v[92:95], v179, s[78:79] offset:1024
	v_add_u32_e32 v178, 0x400000, v178
	v_add_u32_e32 v179, 0x400000, v179
	global_load_dwordx4 v[96:99], v178, s[78:79]
	global_load_dwordx4 v[100:103], v178, s[78:79] offset:1024
	global_load_dwordx4 v[104:107], v179, s[78:79]
	global_load_dwordx4 v[108:111], v179, s[78:79] offset:1024
	v_add_u32_e32 v178, 0x400000, v178
	v_add_u32_e32 v179, 0x400000, v179
	global_load_dwordx4 v[112:115], v178, s[78:79]
	global_load_dwordx4 v[116:119], v178, s[78:79] offset:1024
	global_load_dwordx4 v[120:123], v179, s[78:79]
	global_load_dwordx4 v[124:127], v179, s[78:79] offset:1024
	v_lshl_add_u32 v178, v183, 12, v180
	v_mov_b32_e32 v179, s98
	s_waitcnt vmcnt(28)
	v_lshlrev_b32_e32 v144, 16, v0
	v_and_b32_e32 v145, 0xffff0000, v0
	v_lshlrev_b32_e32 v146, 16, v1
	v_and_b32_e32 v147, 0xffff0000, v1
	v_lshlrev_b32_e32 v148, 16, v2
	v_and_b32_e32 v149, 0xffff0000, v2
	v_lshlrev_b32_e32 v150, 16, v3
	v_and_b32_e32 v151, 0xffff0000, v3
	v_lshlrev_b32_e32 v152, 16, v4
	v_and_b32_e32 v153, 0xffff0000, v4
	v_lshlrev_b32_e32 v154, 16, v5
	v_and_b32_e32 v155, 0xffff0000, v5
	v_lshlrev_b32_e32 v156, 16, v6
	v_and_b32_e32 v157, 0xffff0000, v6
	v_lshlrev_b32_e32 v158, 16, v7
	v_and_b32_e32 v159, 0xffff0000, v7
	v_lshlrev_b32_e32 v160, 16, v8
	v_and_b32_e32 v161, 0xffff0000, v8
	v_lshlrev_b32_e32 v162, 16, v9
	v_and_b32_e32 v163, 0xffff0000, v9
	v_lshlrev_b32_e32 v164, 16, v10
	v_and_b32_e32 v165, 0xffff0000, v10
	v_lshlrev_b32_e32 v166, 16, v11
	v_and_b32_e32 v167, 0xffff0000, v11
	v_lshlrev_b32_e32 v168, 16, v12
	v_and_b32_e32 v169, 0xffff0000, v12
	v_lshlrev_b32_e32 v170, 16, v13
	v_and_b32_e32 v171, 0xffff0000, v13
	v_lshlrev_b32_e32 v172, 16, v14
	v_and_b32_e32 v173, 0xffff0000, v14
	v_lshlrev_b32_e32 v174, 16, v15
	v_and_b32_e32 v175, 0xffff0000, v15
	v_pk_mul_f32 v[252:253], v[160:161], v[160:161]
	v_pk_mul_f32 v[254:255], v[162:163], v[162:163]
	v_pk_fma_f32 v[252:253], v[164:165], v[164:165], v[252:253]
	v_pk_fma_f32 v[254:255], v[166:167], v[166:167], v[254:255]
	v_pk_fma_f32 v[252:253], v[168:169], v[168:169], v[252:253]
	v_pk_fma_f32 v[254:255], v[170:171], v[170:171], v[254:255]
	v_pk_fma_f32 v[252:253], v[172:173], v[172:173], v[252:253]
	v_pk_fma_f32 v[254:255], v[174:175], v[174:175], v[254:255]
	v_pk_add_f32 v[252:253], v[252:253], v[254:255]
	s_nop 0
	v_add_f32_e32 v183, v252, v253
	s_nop 1
	v_add_f32_dpp v183, v183, v183 quad_perm:[1,0,3,2] row_mask:0xf bank_mask:0xf bound_ctrl:1
	s_nop 1
	v_add_f32_dpp v183, v183, v183 quad_perm:[2,3,0,1] row_mask:0xf bank_mask:0xf bound_ctrl:1
	s_nop 1
	v_add_f32_dpp v183, v183, v183 row_half_mirror row_mask:0xf bank_mask:0xf bound_ctrl:1
	s_nop 1
	v_add_f32_dpp v183, v183, v183 row_mirror row_mask:0xf bank_mask:0xf bound_ctrl:1
	s_nop 1
	v_readlane_b32 s98, v183, 0
	v_readlane_b32 s99, v183, 16
	v_readlane_b32 s100, v183, 32
	v_readlane_b32 s101, v183, 48
	s_nop 1
	v_mov_b32_e32 v183, s98
	v_add_f32_e32 v183, s99, v183
	v_add_f32_e32 v183, s100, v183
	v_add_f32_e32 v183, s101, v183
	v_fmamk_f32 v183, v183, 0x3a800000, v182
	v_cmp_gt_f32_e32 vcc, 0x800000, v183
	v_mul_f32_e32 v181, 0x4b800000, v183
	s_nop 1
	v_cndmask_b32_e32 v183, v183, v181, vcc
	v_rsq_f32_e32 v183, v183
	s_nop 0
	v_mul_f32_e32 v181, 0x45800000, v183
	v_cndmask_b32_e32 v184, v183, v181, vcc
	v_mov_b32_e32 v185, v184
	v_pk_mul_f32 v[160:161], v[160:161], v[184:185]
	v_pk_mul_f32 v[162:163], v[162:163], v[184:185]
	v_pk_mul_f32 v[164:165], v[164:165], v[184:185]
	v_pk_mul_f32 v[166:167], v[166:167], v[184:185]
	v_pk_mul_f32 v[168:169], v[168:169], v[184:185]
	v_pk_mul_f32 v[170:171], v[170:171], v[184:185]
	v_pk_mul_f32 v[172:173], v[172:173], v[184:185]
	v_pk_mul_f32 v[174:175], v[174:175], v[184:185]
	v_pk_fma_f32 v[144:145], v[160:161], v[128:129], v[144:145]
	v_pk_fma_f32 v[146:147], v[162:163], v[130:131], v[146:147]
	v_pk_fma_f32 v[148:149], v[164:165], v[132:133], v[148:149]
	v_pk_fma_f32 v[150:151], v[166:167], v[134:135], v[150:151]
	v_pk_fma_f32 v[152:153], v[168:169], v[136:137], v[152:153]
	v_pk_fma_f32 v[154:155], v[170:171], v[138:139], v[154:155]
	v_pk_fma_f32 v[156:157], v[172:173], v[140:141], v[156:157]
	v_pk_fma_f32 v[158:159], v[174:175], v[142:143], v[158:159]
	v_pk_mul_f32 v[252:253], v[144:145], v[144:145]
	v_pk_mul_f32 v[254:255], v[146:147], v[146:147]
	v_pk_fma_f32 v[252:253], v[148:149], v[148:149], v[252:253]
	v_pk_fma_f32 v[254:255], v[150:151], v[150:151], v[254:255]
	v_pk_fma_f32 v[252:253], v[152:153], v[152:153], v[252:253]
	v_pk_fma_f32 v[254:255], v[154:155], v[154:155], v[254:255]
	v_pk_fma_f32 v[252:253], v[156:157], v[156:157], v[252:253]
	v_pk_fma_f32 v[254:255], v[158:159], v[158:159], v[254:255]
	v_pk_add_f32 v[252:253], v[252:253], v[254:255]
	s_nop 0
	v_add_f32_e32 v183, v252, v253
	s_nop 1
	v_add_f32_dpp v183, v183, v183 quad_perm:[1,0,3,2] row_mask:0xf bank_mask:0xf bound_ctrl:1
	s_nop 1
	v_add_f32_dpp v183, v183, v183 quad_perm:[2,3,0,1] row_mask:0xf bank_mask:0xf bound_ctrl:1
	s_nop 1
	v_add_f32_dpp v183, v183, v183 row_half_mirror row_mask:0xf bank_mask:0xf bound_ctrl:1
	s_nop 1
	v_add_f32_dpp v183, v183, v183 row_mirror row_mask:0xf bank_mask:0xf bound_ctrl:1
	s_nop 1
	v_readlane_b32 s98, v183, 0
	v_readlane_b32 s99, v183, 16
	v_readlane_b32 s100, v183, 32
	v_readlane_b32 s101, v183, 48
	s_nop 1
	v_mov_b32_e32 v183, s98
	v_add_f32_e32 v183, s99, v183
	v_add_f32_e32 v183, s100, v183
	v_add_f32_e32 v183, s101, v183
	v_fmamk_f32 v183, v183, 0x3a800000, v182
	v_cmp_gt_f32_e32 vcc, 0x800000, v183
	v_mul_f32_e32 v181, 0x4b800000, v183
	s_nop 1
	v_cndmask_b32_e32 v183, v183, v181, vcc
	v_rsq_f32_e32 v183, v183
	s_nop 0
	v_mul_f32_e32 v181, 0x45800000, v183
	v_cndmask_b32_e32 v184, v183, v181, vcc
	v_mov_b32_e32 v185, v184
	v_pk_mul_f32 v[144:145], v[144:145], v[184:185]
	v_pk_mul_f32 v[146:147], v[146:147], v[184:185]
	v_pk_mul_f32 v[148:149], v[148:149], v[184:185]
	v_pk_mul_f32 v[150:151], v[150:151], v[184:185]
	v_pk_mul_f32 v[152:153], v[152:153], v[184:185]
	v_pk_mul_f32 v[154:155], v[154:155], v[184:185]
	v_pk_mul_f32 v[156:157], v[156:157], v[184:185]
	v_pk_mul_f32 v[158:159], v[158:159], v[184:185]
	v_pk_mul_f32 v[144:145], v[144:145], v[236:237]
	v_pk_mul_f32 v[146:147], v[146:147], v[238:239]
	v_pk_mul_f32 v[148:149], v[148:149], v[240:241]
	v_pk_mul_f32 v[150:151], v[150:151], v[242:243]
	v_pk_mul_f32 v[152:153], v[152:153], v[244:245]
	v_pk_mul_f32 v[154:155], v[154:155], v[246:247]
	v_pk_mul_f32 v[156:157], v[156:157], v[248:249]
	v_pk_mul_f32 v[158:159], v[158:159], v[250:251]
	v_add_u32_e32 v181, 0x0, v178
	global_store_dwordx4 v181, v[144:147], s[76:77]
	global_store_dwordx4 v181, v[148:151], s[76:77] offset:16
	global_store_dwordx4 v181, v[152:155], s[76:77] offset:2048
	global_store_dwordx4 v181, v[156:159], s[76:77] offset:2064
	s_nop 1
	s_waitcnt vmcnt(24)
	v_lshlrev_b32_e32 v144, 16, v16
	v_and_b32_e32 v145, 0xffff0000, v16
	v_lshlrev_b32_e32 v146, 16, v17
	v_and_b32_e32 v147, 0xffff0000, v17
	v_lshlrev_b32_e32 v148, 16, v18
	v_and_b32_e32 v149, 0xffff0000, v18
	v_lshlrev_b32_e32 v150, 16, v19
	v_and_b32_e32 v151, 0xffff0000, v19
	v_lshlrev_b32_e32 v152, 16, v20
	v_and_b32_e32 v153, 0xffff0000, v20
	v_lshlrev_b32_e32 v154, 16, v21
	v_and_b32_e32 v155, 0xffff0000, v21
	v_lshlrev_b32_e32 v156, 16, v22
	v_and_b32_e32 v157, 0xffff0000, v22
	v_lshlrev_b32_e32 v158, 16, v23
	v_and_b32_e32 v159, 0xffff0000, v23
	v_lshlrev_b32_e32 v160, 16, v24
	v_and_b32_e32 v161, 0xffff0000, v24
	v_lshlrev_b32_e32 v162, 16, v25
	v_and_b32_e32 v163, 0xffff0000, v25
	v_lshlrev_b32_e32 v164, 16, v26
	v_and_b32_e32 v165, 0xffff0000, v26
	v_lshlrev_b32_e32 v166, 16, v27
	v_and_b32_e32 v167, 0xffff0000, v27
	v_lshlrev_b32_e32 v168, 16, v28
	v_and_b32_e32 v169, 0xffff0000, v28
	v_lshlrev_b32_e32 v170, 16, v29
	v_and_b32_e32 v171, 0xffff0000, v29
	v_lshlrev_b32_e32 v172, 16, v30
	v_and_b32_e32 v173, 0xffff0000, v30
	v_lshlrev_b32_e32 v174, 16, v31
	v_and_b32_e32 v175, 0xffff0000, v31
	v_pk_mul_f32 v[252:253], v[160:161], v[160:161]
	v_pk_mul_f32 v[254:255], v[162:163], v[162:163]
	v_pk_fma_f32 v[252:253], v[164:165], v[164:165], v[252:253]
	v_pk_fma_f32 v[254:255], v[166:167], v[166:167], v[254:255]
	v_pk_fma_f32 v[252:253], v[168:169], v[168:169], v[252:253]
	v_pk_fma_f32 v[254:255], v[170:171], v[170:171], v[254:255]
	v_pk_fma_f32 v[252:253], v[172:173], v[172:173], v[252:253]
	v_pk_fma_f32 v[254:255], v[174:175], v[174:175], v[254:255]
	v_pk_add_f32 v[252:253], v[252:253], v[254:255]
	s_nop 0
	v_add_f32_e32 v183, v252, v253
	s_nop 1
	v_add_f32_dpp v183, v183, v183 quad_perm:[1,0,3,2] row_mask:0xf bank_mask:0xf bound_ctrl:1
	s_nop 1
	v_add_f32_dpp v183, v183, v183 quad_perm:[2,3,0,1] row_mask:0xf bank_mask:0xf bound_ctrl:1
	s_nop 1
	v_add_f32_dpp v183, v183, v183 row_half_mirror row_mask:0xf bank_mask:0xf bound_ctrl:1
	s_nop 1
	v_add_f32_dpp v183, v183, v183 row_mirror row_mask:0xf bank_mask:0xf bound_ctrl:1
	s_nop 1
	v_readlane_b32 s98, v183, 0
	v_readlane_b32 s99, v183, 16
	v_readlane_b32 s100, v183, 32
	v_readlane_b32 s101, v183, 48
	s_nop 1
	v_mov_b32_e32 v183, s98
	v_add_f32_e32 v183, s99, v183
	v_add_f32_e32 v183, s100, v183
	v_add_f32_e32 v183, s101, v183
	v_fmamk_f32 v183, v183, 0x3a800000, v182
	v_cmp_gt_f32_e32 vcc, 0x800000, v183
	v_mul_f32_e32 v181, 0x4b800000, v183
	s_nop 1
	v_cndmask_b32_e32 v183, v183, v181, vcc
	v_rsq_f32_e32 v183, v183
	s_nop 0
	v_mul_f32_e32 v181, 0x45800000, v183
	v_cndmask_b32_e32 v184, v183, v181, vcc
	v_mov_b32_e32 v185, v184
	v_pk_mul_f32 v[160:161], v[160:161], v[184:185]
	v_pk_mul_f32 v[162:163], v[162:163], v[184:185]
	v_pk_mul_f32 v[164:165], v[164:165], v[184:185]
	v_pk_mul_f32 v[166:167], v[166:167], v[184:185]
	v_pk_mul_f32 v[168:169], v[168:169], v[184:185]
	v_pk_mul_f32 v[170:171], v[170:171], v[184:185]
	v_pk_mul_f32 v[172:173], v[172:173], v[184:185]
	v_pk_mul_f32 v[174:175], v[174:175], v[184:185]
	v_pk_fma_f32 v[144:145], v[160:161], v[128:129], v[144:145]
	v_pk_fma_f32 v[146:147], v[162:163], v[130:131], v[146:147]
	v_pk_fma_f32 v[148:149], v[164:165], v[132:133], v[148:149]
	v_pk_fma_f32 v[150:151], v[166:167], v[134:135], v[150:151]
	v_pk_fma_f32 v[152:153], v[168:169], v[136:137], v[152:153]
	v_pk_fma_f32 v[154:155], v[170:171], v[138:139], v[154:155]
	v_pk_fma_f32 v[156:157], v[172:173], v[140:141], v[156:157]
	v_pk_fma_f32 v[158:159], v[174:175], v[142:143], v[158:159]
	v_pk_mul_f32 v[252:253], v[144:145], v[144:145]
	v_pk_mul_f32 v[254:255], v[146:147], v[146:147]
	v_pk_fma_f32 v[252:253], v[148:149], v[148:149], v[252:253]
	v_pk_fma_f32 v[254:255], v[150:151], v[150:151], v[254:255]
	v_pk_fma_f32 v[252:253], v[152:153], v[152:153], v[252:253]
	v_pk_fma_f32 v[254:255], v[154:155], v[154:155], v[254:255]
	v_pk_fma_f32 v[252:253], v[156:157], v[156:157], v[252:253]
	v_pk_fma_f32 v[254:255], v[158:159], v[158:159], v[254:255]
	v_pk_add_f32 v[252:253], v[252:253], v[254:255]
	s_nop 0
	v_add_f32_e32 v183, v252, v253
	s_nop 1
	v_add_f32_dpp v183, v183, v183 quad_perm:[1,0,3,2] row_mask:0xf bank_mask:0xf bound_ctrl:1
	s_nop 1
	v_add_f32_dpp v183, v183, v183 quad_perm:[2,3,0,1] row_mask:0xf bank_mask:0xf bound_ctrl:1
	s_nop 1
	v_add_f32_dpp v183, v183, v183 row_half_mirror row_mask:0xf bank_mask:0xf bound_ctrl:1
	s_nop 1
	v_add_f32_dpp v183, v183, v183 row_mirror row_mask:0xf bank_mask:0xf bound_ctrl:1
	s_nop 1
	v_readlane_b32 s98, v183, 0
	v_readlane_b32 s99, v183, 16
	v_readlane_b32 s100, v183, 32
	v_readlane_b32 s101, v183, 48
	s_nop 1
	v_mov_b32_e32 v183, s98
	v_add_f32_e32 v183, s99, v183
	v_add_f32_e32 v183, s100, v183
	v_add_f32_e32 v183, s101, v183
	v_fmamk_f32 v183, v183, 0x3a800000, v182
	v_cmp_gt_f32_e32 vcc, 0x800000, v183
	v_mul_f32_e32 v181, 0x4b800000, v183
	s_nop 1
	v_cndmask_b32_e32 v183, v183, v181, vcc
	v_rsq_f32_e32 v183, v183
	s_nop 0
	v_mul_f32_e32 v181, 0x45800000, v183
	v_cndmask_b32_e32 v184, v183, v181, vcc
	v_mov_b32_e32 v185, v184
	v_pk_mul_f32 v[144:145], v[144:145], v[184:185]
	v_pk_mul_f32 v[146:147], v[146:147], v[184:185]
	v_pk_mul_f32 v[148:149], v[148:149], v[184:185]
	v_pk_mul_f32 v[150:151], v[150:151], v[184:185]
	v_pk_mul_f32 v[152:153], v[152:153], v[184:185]
	v_pk_mul_f32 v[154:155], v[154:155], v[184:185]
	v_pk_mul_f32 v[156:157], v[156:157], v[184:185]
	v_pk_mul_f32 v[158:159], v[158:159], v[184:185]
	v_pk_mul_f32 v[144:145], v[144:145], v[236:237]
	v_pk_mul_f32 v[146:147], v[146:147], v[238:239]
	v_pk_mul_f32 v[148:149], v[148:149], v[240:241]
	v_pk_mul_f32 v[150:151], v[150:151], v[242:243]
	v_pk_mul_f32 v[152:153], v[152:153], v[244:245]
	v_pk_mul_f32 v[154:155], v[154:155], v[246:247]
	v_pk_mul_f32 v[156:157], v[156:157], v[248:249]
	v_pk_mul_f32 v[158:159], v[158:159], v[250:251]
	v_add_u32_e32 v181, 0x800000, v178
	global_store_dwordx4 v181, v[144:147], s[76:77]
	global_store_dwordx4 v181, v[148:151], s[76:77] offset:16
	global_store_dwordx4 v181, v[152:155], s[76:77] offset:2048
	global_store_dwordx4 v181, v[156:159], s[76:77] offset:2064
	s_nop 1
	s_waitcnt vmcnt(20)
	v_lshlrev_b32_e32 v144, 16, v32
	v_and_b32_e32 v145, 0xffff0000, v32
	v_lshlrev_b32_e32 v146, 16, v33
	v_and_b32_e32 v147, 0xffff0000, v33
	v_lshlrev_b32_e32 v148, 16, v34
	v_and_b32_e32 v149, 0xffff0000, v34
	v_lshlrev_b32_e32 v150, 16, v35
	v_and_b32_e32 v151, 0xffff0000, v35
	v_lshlrev_b32_e32 v152, 16, v36
	v_and_b32_e32 v153, 0xffff0000, v36
	v_lshlrev_b32_e32 v154, 16, v37
	v_and_b32_e32 v155, 0xffff0000, v37
	v_lshlrev_b32_e32 v156, 16, v38
	v_and_b32_e32 v157, 0xffff0000, v38
	v_lshlrev_b32_e32 v158, 16, v39
	v_and_b32_e32 v159, 0xffff0000, v39
	v_lshlrev_b32_e32 v160, 16, v40
	v_and_b32_e32 v161, 0xffff0000, v40
	v_lshlrev_b32_e32 v162, 16, v41
	v_and_b32_e32 v163, 0xffff0000, v41
	v_lshlrev_b32_e32 v164, 16, v42
	v_and_b32_e32 v165, 0xffff0000, v42
	v_lshlrev_b32_e32 v166, 16, v43
	v_and_b32_e32 v167, 0xffff0000, v43
	v_lshlrev_b32_e32 v168, 16, v44
	v_and_b32_e32 v169, 0xffff0000, v44
	v_lshlrev_b32_e32 v170, 16, v45
	v_and_b32_e32 v171, 0xffff0000, v45
	v_lshlrev_b32_e32 v172, 16, v46
	v_and_b32_e32 v173, 0xffff0000, v46
	v_lshlrev_b32_e32 v174, 16, v47
	v_and_b32_e32 v175, 0xffff0000, v47
	v_pk_mul_f32 v[252:253], v[160:161], v[160:161]
	v_pk_mul_f32 v[254:255], v[162:163], v[162:163]
	v_pk_fma_f32 v[252:253], v[164:165], v[164:165], v[252:253]
	v_pk_fma_f32 v[254:255], v[166:167], v[166:167], v[254:255]
	v_pk_fma_f32 v[252:253], v[168:169], v[168:169], v[252:253]
	v_pk_fma_f32 v[254:255], v[170:171], v[170:171], v[254:255]
	v_pk_fma_f32 v[252:253], v[172:173], v[172:173], v[252:253]
	v_pk_fma_f32 v[254:255], v[174:175], v[174:175], v[254:255]
	v_pk_add_f32 v[252:253], v[252:253], v[254:255]
	s_nop 0
	v_add_f32_e32 v183, v252, v253
	s_nop 1
	v_add_f32_dpp v183, v183, v183 quad_perm:[1,0,3,2] row_mask:0xf bank_mask:0xf bound_ctrl:1
	s_nop 1
	v_add_f32_dpp v183, v183, v183 quad_perm:[2,3,0,1] row_mask:0xf bank_mask:0xf bound_ctrl:1
	s_nop 1
	v_add_f32_dpp v183, v183, v183 row_half_mirror row_mask:0xf bank_mask:0xf bound_ctrl:1
	s_nop 1
	v_add_f32_dpp v183, v183, v183 row_mirror row_mask:0xf bank_mask:0xf bound_ctrl:1
	s_nop 1
	v_readlane_b32 s98, v183, 0
	v_readlane_b32 s99, v183, 16
	v_readlane_b32 s100, v183, 32
	v_readlane_b32 s101, v183, 48
	s_nop 1
	v_mov_b32_e32 v183, s98
	v_add_f32_e32 v183, s99, v183
	v_add_f32_e32 v183, s100, v183
	v_add_f32_e32 v183, s101, v183
	v_fmamk_f32 v183, v183, 0x3a800000, v182
	v_cmp_gt_f32_e32 vcc, 0x800000, v183
	v_mul_f32_e32 v181, 0x4b800000, v183
	s_nop 1
	v_cndmask_b32_e32 v183, v183, v181, vcc
	v_rsq_f32_e32 v183, v183
	s_nop 0
	v_mul_f32_e32 v181, 0x45800000, v183
	v_cndmask_b32_e32 v184, v183, v181, vcc
	v_mov_b32_e32 v185, v184
	v_pk_mul_f32 v[160:161], v[160:161], v[184:185]
	v_pk_mul_f32 v[162:163], v[162:163], v[184:185]
	v_pk_mul_f32 v[164:165], v[164:165], v[184:185]
	v_pk_mul_f32 v[166:167], v[166:167], v[184:185]
	v_pk_mul_f32 v[168:169], v[168:169], v[184:185]
	v_pk_mul_f32 v[170:171], v[170:171], v[184:185]
	v_pk_mul_f32 v[172:173], v[172:173], v[184:185]
	v_pk_mul_f32 v[174:175], v[174:175], v[184:185]
	v_pk_fma_f32 v[144:145], v[160:161], v[128:129], v[144:145]
	v_pk_fma_f32 v[146:147], v[162:163], v[130:131], v[146:147]
	v_pk_fma_f32 v[148:149], v[164:165], v[132:133], v[148:149]
	v_pk_fma_f32 v[150:151], v[166:167], v[134:135], v[150:151]
	v_pk_fma_f32 v[152:153], v[168:169], v[136:137], v[152:153]
	v_pk_fma_f32 v[154:155], v[170:171], v[138:139], v[154:155]
	v_pk_fma_f32 v[156:157], v[172:173], v[140:141], v[156:157]
	v_pk_fma_f32 v[158:159], v[174:175], v[142:143], v[158:159]
	v_pk_mul_f32 v[252:253], v[144:145], v[144:145]
	v_pk_mul_f32 v[254:255], v[146:147], v[146:147]
	v_pk_fma_f32 v[252:253], v[148:149], v[148:149], v[252:253]
	v_pk_fma_f32 v[254:255], v[150:151], v[150:151], v[254:255]
	v_pk_fma_f32 v[252:253], v[152:153], v[152:153], v[252:253]
	v_pk_fma_f32 v[254:255], v[154:155], v[154:155], v[254:255]
	v_pk_fma_f32 v[252:253], v[156:157], v[156:157], v[252:253]
	v_pk_fma_f32 v[254:255], v[158:159], v[158:159], v[254:255]
	v_pk_add_f32 v[252:253], v[252:253], v[254:255]
	s_nop 0
	v_add_f32_e32 v183, v252, v253
	s_nop 1
	v_add_f32_dpp v183, v183, v183 quad_perm:[1,0,3,2] row_mask:0xf bank_mask:0xf bound_ctrl:1
	s_nop 1
	v_add_f32_dpp v183, v183, v183 quad_perm:[2,3,0,1] row_mask:0xf bank_mask:0xf bound_ctrl:1
	s_nop 1
	v_add_f32_dpp v183, v183, v183 row_half_mirror row_mask:0xf bank_mask:0xf bound_ctrl:1
	s_nop 1
	v_add_f32_dpp v183, v183, v183 row_mirror row_mask:0xf bank_mask:0xf bound_ctrl:1
	s_nop 1
	v_readlane_b32 s98, v183, 0
	v_readlane_b32 s99, v183, 16
	v_readlane_b32 s100, v183, 32
	v_readlane_b32 s101, v183, 48
	s_nop 1
	v_mov_b32_e32 v183, s98
	v_add_f32_e32 v183, s99, v183
	v_add_f32_e32 v183, s100, v183
	v_add_f32_e32 v183, s101, v183
	v_fmamk_f32 v183, v183, 0x3a800000, v182
	v_cmp_gt_f32_e32 vcc, 0x800000, v183
	v_mul_f32_e32 v181, 0x4b800000, v183
	s_nop 1
	v_cndmask_b32_e32 v183, v183, v181, vcc
	v_rsq_f32_e32 v183, v183
	s_nop 0
	v_mul_f32_e32 v181, 0x45800000, v183
	v_cndmask_b32_e32 v184, v183, v181, vcc
	v_mov_b32_e32 v185, v184
	v_pk_mul_f32 v[144:145], v[144:145], v[184:185]
	v_pk_mul_f32 v[146:147], v[146:147], v[184:185]
	v_pk_mul_f32 v[148:149], v[148:149], v[184:185]
	v_pk_mul_f32 v[150:151], v[150:151], v[184:185]
	v_pk_mul_f32 v[152:153], v[152:153], v[184:185]
	v_pk_mul_f32 v[154:155], v[154:155], v[184:185]
	v_pk_mul_f32 v[156:157], v[156:157], v[184:185]
	v_pk_mul_f32 v[158:159], v[158:159], v[184:185]
	v_pk_mul_f32 v[144:145], v[144:145], v[236:237]
	v_pk_mul_f32 v[146:147], v[146:147], v[238:239]
	v_pk_mul_f32 v[148:149], v[148:149], v[240:241]
	v_pk_mul_f32 v[150:151], v[150:151], v[242:243]
	v_pk_mul_f32 v[152:153], v[152:153], v[244:245]
	v_pk_mul_f32 v[154:155], v[154:155], v[246:247]
	v_pk_mul_f32 v[156:157], v[156:157], v[248:249]
	v_pk_mul_f32 v[158:159], v[158:159], v[250:251]
	v_add_u32_e32 v181, 0x1000000, v178
	global_store_dwordx4 v181, v[144:147], s[76:77]
	global_store_dwordx4 v181, v[148:151], s[76:77] offset:16
	global_store_dwordx4 v181, v[152:155], s[76:77] offset:2048
	global_store_dwordx4 v181, v[156:159], s[76:77] offset:2064
	s_nop 1
	s_waitcnt vmcnt(16)
	v_lshlrev_b32_e32 v144, 16, v48
	v_and_b32_e32 v145, 0xffff0000, v48
	v_lshlrev_b32_e32 v146, 16, v49
	v_and_b32_e32 v147, 0xffff0000, v49
	v_lshlrev_b32_e32 v148, 16, v50
	v_and_b32_e32 v149, 0xffff0000, v50
	v_lshlrev_b32_e32 v150, 16, v51
	v_and_b32_e32 v151, 0xffff0000, v51
	v_lshlrev_b32_e32 v152, 16, v52
	v_and_b32_e32 v153, 0xffff0000, v52
	v_lshlrev_b32_e32 v154, 16, v53
	v_and_b32_e32 v155, 0xffff0000, v53
	v_lshlrev_b32_e32 v156, 16, v54
	v_and_b32_e32 v157, 0xffff0000, v54
	v_lshlrev_b32_e32 v158, 16, v55
	v_and_b32_e32 v159, 0xffff0000, v55
	v_lshlrev_b32_e32 v160, 16, v56
	v_and_b32_e32 v161, 0xffff0000, v56
	v_lshlrev_b32_e32 v162, 16, v57
	v_and_b32_e32 v163, 0xffff0000, v57
	v_lshlrev_b32_e32 v164, 16, v58
	v_and_b32_e32 v165, 0xffff0000, v58
	v_lshlrev_b32_e32 v166, 16, v59
	v_and_b32_e32 v167, 0xffff0000, v59
	v_lshlrev_b32_e32 v168, 16, v60
	v_and_b32_e32 v169, 0xffff0000, v60
	v_lshlrev_b32_e32 v170, 16, v61
	v_and_b32_e32 v171, 0xffff0000, v61
	v_lshlrev_b32_e32 v172, 16, v62
	v_and_b32_e32 v173, 0xffff0000, v62
	v_lshlrev_b32_e32 v174, 16, v63
	v_and_b32_e32 v175, 0xffff0000, v63
	v_pk_mul_f32 v[252:253], v[160:161], v[160:161]
	v_pk_mul_f32 v[254:255], v[162:163], v[162:163]
	v_pk_fma_f32 v[252:253], v[164:165], v[164:165], v[252:253]
	v_pk_fma_f32 v[254:255], v[166:167], v[166:167], v[254:255]
	v_pk_fma_f32 v[252:253], v[168:169], v[168:169], v[252:253]
	v_pk_fma_f32 v[254:255], v[170:171], v[170:171], v[254:255]
	v_pk_fma_f32 v[252:253], v[172:173], v[172:173], v[252:253]
	v_pk_fma_f32 v[254:255], v[174:175], v[174:175], v[254:255]
	v_pk_add_f32 v[252:253], v[252:253], v[254:255]
	s_nop 0
	v_add_f32_e32 v183, v252, v253
	s_nop 1
	v_add_f32_dpp v183, v183, v183 quad_perm:[1,0,3,2] row_mask:0xf bank_mask:0xf bound_ctrl:1
	s_nop 1
	v_add_f32_dpp v183, v183, v183 quad_perm:[2,3,0,1] row_mask:0xf bank_mask:0xf bound_ctrl:1
	s_nop 1
	v_add_f32_dpp v183, v183, v183 row_half_mirror row_mask:0xf bank_mask:0xf bound_ctrl:1
	s_nop 1
	v_add_f32_dpp v183, v183, v183 row_mirror row_mask:0xf bank_mask:0xf bound_ctrl:1
	s_nop 1
	v_readlane_b32 s98, v183, 0
	v_readlane_b32 s99, v183, 16
	v_readlane_b32 s100, v183, 32
	v_readlane_b32 s101, v183, 48
	s_nop 1
	v_mov_b32_e32 v183, s98
	v_add_f32_e32 v183, s99, v183
	v_add_f32_e32 v183, s100, v183
	v_add_f32_e32 v183, s101, v183
	v_fmamk_f32 v183, v183, 0x3a800000, v182
	v_cmp_gt_f32_e32 vcc, 0x800000, v183
	v_mul_f32_e32 v181, 0x4b800000, v183
	s_nop 1
	v_cndmask_b32_e32 v183, v183, v181, vcc
	v_rsq_f32_e32 v183, v183
	s_nop 0
	v_mul_f32_e32 v181, 0x45800000, v183
	v_cndmask_b32_e32 v184, v183, v181, vcc
	v_mov_b32_e32 v185, v184
	v_pk_mul_f32 v[160:161], v[160:161], v[184:185]
	v_pk_mul_f32 v[162:163], v[162:163], v[184:185]
	v_pk_mul_f32 v[164:165], v[164:165], v[184:185]
	v_pk_mul_f32 v[166:167], v[166:167], v[184:185]
	v_pk_mul_f32 v[168:169], v[168:169], v[184:185]
	v_pk_mul_f32 v[170:171], v[170:171], v[184:185]
	v_pk_mul_f32 v[172:173], v[172:173], v[184:185]
	v_pk_mul_f32 v[174:175], v[174:175], v[184:185]
	v_pk_fma_f32 v[144:145], v[160:161], v[128:129], v[144:145]
	v_pk_fma_f32 v[146:147], v[162:163], v[130:131], v[146:147]
	v_pk_fma_f32 v[148:149], v[164:165], v[132:133], v[148:149]
	v_pk_fma_f32 v[150:151], v[166:167], v[134:135], v[150:151]
	v_pk_fma_f32 v[152:153], v[168:169], v[136:137], v[152:153]
	v_pk_fma_f32 v[154:155], v[170:171], v[138:139], v[154:155]
	v_pk_fma_f32 v[156:157], v[172:173], v[140:141], v[156:157]
	v_pk_fma_f32 v[158:159], v[174:175], v[142:143], v[158:159]
	v_pk_mul_f32 v[252:253], v[144:145], v[144:145]
	v_pk_mul_f32 v[254:255], v[146:147], v[146:147]
	v_pk_fma_f32 v[252:253], v[148:149], v[148:149], v[252:253]
	v_pk_fma_f32 v[254:255], v[150:151], v[150:151], v[254:255]
	v_pk_fma_f32 v[252:253], v[152:153], v[152:153], v[252:253]
	v_pk_fma_f32 v[254:255], v[154:155], v[154:155], v[254:255]
	v_pk_fma_f32 v[252:253], v[156:157], v[156:157], v[252:253]
	v_pk_fma_f32 v[254:255], v[158:159], v[158:159], v[254:255]
	v_pk_add_f32 v[252:253], v[252:253], v[254:255]
	s_nop 0
	v_add_f32_e32 v183, v252, v253
	s_nop 1
	v_add_f32_dpp v183, v183, v183 quad_perm:[1,0,3,2] row_mask:0xf bank_mask:0xf bound_ctrl:1
	s_nop 1
	v_add_f32_dpp v183, v183, v183 quad_perm:[2,3,0,1] row_mask:0xf bank_mask:0xf bound_ctrl:1
	s_nop 1
	v_add_f32_dpp v183, v183, v183 row_half_mirror row_mask:0xf bank_mask:0xf bound_ctrl:1
	s_nop 1
	v_add_f32_dpp v183, v183, v183 row_mirror row_mask:0xf bank_mask:0xf bound_ctrl:1
	s_nop 1
	v_readlane_b32 s98, v183, 0
	v_readlane_b32 s99, v183, 16
	v_readlane_b32 s100, v183, 32
	v_readlane_b32 s101, v183, 48
	s_nop 1
	v_mov_b32_e32 v183, s98
	v_add_f32_e32 v183, s99, v183
	v_add_f32_e32 v183, s100, v183
	v_add_f32_e32 v183, s101, v183
	v_fmamk_f32 v183, v183, 0x3a800000, v182
	v_cmp_gt_f32_e32 vcc, 0x800000, v183
	v_mul_f32_e32 v181, 0x4b800000, v183
	s_nop 1
	v_cndmask_b32_e32 v183, v183, v181, vcc
	v_rsq_f32_e32 v183, v183
	s_nop 0
	v_mul_f32_e32 v181, 0x45800000, v183
	v_cndmask_b32_e32 v184, v183, v181, vcc
	v_mov_b32_e32 v185, v184
	v_pk_mul_f32 v[144:145], v[144:145], v[184:185]
	v_pk_mul_f32 v[146:147], v[146:147], v[184:185]
	v_pk_mul_f32 v[148:149], v[148:149], v[184:185]
	v_pk_mul_f32 v[150:151], v[150:151], v[184:185]
	v_pk_mul_f32 v[152:153], v[152:153], v[184:185]
	v_pk_mul_f32 v[154:155], v[154:155], v[184:185]
	v_pk_mul_f32 v[156:157], v[156:157], v[184:185]
	v_pk_mul_f32 v[158:159], v[158:159], v[184:185]
	v_pk_mul_f32 v[144:145], v[144:145], v[236:237]
	v_pk_mul_f32 v[146:147], v[146:147], v[238:239]
	v_pk_mul_f32 v[148:149], v[148:149], v[240:241]
	v_pk_mul_f32 v[150:151], v[150:151], v[242:243]
	v_pk_mul_f32 v[152:153], v[152:153], v[244:245]
	v_pk_mul_f32 v[154:155], v[154:155], v[246:247]
	v_pk_mul_f32 v[156:157], v[156:157], v[248:249]
	v_pk_mul_f32 v[158:159], v[158:159], v[250:251]
	v_add_u32_e32 v181, 0x1800000, v178
	global_store_dwordx4 v181, v[144:147], s[76:77]
	global_store_dwordx4 v181, v[148:151], s[76:77] offset:16
	global_store_dwordx4 v181, v[152:155], s[76:77] offset:2048
	global_store_dwordx4 v181, v[156:159], s[76:77] offset:2064
	s_nop 1
	s_waitcnt vmcnt(12)
	v_lshlrev_b32_e32 v144, 16, v64
	v_and_b32_e32 v145, 0xffff0000, v64
	v_lshlrev_b32_e32 v146, 16, v65
	v_and_b32_e32 v147, 0xffff0000, v65
	v_lshlrev_b32_e32 v148, 16, v66
	v_and_b32_e32 v149, 0xffff0000, v66
	v_lshlrev_b32_e32 v150, 16, v67
	v_and_b32_e32 v151, 0xffff0000, v67
	v_lshlrev_b32_e32 v152, 16, v68
	v_and_b32_e32 v153, 0xffff0000, v68
	v_lshlrev_b32_e32 v154, 16, v69
	v_and_b32_e32 v155, 0xffff0000, v69
	v_lshlrev_b32_e32 v156, 16, v70
	v_and_b32_e32 v157, 0xffff0000, v70
	v_lshlrev_b32_e32 v158, 16, v71
	v_and_b32_e32 v159, 0xffff0000, v71
	v_lshlrev_b32_e32 v160, 16, v72
	v_and_b32_e32 v161, 0xffff0000, v72
	v_lshlrev_b32_e32 v162, 16, v73
	v_and_b32_e32 v163, 0xffff0000, v73
	v_lshlrev_b32_e32 v164, 16, v74
	v_and_b32_e32 v165, 0xffff0000, v74
	v_lshlrev_b32_e32 v166, 16, v75
	v_and_b32_e32 v167, 0xffff0000, v75
	v_lshlrev_b32_e32 v168, 16, v76
	v_and_b32_e32 v169, 0xffff0000, v76
	v_lshlrev_b32_e32 v170, 16, v77
	v_and_b32_e32 v171, 0xffff0000, v77
	v_lshlrev_b32_e32 v172, 16, v78
	v_and_b32_e32 v173, 0xffff0000, v78
	v_lshlrev_b32_e32 v174, 16, v79
	v_and_b32_e32 v175, 0xffff0000, v79
	v_pk_mul_f32 v[252:253], v[160:161], v[160:161]
	v_pk_mul_f32 v[254:255], v[162:163], v[162:163]
	v_pk_fma_f32 v[252:253], v[164:165], v[164:165], v[252:253]
	v_pk_fma_f32 v[254:255], v[166:167], v[166:167], v[254:255]
	v_pk_fma_f32 v[252:253], v[168:169], v[168:169], v[252:253]
	v_pk_fma_f32 v[254:255], v[170:171], v[170:171], v[254:255]
	v_pk_fma_f32 v[252:253], v[172:173], v[172:173], v[252:253]
	v_pk_fma_f32 v[254:255], v[174:175], v[174:175], v[254:255]
	v_pk_add_f32 v[252:253], v[252:253], v[254:255]
	s_nop 0
	v_add_f32_e32 v183, v252, v253
	s_nop 1
	v_add_f32_dpp v183, v183, v183 quad_perm:[1,0,3,2] row_mask:0xf bank_mask:0xf bound_ctrl:1
	s_nop 1
	v_add_f32_dpp v183, v183, v183 quad_perm:[2,3,0,1] row_mask:0xf bank_mask:0xf bound_ctrl:1
	s_nop 1
	v_add_f32_dpp v183, v183, v183 row_half_mirror row_mask:0xf bank_mask:0xf bound_ctrl:1
	s_nop 1
	v_add_f32_dpp v183, v183, v183 row_mirror row_mask:0xf bank_mask:0xf bound_ctrl:1
	s_nop 1
	v_readlane_b32 s98, v183, 0
	v_readlane_b32 s99, v183, 16
	v_readlane_b32 s100, v183, 32
	v_readlane_b32 s101, v183, 48
	s_nop 1
	v_mov_b32_e32 v183, s98
	v_add_f32_e32 v183, s99, v183
	v_add_f32_e32 v183, s100, v183
	v_add_f32_e32 v183, s101, v183
	v_fmamk_f32 v183, v183, 0x3a800000, v182
	v_cmp_gt_f32_e32 vcc, 0x800000, v183
	v_mul_f32_e32 v181, 0x4b800000, v183
	s_nop 1
	v_cndmask_b32_e32 v183, v183, v181, vcc
	v_rsq_f32_e32 v183, v183
	s_nop 0
	v_mul_f32_e32 v181, 0x45800000, v183
	v_cndmask_b32_e32 v184, v183, v181, vcc
	v_mov_b32_e32 v185, v184
	v_pk_mul_f32 v[160:161], v[160:161], v[184:185]
	v_pk_mul_f32 v[162:163], v[162:163], v[184:185]
	v_pk_mul_f32 v[164:165], v[164:165], v[184:185]
	v_pk_mul_f32 v[166:167], v[166:167], v[184:185]
	v_pk_mul_f32 v[168:169], v[168:169], v[184:185]
	v_pk_mul_f32 v[170:171], v[170:171], v[184:185]
	v_pk_mul_f32 v[172:173], v[172:173], v[184:185]
	v_pk_mul_f32 v[174:175], v[174:175], v[184:185]
	v_pk_fma_f32 v[144:145], v[160:161], v[128:129], v[144:145]
	v_pk_fma_f32 v[146:147], v[162:163], v[130:131], v[146:147]
	v_pk_fma_f32 v[148:149], v[164:165], v[132:133], v[148:149]
	v_pk_fma_f32 v[150:151], v[166:167], v[134:135], v[150:151]
	v_pk_fma_f32 v[152:153], v[168:169], v[136:137], v[152:153]
	v_pk_fma_f32 v[154:155], v[170:171], v[138:139], v[154:155]
	v_pk_fma_f32 v[156:157], v[172:173], v[140:141], v[156:157]
	v_pk_fma_f32 v[158:159], v[174:175], v[142:143], v[158:159]
	v_pk_mul_f32 v[252:253], v[144:145], v[144:145]
	v_pk_mul_f32 v[254:255], v[146:147], v[146:147]
	v_pk_fma_f32 v[252:253], v[148:149], v[148:149], v[252:253]
	v_pk_fma_f32 v[254:255], v[150:151], v[150:151], v[254:255]
	v_pk_fma_f32 v[252:253], v[152:153], v[152:153], v[252:253]
	v_pk_fma_f32 v[254:255], v[154:155], v[154:155], v[254:255]
	v_pk_fma_f32 v[252:253], v[156:157], v[156:157], v[252:253]
	v_pk_fma_f32 v[254:255], v[158:159], v[158:159], v[254:255]
	v_pk_add_f32 v[252:253], v[252:253], v[254:255]
	s_nop 0
	v_add_f32_e32 v183, v252, v253
	s_nop 1
	v_add_f32_dpp v183, v183, v183 quad_perm:[1,0,3,2] row_mask:0xf bank_mask:0xf bound_ctrl:1
	s_nop 1
	v_add_f32_dpp v183, v183, v183 quad_perm:[2,3,0,1] row_mask:0xf bank_mask:0xf bound_ctrl:1
	s_nop 1
	v_add_f32_dpp v183, v183, v183 row_half_mirror row_mask:0xf bank_mask:0xf bound_ctrl:1
	s_nop 1
	v_add_f32_dpp v183, v183, v183 row_mirror row_mask:0xf bank_mask:0xf bound_ctrl:1
	s_nop 1
	v_readlane_b32 s98, v183, 0
	v_readlane_b32 s99, v183, 16
	v_readlane_b32 s100, v183, 32
	v_readlane_b32 s101, v183, 48
	s_nop 1
	v_mov_b32_e32 v183, s98
	v_add_f32_e32 v183, s99, v183
	v_add_f32_e32 v183, s100, v183
	v_add_f32_e32 v183, s101, v183
	v_fmamk_f32 v183, v183, 0x3a800000, v182
	v_cmp_gt_f32_e32 vcc, 0x800000, v183
	v_mul_f32_e32 v181, 0x4b800000, v183
	s_nop 1
	v_cndmask_b32_e32 v183, v183, v181, vcc
	v_rsq_f32_e32 v183, v183
	s_nop 0
	v_mul_f32_e32 v181, 0x45800000, v183
	v_cndmask_b32_e32 v184, v183, v181, vcc
	v_mov_b32_e32 v185, v184
	v_pk_mul_f32 v[144:145], v[144:145], v[184:185]
	v_pk_mul_f32 v[146:147], v[146:147], v[184:185]
	v_pk_mul_f32 v[148:149], v[148:149], v[184:185]
	v_pk_mul_f32 v[150:151], v[150:151], v[184:185]
	v_pk_mul_f32 v[152:153], v[152:153], v[184:185]
	v_pk_mul_f32 v[154:155], v[154:155], v[184:185]
	v_pk_mul_f32 v[156:157], v[156:157], v[184:185]
	v_pk_mul_f32 v[158:159], v[158:159], v[184:185]
	v_pk_mul_f32 v[144:145], v[144:145], v[236:237]
	v_pk_mul_f32 v[146:147], v[146:147], v[238:239]
	v_pk_mul_f32 v[148:149], v[148:149], v[240:241]
	v_pk_mul_f32 v[150:151], v[150:151], v[242:243]
	v_pk_mul_f32 v[152:153], v[152:153], v[244:245]
	v_pk_mul_f32 v[154:155], v[154:155], v[246:247]
	v_pk_mul_f32 v[156:157], v[156:157], v[248:249]
	v_pk_mul_f32 v[158:159], v[158:159], v[250:251]
	v_add_u32_e32 v181, 0x2000000, v178
	global_store_dwordx4 v181, v[144:147], s[76:77]
	global_store_dwordx4 v181, v[148:151], s[76:77] offset:16
	global_store_dwordx4 v181, v[152:155], s[76:77] offset:2048
	global_store_dwordx4 v181, v[156:159], s[76:77] offset:2064
	s_nop 1
	s_waitcnt vmcnt(8)
	v_lshlrev_b32_e32 v144, 16, v80
	v_and_b32_e32 v145, 0xffff0000, v80
	v_lshlrev_b32_e32 v146, 16, v81
	v_and_b32_e32 v147, 0xffff0000, v81
	v_lshlrev_b32_e32 v148, 16, v82
	v_and_b32_e32 v149, 0xffff0000, v82
	v_lshlrev_b32_e32 v150, 16, v83
	v_and_b32_e32 v151, 0xffff0000, v83
	v_lshlrev_b32_e32 v152, 16, v84
	v_and_b32_e32 v153, 0xffff0000, v84
	v_lshlrev_b32_e32 v154, 16, v85
	v_and_b32_e32 v155, 0xffff0000, v85
	v_lshlrev_b32_e32 v156, 16, v86
	v_and_b32_e32 v157, 0xffff0000, v86
	v_lshlrev_b32_e32 v158, 16, v87
	v_and_b32_e32 v159, 0xffff0000, v87
	v_lshlrev_b32_e32 v160, 16, v88
	v_and_b32_e32 v161, 0xffff0000, v88
	v_lshlrev_b32_e32 v162, 16, v89
	v_and_b32_e32 v163, 0xffff0000, v89
	v_lshlrev_b32_e32 v164, 16, v90
	v_and_b32_e32 v165, 0xffff0000, v90
	v_lshlrev_b32_e32 v166, 16, v91
	v_and_b32_e32 v167, 0xffff0000, v91
	v_lshlrev_b32_e32 v168, 16, v92
	v_and_b32_e32 v169, 0xffff0000, v92
	v_lshlrev_b32_e32 v170, 16, v93
	v_and_b32_e32 v171, 0xffff0000, v93
	v_lshlrev_b32_e32 v172, 16, v94
	v_and_b32_e32 v173, 0xffff0000, v94
	v_lshlrev_b32_e32 v174, 16, v95
	v_and_b32_e32 v175, 0xffff0000, v95
	v_pk_mul_f32 v[252:253], v[160:161], v[160:161]
	v_pk_mul_f32 v[254:255], v[162:163], v[162:163]
	v_pk_fma_f32 v[252:253], v[164:165], v[164:165], v[252:253]
	v_pk_fma_f32 v[254:255], v[166:167], v[166:167], v[254:255]
	v_pk_fma_f32 v[252:253], v[168:169], v[168:169], v[252:253]
	v_pk_fma_f32 v[254:255], v[170:171], v[170:171], v[254:255]
	v_pk_fma_f32 v[252:253], v[172:173], v[172:173], v[252:253]
	v_pk_fma_f32 v[254:255], v[174:175], v[174:175], v[254:255]
	v_pk_add_f32 v[252:253], v[252:253], v[254:255]
	s_nop 0
	v_add_f32_e32 v183, v252, v253
	s_nop 1
	v_add_f32_dpp v183, v183, v183 quad_perm:[1,0,3,2] row_mask:0xf bank_mask:0xf bound_ctrl:1
	s_nop 1
	v_add_f32_dpp v183, v183, v183 quad_perm:[2,3,0,1] row_mask:0xf bank_mask:0xf bound_ctrl:1
	s_nop 1
	v_add_f32_dpp v183, v183, v183 row_half_mirror row_mask:0xf bank_mask:0xf bound_ctrl:1
	s_nop 1
	v_add_f32_dpp v183, v183, v183 row_mirror row_mask:0xf bank_mask:0xf bound_ctrl:1
	s_nop 1
	v_readlane_b32 s98, v183, 0
	v_readlane_b32 s99, v183, 16
	v_readlane_b32 s100, v183, 32
	v_readlane_b32 s101, v183, 48
	s_nop 1
	v_mov_b32_e32 v183, s98
	v_add_f32_e32 v183, s99, v183
	v_add_f32_e32 v183, s100, v183
	v_add_f32_e32 v183, s101, v183
	v_fmamk_f32 v183, v183, 0x3a800000, v182
	v_cmp_gt_f32_e32 vcc, 0x800000, v183
	v_mul_f32_e32 v181, 0x4b800000, v183
	s_nop 1
	v_cndmask_b32_e32 v183, v183, v181, vcc
	v_rsq_f32_e32 v183, v183
	s_nop 0
	v_mul_f32_e32 v181, 0x45800000, v183
	v_cndmask_b32_e32 v184, v183, v181, vcc
	v_mov_b32_e32 v185, v184
	v_pk_mul_f32 v[160:161], v[160:161], v[184:185]
	v_pk_mul_f32 v[162:163], v[162:163], v[184:185]
	v_pk_mul_f32 v[164:165], v[164:165], v[184:185]
	v_pk_mul_f32 v[166:167], v[166:167], v[184:185]
	v_pk_mul_f32 v[168:169], v[168:169], v[184:185]
	v_pk_mul_f32 v[170:171], v[170:171], v[184:185]
	v_pk_mul_f32 v[172:173], v[172:173], v[184:185]
	v_pk_mul_f32 v[174:175], v[174:175], v[184:185]
	v_pk_fma_f32 v[144:145], v[160:161], v[128:129], v[144:145]
	v_pk_fma_f32 v[146:147], v[162:163], v[130:131], v[146:147]
	v_pk_fma_f32 v[148:149], v[164:165], v[132:133], v[148:149]
	v_pk_fma_f32 v[150:151], v[166:167], v[134:135], v[150:151]
	v_pk_fma_f32 v[152:153], v[168:169], v[136:137], v[152:153]
	v_pk_fma_f32 v[154:155], v[170:171], v[138:139], v[154:155]
	v_pk_fma_f32 v[156:157], v[172:173], v[140:141], v[156:157]
	v_pk_fma_f32 v[158:159], v[174:175], v[142:143], v[158:159]
	v_pk_mul_f32 v[252:253], v[144:145], v[144:145]
	v_pk_mul_f32 v[254:255], v[146:147], v[146:147]
	v_pk_fma_f32 v[252:253], v[148:149], v[148:149], v[252:253]
	v_pk_fma_f32 v[254:255], v[150:151], v[150:151], v[254:255]
	v_pk_fma_f32 v[252:253], v[152:153], v[152:153], v[252:253]
	v_pk_fma_f32 v[254:255], v[154:155], v[154:155], v[254:255]
	v_pk_fma_f32 v[252:253], v[156:157], v[156:157], v[252:253]
	v_pk_fma_f32 v[254:255], v[158:159], v[158:159], v[254:255]
	v_pk_add_f32 v[252:253], v[252:253], v[254:255]
	s_nop 0
	v_add_f32_e32 v183, v252, v253
	s_nop 1
	v_add_f32_dpp v183, v183, v183 quad_perm:[1,0,3,2] row_mask:0xf bank_mask:0xf bound_ctrl:1
	s_nop 1
	v_add_f32_dpp v183, v183, v183 quad_perm:[2,3,0,1] row_mask:0xf bank_mask:0xf bound_ctrl:1
	s_nop 1
	v_add_f32_dpp v183, v183, v183 row_half_mirror row_mask:0xf bank_mask:0xf bound_ctrl:1
	s_nop 1
	v_add_f32_dpp v183, v183, v183 row_mirror row_mask:0xf bank_mask:0xf bound_ctrl:1
	s_nop 1
	v_readlane_b32 s98, v183, 0
	v_readlane_b32 s99, v183, 16
	v_readlane_b32 s100, v183, 32
	v_readlane_b32 s101, v183, 48
	s_nop 1
	v_mov_b32_e32 v183, s98
	v_add_f32_e32 v183, s99, v183
	v_add_f32_e32 v183, s100, v183
	v_add_f32_e32 v183, s101, v183
	v_fmamk_f32 v183, v183, 0x3a800000, v182
	v_cmp_gt_f32_e32 vcc, 0x800000, v183
	v_mul_f32_e32 v181, 0x4b800000, v183
	s_nop 1
	v_cndmask_b32_e32 v183, v183, v181, vcc
	v_rsq_f32_e32 v183, v183
	s_nop 0
	v_mul_f32_e32 v181, 0x45800000, v183
	v_cndmask_b32_e32 v184, v183, v181, vcc
	v_mov_b32_e32 v185, v184
	v_pk_mul_f32 v[144:145], v[144:145], v[184:185]
	v_pk_mul_f32 v[146:147], v[146:147], v[184:185]
	v_pk_mul_f32 v[148:149], v[148:149], v[184:185]
	v_pk_mul_f32 v[150:151], v[150:151], v[184:185]
	v_pk_mul_f32 v[152:153], v[152:153], v[184:185]
	v_pk_mul_f32 v[154:155], v[154:155], v[184:185]
	v_pk_mul_f32 v[156:157], v[156:157], v[184:185]
	v_pk_mul_f32 v[158:159], v[158:159], v[184:185]
	v_pk_mul_f32 v[144:145], v[144:145], v[236:237]
	v_pk_mul_f32 v[146:147], v[146:147], v[238:239]
	v_pk_mul_f32 v[148:149], v[148:149], v[240:241]
	v_pk_mul_f32 v[150:151], v[150:151], v[242:243]
	v_pk_mul_f32 v[152:153], v[152:153], v[244:245]
	v_pk_mul_f32 v[154:155], v[154:155], v[246:247]
	v_pk_mul_f32 v[156:157], v[156:157], v[248:249]
	v_pk_mul_f32 v[158:159], v[158:159], v[250:251]
	v_add_u32_e32 v181, 0x2800000, v178
	global_store_dwordx4 v181, v[144:147], s[76:77]
	global_store_dwordx4 v181, v[148:151], s[76:77] offset:16
	global_store_dwordx4 v181, v[152:155], s[76:77] offset:2048
	global_store_dwordx4 v181, v[156:159], s[76:77] offset:2064
	s_nop 1
	s_waitcnt vmcnt(4)
	v_lshlrev_b32_e32 v144, 16, v96
	v_and_b32_e32 v145, 0xffff0000, v96
	v_lshlrev_b32_e32 v146, 16, v97
	v_and_b32_e32 v147, 0xffff0000, v97
	v_lshlrev_b32_e32 v148, 16, v98
	v_and_b32_e32 v149, 0xffff0000, v98
	v_lshlrev_b32_e32 v150, 16, v99
	v_and_b32_e32 v151, 0xffff0000, v99
	v_lshlrev_b32_e32 v152, 16, v100
	v_and_b32_e32 v153, 0xffff0000, v100
	v_lshlrev_b32_e32 v154, 16, v101
	v_and_b32_e32 v155, 0xffff0000, v101
	v_lshlrev_b32_e32 v156, 16, v102
	v_and_b32_e32 v157, 0xffff0000, v102
	v_lshlrev_b32_e32 v158, 16, v103
	v_and_b32_e32 v159, 0xffff0000, v103
	v_lshlrev_b32_e32 v160, 16, v104
	v_and_b32_e32 v161, 0xffff0000, v104
	v_lshlrev_b32_e32 v162, 16, v105
	v_and_b32_e32 v163, 0xffff0000, v105
	v_lshlrev_b32_e32 v164, 16, v106
	v_and_b32_e32 v165, 0xffff0000, v106
	v_lshlrev_b32_e32 v166, 16, v107
	v_and_b32_e32 v167, 0xffff0000, v107
	v_lshlrev_b32_e32 v168, 16, v108
	v_and_b32_e32 v169, 0xffff0000, v108
	v_lshlrev_b32_e32 v170, 16, v109
	v_and_b32_e32 v171, 0xffff0000, v109
	v_lshlrev_b32_e32 v172, 16, v110
	v_and_b32_e32 v173, 0xffff0000, v110
	v_lshlrev_b32_e32 v174, 16, v111
	v_and_b32_e32 v175, 0xffff0000, v111
	v_pk_mul_f32 v[252:253], v[160:161], v[160:161]
	v_pk_mul_f32 v[254:255], v[162:163], v[162:163]
	v_pk_fma_f32 v[252:253], v[164:165], v[164:165], v[252:253]
	v_pk_fma_f32 v[254:255], v[166:167], v[166:167], v[254:255]
	v_pk_fma_f32 v[252:253], v[168:169], v[168:169], v[252:253]
	v_pk_fma_f32 v[254:255], v[170:171], v[170:171], v[254:255]
	v_pk_fma_f32 v[252:253], v[172:173], v[172:173], v[252:253]
	v_pk_fma_f32 v[254:255], v[174:175], v[174:175], v[254:255]
	v_pk_add_f32 v[252:253], v[252:253], v[254:255]
	s_nop 0
	v_add_f32_e32 v183, v252, v253
	s_nop 1
	v_add_f32_dpp v183, v183, v183 quad_perm:[1,0,3,2] row_mask:0xf bank_mask:0xf bound_ctrl:1
	s_nop 1
	v_add_f32_dpp v183, v183, v183 quad_perm:[2,3,0,1] row_mask:0xf bank_mask:0xf bound_ctrl:1
	s_nop 1
	v_add_f32_dpp v183, v183, v183 row_half_mirror row_mask:0xf bank_mask:0xf bound_ctrl:1
	s_nop 1
	v_add_f32_dpp v183, v183, v183 row_mirror row_mask:0xf bank_mask:0xf bound_ctrl:1
	s_nop 1
	v_readlane_b32 s98, v183, 0
	v_readlane_b32 s99, v183, 16
	v_readlane_b32 s100, v183, 32
	v_readlane_b32 s101, v183, 48
	s_nop 1
	v_mov_b32_e32 v183, s98
	v_add_f32_e32 v183, s99, v183
	v_add_f32_e32 v183, s100, v183
	v_add_f32_e32 v183, s101, v183
	v_fmamk_f32 v183, v183, 0x3a800000, v182
	v_cmp_gt_f32_e32 vcc, 0x800000, v183
	v_mul_f32_e32 v181, 0x4b800000, v183
	s_nop 1
	v_cndmask_b32_e32 v183, v183, v181, vcc
	v_rsq_f32_e32 v183, v183
	s_nop 0
	v_mul_f32_e32 v181, 0x45800000, v183
	v_cndmask_b32_e32 v184, v183, v181, vcc
	v_mov_b32_e32 v185, v184
	v_pk_mul_f32 v[160:161], v[160:161], v[184:185]
	v_pk_mul_f32 v[162:163], v[162:163], v[184:185]
	v_pk_mul_f32 v[164:165], v[164:165], v[184:185]
	v_pk_mul_f32 v[166:167], v[166:167], v[184:185]
	v_pk_mul_f32 v[168:169], v[168:169], v[184:185]
	v_pk_mul_f32 v[170:171], v[170:171], v[184:185]
	v_pk_mul_f32 v[172:173], v[172:173], v[184:185]
	v_pk_mul_f32 v[174:175], v[174:175], v[184:185]
	v_pk_fma_f32 v[144:145], v[160:161], v[128:129], v[144:145]
	v_pk_fma_f32 v[146:147], v[162:163], v[130:131], v[146:147]
	v_pk_fma_f32 v[148:149], v[164:165], v[132:133], v[148:149]
	v_pk_fma_f32 v[150:151], v[166:167], v[134:135], v[150:151]
	v_pk_fma_f32 v[152:153], v[168:169], v[136:137], v[152:153]
	v_pk_fma_f32 v[154:155], v[170:171], v[138:139], v[154:155]
	v_pk_fma_f32 v[156:157], v[172:173], v[140:141], v[156:157]
	v_pk_fma_f32 v[158:159], v[174:175], v[142:143], v[158:159]
	v_pk_mul_f32 v[252:253], v[144:145], v[144:145]
	v_pk_mul_f32 v[254:255], v[146:147], v[146:147]
	v_pk_fma_f32 v[252:253], v[148:149], v[148:149], v[252:253]
	v_pk_fma_f32 v[254:255], v[150:151], v[150:151], v[254:255]
	v_pk_fma_f32 v[252:253], v[152:153], v[152:153], v[252:253]
	v_pk_fma_f32 v[254:255], v[154:155], v[154:155], v[254:255]
	v_pk_fma_f32 v[252:253], v[156:157], v[156:157], v[252:253]
	v_pk_fma_f32 v[254:255], v[158:159], v[158:159], v[254:255]
	v_pk_add_f32 v[252:253], v[252:253], v[254:255]
	s_nop 0
	v_add_f32_e32 v183, v252, v253
	s_nop 1
	v_add_f32_dpp v183, v183, v183 quad_perm:[1,0,3,2] row_mask:0xf bank_mask:0xf bound_ctrl:1
	s_nop 1
	v_add_f32_dpp v183, v183, v183 quad_perm:[2,3,0,1] row_mask:0xf bank_mask:0xf bound_ctrl:1
	s_nop 1
	v_add_f32_dpp v183, v183, v183 row_half_mirror row_mask:0xf bank_mask:0xf bound_ctrl:1
	s_nop 1
	v_add_f32_dpp v183, v183, v183 row_mirror row_mask:0xf bank_mask:0xf bound_ctrl:1
	s_nop 1
	v_readlane_b32 s98, v183, 0
	v_readlane_b32 s99, v183, 16
	v_readlane_b32 s100, v183, 32
	v_readlane_b32 s101, v183, 48
	s_nop 1
	v_mov_b32_e32 v183, s98
	v_add_f32_e32 v183, s99, v183
	v_add_f32_e32 v183, s100, v183
	v_add_f32_e32 v183, s101, v183
	v_fmamk_f32 v183, v183, 0x3a800000, v182
	v_cmp_gt_f32_e32 vcc, 0x800000, v183
	v_mul_f32_e32 v181, 0x4b800000, v183
	s_nop 1
	v_cndmask_b32_e32 v183, v183, v181, vcc
	v_rsq_f32_e32 v183, v183
	s_nop 0
	v_mul_f32_e32 v181, 0x45800000, v183
	v_cndmask_b32_e32 v184, v183, v181, vcc
	v_mov_b32_e32 v185, v184
	v_pk_mul_f32 v[144:145], v[144:145], v[184:185]
	v_pk_mul_f32 v[146:147], v[146:147], v[184:185]
	v_pk_mul_f32 v[148:149], v[148:149], v[184:185]
	v_pk_mul_f32 v[150:151], v[150:151], v[184:185]
	v_pk_mul_f32 v[152:153], v[152:153], v[184:185]
	v_pk_mul_f32 v[154:155], v[154:155], v[184:185]
	v_pk_mul_f32 v[156:157], v[156:157], v[184:185]
	v_pk_mul_f32 v[158:159], v[158:159], v[184:185]
	v_pk_mul_f32 v[144:145], v[144:145], v[236:237]
	v_pk_mul_f32 v[146:147], v[146:147], v[238:239]
	v_pk_mul_f32 v[148:149], v[148:149], v[240:241]
	v_pk_mul_f32 v[150:151], v[150:151], v[242:243]
	v_pk_mul_f32 v[152:153], v[152:153], v[244:245]
	v_pk_mul_f32 v[154:155], v[154:155], v[246:247]
	v_pk_mul_f32 v[156:157], v[156:157], v[248:249]
	v_pk_mul_f32 v[158:159], v[158:159], v[250:251]
	v_add_u32_e32 v181, 0x3000000, v178
	global_store_dwordx4 v181, v[144:147], s[76:77]
	global_store_dwordx4 v181, v[148:151], s[76:77] offset:16
	global_store_dwordx4 v181, v[152:155], s[76:77] offset:2048
	global_store_dwordx4 v181, v[156:159], s[76:77] offset:2064
	s_nop 1
	s_waitcnt vmcnt(0)
	v_lshlrev_b32_e32 v144, 16, v112
	v_and_b32_e32 v145, 0xffff0000, v112
	v_lshlrev_b32_e32 v146, 16, v113
	v_and_b32_e32 v147, 0xffff0000, v113
	v_lshlrev_b32_e32 v148, 16, v114
	v_and_b32_e32 v149, 0xffff0000, v114
	v_lshlrev_b32_e32 v150, 16, v115
	v_and_b32_e32 v151, 0xffff0000, v115
	v_lshlrev_b32_e32 v152, 16, v116
	v_and_b32_e32 v153, 0xffff0000, v116
	v_lshlrev_b32_e32 v154, 16, v117
	v_and_b32_e32 v155, 0xffff0000, v117
	v_lshlrev_b32_e32 v156, 16, v118
	v_and_b32_e32 v157, 0xffff0000, v118
	v_lshlrev_b32_e32 v158, 16, v119
	v_and_b32_e32 v159, 0xffff0000, v119
	v_lshlrev_b32_e32 v160, 16, v120
	v_and_b32_e32 v161, 0xffff0000, v120
	v_lshlrev_b32_e32 v162, 16, v121
	v_and_b32_e32 v163, 0xffff0000, v121
	v_lshlrev_b32_e32 v164, 16, v122
	v_and_b32_e32 v165, 0xffff0000, v122
	v_lshlrev_b32_e32 v166, 16, v123
	v_and_b32_e32 v167, 0xffff0000, v123
	v_lshlrev_b32_e32 v168, 16, v124
	v_and_b32_e32 v169, 0xffff0000, v124
	v_lshlrev_b32_e32 v170, 16, v125
	v_and_b32_e32 v171, 0xffff0000, v125
	v_lshlrev_b32_e32 v172, 16, v126
	v_and_b32_e32 v173, 0xffff0000, v126
	v_lshlrev_b32_e32 v174, 16, v127
	v_and_b32_e32 v175, 0xffff0000, v127
	v_pk_mul_f32 v[252:253], v[160:161], v[160:161]
	v_pk_mul_f32 v[254:255], v[162:163], v[162:163]
	v_pk_fma_f32 v[252:253], v[164:165], v[164:165], v[252:253]
	v_pk_fma_f32 v[254:255], v[166:167], v[166:167], v[254:255]
	v_pk_fma_f32 v[252:253], v[168:169], v[168:169], v[252:253]
	v_pk_fma_f32 v[254:255], v[170:171], v[170:171], v[254:255]
	v_pk_fma_f32 v[252:253], v[172:173], v[172:173], v[252:253]
	v_pk_fma_f32 v[254:255], v[174:175], v[174:175], v[254:255]
	v_pk_add_f32 v[252:253], v[252:253], v[254:255]
	s_nop 0
	v_add_f32_e32 v183, v252, v253
	s_nop 1
	v_add_f32_dpp v183, v183, v183 quad_perm:[1,0,3,2] row_mask:0xf bank_mask:0xf bound_ctrl:1
	s_nop 1
	v_add_f32_dpp v183, v183, v183 quad_perm:[2,3,0,1] row_mask:0xf bank_mask:0xf bound_ctrl:1
	s_nop 1
	v_add_f32_dpp v183, v183, v183 row_half_mirror row_mask:0xf bank_mask:0xf bound_ctrl:1
	s_nop 1
	v_add_f32_dpp v183, v183, v183 row_mirror row_mask:0xf bank_mask:0xf bound_ctrl:1
	s_nop 1
	v_readlane_b32 s98, v183, 0
	v_readlane_b32 s99, v183, 16
	v_readlane_b32 s100, v183, 32
	v_readlane_b32 s101, v183, 48
	s_nop 1
	v_mov_b32_e32 v183, s98
	v_add_f32_e32 v183, s99, v183
	v_add_f32_e32 v183, s100, v183
	v_add_f32_e32 v183, s101, v183
	v_fmamk_f32 v183, v183, 0x3a800000, v182
	v_cmp_gt_f32_e32 vcc, 0x800000, v183
	v_mul_f32_e32 v181, 0x4b800000, v183
	s_nop 1
	v_cndmask_b32_e32 v183, v183, v181, vcc
	v_rsq_f32_e32 v183, v183
	s_nop 0
	v_mul_f32_e32 v181, 0x45800000, v183
	v_cndmask_b32_e32 v184, v183, v181, vcc
	v_mov_b32_e32 v185, v184
	v_pk_mul_f32 v[160:161], v[160:161], v[184:185]
	v_pk_mul_f32 v[162:163], v[162:163], v[184:185]
	v_pk_mul_f32 v[164:165], v[164:165], v[184:185]
	v_pk_mul_f32 v[166:167], v[166:167], v[184:185]
	v_pk_mul_f32 v[168:169], v[168:169], v[184:185]
	v_pk_mul_f32 v[170:171], v[170:171], v[184:185]
	v_pk_mul_f32 v[172:173], v[172:173], v[184:185]
	v_pk_mul_f32 v[174:175], v[174:175], v[184:185]
	v_pk_fma_f32 v[144:145], v[160:161], v[128:129], v[144:145]
	v_pk_fma_f32 v[146:147], v[162:163], v[130:131], v[146:147]
	v_pk_fma_f32 v[148:149], v[164:165], v[132:133], v[148:149]
	v_pk_fma_f32 v[150:151], v[166:167], v[134:135], v[150:151]
	v_pk_fma_f32 v[152:153], v[168:169], v[136:137], v[152:153]
	v_pk_fma_f32 v[154:155], v[170:171], v[138:139], v[154:155]
	v_pk_fma_f32 v[156:157], v[172:173], v[140:141], v[156:157]
	v_pk_fma_f32 v[158:159], v[174:175], v[142:143], v[158:159]
	v_pk_mul_f32 v[252:253], v[144:145], v[144:145]
	v_pk_mul_f32 v[254:255], v[146:147], v[146:147]
	v_pk_fma_f32 v[252:253], v[148:149], v[148:149], v[252:253]
	v_pk_fma_f32 v[254:255], v[150:151], v[150:151], v[254:255]
	v_pk_fma_f32 v[252:253], v[152:153], v[152:153], v[252:253]
	v_pk_fma_f32 v[254:255], v[154:155], v[154:155], v[254:255]
	v_pk_fma_f32 v[252:253], v[156:157], v[156:157], v[252:253]
	v_pk_fma_f32 v[254:255], v[158:159], v[158:159], v[254:255]
	v_pk_add_f32 v[252:253], v[252:253], v[254:255]
	s_nop 0
	v_add_f32_e32 v183, v252, v253
	s_nop 1
	v_add_f32_dpp v183, v183, v183 quad_perm:[1,0,3,2] row_mask:0xf bank_mask:0xf bound_ctrl:1
	s_nop 1
	v_add_f32_dpp v183, v183, v183 quad_perm:[2,3,0,1] row_mask:0xf bank_mask:0xf bound_ctrl:1
	s_nop 1
	v_add_f32_dpp v183, v183, v183 row_half_mirror row_mask:0xf bank_mask:0xf bound_ctrl:1
	s_nop 1
	v_add_f32_dpp v183, v183, v183 row_mirror row_mask:0xf bank_mask:0xf bound_ctrl:1
	s_nop 1
	v_readlane_b32 s98, v183, 0
	v_readlane_b32 s99, v183, 16
	v_readlane_b32 s100, v183, 32
	v_readlane_b32 s101, v183, 48
	s_nop 1
	v_mov_b32_e32 v183, s98
	v_add_f32_e32 v183, s99, v183
	v_add_f32_e32 v183, s100, v183
	v_add_f32_e32 v183, s101, v183
	v_fmamk_f32 v183, v183, 0x3a800000, v182
	v_cmp_gt_f32_e32 vcc, 0x800000, v183
	v_mul_f32_e32 v181, 0x4b800000, v183
	s_nop 1
	v_cndmask_b32_e32 v183, v183, v181, vcc
	v_rsq_f32_e32 v183, v183
	s_nop 0
	v_mul_f32_e32 v181, 0x45800000, v183
	v_cndmask_b32_e32 v184, v183, v181, vcc
	v_mov_b32_e32 v185, v184
	v_pk_mul_f32 v[144:145], v[144:145], v[184:185]
	v_pk_mul_f32 v[146:147], v[146:147], v[184:185]
	v_pk_mul_f32 v[148:149], v[148:149], v[184:185]
	v_pk_mul_f32 v[150:151], v[150:151], v[184:185]
	v_pk_mul_f32 v[152:153], v[152:153], v[184:185]
	v_pk_mul_f32 v[154:155], v[154:155], v[184:185]
	v_pk_mul_f32 v[156:157], v[156:157], v[184:185]
	v_pk_mul_f32 v[158:159], v[158:159], v[184:185]
	v_pk_mul_f32 v[144:145], v[144:145], v[236:237]
	v_pk_mul_f32 v[146:147], v[146:147], v[238:239]
	v_pk_mul_f32 v[148:149], v[148:149], v[240:241]
	v_pk_mul_f32 v[150:151], v[150:151], v[242:243]
	v_pk_mul_f32 v[152:153], v[152:153], v[244:245]
	v_pk_mul_f32 v[154:155], v[154:155], v[246:247]
	v_pk_mul_f32 v[156:157], v[156:157], v[248:249]
	v_pk_mul_f32 v[158:159], v[158:159], v[250:251]
	v_add_u32_e32 v181, 0x3800000, v178
	global_store_dwordx4 v181, v[144:147], s[76:77]
	global_store_dwordx4 v181, v[148:151], s[76:77] offset:16
	global_store_dwordx4 v181, v[152:155], s[76:77] offset:2048
	global_store_dwordx4 v181, v[156:159], s[76:77] offset:2064
	s_nop 1
	v_readfirstlane_b32 s98, v179
	s_nop 3
	s_and_b32 s99, s98, 3
	s_cmp_lg_u32 s99, 0
	s_cbranch_scc1 .Lmyxupd_done_7
	v_lshrrev_b32_e32 v179, 2, v179
	v_lshlrev_b32_e32 v177, 4, v176
	v_lshl_add_u32 v177, v179, 11, v177
	v_lshl_add_u32 v178, v179, 12, v180
	v_add_u32_e32 v181, 0x3800000, v177
	global_load_dwordx4 v[0:3], v181, s[78:79]
	global_load_dwordx4 v[4:7], v181, s[78:79] offset:1024
	v_lshl_add_u32 v183, v179, 12, v180
	v_add_u32_e32 v183, 0xbf00000, v183
	v_add_u32_e32 v181, 0x0, v183
	global_load_dwordx4 v[8:11], v181, s[78:79]
	global_load_dwordx4 v[12:15], v181, s[78:79] offset:16
	global_load_dwordx4 v[16:19], v181, s[78:79] offset:2048
	global_load_dwordx4 v[20:23], v181, s[78:79] offset:2064
	v_add_u32_e32 v181, 0x200000, v183
	global_load_dwordx4 v[24:27], v181, s[78:79]
	global_load_dwordx4 v[28:31], v181, s[78:79] offset:16
	global_load_dwordx4 v[32:35], v181, s[78:79] offset:2048
	global_load_dwordx4 v[36:39], v181, s[78:79] offset:2064
	v_add_u32_e32 v181, 0x400000, v183
	global_load_dwordx4 v[40:43], v181, s[78:79]
	global_load_dwordx4 v[44:47], v181, s[78:79] offset:16
	global_load_dwordx4 v[48:51], v181, s[78:79] offset:2048
	global_load_dwordx4 v[52:55], v181, s[78:79] offset:2064
	v_add_u32_e32 v181, 0x600000, v183
	global_load_dwordx4 v[56:59], v181, s[78:79]
	global_load_dwordx4 v[60:63], v181, s[78:79] offset:16
	global_load_dwordx4 v[64:67], v181, s[78:79] offset:2048
	global_load_dwordx4 v[68:71], v181, s[78:79] offset:2064
	v_add_u32_e32 v181, 0x800000, v183
	global_load_dwordx4 v[72:75], v181, s[78:79]
	global_load_dwordx4 v[76:79], v181, s[78:79] offset:16
	global_load_dwordx4 v[80:83], v181, s[78:79] offset:2048
	global_load_dwordx4 v[84:87], v181, s[78:79] offset:2064
	v_add_u32_e32 v181, 0xa00000, v183
	global_load_dwordx4 v[88:91], v181, s[78:79]
	global_load_dwordx4 v[92:95], v181, s[78:79] offset:16
	global_load_dwordx4 v[96:99], v181, s[78:79] offset:2048
	global_load_dwordx4 v[100:103], v181, s[78:79] offset:2064
	s_waitcnt vmcnt(20)
	v_pk_add_f32 v[160:161], v[8:9], 0 op_sel_hi:[1,0]
	v_pk_add_f32 v[162:163], v[10:11], 0 op_sel_hi:[1,0]
	v_pk_add_f32 v[164:165], v[12:13], 0 op_sel_hi:[1,0]
	v_pk_add_f32 v[166:167], v[14:15], 0 op_sel_hi:[1,0]
	v_pk_add_f32 v[168:169], v[16:17], 0 op_sel_hi:[1,0]
	v_pk_add_f32 v[170:171], v[18:19], 0 op_sel_hi:[1,0]
	v_pk_add_f32 v[172:173], v[20:21], 0 op_sel_hi:[1,0]
	v_pk_add_f32 v[174:175], v[22:23], 0 op_sel_hi:[1,0]
	s_waitcnt vmcnt(16)
	v_pk_add_f32 v[160:161], v[160:161], v[24:25]
	v_pk_add_f32 v[162:163], v[162:163], v[26:27]
	v_pk_add_f32 v[164:165], v[164:165], v[28:29]
	v_pk_add_f32 v[166:167], v[166:167], v[30:31]
	v_pk_add_f32 v[168:169], v[168:169], v[32:33]
	v_pk_add_f32 v[170:171], v[170:171], v[34:35]
	v_pk_add_f32 v[172:173], v[172:173], v[36:37]
	v_pk_add_f32 v[174:175], v[174:175], v[38:39]
	s_waitcnt vmcnt(12)
	v_pk_add_f32 v[160:161], v[160:161], v[40:41]
	v_pk_add_f32 v[162:163], v[162:163], v[42:43]
	v_pk_add_f32 v[164:165], v[164:165], v[44:45]
	v_pk_add_f32 v[166:167], v[166:167], v[46:47]
	v_pk_add_f32 v[168:169], v[168:169], v[48:49]
	v_pk_add_f32 v[170:171], v[170:171], v[50:51]
	v_pk_add_f32 v[172:173], v[172:173], v[52:53]
	v_pk_add_f32 v[174:175], v[174:175], v[54:55]
	s_waitcnt vmcnt(8)
	v_pk_add_f32 v[160:161], v[160:161], v[56:57]
	v_pk_add_f32 v[162:163], v[162:163], v[58:59]
	v_pk_add_f32 v[164:165], v[164:165], v[60:61]
	v_pk_add_f32 v[166:167], v[166:167], v[62:63]
	v_pk_add_f32 v[168:169], v[168:169], v[64:65]
	v_pk_add_f32 v[170:171], v[170:171], v[66:67]
	v_pk_add_f32 v[172:173], v[172:173], v[68:69]
	v_pk_add_f32 v[174:175], v[174:175], v[70:71]
	s_waitcnt vmcnt(4)
	v_pk_add_f32 v[160:161], v[160:161], v[72:73]
	v_pk_add_f32 v[162:163], v[162:163], v[74:75]
	v_pk_add_f32 v[164:165], v[164:165], v[76:77]
	v_pk_add_f32 v[166:167], v[166:167], v[78:79]
	v_pk_add_f32 v[168:169], v[168:169], v[80:81]
	v_pk_add_f32 v[170:171], v[170:171], v[82:83]
	v_pk_add_f32 v[172:173], v[172:173], v[84:85]
	v_pk_add_f32 v[174:175], v[174:175], v[86:87]
	s_waitcnt vmcnt(0)
	v_pk_add_f32 v[160:161], v[160:161], v[88:89]
	v_pk_add_f32 v[162:163], v[162:163], v[90:91]
	v_pk_add_f32 v[164:165], v[164:165], v[92:93]
	v_pk_add_f32 v[166:167], v[166:167], v[94:95]
	v_pk_add_f32 v[168:169], v[168:169], v[96:97]
	v_pk_add_f32 v[170:171], v[170:171], v[98:99]
	v_pk_add_f32 v[172:173], v[172:173], v[100:101]
	v_pk_add_f32 v[174:175], v[174:175], v[102:103]
	v_lshlrev_b32_e32 v144, 16, v0
	v_and_b32_e32 v145, 0xffff0000, v0
	v_lshlrev_b32_e32 v146, 16, v1
	v_and_b32_e32 v147, 0xffff0000, v1
	v_lshlrev_b32_e32 v148, 16, v2
	v_and_b32_e32 v149, 0xffff0000, v2
	v_lshlrev_b32_e32 v150, 16, v3
	v_and_b32_e32 v151, 0xffff0000, v3
	v_lshlrev_b32_e32 v152, 16, v4
	v_and_b32_e32 v153, 0xffff0000, v4
	v_lshlrev_b32_e32 v154, 16, v5
	v_and_b32_e32 v155, 0xffff0000, v5
	v_lshlrev_b32_e32 v156, 16, v6
	v_and_b32_e32 v157, 0xffff0000, v6
	v_lshlrev_b32_e32 v158, 16, v7
	v_and_b32_e32 v159, 0xffff0000, v7
	v_add_u32_e32 v181, 0xc00000, v183
	global_load_dwordx4 v[8:11], v181, s[78:79]
	global_load_dwordx4 v[12:15], v181, s[78:79] offset:16
	global_load_dwordx4 v[16:19], v181, s[78:79] offset:2048
	global_load_dwordx4 v[20:23], v181, s[78:79] offset:2064
	v_add_u32_e32 v181, 0xe00000, v183
	global_load_dwordx4 v[24:27], v181, s[78:79]
	global_load_dwordx4 v[28:31], v181, s[78:79] offset:16
	global_load_dwordx4 v[32:35], v181, s[78:79] offset:2048
	global_load_dwordx4 v[36:39], v181, s[78:79] offset:2064
	v_add_u32_e32 v181, 0x1000000, v183
	global_load_dwordx4 v[40:43], v181, s[78:79]
	global_load_dwordx4 v[44:47], v181, s[78:79] offset:16
	global_load_dwordx4 v[48:51], v181, s[78:79] offset:2048
	global_load_dwordx4 v[52:55], v181, s[78:79] offset:2064
	v_add_u32_e32 v181, 0x1200000, v183
	global_load_dwordx4 v[56:59], v181, s[78:79]
	global_load_dwordx4 v[60:63], v181, s[78:79] offset:16
	global_load_dwordx4 v[64:67], v181, s[78:79] offset:2048
	global_load_dwordx4 v[68:71], v181, s[78:79] offset:2064
	v_add_u32_e32 v181, 0x1400000, v183
	global_load_dwordx4 v[72:75], v181, s[78:79]
	global_load_dwordx4 v[76:79], v181, s[78:79] offset:16
	global_load_dwordx4 v[80:83], v181, s[78:79] offset:2048
	global_load_dwordx4 v[84:87], v181, s[78:79] offset:2064
	s_waitcnt vmcnt(16)
	v_pk_add_f32 v[160:161], v[160:161], v[8:9]
	v_pk_add_f32 v[162:163], v[162:163], v[10:11]
	v_pk_add_f32 v[164:165], v[164:165], v[12:13]
	v_pk_add_f32 v[166:167], v[166:167], v[14:15]
	v_pk_add_f32 v[168:169], v[168:169], v[16:17]
	v_pk_add_f32 v[170:171], v[170:171], v[18:19]
	v_pk_add_f32 v[172:173], v[172:173], v[20:21]
	v_pk_add_f32 v[174:175], v[174:175], v[22:23]
	s_waitcnt vmcnt(12)
	v_pk_add_f32 v[160:161], v[160:161], v[24:25]
	v_pk_add_f32 v[162:163], v[162:163], v[26:27]
	v_pk_add_f32 v[164:165], v[164:165], v[28:29]
	v_pk_add_f32 v[166:167], v[166:167], v[30:31]
	v_pk_add_f32 v[168:169], v[168:169], v[32:33]
	v_pk_add_f32 v[170:171], v[170:171], v[34:35]
	v_pk_add_f32 v[172:173], v[172:173], v[36:37]
	v_pk_add_f32 v[174:175], v[174:175], v[38:39]
	s_waitcnt vmcnt(8)
	v_pk_add_f32 v[160:161], v[160:161], v[40:41]
	v_pk_add_f32 v[162:163], v[162:163], v[42:43]
	v_pk_add_f32 v[164:165], v[164:165], v[44:45]
	v_pk_add_f32 v[166:167], v[166:167], v[46:47]
	v_pk_add_f32 v[168:169], v[168:169], v[48:49]
	v_pk_add_f32 v[170:171], v[170:171], v[50:51]
	v_pk_add_f32 v[172:173], v[172:173], v[52:53]
	v_pk_add_f32 v[174:175], v[174:175], v[54:55]
	s_waitcnt vmcnt(4)
	v_pk_add_f32 v[160:161], v[160:161], v[56:57]
	v_pk_add_f32 v[162:163], v[162:163], v[58:59]
	v_pk_add_f32 v[164:165], v[164:165], v[60:61]
	v_pk_add_f32 v[166:167], v[166:167], v[62:63]
	v_pk_add_f32 v[168:169], v[168:169], v[64:65]
	v_pk_add_f32 v[170:171], v[170:171], v[66:67]
	v_pk_add_f32 v[172:173], v[172:173], v[68:69]
	v_pk_add_f32 v[174:175], v[174:175], v[70:71]
	s_waitcnt vmcnt(0)
	v_pk_add_f32 v[160:161], v[160:161], v[72:73]
	v_pk_add_f32 v[162:163], v[162:163], v[74:75]
	v_pk_add_f32 v[164:165], v[164:165], v[76:77]
	v_pk_add_f32 v[166:167], v[166:167], v[78:79]
	v_pk_add_f32 v[168:169], v[168:169], v[80:81]
	v_pk_add_f32 v[170:171], v[170:171], v[82:83]
	v_pk_add_f32 v[172:173], v[172:173], v[84:85]
	v_pk_add_f32 v[174:175], v[174:175], v[86:87]
	v_pk_mul_f32 v[252:253], v[160:161], v[160:161]
	v_pk_mul_f32 v[254:255], v[162:163], v[162:163]
	v_pk_fma_f32 v[252:253], v[164:165], v[164:165], v[252:253]
	v_pk_fma_f32 v[254:255], v[166:167], v[166:167], v[254:255]
	v_pk_fma_f32 v[252:253], v[168:169], v[168:169], v[252:253]
	v_pk_fma_f32 v[254:255], v[170:171], v[170:171], v[254:255]
	v_pk_fma_f32 v[252:253], v[172:173], v[172:173], v[252:253]
	v_pk_fma_f32 v[254:255], v[174:175], v[174:175], v[254:255]
	v_pk_add_f32 v[252:253], v[252:253], v[254:255]
	s_nop 0
	v_add_f32_e32 v183, v252, v253
	s_nop 1
	v_add_f32_dpp v183, v183, v183 quad_perm:[1,0,3,2] row_mask:0xf bank_mask:0xf bound_ctrl:1
	s_nop 1
	v_add_f32_dpp v183, v183, v183 quad_perm:[2,3,0,1] row_mask:0xf bank_mask:0xf bound_ctrl:1
	s_nop 1
	v_add_f32_dpp v183, v183, v183 row_half_mirror row_mask:0xf bank_mask:0xf bound_ctrl:1
	s_nop 1
	v_add_f32_dpp v183, v183, v183 row_mirror row_mask:0xf bank_mask:0xf bound_ctrl:1
	s_nop 1
	v_readlane_b32 s98, v183, 0
	v_readlane_b32 s99, v183, 16
	v_readlane_b32 s100, v183, 32
	v_readlane_b32 s101, v183, 48
	s_nop 1
	v_mov_b32_e32 v183, s98
	v_add_f32_e32 v183, s99, v183
	v_add_f32_e32 v183, s100, v183
	v_add_f32_e32 v183, s101, v183
	v_fmamk_f32 v183, v183, 0x3a800000, v182
	v_cmp_gt_f32_e32 vcc, 0x800000, v183
	v_mul_f32_e32 v181, 0x4b800000, v183
	s_nop 1
	v_cndmask_b32_e32 v183, v183, v181, vcc
	v_rsq_f32_e32 v183, v183
	s_nop 0
	v_mul_f32_e32 v181, 0x45800000, v183
	v_cndmask_b32_e32 v184, v183, v181, vcc
	v_mov_b32_e32 v185, v184
	v_pk_mul_f32 v[160:161], v[160:161], v[184:185]
	v_pk_mul_f32 v[162:163], v[162:163], v[184:185]
	v_pk_mul_f32 v[164:165], v[164:165], v[184:185]
	v_pk_mul_f32 v[166:167], v[166:167], v[184:185]
	v_pk_mul_f32 v[168:169], v[168:169], v[184:185]
	v_pk_mul_f32 v[170:171], v[170:171], v[184:185]
	v_pk_mul_f32 v[172:173], v[172:173], v[184:185]
	v_pk_mul_f32 v[174:175], v[174:175], v[184:185]
	v_pk_fma_f32 v[144:145], v[160:161], v[128:129], v[144:145]
	v_pk_fma_f32 v[146:147], v[162:163], v[130:131], v[146:147]
	v_pk_fma_f32 v[148:149], v[164:165], v[132:133], v[148:149]
	v_pk_fma_f32 v[150:151], v[166:167], v[134:135], v[150:151]
	v_pk_fma_f32 v[152:153], v[168:169], v[136:137], v[152:153]
	v_pk_fma_f32 v[154:155], v[170:171], v[138:139], v[154:155]
	v_pk_fma_f32 v[156:157], v[172:173], v[140:141], v[156:157]
	v_pk_fma_f32 v[158:159], v[174:175], v[142:143], v[158:159]
	v_pk_mul_f32 v[252:253], v[144:145], v[144:145]
	v_pk_mul_f32 v[254:255], v[146:147], v[146:147]
	v_pk_fma_f32 v[252:253], v[148:149], v[148:149], v[252:253]
	v_pk_fma_f32 v[254:255], v[150:151], v[150:151], v[254:255]
	v_pk_fma_f32 v[252:253], v[152:153], v[152:153], v[252:253]
	v_pk_fma_f32 v[254:255], v[154:155], v[154:155], v[254:255]
	v_pk_fma_f32 v[252:253], v[156:157], v[156:157], v[252:253]
	v_pk_fma_f32 v[254:255], v[158:159], v[158:159], v[254:255]
	v_pk_add_f32 v[252:253], v[252:253], v[254:255]
	s_nop 0
	v_add_f32_e32 v183, v252, v253
	s_nop 1
	v_add_f32_dpp v183, v183, v183 quad_perm:[1,0,3,2] row_mask:0xf bank_mask:0xf bound_ctrl:1
	s_nop 1
	v_add_f32_dpp v183, v183, v183 quad_perm:[2,3,0,1] row_mask:0xf bank_mask:0xf bound_ctrl:1
	s_nop 1
	v_add_f32_dpp v183, v183, v183 row_half_mirror row_mask:0xf bank_mask:0xf bound_ctrl:1
	s_nop 1
	v_add_f32_dpp v183, v183, v183 row_mirror row_mask:0xf bank_mask:0xf bound_ctrl:1
	s_nop 1
	v_readlane_b32 s98, v183, 0
	v_readlane_b32 s99, v183, 16
	v_readlane_b32 s100, v183, 32
	v_readlane_b32 s101, v183, 48
	s_nop 1
	v_mov_b32_e32 v183, s98
	v_add_f32_e32 v183, s99, v183
	v_add_f32_e32 v183, s100, v183
	v_add_f32_e32 v183, s101, v183
	v_fmamk_f32 v183, v183, 0x3a800000, v182
	v_cmp_gt_f32_e32 vcc, 0x800000, v183
	v_mul_f32_e32 v181, 0x4b800000, v183
	s_nop 1
	v_cndmask_b32_e32 v183, v183, v181, vcc
	v_rsq_f32_e32 v183, v183
	s_nop 0
	v_mul_f32_e32 v181, 0x45800000, v183
	v_cndmask_b32_e32 v184, v183, v181, vcc
	v_mov_b32_e32 v185, v184
	v_pk_mul_f32 v[144:145], v[144:145], v[184:185]
	v_pk_mul_f32 v[146:147], v[146:147], v[184:185]
	v_pk_mul_f32 v[148:149], v[148:149], v[184:185]
	v_pk_mul_f32 v[150:151], v[150:151], v[184:185]
	v_pk_mul_f32 v[152:153], v[152:153], v[184:185]
	v_pk_mul_f32 v[154:155], v[154:155], v[184:185]
	v_pk_mul_f32 v[156:157], v[156:157], v[184:185]
	v_pk_mul_f32 v[158:159], v[158:159], v[184:185]
	v_pk_mul_f32 v[144:145], v[144:145], v[236:237]
	v_pk_mul_f32 v[146:147], v[146:147], v[238:239]
	v_pk_mul_f32 v[148:149], v[148:149], v[240:241]
	v_pk_mul_f32 v[150:151], v[150:151], v[242:243]
	v_pk_mul_f32 v[152:153], v[152:153], v[244:245]
	v_pk_mul_f32 v[154:155], v[154:155], v[246:247]
	v_pk_mul_f32 v[156:157], v[156:157], v[248:249]
	v_pk_mul_f32 v[158:159], v[158:159], v[250:251]
	v_add_u32_e32 v181, 0x4000000, v178
	global_store_dwordx4 v181, v[144:147], s[76:77]
	global_store_dwordx4 v181, v[148:151], s[76:77] offset:16
	global_store_dwordx4 v181, v[152:155], s[76:77] offset:2048
	global_store_dwordx4 v181, v[156:159], s[76:77] offset:2064
	s_nop 1
